# hand-off with priority staging, closing barrier 4 MFMAs early (two pairs)
# baseline (speedup 1.0000x reference)
.LBB0_183:
	s_ashr_i32 s13, s12, 31
	s_lshl_b64 s[24:25], s[12:13], 19
	s_add_u32 s24, s80, s24
	s_addc_u32 s25, s81, s25
	s_and_b64 s[30:31], s[4:5], exec
	s_cselect_b32 s13, s25, s45
	s_cselect_b32 s66, s24, s44
	s_ashr_i32 s11, s10, 31
	s_lshl_b64 s[30:31], s[10:11], 19
	s_add_u32 s30, s52, s30
	s_addc_u32 s31, s53, s31
	s_and_b64 s[48:49], s[4:5], exec
	s_cselect_b32 s11, s31, s47
	s_cselect_b32 s67, s30, s46
	s_add_u32 s44, s44, 0x40080
	s_addc_u32 s45, s45, 0
	s_add_u32 s68, s46, 0x100
	s_addc_u32 s69, s47, 0
	s_mov_b32 s70, -2
	ds_read_b128 v[140:143], v147
	ds_read_b128 v[150:153], v147 offset:1024
	ds_read_b128 v[154:157], v147 offset:2048
	ds_read_b128 v[158:161], v147 offset:3072
	ds_read_b128 v[162:165], v148
	ds_read_b128 v[166:169], v148 offset:1024
	ds_read_b128 v[170:173], v148 offset:2048
	ds_read_b128 v[174:177], v148 offset:3072
	s_add_u32 s18, s44, 0xfffc0080
	s_addc_u32 s19, s45, -1
	s_cmp_eq_u32 s70, 12
	s_cselect_b32 s49, s13, s19
	s_cselect_b32 s48, s66, s18
	s_cselect_b32 s47, s11, s69
	s_cselect_b32 s46, s67, s68
	v_lshl_add_u64 v[178:179], s[44:45], 0, v[132:133]
	s_add_i32 m0, s37, 0xc000
	ds_read_b128 v[184:187], v149
	ds_read_b128 v[188:191], v149 offset:1024
	ds_read_b128 v[192:195], v149 offset:2048
	ds_read_b128 v[196:199], v149 offset:3072
	ds_read_b128 v[200:203], v149 offset:4096
	ds_read_b128 v[204:207], v149 offset:5120
	ds_read_b128 v[208:211], v149 offset:6144
	ds_read_b128 v[212:215], v149 offset:7168
	global_load_lds_dwordx4 v[178:179], off
	v_lshl_add_u64 v[178:179], s[44:45], 0, v[134:135]
	s_add_i32 m0, s37, 0xe000
	s_nop 0
	global_load_lds_dwordx4 v[178:179], off
	s_waitcnt vmcnt(8)
	s_waitcnt lgkmcnt(0)
	s_barrier
	s_waitcnt lgkmcnt(0)
	v_mfma_f32_16x16x32_bf16 v[124:127], v[140:143], v[184:187], 0
	v_mfma_f32_16x16x32_bf16 v[124:127], v[150:153], v[188:191], v[124:127]
	v_mfma_f32_16x16x32_bf16 v[120:123], v[154:157], v[184:187], 0
	v_mfma_f32_16x16x32_bf16 v[120:123], v[158:161], v[188:191], v[120:123]
	s_setprio 1
	v_mfma_f32_16x16x32_bf16 v[108:111], v[140:143], v[192:195], 0
	v_mfma_f32_16x16x32_bf16 v[108:111], v[150:153], v[196:199], v[108:111]
	v_mfma_f32_16x16x32_bf16 v[104:107], v[154:157], v[192:195], 0
	v_mfma_f32_16x16x32_bf16 v[104:107], v[158:161], v[196:199], v[104:107]
	v_mfma_f32_16x16x32_bf16 v[92:95], v[140:143], v[200:203], 0
	v_mfma_f32_16x16x32_bf16 v[92:95], v[150:153], v[204:207], v[92:95]
	v_mfma_f32_16x16x32_bf16 v[88:91], v[154:157], v[200:203], 0
	v_mfma_f32_16x16x32_bf16 v[88:91], v[158:161], v[204:207], v[88:91]
	v_mfma_f32_16x16x32_bf16 v[76:79], v[140:143], v[208:211], 0
	v_mfma_f32_16x16x32_bf16 v[76:79], v[150:153], v[212:215], v[76:79]
	v_mfma_f32_16x16x32_bf16 v[72:75], v[154:157], v[208:211], 0
	v_mfma_f32_16x16x32_bf16 v[72:75], v[158:161], v[212:215], v[72:75]
	v_mfma_f32_16x16x32_bf16 v[116:119], v[162:165], v[184:187], 0
	v_mfma_f32_16x16x32_bf16 v[116:119], v[166:169], v[188:191], v[116:119]
	v_mfma_f32_16x16x32_bf16 v[112:115], v[170:173], v[184:187], 0
	v_mfma_f32_16x16x32_bf16 v[112:115], v[174:177], v[188:191], v[112:115]
	v_mfma_f32_16x16x32_bf16 v[100:103], v[162:165], v[192:195], 0
	v_mfma_f32_16x16x32_bf16 v[100:103], v[166:169], v[196:199], v[100:103]
	v_mfma_f32_16x16x32_bf16 v[96:99], v[170:173], v[192:195], 0
	v_mfma_f32_16x16x32_bf16 v[96:99], v[174:177], v[196:199], v[96:99]
	v_mfma_f32_16x16x32_bf16 v[84:87], v[162:165], v[200:203], 0
	v_mfma_f32_16x16x32_bf16 v[84:87], v[166:169], v[204:207], v[84:87]
	v_mfma_f32_16x16x32_bf16 v[80:83], v[170:173], v[200:203], 0
	v_mfma_f32_16x16x32_bf16 v[80:83], v[174:177], v[204:207], v[80:83]
	s_barrier
	v_mfma_f32_16x16x32_bf16 v[68:71], v[162:165], v[208:211], 0
	v_mfma_f32_16x16x32_bf16 v[68:71], v[166:169], v[212:215], v[68:71]
	v_mfma_f32_16x16x32_bf16 v[64:67], v[170:173], v[208:211], 0
	v_mfma_f32_16x16x32_bf16 v[64:67], v[174:177], v[212:215], v[64:67]
	s_setprio 0
	s_add_i32 s18, s62, s54
	v_lshl_add_u64 v[178:179], s[46:47], 0, v[130:131]
	s_mov_b32 m0, s18
	ds_read_b128 v[184:187], v149 offset:16384
	ds_read_b128 v[188:191], v149 offset:17408
	ds_read_b128 v[192:195], v149 offset:18432
	ds_read_b128 v[196:199], v149 offset:19456
	ds_read_b128 v[200:203], v149 offset:20480
	ds_read_b128 v[204:207], v149 offset:21504
	ds_read_b128 v[208:211], v149 offset:22528
	ds_read_b128 v[212:215], v149 offset:23552
	global_load_lds_dwordx4 v[178:179], off
	s_add_i32 m0, s18, 0x2000
	s_add_u32 s72, s46, 0x40000
	v_lshl_add_u64 v[216:217], s[46:47], 0, v[128:129]
	s_addc_u32 s73, s47, 0
	s_add_i32 s18, s63, s54
	global_load_lds_dwordx4 v[216:217], off
	v_lshl_add_u64 v[218:219], s[72:73], 0, v[130:131]
	s_mov_b32 m0, s18
	v_lshl_add_u64 v[220:221], s[48:49], 0, v[128:129]
	global_load_lds_dwordx4 v[218:219], off
	v_lshl_add_u64 v[218:219], s[72:73], 0, v[128:129]
	s_add_i32 m0, s18, 0x2000
	s_nop 0
	global_load_lds_dwordx4 v[218:219], off
	v_lshl_add_u64 v[218:219], s[48:49], 0, v[130:131]
	s_mov_b32 m0, s37
	s_nop 0
	global_load_lds_dwordx4 v[218:219], off
	s_mov_b32 m0, s56
	s_nop 0
	global_load_lds_dwordx4 v[220:221], off
	s_waitcnt vmcnt(8)
	s_waitcnt lgkmcnt(0)
	s_barrier
	s_waitcnt lgkmcnt(0)
	v_mfma_f32_16x16x32_bf16 v[60:63], v[140:143], v[184:187], 0
	v_mfma_f32_16x16x32_bf16 v[60:63], v[150:153], v[188:191], v[60:63]
	v_mfma_f32_16x16x32_bf16 v[56:59], v[154:157], v[184:187], 0
	v_mfma_f32_16x16x32_bf16 v[56:59], v[158:161], v[188:191], v[56:59]
	s_setprio 1
	v_mfma_f32_16x16x32_bf16 v[44:47], v[140:143], v[192:195], 0
	v_mfma_f32_16x16x32_bf16 v[44:47], v[150:153], v[196:199], v[44:47]
	v_mfma_f32_16x16x32_bf16 v[40:43], v[154:157], v[192:195], 0
	v_mfma_f32_16x16x32_bf16 v[40:43], v[158:161], v[196:199], v[40:43]
	v_mfma_f32_16x16x32_bf16 v[28:31], v[140:143], v[200:203], 0
	v_mfma_f32_16x16x32_bf16 v[28:31], v[150:153], v[204:207], v[28:31]
	v_mfma_f32_16x16x32_bf16 v[24:27], v[154:157], v[200:203], 0
	v_mfma_f32_16x16x32_bf16 v[24:27], v[158:161], v[204:207], v[24:27]
	v_mfma_f32_16x16x32_bf16 v[12:15], v[140:143], v[208:211], 0
	v_mfma_f32_16x16x32_bf16 v[12:15], v[150:153], v[212:215], v[12:15]
	v_mfma_f32_16x16x32_bf16 v[8:11], v[154:157], v[208:211], 0
	v_mfma_f32_16x16x32_bf16 v[8:11], v[158:161], v[212:215], v[8:11]
	v_mfma_f32_16x16x32_bf16 v[52:55], v[162:165], v[184:187], 0
	v_mfma_f32_16x16x32_bf16 v[52:55], v[166:169], v[188:191], v[52:55]
	v_mfma_f32_16x16x32_bf16 v[48:51], v[170:173], v[184:187], 0
	v_mfma_f32_16x16x32_bf16 v[48:51], v[174:177], v[188:191], v[48:51]
	v_mfma_f32_16x16x32_bf16 v[36:39], v[162:165], v[192:195], 0
	v_mfma_f32_16x16x32_bf16 v[36:39], v[166:169], v[196:199], v[36:39]
	v_mfma_f32_16x16x32_bf16 v[32:35], v[170:173], v[192:195], 0
	v_mfma_f32_16x16x32_bf16 v[32:35], v[174:177], v[196:199], v[32:35]
	v_mfma_f32_16x16x32_bf16 v[20:23], v[162:165], v[200:203], 0
	v_mfma_f32_16x16x32_bf16 v[20:23], v[166:169], v[204:207], v[20:23]
	v_mfma_f32_16x16x32_bf16 v[16:19], v[170:173], v[200:203], 0
	v_mfma_f32_16x16x32_bf16 v[16:19], v[174:177], v[204:207], v[16:19]
	s_barrier
	v_mfma_f32_16x16x32_bf16 v[4:7], v[162:165], v[208:211], 0
	v_mfma_f32_16x16x32_bf16 v[4:7], v[166:169], v[212:215], v[4:7]
	v_mfma_f32_16x16x32_bf16 v[0:3], v[170:173], v[208:211], 0
	v_mfma_f32_16x16x32_bf16 v[0:3], v[174:177], v[212:215], v[0:3]
	s_setprio 0
	s_branch .Lmid_gemm0
.LBB0_184:
	ds_read_b128 v[140:143], v147
	ds_read_b128 v[150:153], v147 offset:1024
	ds_read_b128 v[154:157], v147 offset:2048
	ds_read_b128 v[158:161], v147 offset:3072
	ds_read_b128 v[162:165], v148
	ds_read_b128 v[166:169], v148 offset:1024
	ds_read_b128 v[170:173], v148 offset:2048
	ds_read_b128 v[174:177], v148 offset:3072
	s_add_u32 s18, s44, 0xfffc0080
	s_addc_u32 s19, s45, -1
	s_cmp_eq_u32 s70, 12
	s_cselect_b32 s49, s13, s19
	s_cselect_b32 s48, s66, s18
	s_cselect_b32 s47, s11, s69
	s_cselect_b32 s46, s67, s68
	v_lshl_add_u64 v[178:179], s[44:45], 0, v[132:133]
	s_add_i32 m0, s37, 0xc000
	ds_read_b128 v[184:187], v149
	ds_read_b128 v[188:191], v149 offset:1024
	ds_read_b128 v[192:195], v149 offset:2048
	ds_read_b128 v[196:199], v149 offset:3072
	ds_read_b128 v[200:203], v149 offset:4096
	ds_read_b128 v[204:207], v149 offset:5120
	ds_read_b128 v[208:211], v149 offset:6144
	ds_read_b128 v[212:215], v149 offset:7168
	global_load_lds_dwordx4 v[178:179], off
	v_lshl_add_u64 v[178:179], s[44:45], 0, v[134:135]
	s_add_i32 m0, s37, 0xe000
	s_nop 0
	global_load_lds_dwordx4 v[178:179], off
	s_waitcnt vmcnt(8)
	s_waitcnt lgkmcnt(0)
	s_barrier
	s_waitcnt lgkmcnt(0)
	v_mfma_f32_16x16x32_bf16 v[124:127], v[140:143], v[184:187], v[124:127]
	v_mfma_f32_16x16x32_bf16 v[124:127], v[150:153], v[188:191], v[124:127]
	v_mfma_f32_16x16x32_bf16 v[120:123], v[154:157], v[184:187], v[120:123]
	v_mfma_f32_16x16x32_bf16 v[120:123], v[158:161], v[188:191], v[120:123]
	s_setprio 1
	v_mfma_f32_16x16x32_bf16 v[108:111], v[140:143], v[192:195], v[108:111]
	v_mfma_f32_16x16x32_bf16 v[108:111], v[150:153], v[196:199], v[108:111]
	v_mfma_f32_16x16x32_bf16 v[104:107], v[154:157], v[192:195], v[104:107]
	v_mfma_f32_16x16x32_bf16 v[104:107], v[158:161], v[196:199], v[104:107]
	v_mfma_f32_16x16x32_bf16 v[92:95], v[140:143], v[200:203], v[92:95]
	v_mfma_f32_16x16x32_bf16 v[92:95], v[150:153], v[204:207], v[92:95]
	v_mfma_f32_16x16x32_bf16 v[88:91], v[154:157], v[200:203], v[88:91]
	v_mfma_f32_16x16x32_bf16 v[88:91], v[158:161], v[204:207], v[88:91]
	v_mfma_f32_16x16x32_bf16 v[76:79], v[140:143], v[208:211], v[76:79]
	v_mfma_f32_16x16x32_bf16 v[76:79], v[150:153], v[212:215], v[76:79]
	v_mfma_f32_16x16x32_bf16 v[72:75], v[154:157], v[208:211], v[72:75]
	v_mfma_f32_16x16x32_bf16 v[72:75], v[158:161], v[212:215], v[72:75]
	v_mfma_f32_16x16x32_bf16 v[116:119], v[162:165], v[184:187], v[116:119]
	v_mfma_f32_16x16x32_bf16 v[116:119], v[166:169], v[188:191], v[116:119]
	v_mfma_f32_16x16x32_bf16 v[112:115], v[170:173], v[184:187], v[112:115]
	v_mfma_f32_16x16x32_bf16 v[112:115], v[174:177], v[188:191], v[112:115]
	v_mfma_f32_16x16x32_bf16 v[100:103], v[162:165], v[192:195], v[100:103]
	v_mfma_f32_16x16x32_bf16 v[100:103], v[166:169], v[196:199], v[100:103]
	v_mfma_f32_16x16x32_bf16 v[96:99], v[170:173], v[192:195], v[96:99]
	v_mfma_f32_16x16x32_bf16 v[96:99], v[174:177], v[196:199], v[96:99]
	v_mfma_f32_16x16x32_bf16 v[84:87], v[162:165], v[200:203], v[84:87]
	v_mfma_f32_16x16x32_bf16 v[84:87], v[166:169], v[204:207], v[84:87]
	v_mfma_f32_16x16x32_bf16 v[80:83], v[170:173], v[200:203], v[80:83]
	v_mfma_f32_16x16x32_bf16 v[80:83], v[174:177], v[204:207], v[80:83]
	s_barrier
	v_mfma_f32_16x16x32_bf16 v[68:71], v[162:165], v[208:211], v[68:71]
	v_mfma_f32_16x16x32_bf16 v[68:71], v[166:169], v[212:215], v[68:71]
	v_mfma_f32_16x16x32_bf16 v[64:67], v[170:173], v[208:211], v[64:67]
	v_mfma_f32_16x16x32_bf16 v[64:67], v[174:177], v[212:215], v[64:67]
	s_setprio 0
	s_add_i32 s18, s62, s54
	v_lshl_add_u64 v[178:179], s[46:47], 0, v[130:131]
	s_mov_b32 m0, s18
	ds_read_b128 v[184:187], v149 offset:16384
	ds_read_b128 v[188:191], v149 offset:17408
	ds_read_b128 v[192:195], v149 offset:18432
	ds_read_b128 v[196:199], v149 offset:19456
	ds_read_b128 v[200:203], v149 offset:20480
	ds_read_b128 v[204:207], v149 offset:21504
	ds_read_b128 v[208:211], v149 offset:22528
	ds_read_b128 v[212:215], v149 offset:23552
	global_load_lds_dwordx4 v[178:179], off
	s_add_i32 m0, s18, 0x2000
	s_add_u32 s72, s46, 0x40000
	v_lshl_add_u64 v[216:217], s[46:47], 0, v[128:129]
	s_addc_u32 s73, s47, 0
	s_add_i32 s18, s63, s54
	global_load_lds_dwordx4 v[216:217], off
	v_lshl_add_u64 v[218:219], s[72:73], 0, v[130:131]
	s_mov_b32 m0, s18
	v_lshl_add_u64 v[220:221], s[48:49], 0, v[128:129]
	global_load_lds_dwordx4 v[218:219], off
	v_lshl_add_u64 v[218:219], s[72:73], 0, v[128:129]
	s_add_i32 m0, s18, 0x2000
	s_nop 0
	global_load_lds_dwordx4 v[218:219], off
	v_lshl_add_u64 v[218:219], s[48:49], 0, v[130:131]
	s_mov_b32 m0, s37
	s_nop 0
	global_load_lds_dwordx4 v[218:219], off
	s_mov_b32 m0, s56
	s_nop 0
	global_load_lds_dwordx4 v[220:221], off
	s_waitcnt vmcnt(8)
	s_waitcnt lgkmcnt(0)
	s_barrier
	s_waitcnt lgkmcnt(0)
	v_mfma_f32_16x16x32_bf16 v[60:63], v[140:143], v[184:187], v[60:63]
	v_mfma_f32_16x16x32_bf16 v[60:63], v[150:153], v[188:191], v[60:63]
	v_mfma_f32_16x16x32_bf16 v[56:59], v[154:157], v[184:187], v[56:59]
	v_mfma_f32_16x16x32_bf16 v[56:59], v[158:161], v[188:191], v[56:59]
	s_setprio 1
	v_mfma_f32_16x16x32_bf16 v[44:47], v[140:143], v[192:195], v[44:47]
	v_mfma_f32_16x16x32_bf16 v[44:47], v[150:153], v[196:199], v[44:47]
	v_mfma_f32_16x16x32_bf16 v[40:43], v[154:157], v[192:195], v[40:43]
	v_mfma_f32_16x16x32_bf16 v[40:43], v[158:161], v[196:199], v[40:43]
	v_mfma_f32_16x16x32_bf16 v[28:31], v[140:143], v[200:203], v[28:31]
	v_mfma_f32_16x16x32_bf16 v[28:31], v[150:153], v[204:207], v[28:31]
	v_mfma_f32_16x16x32_bf16 v[24:27], v[154:157], v[200:203], v[24:27]
	v_mfma_f32_16x16x32_bf16 v[24:27], v[158:161], v[204:207], v[24:27]
	v_mfma_f32_16x16x32_bf16 v[12:15], v[140:143], v[208:211], v[12:15]
	v_mfma_f32_16x16x32_bf16 v[12:15], v[150:153], v[212:215], v[12:15]
	v_mfma_f32_16x16x32_bf16 v[8:11], v[154:157], v[208:211], v[8:11]
	v_mfma_f32_16x16x32_bf16 v[8:11], v[158:161], v[212:215], v[8:11]
	v_mfma_f32_16x16x32_bf16 v[52:55], v[162:165], v[184:187], v[52:55]
	v_mfma_f32_16x16x32_bf16 v[52:55], v[166:169], v[188:191], v[52:55]
	v_mfma_f32_16x16x32_bf16 v[48:51], v[170:173], v[184:187], v[48:51]
	v_mfma_f32_16x16x32_bf16 v[48:51], v[174:177], v[188:191], v[48:51]
	v_mfma_f32_16x16x32_bf16 v[36:39], v[162:165], v[192:195], v[36:39]
	v_mfma_f32_16x16x32_bf16 v[36:39], v[166:169], v[196:199], v[36:39]
	v_mfma_f32_16x16x32_bf16 v[32:35], v[170:173], v[192:195], v[32:35]
	v_mfma_f32_16x16x32_bf16 v[32:35], v[174:177], v[196:199], v[32:35]
	v_mfma_f32_16x16x32_bf16 v[20:23], v[162:165], v[200:203], v[20:23]
	v_mfma_f32_16x16x32_bf16 v[20:23], v[166:169], v[204:207], v[20:23]
	v_mfma_f32_16x16x32_bf16 v[16:19], v[170:173], v[200:203], v[16:19]
	v_mfma_f32_16x16x32_bf16 v[16:19], v[174:177], v[204:207], v[16:19]
	s_barrier
	v_mfma_f32_16x16x32_bf16 v[4:7], v[162:165], v[208:211], v[4:7]
	v_mfma_f32_16x16x32_bf16 v[4:7], v[166:169], v[212:215], v[4:7]
	v_mfma_f32_16x16x32_bf16 v[0:3], v[170:173], v[208:211], v[0:3]
	v_mfma_f32_16x16x32_bf16 v[0:3], v[174:177], v[212:215], v[0:3]
	s_setprio 0
.Lmid_gemm0:
	s_add_i32 s18, 0, 0x18000
	s_add_i32 s19, 0, 0x1c000
	v_add_u32_e32 v158, s18, v145
	v_add_u32_e32 v174, s19, v145
	ds_read_b128 v[140:143], v158
	ds_read_b128 v[150:153], v158 offset:1024
	ds_read_b128 v[154:157], v158 offset:2048
	ds_read_b128 v[158:161], v158 offset:3072
	ds_read_b128 v[162:165], v174
	ds_read_b128 v[166:169], v174 offset:1024
	ds_read_b128 v[170:173], v174 offset:2048
	ds_read_b128 v[174:177], v174 offset:3072
	s_add_u32 s48, s48, 0x40000
	s_addc_u32 s49, s49, 0
	s_mov_b32 m0, s57
	v_lshl_add_u64 v[222:223], s[48:49], 0, v[130:131]
	ds_read_b128 v[184:187], v149 offset:32768
	ds_read_b128 v[188:191], v149 offset:33792
	ds_read_b128 v[192:195], v149 offset:34816
	ds_read_b128 v[196:199], v149 offset:35840
	ds_read_b128 v[200:203], v149 offset:36864
	ds_read_b128 v[204:207], v149 offset:37888
	ds_read_b128 v[208:211], v149 offset:38912
	ds_read_b128 v[212:215], v149 offset:39936
	global_load_lds_dwordx4 v[222:223], off
	v_lshl_add_u64 v[222:223], s[48:49], 0, v[128:129]
	s_mov_b32 m0, s58
	s_nop 0
	global_load_lds_dwordx4 v[222:223], off
	s_waitcnt vmcnt(8)
	s_waitcnt lgkmcnt(0)
	s_barrier
	s_waitcnt lgkmcnt(0)
	v_mfma_f32_16x16x32_bf16 v[124:127], v[140:143], v[184:187], v[124:127]
	v_mfma_f32_16x16x32_bf16 v[124:127], v[150:153], v[188:191], v[124:127]
	v_mfma_f32_16x16x32_bf16 v[120:123], v[154:157], v[184:187], v[120:123]
	v_mfma_f32_16x16x32_bf16 v[120:123], v[158:161], v[188:191], v[120:123]
	s_setprio 1
	v_mfma_f32_16x16x32_bf16 v[108:111], v[140:143], v[192:195], v[108:111]
	v_mfma_f32_16x16x32_bf16 v[108:111], v[150:153], v[196:199], v[108:111]
	v_mfma_f32_16x16x32_bf16 v[104:107], v[154:157], v[192:195], v[104:107]
	v_mfma_f32_16x16x32_bf16 v[104:107], v[158:161], v[196:199], v[104:107]
	v_mfma_f32_16x16x32_bf16 v[92:95], v[140:143], v[200:203], v[92:95]
	v_mfma_f32_16x16x32_bf16 v[92:95], v[150:153], v[204:207], v[92:95]
	v_mfma_f32_16x16x32_bf16 v[88:91], v[154:157], v[200:203], v[88:91]
	v_mfma_f32_16x16x32_bf16 v[88:91], v[158:161], v[204:207], v[88:91]
	v_mfma_f32_16x16x32_bf16 v[76:79], v[140:143], v[208:211], v[76:79]
	v_mfma_f32_16x16x32_bf16 v[76:79], v[150:153], v[212:215], v[76:79]
	v_mfma_f32_16x16x32_bf16 v[72:75], v[154:157], v[208:211], v[72:75]
	v_mfma_f32_16x16x32_bf16 v[72:75], v[158:161], v[212:215], v[72:75]
	v_mfma_f32_16x16x32_bf16 v[116:119], v[162:165], v[184:187], v[116:119]
	v_mfma_f32_16x16x32_bf16 v[116:119], v[166:169], v[188:191], v[116:119]
	v_mfma_f32_16x16x32_bf16 v[112:115], v[170:173], v[184:187], v[112:115]
	v_mfma_f32_16x16x32_bf16 v[112:115], v[174:177], v[188:191], v[112:115]
	v_mfma_f32_16x16x32_bf16 v[100:103], v[162:165], v[192:195], v[100:103]
	v_mfma_f32_16x16x32_bf16 v[100:103], v[166:169], v[196:199], v[100:103]
	v_mfma_f32_16x16x32_bf16 v[96:99], v[170:173], v[192:195], v[96:99]
	v_mfma_f32_16x16x32_bf16 v[96:99], v[174:177], v[196:199], v[96:99]
	v_mfma_f32_16x16x32_bf16 v[84:87], v[162:165], v[200:203], v[84:87]
	v_mfma_f32_16x16x32_bf16 v[84:87], v[166:169], v[204:207], v[84:87]
	v_mfma_f32_16x16x32_bf16 v[80:83], v[170:173], v[200:203], v[80:83]
	v_mfma_f32_16x16x32_bf16 v[80:83], v[174:177], v[204:207], v[80:83]
	s_barrier
	v_mfma_f32_16x16x32_bf16 v[68:71], v[162:165], v[208:211], v[68:71]
	v_mfma_f32_16x16x32_bf16 v[68:71], v[166:169], v[212:215], v[68:71]
	v_mfma_f32_16x16x32_bf16 v[64:67], v[170:173], v[208:211], v[64:67]
	v_mfma_f32_16x16x32_bf16 v[64:67], v[174:177], v[212:215], v[64:67]
	s_setprio 0
	s_add_i32 s18, s18, s54
	v_lshl_add_u64 v[178:179], v[178:179], 0, s[6:7]
	s_mov_b32 m0, s18
	ds_read_b128 v[184:187], v149 offset:49152
	ds_read_b128 v[188:191], v149 offset:50176
	ds_read_b128 v[192:195], v149 offset:51200
	ds_read_b128 v[196:199], v149 offset:52224
	ds_read_b128 v[200:203], v149 offset:53248
	ds_read_b128 v[204:207], v149 offset:54272
	ds_read_b128 v[208:211], v149 offset:55296
	ds_read_b128 v[212:215], v149 offset:56320
	global_load_lds_dwordx4 v[178:179], off
	s_add_i32 m0, s18, 0x2000
	s_add_u32 s46, s46, 0x40080
	v_lshl_add_u64 v[178:179], v[216:217], 0, s[6:7]
	s_addc_u32 s47, s47, 0
	s_add_i32 s18, s19, s54
	global_load_lds_dwordx4 v[178:179], off
	v_lshl_add_u64 v[178:179], s[46:47], 0, v[130:131]
	s_mov_b32 m0, s18
	s_nop 0
	global_load_lds_dwordx4 v[178:179], off
	v_lshl_add_u64 v[178:179], s[46:47], 0, v[128:129]
	s_add_i32 m0, s18, 0x2000
	s_nop 0
	global_load_lds_dwordx4 v[178:179], off
	v_lshl_add_u64 v[178:179], v[218:219], 0, s[6:7]
	s_mov_b32 m0, s60
	s_nop 0
	global_load_lds_dwordx4 v[178:179], off
	v_lshl_add_u64 v[178:179], v[220:221], 0, s[6:7]
	s_mov_b32 m0, s61
	s_nop 0
	global_load_lds_dwordx4 v[178:179], off
	s_waitcnt vmcnt(8)
	s_waitcnt lgkmcnt(0)
	s_barrier
	s_waitcnt lgkmcnt(0)
	v_mfma_f32_16x16x32_bf16 v[60:63], v[140:143], v[184:187], v[60:63]
	v_mfma_f32_16x16x32_bf16 v[60:63], v[150:153], v[188:191], v[60:63]
	v_mfma_f32_16x16x32_bf16 v[56:59], v[154:157], v[184:187], v[56:59]
	v_mfma_f32_16x16x32_bf16 v[56:59], v[158:161], v[188:191], v[56:59]
	s_setprio 1
	v_mfma_f32_16x16x32_bf16 v[44:47], v[140:143], v[192:195], v[44:47]
	v_mfma_f32_16x16x32_bf16 v[44:47], v[150:153], v[196:199], v[44:47]
	v_mfma_f32_16x16x32_bf16 v[40:43], v[154:157], v[192:195], v[40:43]
	v_mfma_f32_16x16x32_bf16 v[40:43], v[158:161], v[196:199], v[40:43]
	v_mfma_f32_16x16x32_bf16 v[28:31], v[140:143], v[200:203], v[28:31]
	v_mfma_f32_16x16x32_bf16 v[28:31], v[150:153], v[204:207], v[28:31]
	v_mfma_f32_16x16x32_bf16 v[24:27], v[154:157], v[200:203], v[24:27]
	v_mfma_f32_16x16x32_bf16 v[24:27], v[158:161], v[204:207], v[24:27]
	v_mfma_f32_16x16x32_bf16 v[12:15], v[140:143], v[208:211], v[12:15]
	v_mfma_f32_16x16x32_bf16 v[12:15], v[150:153], v[212:215], v[12:15]
	v_mfma_f32_16x16x32_bf16 v[8:11], v[154:157], v[208:211], v[8:11]
	v_mfma_f32_16x16x32_bf16 v[8:11], v[158:161], v[212:215], v[8:11]
	v_mfma_f32_16x16x32_bf16 v[52:55], v[162:165], v[184:187], v[52:55]
	v_mfma_f32_16x16x32_bf16 v[52:55], v[166:169], v[188:191], v[52:55]
	v_mfma_f32_16x16x32_bf16 v[48:51], v[170:173], v[184:187], v[48:51]
	v_mfma_f32_16x16x32_bf16 v[48:51], v[174:177], v[188:191], v[48:51]
	v_mfma_f32_16x16x32_bf16 v[36:39], v[162:165], v[192:195], v[36:39]
	v_mfma_f32_16x16x32_bf16 v[36:39], v[166:169], v[196:199], v[36:39]
	v_mfma_f32_16x16x32_bf16 v[32:35], v[170:173], v[192:195], v[32:35]
	v_mfma_f32_16x16x32_bf16 v[32:35], v[174:177], v[196:199], v[32:35]
	v_mfma_f32_16x16x32_bf16 v[20:23], v[162:165], v[200:203], v[20:23]
	v_mfma_f32_16x16x32_bf16 v[20:23], v[166:169], v[204:207], v[20:23]
	v_mfma_f32_16x16x32_bf16 v[16:19], v[170:173], v[200:203], v[16:19]
	v_mfma_f32_16x16x32_bf16 v[16:19], v[174:177], v[204:207], v[16:19]
	s_barrier
	v_mfma_f32_16x16x32_bf16 v[4:7], v[162:165], v[208:211], v[4:7]
	v_mfma_f32_16x16x32_bf16 v[4:7], v[166:169], v[212:215], v[4:7]
	v_mfma_f32_16x16x32_bf16 v[0:3], v[170:173], v[208:211], v[0:3]
	v_mfma_f32_16x16x32_bf16 v[0:3], v[174:177], v[212:215], v[0:3]
	s_setprio 0
	s_add_i32 s70, s70, 2
	s_add_u32 s44, s44, 0x100
	s_addc_u32 s45, s45, 0
	s_add_u32 s68, s68, 0x100
	s_addc_u32 s69, s69, 0
	s_cmp_gt_u32 s70, 13
	s_cbranch_scc0 .LBB0_184
	s_and_b64 vcc, exec, s[8:9]
	s_cbranch_vccz .LBB0_187
	s_barrier

.LBB0_263:
	s_add_u32 s84, s54, 0x100
	s_addc_u32 s85, s55, 0
	s_mov_b32 s86, -2
	ds_read_b128 v[152:155], v149
	ds_read_b128 v[156:159], v149 offset:1024
	ds_read_b128 v[160:163], v149 offset:2048
	ds_read_b128 v[164:167], v149 offset:3072
	ds_read_b128 v[168:171], v150
	ds_read_b128 v[172:175], v150 offset:1024
	ds_read_b128 v[176:179], v150 offset:2048
	ds_read_b128 v[184:187], v150 offset:3072
	s_add_u32 s54, s52, 0x100
	s_addc_u32 s55, s53, 0
	s_cmp_eq_u32 s86, 40
	s_cselect_b32 s59, s7, s55
	s_cselect_b32 s58, s6, s54
	s_cselect_b32 s57, s49, s85
	s_cselect_b32 s56, s48, s84
	v_lshl_add_u64 v[144:145], s[52:53], 0, v[136:137]
	s_add_i32 m0, s63, 0xc000
	ds_read_b128 v[188:191], v151
	ds_read_b128 v[192:195], v151 offset:1024
	ds_read_b128 v[196:199], v151 offset:2048
	ds_read_b128 v[200:203], v151 offset:3072
	ds_read_b128 v[204:207], v151 offset:4096
	ds_read_b128 v[208:211], v151 offset:5120
	ds_read_b128 v[212:215], v151 offset:6144
	ds_read_b128 v[216:219], v151 offset:7168
	global_load_lds_dwordx4 v[144:145], off
	v_lshl_add_u64 v[144:145], s[52:53], 0, v[138:139]
	s_add_i32 m0, s63, 0xe000
	s_nop 0
	global_load_lds_dwordx4 v[144:145], off
	s_waitcnt vmcnt(8)
	s_waitcnt lgkmcnt(0)
	s_barrier
	s_waitcnt lgkmcnt(0)
	v_mfma_f32_16x16x32_bf16 v[124:127], v[152:155], v[188:191], 0
	v_mfma_f32_16x16x32_bf16 v[124:127], v[156:159], v[192:195], v[124:127]
	v_mfma_f32_16x16x32_bf16 v[120:123], v[160:163], v[188:191], 0
	v_mfma_f32_16x16x32_bf16 v[120:123], v[164:167], v[192:195], v[120:123]
	s_setprio 1
	v_mfma_f32_16x16x32_bf16 v[116:119], v[152:155], v[196:199], 0
	v_mfma_f32_16x16x32_bf16 v[116:119], v[156:159], v[200:203], v[116:119]
	v_mfma_f32_16x16x32_bf16 v[108:111], v[160:163], v[196:199], 0
	v_mfma_f32_16x16x32_bf16 v[108:111], v[164:167], v[200:203], v[108:111]
	v_mfma_f32_16x16x32_bf16 v[100:103], v[152:155], v[204:207], 0
	v_mfma_f32_16x16x32_bf16 v[100:103], v[156:159], v[208:211], v[100:103]
	v_mfma_f32_16x16x32_bf16 v[92:95], v[160:163], v[204:207], 0
	v_mfma_f32_16x16x32_bf16 v[92:95], v[164:167], v[208:211], v[92:95]
	v_mfma_f32_16x16x32_bf16 v[84:87], v[152:155], v[212:215], 0
	v_mfma_f32_16x16x32_bf16 v[84:87], v[156:159], v[216:219], v[84:87]
	v_mfma_f32_16x16x32_bf16 v[76:79], v[160:163], v[212:215], 0
	v_mfma_f32_16x16x32_bf16 v[76:79], v[164:167], v[216:219], v[76:79]
	v_mfma_f32_16x16x32_bf16 v[112:115], v[168:171], v[188:191], 0
	v_mfma_f32_16x16x32_bf16 v[112:115], v[172:175], v[192:195], v[112:115]
	v_mfma_f32_16x16x32_bf16 v[104:107], v[176:179], v[188:191], 0
	v_mfma_f32_16x16x32_bf16 v[104:107], v[184:187], v[192:195], v[104:107]
	v_mfma_f32_16x16x32_bf16 v[96:99], v[168:171], v[196:199], 0
	v_mfma_f32_16x16x32_bf16 v[96:99], v[172:175], v[200:203], v[96:99]
	v_mfma_f32_16x16x32_bf16 v[88:91], v[176:179], v[196:199], 0
	v_mfma_f32_16x16x32_bf16 v[88:91], v[184:187], v[200:203], v[88:91]
	v_mfma_f32_16x16x32_bf16 v[80:83], v[168:171], v[204:207], 0
	v_mfma_f32_16x16x32_bf16 v[80:83], v[172:175], v[208:211], v[80:83]
	v_mfma_f32_16x16x32_bf16 v[72:75], v[176:179], v[204:207], 0
	v_mfma_f32_16x16x32_bf16 v[72:75], v[184:187], v[208:211], v[72:75]
	s_barrier
	v_mfma_f32_16x16x32_bf16 v[68:71], v[168:171], v[212:215], 0
	v_mfma_f32_16x16x32_bf16 v[68:71], v[172:175], v[216:219], v[68:71]
	v_mfma_f32_16x16x32_bf16 v[64:67], v[176:179], v[212:215], 0
	v_mfma_f32_16x16x32_bf16 v[64:67], v[184:187], v[216:219], v[64:67]
	s_setprio 0
	s_add_i32 s18, s70, s62
	v_lshl_add_u64 v[144:145], s[56:57], 0, v[130:131]
	s_mov_b32 m0, s18
	ds_read_b128 v[188:191], v151 offset:16384
	ds_read_b128 v[192:195], v151 offset:17408
	ds_read_b128 v[196:199], v151 offset:18432
	ds_read_b128 v[200:203], v151 offset:19456
	ds_read_b128 v[204:207], v151 offset:20480
	ds_read_b128 v[208:211], v151 offset:21504
	ds_read_b128 v[212:215], v151 offset:22528
	ds_read_b128 v[216:219], v151 offset:23552
	global_load_lds_dwordx4 v[144:145], off
	s_add_i32 m0, s18, 0x2000
	s_add_u32 s52, s56, 0xb0000
	v_lshl_add_u64 v[220:221], s[56:57], 0, v[134:135]
	s_addc_u32 s53, s57, 0
	s_add_i32 s18, s71, s62
	global_load_lds_dwordx4 v[220:221], off
	v_lshl_add_u64 v[222:223], s[52:53], 0, v[130:131]
	s_mov_b32 m0, s18
	v_lshl_add_u64 v[224:225], s[58:59], 0, v[132:133]
	global_load_lds_dwordx4 v[222:223], off
	v_lshl_add_u64 v[222:223], s[52:53], 0, v[134:135]
	s_add_i32 m0, s18, 0x2000
	s_nop 0
	global_load_lds_dwordx4 v[222:223], off
	v_lshl_add_u64 v[222:223], s[58:59], 0, v[128:129]
	s_mov_b32 m0, s63
	s_nop 0
	global_load_lds_dwordx4 v[222:223], off
	s_mov_b32 m0, s64
	s_nop 0
	global_load_lds_dwordx4 v[224:225], off
	s_waitcnt vmcnt(8)
	s_waitcnt lgkmcnt(0)
	s_barrier
	s_waitcnt lgkmcnt(0)
	v_mfma_f32_16x16x32_bf16 v[60:63], v[152:155], v[188:191], 0
	v_mfma_f32_16x16x32_bf16 v[60:63], v[156:159], v[192:195], v[60:63]
	v_mfma_f32_16x16x32_bf16 v[56:59], v[160:163], v[188:191], 0
	v_mfma_f32_16x16x32_bf16 v[56:59], v[164:167], v[192:195], v[56:59]
	s_setprio 1
	v_mfma_f32_16x16x32_bf16 v[52:55], v[152:155], v[196:199], 0
	v_mfma_f32_16x16x32_bf16 v[52:55], v[156:159], v[200:203], v[52:55]
	v_mfma_f32_16x16x32_bf16 v[44:47], v[160:163], v[196:199], 0
	v_mfma_f32_16x16x32_bf16 v[44:47], v[164:167], v[200:203], v[44:47]
	v_mfma_f32_16x16x32_bf16 v[36:39], v[152:155], v[204:207], 0
	v_mfma_f32_16x16x32_bf16 v[36:39], v[156:159], v[208:211], v[36:39]
	v_mfma_f32_16x16x32_bf16 v[28:31], v[160:163], v[204:207], 0
	v_mfma_f32_16x16x32_bf16 v[28:31], v[164:167], v[208:211], v[28:31]
	v_mfma_f32_16x16x32_bf16 v[20:23], v[152:155], v[212:215], 0
	v_mfma_f32_16x16x32_bf16 v[20:23], v[156:159], v[216:219], v[20:23]
	v_mfma_f32_16x16x32_bf16 v[12:15], v[160:163], v[212:215], 0
	v_mfma_f32_16x16x32_bf16 v[12:15], v[164:167], v[216:219], v[12:15]
	v_mfma_f32_16x16x32_bf16 v[48:51], v[168:171], v[188:191], 0
	v_mfma_f32_16x16x32_bf16 v[48:51], v[172:175], v[192:195], v[48:51]
	v_mfma_f32_16x16x32_bf16 v[40:43], v[176:179], v[188:191], 0
	v_mfma_f32_16x16x32_bf16 v[40:43], v[184:187], v[192:195], v[40:43]
	v_mfma_f32_16x16x32_bf16 v[32:35], v[168:171], v[196:199], 0
	v_mfma_f32_16x16x32_bf16 v[32:35], v[172:175], v[200:203], v[32:35]
	v_mfma_f32_16x16x32_bf16 v[24:27], v[176:179], v[196:199], 0
	v_mfma_f32_16x16x32_bf16 v[24:27], v[184:187], v[200:203], v[24:27]
	v_mfma_f32_16x16x32_bf16 v[16:19], v[168:171], v[204:207], 0
	v_mfma_f32_16x16x32_bf16 v[16:19], v[172:175], v[208:211], v[16:19]
	v_mfma_f32_16x16x32_bf16 v[8:11], v[176:179], v[204:207], 0
	v_mfma_f32_16x16x32_bf16 v[8:11], v[184:187], v[208:211], v[8:11]
	s_barrier
	v_mfma_f32_16x16x32_bf16 v[4:7], v[168:171], v[212:215], 0
	v_mfma_f32_16x16x32_bf16 v[4:7], v[172:175], v[216:219], v[4:7]
	v_mfma_f32_16x16x32_bf16 v[0:3], v[176:179], v[212:215], 0
	v_mfma_f32_16x16x32_bf16 v[0:3], v[184:187], v[216:219], v[0:3]
	s_setprio 0
	s_branch .Lmid_gemm1
.LBB0_264:
	ds_read_b128 v[152:155], v149
	ds_read_b128 v[156:159], v149 offset:1024
	ds_read_b128 v[160:163], v149 offset:2048
	ds_read_b128 v[164:167], v149 offset:3072
	ds_read_b128 v[168:171], v150
	ds_read_b128 v[172:175], v150 offset:1024
	ds_read_b128 v[176:179], v150 offset:2048
	ds_read_b128 v[184:187], v150 offset:3072
	s_add_u32 s54, s52, 0x100
	s_addc_u32 s55, s53, 0
	s_cmp_eq_u32 s86, 40
	s_cselect_b32 s59, s7, s55
	s_cselect_b32 s58, s6, s54
	s_cselect_b32 s57, s49, s85
	s_cselect_b32 s56, s48, s84
	v_lshl_add_u64 v[144:145], s[52:53], 0, v[136:137]
	s_add_i32 m0, s63, 0xc000
	ds_read_b128 v[188:191], v151
	ds_read_b128 v[192:195], v151 offset:1024
	ds_read_b128 v[196:199], v151 offset:2048
	ds_read_b128 v[200:203], v151 offset:3072
	ds_read_b128 v[204:207], v151 offset:4096
	ds_read_b128 v[208:211], v151 offset:5120
	ds_read_b128 v[212:215], v151 offset:6144
	ds_read_b128 v[216:219], v151 offset:7168
	global_load_lds_dwordx4 v[144:145], off
	v_lshl_add_u64 v[144:145], s[52:53], 0, v[138:139]
	s_add_i32 m0, s63, 0xe000
	s_nop 0
	global_load_lds_dwordx4 v[144:145], off
	s_waitcnt vmcnt(8)
	s_waitcnt lgkmcnt(0)
	s_barrier
	s_waitcnt lgkmcnt(0)
	v_mfma_f32_16x16x32_bf16 v[124:127], v[152:155], v[188:191], v[124:127]
	v_mfma_f32_16x16x32_bf16 v[124:127], v[156:159], v[192:195], v[124:127]
	v_mfma_f32_16x16x32_bf16 v[120:123], v[160:163], v[188:191], v[120:123]
	v_mfma_f32_16x16x32_bf16 v[120:123], v[164:167], v[192:195], v[120:123]
	s_setprio 1
	v_mfma_f32_16x16x32_bf16 v[116:119], v[152:155], v[196:199], v[116:119]
	v_mfma_f32_16x16x32_bf16 v[116:119], v[156:159], v[200:203], v[116:119]
	v_mfma_f32_16x16x32_bf16 v[108:111], v[160:163], v[196:199], v[108:111]
	v_mfma_f32_16x16x32_bf16 v[108:111], v[164:167], v[200:203], v[108:111]
	v_mfma_f32_16x16x32_bf16 v[100:103], v[152:155], v[204:207], v[100:103]
	v_mfma_f32_16x16x32_bf16 v[100:103], v[156:159], v[208:211], v[100:103]
	v_mfma_f32_16x16x32_bf16 v[92:95], v[160:163], v[204:207], v[92:95]
	v_mfma_f32_16x16x32_bf16 v[92:95], v[164:167], v[208:211], v[92:95]
	v_mfma_f32_16x16x32_bf16 v[84:87], v[152:155], v[212:215], v[84:87]
	v_mfma_f32_16x16x32_bf16 v[84:87], v[156:159], v[216:219], v[84:87]
	v_mfma_f32_16x16x32_bf16 v[76:79], v[160:163], v[212:215], v[76:79]
	v_mfma_f32_16x16x32_bf16 v[76:79], v[164:167], v[216:219], v[76:79]
	v_mfma_f32_16x16x32_bf16 v[112:115], v[168:171], v[188:191], v[112:115]
	v_mfma_f32_16x16x32_bf16 v[112:115], v[172:175], v[192:195], v[112:115]
	v_mfma_f32_16x16x32_bf16 v[104:107], v[176:179], v[188:191], v[104:107]
	v_mfma_f32_16x16x32_bf16 v[104:107], v[184:187], v[192:195], v[104:107]
	v_mfma_f32_16x16x32_bf16 v[96:99], v[168:171], v[196:199], v[96:99]
	v_mfma_f32_16x16x32_bf16 v[96:99], v[172:175], v[200:203], v[96:99]
	v_mfma_f32_16x16x32_bf16 v[88:91], v[176:179], v[196:199], v[88:91]
	v_mfma_f32_16x16x32_bf16 v[88:91], v[184:187], v[200:203], v[88:91]
	v_mfma_f32_16x16x32_bf16 v[80:83], v[168:171], v[204:207], v[80:83]
	v_mfma_f32_16x16x32_bf16 v[80:83], v[172:175], v[208:211], v[80:83]
	v_mfma_f32_16x16x32_bf16 v[72:75], v[176:179], v[204:207], v[72:75]
	v_mfma_f32_16x16x32_bf16 v[72:75], v[184:187], v[208:211], v[72:75]
	s_barrier
	v_mfma_f32_16x16x32_bf16 v[68:71], v[168:171], v[212:215], v[68:71]
	v_mfma_f32_16x16x32_bf16 v[68:71], v[172:175], v[216:219], v[68:71]
	v_mfma_f32_16x16x32_bf16 v[64:67], v[176:179], v[212:215], v[64:67]
	v_mfma_f32_16x16x32_bf16 v[64:67], v[184:187], v[216:219], v[64:67]
	s_setprio 0
	s_add_i32 s18, s70, s62
	v_lshl_add_u64 v[144:145], s[56:57], 0, v[130:131]
	s_mov_b32 m0, s18
	ds_read_b128 v[188:191], v151 offset:16384
	ds_read_b128 v[192:195], v151 offset:17408
	ds_read_b128 v[196:199], v151 offset:18432
	ds_read_b128 v[200:203], v151 offset:19456
	ds_read_b128 v[204:207], v151 offset:20480
	ds_read_b128 v[208:211], v151 offset:21504
	ds_read_b128 v[212:215], v151 offset:22528
	ds_read_b128 v[216:219], v151 offset:23552
	global_load_lds_dwordx4 v[144:145], off
	s_add_i32 m0, s18, 0x2000
	s_add_u32 s52, s56, 0xb0000
	v_lshl_add_u64 v[220:221], s[56:57], 0, v[134:135]
	s_addc_u32 s53, s57, 0
	s_add_i32 s18, s71, s62
	global_load_lds_dwordx4 v[220:221], off
	v_lshl_add_u64 v[222:223], s[52:53], 0, v[130:131]
	s_mov_b32 m0, s18
	v_lshl_add_u64 v[224:225], s[58:59], 0, v[132:133]
	global_load_lds_dwordx4 v[222:223], off
	v_lshl_add_u64 v[222:223], s[52:53], 0, v[134:135]
	s_add_i32 m0, s18, 0x2000
	s_nop 0
	global_load_lds_dwordx4 v[222:223], off
	v_lshl_add_u64 v[222:223], s[58:59], 0, v[128:129]
	s_mov_b32 m0, s63
	s_nop 0
	global_load_lds_dwordx4 v[222:223], off
	s_mov_b32 m0, s64
	s_nop 0
	global_load_lds_dwordx4 v[224:225], off
	s_waitcnt vmcnt(8)
	s_waitcnt lgkmcnt(0)
	s_barrier
	s_waitcnt lgkmcnt(0)
	v_mfma_f32_16x16x32_bf16 v[60:63], v[152:155], v[188:191], v[60:63]
	v_mfma_f32_16x16x32_bf16 v[60:63], v[156:159], v[192:195], v[60:63]
	v_mfma_f32_16x16x32_bf16 v[56:59], v[160:163], v[188:191], v[56:59]
	v_mfma_f32_16x16x32_bf16 v[56:59], v[164:167], v[192:195], v[56:59]
	s_setprio 1
	v_mfma_f32_16x16x32_bf16 v[52:55], v[152:155], v[196:199], v[52:55]
	v_mfma_f32_16x16x32_bf16 v[52:55], v[156:159], v[200:203], v[52:55]
	v_mfma_f32_16x16x32_bf16 v[44:47], v[160:163], v[196:199], v[44:47]
	v_mfma_f32_16x16x32_bf16 v[44:47], v[164:167], v[200:203], v[44:47]
	v_mfma_f32_16x16x32_bf16 v[36:39], v[152:155], v[204:207], v[36:39]
	v_mfma_f32_16x16x32_bf16 v[36:39], v[156:159], v[208:211], v[36:39]
	v_mfma_f32_16x16x32_bf16 v[28:31], v[160:163], v[204:207], v[28:31]
	v_mfma_f32_16x16x32_bf16 v[28:31], v[164:167], v[208:211], v[28:31]
	v_mfma_f32_16x16x32_bf16 v[20:23], v[152:155], v[212:215], v[20:23]
	v_mfma_f32_16x16x32_bf16 v[20:23], v[156:159], v[216:219], v[20:23]
	v_mfma_f32_16x16x32_bf16 v[12:15], v[160:163], v[212:215], v[12:15]
	v_mfma_f32_16x16x32_bf16 v[12:15], v[164:167], v[216:219], v[12:15]
	v_mfma_f32_16x16x32_bf16 v[48:51], v[168:171], v[188:191], v[48:51]
	v_mfma_f32_16x16x32_bf16 v[48:51], v[172:175], v[192:195], v[48:51]
	v_mfma_f32_16x16x32_bf16 v[40:43], v[176:179], v[188:191], v[40:43]
	v_mfma_f32_16x16x32_bf16 v[40:43], v[184:187], v[192:195], v[40:43]
	v_mfma_f32_16x16x32_bf16 v[32:35], v[168:171], v[196:199], v[32:35]
	v_mfma_f32_16x16x32_bf16 v[32:35], v[172:175], v[200:203], v[32:35]
	v_mfma_f32_16x16x32_bf16 v[24:27], v[176:179], v[196:199], v[24:27]
	v_mfma_f32_16x16x32_bf16 v[24:27], v[184:187], v[200:203], v[24:27]
	v_mfma_f32_16x16x32_bf16 v[16:19], v[168:171], v[204:207], v[16:19]
	v_mfma_f32_16x16x32_bf16 v[16:19], v[172:175], v[208:211], v[16:19]
	v_mfma_f32_16x16x32_bf16 v[8:11], v[176:179], v[204:207], v[8:11]
	v_mfma_f32_16x16x32_bf16 v[8:11], v[184:187], v[208:211], v[8:11]
	s_barrier
	v_mfma_f32_16x16x32_bf16 v[4:7], v[168:171], v[212:215], v[4:7]
	v_mfma_f32_16x16x32_bf16 v[4:7], v[172:175], v[216:219], v[4:7]
	v_mfma_f32_16x16x32_bf16 v[0:3], v[176:179], v[212:215], v[0:3]
	v_mfma_f32_16x16x32_bf16 v[0:3], v[184:187], v[216:219], v[0:3]
	s_setprio 0
.Lmid_gemm1:
	s_add_i32 s18, 0, 0x18000
	s_add_i32 s19, 0, 0x1c000
	v_add_u32_e32 v164, s18, v147
	v_add_u32_e32 v181, s19, v147
	ds_read_b128 v[152:155], v164
	ds_read_b128 v[156:159], v164 offset:1024
	ds_read_b128 v[160:163], v164 offset:2048
	ds_read_b128 v[164:167], v164 offset:3072
	ds_read_b128 v[168:171], v181
	ds_read_b128 v[172:175], v181 offset:1024
	ds_read_b128 v[176:179], v181 offset:2048
	ds_read_b128 v[184:187], v181 offset:3072
	s_add_u32 s52, s58, 0xb0000
	s_addc_u32 s53, s59, 0
	s_mov_b32 m0, s65
	v_lshl_add_u64 v[226:227], s[52:53], 0, v[128:129]
	ds_read_b128 v[188:191], v151 offset:32768
	ds_read_b128 v[192:195], v151 offset:33792
	ds_read_b128 v[196:199], v151 offset:34816
	ds_read_b128 v[200:203], v151 offset:35840
	ds_read_b128 v[204:207], v151 offset:36864
	ds_read_b128 v[208:211], v151 offset:37888
	ds_read_b128 v[212:215], v151 offset:38912
	ds_read_b128 v[216:219], v151 offset:39936
	global_load_lds_dwordx4 v[226:227], off
	v_lshl_add_u64 v[226:227], s[52:53], 0, v[132:133]
	s_mov_b32 m0, s66
	s_nop 0
	global_load_lds_dwordx4 v[226:227], off
	s_waitcnt vmcnt(8)
	s_waitcnt lgkmcnt(0)
	s_barrier
	s_waitcnt lgkmcnt(0)
	v_mfma_f32_16x16x32_bf16 v[124:127], v[152:155], v[188:191], v[124:127]
	v_mfma_f32_16x16x32_bf16 v[124:127], v[156:159], v[192:195], v[124:127]
	v_mfma_f32_16x16x32_bf16 v[120:123], v[160:163], v[188:191], v[120:123]
	v_mfma_f32_16x16x32_bf16 v[120:123], v[164:167], v[192:195], v[120:123]
	s_setprio 1
	v_mfma_f32_16x16x32_bf16 v[116:119], v[152:155], v[196:199], v[116:119]
	v_mfma_f32_16x16x32_bf16 v[116:119], v[156:159], v[200:203], v[116:119]
	v_mfma_f32_16x16x32_bf16 v[108:111], v[160:163], v[196:199], v[108:111]
	v_mfma_f32_16x16x32_bf16 v[108:111], v[164:167], v[200:203], v[108:111]
	v_mfma_f32_16x16x32_bf16 v[100:103], v[152:155], v[204:207], v[100:103]
	v_mfma_f32_16x16x32_bf16 v[100:103], v[156:159], v[208:211], v[100:103]
	v_mfma_f32_16x16x32_bf16 v[92:95], v[160:163], v[204:207], v[92:95]
	v_mfma_f32_16x16x32_bf16 v[92:95], v[164:167], v[208:211], v[92:95]
	v_mfma_f32_16x16x32_bf16 v[84:87], v[152:155], v[212:215], v[84:87]
	v_mfma_f32_16x16x32_bf16 v[84:87], v[156:159], v[216:219], v[84:87]
	v_mfma_f32_16x16x32_bf16 v[76:79], v[160:163], v[212:215], v[76:79]
	v_mfma_f32_16x16x32_bf16 v[76:79], v[164:167], v[216:219], v[76:79]
	v_mfma_f32_16x16x32_bf16 v[112:115], v[168:171], v[188:191], v[112:115]
	v_mfma_f32_16x16x32_bf16 v[112:115], v[172:175], v[192:195], v[112:115]
	v_mfma_f32_16x16x32_bf16 v[104:107], v[176:179], v[188:191], v[104:107]
	v_mfma_f32_16x16x32_bf16 v[104:107], v[184:187], v[192:195], v[104:107]
	v_mfma_f32_16x16x32_bf16 v[96:99], v[168:171], v[196:199], v[96:99]
	v_mfma_f32_16x16x32_bf16 v[96:99], v[172:175], v[200:203], v[96:99]
	v_mfma_f32_16x16x32_bf16 v[88:91], v[176:179], v[196:199], v[88:91]
	v_mfma_f32_16x16x32_bf16 v[88:91], v[184:187], v[200:203], v[88:91]
	v_mfma_f32_16x16x32_bf16 v[80:83], v[168:171], v[204:207], v[80:83]
	v_mfma_f32_16x16x32_bf16 v[80:83], v[172:175], v[208:211], v[80:83]
	v_mfma_f32_16x16x32_bf16 v[72:75], v[176:179], v[204:207], v[72:75]
	v_mfma_f32_16x16x32_bf16 v[72:75], v[184:187], v[208:211], v[72:75]
	s_barrier
	v_mfma_f32_16x16x32_bf16 v[68:71], v[168:171], v[212:215], v[68:71]
	v_mfma_f32_16x16x32_bf16 v[68:71], v[172:175], v[216:219], v[68:71]
	v_mfma_f32_16x16x32_bf16 v[64:67], v[176:179], v[212:215], v[64:67]
	v_mfma_f32_16x16x32_bf16 v[64:67], v[184:187], v[216:219], v[64:67]
	s_setprio 0
	s_add_i32 s18, s18, s62
	v_lshl_add_u64 v[144:145], v[144:145], 0, s[8:9]
	s_mov_b32 m0, s18
	ds_read_b128 v[188:191], v151 offset:49152
	ds_read_b128 v[192:195], v151 offset:50176
	ds_read_b128 v[196:199], v151 offset:51200
	ds_read_b128 v[200:203], v151 offset:52224
	ds_read_b128 v[204:207], v151 offset:53248
	ds_read_b128 v[208:211], v151 offset:54272
	ds_read_b128 v[212:215], v151 offset:55296
	ds_read_b128 v[216:219], v151 offset:56320
	global_load_lds_dwordx4 v[144:145], off
	s_add_i32 m0, s18, 0x2000
	s_add_u32 s52, s56, 0xb0080
	v_lshl_add_u64 v[144:145], v[220:221], 0, s[8:9]
	s_addc_u32 s53, s57, 0
	s_add_i32 s18, s19, s62
	global_load_lds_dwordx4 v[144:145], off
	v_lshl_add_u64 v[144:145], s[52:53], 0, v[130:131]
	s_mov_b32 m0, s18
	s_nop 0
	global_load_lds_dwordx4 v[144:145], off
	v_lshl_add_u64 v[144:145], s[52:53], 0, v[134:135]
	s_add_i32 m0, s18, 0x2000
	s_nop 0
	global_load_lds_dwordx4 v[144:145], off
	v_lshl_add_u64 v[144:145], v[222:223], 0, s[8:9]
	s_mov_b32 m0, s68
	s_nop 0
	global_load_lds_dwordx4 v[144:145], off
	v_lshl_add_u64 v[144:145], v[224:225], 0, s[8:9]
	s_mov_b32 m0, s69
	s_nop 0
	global_load_lds_dwordx4 v[144:145], off
	s_waitcnt vmcnt(8)
	s_waitcnt lgkmcnt(0)
	s_barrier
	s_waitcnt lgkmcnt(0)
	v_mfma_f32_16x16x32_bf16 v[60:63], v[152:155], v[188:191], v[60:63]
	v_mfma_f32_16x16x32_bf16 v[60:63], v[156:159], v[192:195], v[60:63]
	v_mfma_f32_16x16x32_bf16 v[56:59], v[160:163], v[188:191], v[56:59]
	v_mfma_f32_16x16x32_bf16 v[56:59], v[164:167], v[192:195], v[56:59]
	s_setprio 1
	v_mfma_f32_16x16x32_bf16 v[52:55], v[152:155], v[196:199], v[52:55]
	v_mfma_f32_16x16x32_bf16 v[52:55], v[156:159], v[200:203], v[52:55]
	v_mfma_f32_16x16x32_bf16 v[44:47], v[160:163], v[196:199], v[44:47]
	v_mfma_f32_16x16x32_bf16 v[44:47], v[164:167], v[200:203], v[44:47]
	v_mfma_f32_16x16x32_bf16 v[36:39], v[152:155], v[204:207], v[36:39]
	v_mfma_f32_16x16x32_bf16 v[36:39], v[156:159], v[208:211], v[36:39]
	v_mfma_f32_16x16x32_bf16 v[28:31], v[160:163], v[204:207], v[28:31]
	v_mfma_f32_16x16x32_bf16 v[28:31], v[164:167], v[208:211], v[28:31]
	v_mfma_f32_16x16x32_bf16 v[20:23], v[152:155], v[212:215], v[20:23]
	v_mfma_f32_16x16x32_bf16 v[20:23], v[156:159], v[216:219], v[20:23]
	v_mfma_f32_16x16x32_bf16 v[12:15], v[160:163], v[212:215], v[12:15]
	v_mfma_f32_16x16x32_bf16 v[12:15], v[164:167], v[216:219], v[12:15]
	v_mfma_f32_16x16x32_bf16 v[48:51], v[168:171], v[188:191], v[48:51]
	v_mfma_f32_16x16x32_bf16 v[48:51], v[172:175], v[192:195], v[48:51]
	v_mfma_f32_16x16x32_bf16 v[40:43], v[176:179], v[188:191], v[40:43]
	v_mfma_f32_16x16x32_bf16 v[40:43], v[184:187], v[192:195], v[40:43]
	v_mfma_f32_16x16x32_bf16 v[32:35], v[168:171], v[196:199], v[32:35]
	v_mfma_f32_16x16x32_bf16 v[32:35], v[172:175], v[200:203], v[32:35]
	v_mfma_f32_16x16x32_bf16 v[24:27], v[176:179], v[196:199], v[24:27]
	v_mfma_f32_16x16x32_bf16 v[24:27], v[184:187], v[200:203], v[24:27]
	v_mfma_f32_16x16x32_bf16 v[16:19], v[168:171], v[204:207], v[16:19]
	v_mfma_f32_16x16x32_bf16 v[16:19], v[172:175], v[208:211], v[16:19]
	v_mfma_f32_16x16x32_bf16 v[8:11], v[176:179], v[204:207], v[8:11]
	v_mfma_f32_16x16x32_bf16 v[8:11], v[184:187], v[208:211], v[8:11]
	s_barrier
	v_mfma_f32_16x16x32_bf16 v[4:7], v[168:171], v[212:215], v[4:7]
	v_mfma_f32_16x16x32_bf16 v[4:7], v[172:175], v[216:219], v[4:7]
	v_mfma_f32_16x16x32_bf16 v[0:3], v[176:179], v[212:215], v[0:3]
	v_mfma_f32_16x16x32_bf16 v[0:3], v[184:187], v[216:219], v[0:3]
	s_setprio 0
	s_add_i32 s86, s86, 2
	s_add_u32 s84, s84, 0x100
	s_addc_u32 s85, s85, 0
	s_cmp_gt_u32 s86, 41
	s_mov_b64 s[52:53], s[54:55]
	s_cbranch_scc0 .LBB0_264
	s_and_b64 vcc, exec, s[10:11]
	s_cbranch_vccz .LBB0_267
	s_barrier

.LBB0_386:
	s_ashr_i32 s49, s48, 31
	s_lshl_b64 s[52:53], s[48:49], 19
	s_add_u32 s52, s80, s52
	s_addc_u32 s53, s81, s53
	s_and_b64 s[54:55], s[4:5], exec
	s_cselect_b32 s49, s53, s59
	s_cselect_b32 s82, s52, s58
	s_ashr_i32 s47, s46, 31
	s_lshl_b64 s[54:55], s[46:47], 19
	s_add_u32 s54, s64, s54
	s_addc_u32 s55, s65, s55
	s_and_b64 s[62:63], s[4:5], exec
	s_cselect_b32 s47, s55, s61
	s_cselect_b32 s83, s54, s60
	s_add_u32 s58, s58, 0x40080
	s_addc_u32 s59, s59, 0
	s_add_u32 s84, s60, 0x100
	s_addc_u32 s85, s61, 0
	s_mov_b32 s86, -2
	ds_read_b128 v[152:155], v148
	ds_read_b128 v[156:159], v148 offset:1024
	ds_read_b128 v[160:163], v148 offset:2048
	ds_read_b128 v[164:167], v148 offset:3072
	ds_read_b128 v[168:171], v149
	ds_read_b128 v[172:175], v149 offset:1024
	ds_read_b128 v[176:179], v149 offset:2048
	ds_read_b128 v[184:187], v149 offset:3072
	s_add_u32 s18, s58, 0xfffc0080
	s_addc_u32 s19, s59, -1
	s_cmp_eq_u32 s86, 12
	s_cselect_b32 s63, s49, s19
	s_cselect_b32 s62, s82, s18
	s_cselect_b32 s61, s47, s85
	s_cselect_b32 s60, s83, s84
	v_lshl_add_u64 v[220:221], s[58:59], 0, v[138:139]
	s_add_i32 m0, s68, 0xc000
	ds_read_b128 v[188:191], v150
	ds_read_b128 v[192:195], v150 offset:1024
	ds_read_b128 v[196:199], v150 offset:2048
	ds_read_b128 v[200:203], v150 offset:3072
	ds_read_b128 v[204:207], v150 offset:4096
	ds_read_b128 v[208:211], v150 offset:5120
	ds_read_b128 v[212:215], v150 offset:6144
	ds_read_b128 v[216:219], v150 offset:7168
	global_load_lds_dwordx4 v[220:221], off
	v_lshl_add_u64 v[220:221], s[58:59], 0, v[140:141]
	s_add_i32 m0, s68, 0xe000
	s_nop 0
	global_load_lds_dwordx4 v[220:221], off
	s_waitcnt vmcnt(8)
	s_waitcnt lgkmcnt(0)
	s_barrier
	s_waitcnt lgkmcnt(0)
	v_mfma_f32_16x16x32_bf16 v[124:127], v[152:155], v[188:191], 0
	v_mfma_f32_16x16x32_bf16 v[124:127], v[156:159], v[192:195], v[124:127]
	v_mfma_f32_16x16x32_bf16 v[120:123], v[160:163], v[188:191], 0
	v_mfma_f32_16x16x32_bf16 v[120:123], v[164:167], v[192:195], v[120:123]
	s_setprio 1
	v_mfma_f32_16x16x32_bf16 v[116:119], v[152:155], v[196:199], 0
	v_mfma_f32_16x16x32_bf16 v[116:119], v[156:159], v[200:203], v[116:119]
	v_mfma_f32_16x16x32_bf16 v[112:115], v[160:163], v[196:199], 0
	v_mfma_f32_16x16x32_bf16 v[112:115], v[164:167], v[200:203], v[112:115]
	v_mfma_f32_16x16x32_bf16 v[108:111], v[152:155], v[204:207], 0
	v_mfma_f32_16x16x32_bf16 v[108:111], v[156:159], v[208:211], v[108:111]
	v_mfma_f32_16x16x32_bf16 v[104:107], v[160:163], v[204:207], 0
	v_mfma_f32_16x16x32_bf16 v[104:107], v[164:167], v[208:211], v[104:107]
	v_mfma_f32_16x16x32_bf16 v[100:103], v[152:155], v[212:215], 0
	v_mfma_f32_16x16x32_bf16 v[100:103], v[156:159], v[216:219], v[100:103]
	v_mfma_f32_16x16x32_bf16 v[96:99], v[160:163], v[212:215], 0
	v_mfma_f32_16x16x32_bf16 v[96:99], v[164:167], v[216:219], v[96:99]
	v_mfma_f32_16x16x32_bf16 v[68:71], v[168:171], v[188:191], 0
	v_mfma_f32_16x16x32_bf16 v[68:71], v[172:175], v[192:195], v[68:71]
	v_mfma_f32_16x16x32_bf16 v[64:67], v[176:179], v[188:191], 0
	v_mfma_f32_16x16x32_bf16 v[64:67], v[184:187], v[192:195], v[64:67]
	v_mfma_f32_16x16x32_bf16 v[52:55], v[168:171], v[196:199], 0
	v_mfma_f32_16x16x32_bf16 v[52:55], v[172:175], v[200:203], v[52:55]
	v_mfma_f32_16x16x32_bf16 v[48:51], v[176:179], v[196:199], 0
	v_mfma_f32_16x16x32_bf16 v[48:51], v[184:187], v[200:203], v[48:51]
	v_mfma_f32_16x16x32_bf16 v[44:47], v[168:171], v[204:207], 0
	v_mfma_f32_16x16x32_bf16 v[44:47], v[172:175], v[208:211], v[44:47]
	v_mfma_f32_16x16x32_bf16 v[40:43], v[176:179], v[204:207], 0
	v_mfma_f32_16x16x32_bf16 v[40:43], v[184:187], v[208:211], v[40:43]
	s_barrier
	v_mfma_f32_16x16x32_bf16 v[36:39], v[168:171], v[212:215], 0
	v_mfma_f32_16x16x32_bf16 v[36:39], v[172:175], v[216:219], v[36:39]
	v_mfma_f32_16x16x32_bf16 v[32:35], v[176:179], v[212:215], 0
	v_mfma_f32_16x16x32_bf16 v[32:35], v[184:187], v[216:219], v[32:35]
	s_setprio 0
	s_add_i32 s18, s76, s66
	v_lshl_add_u64 v[220:221], s[60:61], 0, v[132:133]
	s_mov_b32 m0, s18
	ds_read_b128 v[188:191], v150 offset:16384
	ds_read_b128 v[192:195], v150 offset:17408
	ds_read_b128 v[196:199], v150 offset:18432
	ds_read_b128 v[200:203], v150 offset:19456
	ds_read_b128 v[204:207], v150 offset:20480
	ds_read_b128 v[208:211], v150 offset:21504
	ds_read_b128 v[212:215], v150 offset:22528
	ds_read_b128 v[216:219], v150 offset:23552
	global_load_lds_dwordx4 v[220:221], off
	s_add_i32 m0, s18, 0x2000
	s_add_u32 s88, s60, 0x40000
	v_lshl_add_u64 v[222:223], s[60:61], 0, v[128:129]
	s_addc_u32 s89, s61, 0
	s_add_i32 s18, s77, s66
	global_load_lds_dwordx4 v[222:223], off
	v_lshl_add_u64 v[224:225], s[88:89], 0, v[132:133]
	s_mov_b32 m0, s18
	v_lshl_add_u64 v[226:227], s[62:63], 0, v[130:131]
	global_load_lds_dwordx4 v[224:225], off
	v_lshl_add_u64 v[224:225], s[88:89], 0, v[128:129]
	s_add_i32 m0, s18, 0x2000
	s_nop 0
	global_load_lds_dwordx4 v[224:225], off
	v_lshl_add_u64 v[224:225], s[62:63], 0, v[134:135]
	s_mov_b32 m0, s68
	s_nop 0
	global_load_lds_dwordx4 v[224:225], off
	s_mov_b32 m0, s69
	s_nop 0
	global_load_lds_dwordx4 v[226:227], off
	s_waitcnt vmcnt(8)
	s_waitcnt lgkmcnt(0)
	s_barrier
	s_waitcnt lgkmcnt(0)
	v_mfma_f32_16x16x32_bf16 v[92:95], v[152:155], v[188:191], 0
	v_mfma_f32_16x16x32_bf16 v[92:95], v[156:159], v[192:195], v[92:95]
	v_mfma_f32_16x16x32_bf16 v[88:91], v[160:163], v[188:191], 0
	v_mfma_f32_16x16x32_bf16 v[88:91], v[164:167], v[192:195], v[88:91]
	s_setprio 1
	v_mfma_f32_16x16x32_bf16 v[84:87], v[152:155], v[196:199], 0
	v_mfma_f32_16x16x32_bf16 v[84:87], v[156:159], v[200:203], v[84:87]
	v_mfma_f32_16x16x32_bf16 v[80:83], v[160:163], v[196:199], 0
	v_mfma_f32_16x16x32_bf16 v[80:83], v[164:167], v[200:203], v[80:83]
	v_mfma_f32_16x16x32_bf16 v[76:79], v[152:155], v[204:207], 0
	v_mfma_f32_16x16x32_bf16 v[76:79], v[156:159], v[208:211], v[76:79]
	v_mfma_f32_16x16x32_bf16 v[72:75], v[160:163], v[204:207], 0
	v_mfma_f32_16x16x32_bf16 v[72:75], v[164:167], v[208:211], v[72:75]
	v_mfma_f32_16x16x32_bf16 v[60:63], v[152:155], v[212:215], 0
	v_mfma_f32_16x16x32_bf16 v[60:63], v[156:159], v[216:219], v[60:63]
	v_mfma_f32_16x16x32_bf16 v[56:59], v[160:163], v[212:215], 0
	v_mfma_f32_16x16x32_bf16 v[56:59], v[164:167], v[216:219], v[56:59]
	v_mfma_f32_16x16x32_bf16 v[28:31], v[168:171], v[188:191], 0
	v_mfma_f32_16x16x32_bf16 v[28:31], v[172:175], v[192:195], v[28:31]
	v_mfma_f32_16x16x32_bf16 v[24:27], v[176:179], v[188:191], 0
	v_mfma_f32_16x16x32_bf16 v[24:27], v[184:187], v[192:195], v[24:27]
	v_mfma_f32_16x16x32_bf16 v[20:23], v[168:171], v[196:199], 0
	v_mfma_f32_16x16x32_bf16 v[20:23], v[172:175], v[200:203], v[20:23]
	v_mfma_f32_16x16x32_bf16 v[16:19], v[176:179], v[196:199], 0
	v_mfma_f32_16x16x32_bf16 v[16:19], v[184:187], v[200:203], v[16:19]
	v_mfma_f32_16x16x32_bf16 v[12:15], v[168:171], v[204:207], 0
	v_mfma_f32_16x16x32_bf16 v[12:15], v[172:175], v[208:211], v[12:15]
	v_mfma_f32_16x16x32_bf16 v[8:11], v[176:179], v[204:207], 0
	v_mfma_f32_16x16x32_bf16 v[8:11], v[184:187], v[208:211], v[8:11]
	s_barrier
	v_mfma_f32_16x16x32_bf16 v[4:7], v[168:171], v[212:215], 0
	v_mfma_f32_16x16x32_bf16 v[4:7], v[172:175], v[216:219], v[4:7]
	v_mfma_f32_16x16x32_bf16 v[0:3], v[176:179], v[212:215], 0
	v_mfma_f32_16x16x32_bf16 v[0:3], v[184:187], v[216:219], v[0:3]
	s_setprio 0
	s_branch .Lmid_gemm2
.LBB0_387:
	ds_read_b128 v[152:155], v148
	ds_read_b128 v[156:159], v148 offset:1024
	ds_read_b128 v[160:163], v148 offset:2048
	ds_read_b128 v[164:167], v148 offset:3072
	ds_read_b128 v[168:171], v149
	ds_read_b128 v[172:175], v149 offset:1024
	ds_read_b128 v[176:179], v149 offset:2048
	ds_read_b128 v[184:187], v149 offset:3072
	s_add_u32 s18, s58, 0xfffc0080
	s_addc_u32 s19, s59, -1
	s_cmp_eq_u32 s86, 12
	s_cselect_b32 s63, s49, s19
	s_cselect_b32 s62, s82, s18
	s_cselect_b32 s61, s47, s85
	s_cselect_b32 s60, s83, s84
	v_lshl_add_u64 v[220:221], s[58:59], 0, v[138:139]
	s_add_i32 m0, s68, 0xc000
	ds_read_b128 v[188:191], v150
	ds_read_b128 v[192:195], v150 offset:1024
	ds_read_b128 v[196:199], v150 offset:2048
	ds_read_b128 v[200:203], v150 offset:3072
	ds_read_b128 v[204:207], v150 offset:4096
	ds_read_b128 v[208:211], v150 offset:5120
	ds_read_b128 v[212:215], v150 offset:6144
	ds_read_b128 v[216:219], v150 offset:7168
	global_load_lds_dwordx4 v[220:221], off
	v_lshl_add_u64 v[220:221], s[58:59], 0, v[140:141]
	s_add_i32 m0, s68, 0xe000
	s_nop 0
	global_load_lds_dwordx4 v[220:221], off
	s_waitcnt vmcnt(8)
	s_waitcnt lgkmcnt(0)
	s_barrier
	s_waitcnt lgkmcnt(0)
	v_mfma_f32_16x16x32_bf16 v[124:127], v[152:155], v[188:191], v[124:127]
	v_mfma_f32_16x16x32_bf16 v[124:127], v[156:159], v[192:195], v[124:127]
	v_mfma_f32_16x16x32_bf16 v[120:123], v[160:163], v[188:191], v[120:123]
	v_mfma_f32_16x16x32_bf16 v[120:123], v[164:167], v[192:195], v[120:123]
	s_setprio 1
	v_mfma_f32_16x16x32_bf16 v[116:119], v[152:155], v[196:199], v[116:119]
	v_mfma_f32_16x16x32_bf16 v[116:119], v[156:159], v[200:203], v[116:119]
	v_mfma_f32_16x16x32_bf16 v[112:115], v[160:163], v[196:199], v[112:115]
	v_mfma_f32_16x16x32_bf16 v[112:115], v[164:167], v[200:203], v[112:115]
	v_mfma_f32_16x16x32_bf16 v[108:111], v[152:155], v[204:207], v[108:111]
	v_mfma_f32_16x16x32_bf16 v[108:111], v[156:159], v[208:211], v[108:111]
	v_mfma_f32_16x16x32_bf16 v[104:107], v[160:163], v[204:207], v[104:107]
	v_mfma_f32_16x16x32_bf16 v[104:107], v[164:167], v[208:211], v[104:107]
	v_mfma_f32_16x16x32_bf16 v[100:103], v[152:155], v[212:215], v[100:103]
	v_mfma_f32_16x16x32_bf16 v[100:103], v[156:159], v[216:219], v[100:103]
	v_mfma_f32_16x16x32_bf16 v[96:99], v[160:163], v[212:215], v[96:99]
	v_mfma_f32_16x16x32_bf16 v[96:99], v[164:167], v[216:219], v[96:99]
	v_mfma_f32_16x16x32_bf16 v[68:71], v[168:171], v[188:191], v[68:71]
	v_mfma_f32_16x16x32_bf16 v[68:71], v[172:175], v[192:195], v[68:71]
	v_mfma_f32_16x16x32_bf16 v[64:67], v[176:179], v[188:191], v[64:67]
	v_mfma_f32_16x16x32_bf16 v[64:67], v[184:187], v[192:195], v[64:67]
	v_mfma_f32_16x16x32_bf16 v[52:55], v[168:171], v[196:199], v[52:55]
	v_mfma_f32_16x16x32_bf16 v[52:55], v[172:175], v[200:203], v[52:55]
	v_mfma_f32_16x16x32_bf16 v[48:51], v[176:179], v[196:199], v[48:51]
	v_mfma_f32_16x16x32_bf16 v[48:51], v[184:187], v[200:203], v[48:51]
	v_mfma_f32_16x16x32_bf16 v[44:47], v[168:171], v[204:207], v[44:47]
	v_mfma_f32_16x16x32_bf16 v[44:47], v[172:175], v[208:211], v[44:47]
	v_mfma_f32_16x16x32_bf16 v[40:43], v[176:179], v[204:207], v[40:43]
	v_mfma_f32_16x16x32_bf16 v[40:43], v[184:187], v[208:211], v[40:43]
	s_barrier
	v_mfma_f32_16x16x32_bf16 v[36:39], v[168:171], v[212:215], v[36:39]
	v_mfma_f32_16x16x32_bf16 v[36:39], v[172:175], v[216:219], v[36:39]
	v_mfma_f32_16x16x32_bf16 v[32:35], v[176:179], v[212:215], v[32:35]
	v_mfma_f32_16x16x32_bf16 v[32:35], v[184:187], v[216:219], v[32:35]
	s_setprio 0
	s_add_i32 s18, s76, s66
	v_lshl_add_u64 v[220:221], s[60:61], 0, v[132:133]
	s_mov_b32 m0, s18
	ds_read_b128 v[188:191], v150 offset:16384
	ds_read_b128 v[192:195], v150 offset:17408
	ds_read_b128 v[196:199], v150 offset:18432
	ds_read_b128 v[200:203], v150 offset:19456
	ds_read_b128 v[204:207], v150 offset:20480
	ds_read_b128 v[208:211], v150 offset:21504
	ds_read_b128 v[212:215], v150 offset:22528
	ds_read_b128 v[216:219], v150 offset:23552
	global_load_lds_dwordx4 v[220:221], off
	s_add_i32 m0, s18, 0x2000
	s_add_u32 s88, s60, 0x40000
	v_lshl_add_u64 v[222:223], s[60:61], 0, v[128:129]
	s_addc_u32 s89, s61, 0
	s_add_i32 s18, s77, s66
	global_load_lds_dwordx4 v[222:223], off
	v_lshl_add_u64 v[224:225], s[88:89], 0, v[132:133]
	s_mov_b32 m0, s18
	v_lshl_add_u64 v[226:227], s[62:63], 0, v[130:131]
	global_load_lds_dwordx4 v[224:225], off
	v_lshl_add_u64 v[224:225], s[88:89], 0, v[128:129]
	s_add_i32 m0, s18, 0x2000
	s_nop 0
	global_load_lds_dwordx4 v[224:225], off
	v_lshl_add_u64 v[224:225], s[62:63], 0, v[134:135]
	s_mov_b32 m0, s68
	s_nop 0
	global_load_lds_dwordx4 v[224:225], off
	s_mov_b32 m0, s69
	s_nop 0
	global_load_lds_dwordx4 v[226:227], off
	s_waitcnt vmcnt(8)
	s_waitcnt lgkmcnt(0)
	s_barrier
	s_waitcnt lgkmcnt(0)
	v_mfma_f32_16x16x32_bf16 v[92:95], v[152:155], v[188:191], v[92:95]
	v_mfma_f32_16x16x32_bf16 v[92:95], v[156:159], v[192:195], v[92:95]
	v_mfma_f32_16x16x32_bf16 v[88:91], v[160:163], v[188:191], v[88:91]
	v_mfma_f32_16x16x32_bf16 v[88:91], v[164:167], v[192:195], v[88:91]
	s_setprio 1
	v_mfma_f32_16x16x32_bf16 v[84:87], v[152:155], v[196:199], v[84:87]
	v_mfma_f32_16x16x32_bf16 v[84:87], v[156:159], v[200:203], v[84:87]
	v_mfma_f32_16x16x32_bf16 v[80:83], v[160:163], v[196:199], v[80:83]
	v_mfma_f32_16x16x32_bf16 v[80:83], v[164:167], v[200:203], v[80:83]
	v_mfma_f32_16x16x32_bf16 v[76:79], v[152:155], v[204:207], v[76:79]
	v_mfma_f32_16x16x32_bf16 v[76:79], v[156:159], v[208:211], v[76:79]
	v_mfma_f32_16x16x32_bf16 v[72:75], v[160:163], v[204:207], v[72:75]
	v_mfma_f32_16x16x32_bf16 v[72:75], v[164:167], v[208:211], v[72:75]
	v_mfma_f32_16x16x32_bf16 v[60:63], v[152:155], v[212:215], v[60:63]
	v_mfma_f32_16x16x32_bf16 v[60:63], v[156:159], v[216:219], v[60:63]
	v_mfma_f32_16x16x32_bf16 v[56:59], v[160:163], v[212:215], v[56:59]
	v_mfma_f32_16x16x32_bf16 v[56:59], v[164:167], v[216:219], v[56:59]
	v_mfma_f32_16x16x32_bf16 v[28:31], v[168:171], v[188:191], v[28:31]
	v_mfma_f32_16x16x32_bf16 v[28:31], v[172:175], v[192:195], v[28:31]
	v_mfma_f32_16x16x32_bf16 v[24:27], v[176:179], v[188:191], v[24:27]
	v_mfma_f32_16x16x32_bf16 v[24:27], v[184:187], v[192:195], v[24:27]
	v_mfma_f32_16x16x32_bf16 v[20:23], v[168:171], v[196:199], v[20:23]
	v_mfma_f32_16x16x32_bf16 v[20:23], v[172:175], v[200:203], v[20:23]
	v_mfma_f32_16x16x32_bf16 v[16:19], v[176:179], v[196:199], v[16:19]
	v_mfma_f32_16x16x32_bf16 v[16:19], v[184:187], v[200:203], v[16:19]
	v_mfma_f32_16x16x32_bf16 v[12:15], v[168:171], v[204:207], v[12:15]
	v_mfma_f32_16x16x32_bf16 v[12:15], v[172:175], v[208:211], v[12:15]
	v_mfma_f32_16x16x32_bf16 v[8:11], v[176:179], v[204:207], v[8:11]
	v_mfma_f32_16x16x32_bf16 v[8:11], v[184:187], v[208:211], v[8:11]
	s_barrier
	v_mfma_f32_16x16x32_bf16 v[4:7], v[168:171], v[212:215], v[4:7]
	v_mfma_f32_16x16x32_bf16 v[4:7], v[172:175], v[216:219], v[4:7]
	v_mfma_f32_16x16x32_bf16 v[0:3], v[176:179], v[212:215], v[0:3]
	v_mfma_f32_16x16x32_bf16 v[0:3], v[184:187], v[216:219], v[0:3]
	s_setprio 0
.Lmid_gemm2:
	s_add_i32 s18, 0, 0x18000
	s_add_i32 s19, 0, 0x1c000
	v_add_u32_e32 v164, s18, v147
	v_add_u32_e32 v181, s19, v147
	ds_read_b128 v[152:155], v164
	ds_read_b128 v[156:159], v164 offset:1024
	ds_read_b128 v[160:163], v164 offset:2048
	ds_read_b128 v[164:167], v164 offset:3072
	ds_read_b128 v[168:171], v181
	ds_read_b128 v[172:175], v181 offset:1024
	ds_read_b128 v[176:179], v181 offset:2048
	ds_read_b128 v[184:187], v181 offset:3072
	s_add_u32 s62, s62, 0x40000
	s_addc_u32 s63, s63, 0
	s_mov_b32 m0, s70
	v_lshl_add_u64 v[228:229], s[62:63], 0, v[134:135]
	ds_read_b128 v[188:191], v150 offset:32768
	ds_read_b128 v[192:195], v150 offset:33792
	ds_read_b128 v[196:199], v150 offset:34816
	ds_read_b128 v[200:203], v150 offset:35840
	ds_read_b128 v[204:207], v150 offset:36864
	ds_read_b128 v[208:211], v150 offset:37888
	ds_read_b128 v[212:215], v150 offset:38912
	ds_read_b128 v[216:219], v150 offset:39936
	global_load_lds_dwordx4 v[228:229], off
	v_lshl_add_u64 v[228:229], s[62:63], 0, v[130:131]
	s_mov_b32 m0, s71
	s_nop 0
	global_load_lds_dwordx4 v[228:229], off
	s_waitcnt vmcnt(8)
	s_waitcnt lgkmcnt(0)
	s_barrier
	s_waitcnt lgkmcnt(0)
	v_mfma_f32_16x16x32_bf16 v[124:127], v[152:155], v[188:191], v[124:127]
	v_mfma_f32_16x16x32_bf16 v[124:127], v[156:159], v[192:195], v[124:127]
	v_mfma_f32_16x16x32_bf16 v[120:123], v[160:163], v[188:191], v[120:123]
	v_mfma_f32_16x16x32_bf16 v[120:123], v[164:167], v[192:195], v[120:123]
	s_setprio 1
	v_mfma_f32_16x16x32_bf16 v[116:119], v[152:155], v[196:199], v[116:119]
	v_mfma_f32_16x16x32_bf16 v[116:119], v[156:159], v[200:203], v[116:119]
	v_mfma_f32_16x16x32_bf16 v[112:115], v[160:163], v[196:199], v[112:115]
	v_mfma_f32_16x16x32_bf16 v[112:115], v[164:167], v[200:203], v[112:115]
	v_mfma_f32_16x16x32_bf16 v[108:111], v[152:155], v[204:207], v[108:111]
	v_mfma_f32_16x16x32_bf16 v[108:111], v[156:159], v[208:211], v[108:111]
	v_mfma_f32_16x16x32_bf16 v[104:107], v[160:163], v[204:207], v[104:107]
	v_mfma_f32_16x16x32_bf16 v[104:107], v[164:167], v[208:211], v[104:107]
	v_mfma_f32_16x16x32_bf16 v[100:103], v[152:155], v[212:215], v[100:103]
	v_mfma_f32_16x16x32_bf16 v[100:103], v[156:159], v[216:219], v[100:103]
	v_mfma_f32_16x16x32_bf16 v[96:99], v[160:163], v[212:215], v[96:99]
	v_mfma_f32_16x16x32_bf16 v[96:99], v[164:167], v[216:219], v[96:99]
	v_mfma_f32_16x16x32_bf16 v[68:71], v[168:171], v[188:191], v[68:71]
	v_mfma_f32_16x16x32_bf16 v[68:71], v[172:175], v[192:195], v[68:71]
	v_mfma_f32_16x16x32_bf16 v[64:67], v[176:179], v[188:191], v[64:67]
	v_mfma_f32_16x16x32_bf16 v[64:67], v[184:187], v[192:195], v[64:67]
	v_mfma_f32_16x16x32_bf16 v[52:55], v[168:171], v[196:199], v[52:55]
	v_mfma_f32_16x16x32_bf16 v[52:55], v[172:175], v[200:203], v[52:55]
	v_mfma_f32_16x16x32_bf16 v[48:51], v[176:179], v[196:199], v[48:51]
	v_mfma_f32_16x16x32_bf16 v[48:51], v[184:187], v[200:203], v[48:51]
	v_mfma_f32_16x16x32_bf16 v[44:47], v[168:171], v[204:207], v[44:47]
	v_mfma_f32_16x16x32_bf16 v[44:47], v[172:175], v[208:211], v[44:47]
	v_mfma_f32_16x16x32_bf16 v[40:43], v[176:179], v[204:207], v[40:43]
	v_mfma_f32_16x16x32_bf16 v[40:43], v[184:187], v[208:211], v[40:43]
	s_barrier
	v_mfma_f32_16x16x32_bf16 v[36:39], v[168:171], v[212:215], v[36:39]
	v_mfma_f32_16x16x32_bf16 v[36:39], v[172:175], v[216:219], v[36:39]
	v_mfma_f32_16x16x32_bf16 v[32:35], v[176:179], v[212:215], v[32:35]
	v_mfma_f32_16x16x32_bf16 v[32:35], v[184:187], v[216:219], v[32:35]
	s_setprio 0
	s_add_i32 s18, s18, s66
	v_lshl_add_u64 v[220:221], v[220:221], 0, s[6:7]
	s_mov_b32 m0, s18
	ds_read_b128 v[188:191], v150 offset:49152
	ds_read_b128 v[192:195], v150 offset:50176
	ds_read_b128 v[196:199], v150 offset:51200
	ds_read_b128 v[200:203], v150 offset:52224
	ds_read_b128 v[204:207], v150 offset:53248
	ds_read_b128 v[208:211], v150 offset:54272
	ds_read_b128 v[212:215], v150 offset:55296
	ds_read_b128 v[216:219], v150 offset:56320
	global_load_lds_dwordx4 v[220:221], off
	s_add_i32 m0, s18, 0x2000
	s_add_u32 s60, s60, 0x40080
	v_lshl_add_u64 v[220:221], v[222:223], 0, s[6:7]
	s_addc_u32 s61, s61, 0
	s_add_i32 s18, s19, s66
	global_load_lds_dwordx4 v[220:221], off
	v_lshl_add_u64 v[220:221], s[60:61], 0, v[132:133]
	s_mov_b32 m0, s18
	s_nop 0
	global_load_lds_dwordx4 v[220:221], off
	v_lshl_add_u64 v[220:221], s[60:61], 0, v[128:129]
	s_add_i32 m0, s18, 0x2000
	s_nop 0
	global_load_lds_dwordx4 v[220:221], off
	v_lshl_add_u64 v[220:221], v[224:225], 0, s[6:7]
	s_mov_b32 m0, s74
	s_nop 0
	global_load_lds_dwordx4 v[220:221], off
	v_lshl_add_u64 v[220:221], v[226:227], 0, s[6:7]
	s_mov_b32 m0, s75
	s_nop 0
	global_load_lds_dwordx4 v[220:221], off
	s_waitcnt vmcnt(8)
	s_waitcnt lgkmcnt(0)
	s_barrier
	s_waitcnt lgkmcnt(0)
	v_mfma_f32_16x16x32_bf16 v[92:95], v[152:155], v[188:191], v[92:95]
	v_mfma_f32_16x16x32_bf16 v[92:95], v[156:159], v[192:195], v[92:95]
	v_mfma_f32_16x16x32_bf16 v[88:91], v[160:163], v[188:191], v[88:91]
	v_mfma_f32_16x16x32_bf16 v[88:91], v[164:167], v[192:195], v[88:91]
	s_setprio 1
	v_mfma_f32_16x16x32_bf16 v[84:87], v[152:155], v[196:199], v[84:87]
	v_mfma_f32_16x16x32_bf16 v[84:87], v[156:159], v[200:203], v[84:87]
	v_mfma_f32_16x16x32_bf16 v[80:83], v[160:163], v[196:199], v[80:83]
	v_mfma_f32_16x16x32_bf16 v[80:83], v[164:167], v[200:203], v[80:83]
	v_mfma_f32_16x16x32_bf16 v[76:79], v[152:155], v[204:207], v[76:79]
	v_mfma_f32_16x16x32_bf16 v[76:79], v[156:159], v[208:211], v[76:79]
	v_mfma_f32_16x16x32_bf16 v[72:75], v[160:163], v[204:207], v[72:75]
	v_mfma_f32_16x16x32_bf16 v[72:75], v[164:167], v[208:211], v[72:75]
	v_mfma_f32_16x16x32_bf16 v[60:63], v[152:155], v[212:215], v[60:63]
	v_mfma_f32_16x16x32_bf16 v[60:63], v[156:159], v[216:219], v[60:63]
	v_mfma_f32_16x16x32_bf16 v[56:59], v[160:163], v[212:215], v[56:59]
	v_mfma_f32_16x16x32_bf16 v[56:59], v[164:167], v[216:219], v[56:59]
	v_mfma_f32_16x16x32_bf16 v[28:31], v[168:171], v[188:191], v[28:31]
	v_mfma_f32_16x16x32_bf16 v[28:31], v[172:175], v[192:195], v[28:31]
	v_mfma_f32_16x16x32_bf16 v[24:27], v[176:179], v[188:191], v[24:27]
	v_mfma_f32_16x16x32_bf16 v[24:27], v[184:187], v[192:195], v[24:27]
	v_mfma_f32_16x16x32_bf16 v[20:23], v[168:171], v[196:199], v[20:23]
	v_mfma_f32_16x16x32_bf16 v[20:23], v[172:175], v[200:203], v[20:23]
	v_mfma_f32_16x16x32_bf16 v[16:19], v[176:179], v[196:199], v[16:19]
	v_mfma_f32_16x16x32_bf16 v[16:19], v[184:187], v[200:203], v[16:19]
	v_mfma_f32_16x16x32_bf16 v[12:15], v[168:171], v[204:207], v[12:15]
	v_mfma_f32_16x16x32_bf16 v[12:15], v[172:175], v[208:211], v[12:15]
	v_mfma_f32_16x16x32_bf16 v[8:11], v[176:179], v[204:207], v[8:11]
	v_mfma_f32_16x16x32_bf16 v[8:11], v[184:187], v[208:211], v[8:11]
	s_barrier
	v_mfma_f32_16x16x32_bf16 v[4:7], v[168:171], v[212:215], v[4:7]
	v_mfma_f32_16x16x32_bf16 v[4:7], v[172:175], v[216:219], v[4:7]
	v_mfma_f32_16x16x32_bf16 v[0:3], v[176:179], v[212:215], v[0:3]
	v_mfma_f32_16x16x32_bf16 v[0:3], v[184:187], v[216:219], v[0:3]
	s_setprio 0
	s_add_i32 s86, s86, 2
	s_add_u32 s58, s58, 0x100
	s_addc_u32 s59, s59, 0
	s_add_u32 s84, s84, 0x100
	s_addc_u32 s85, s85, 0
	s_cmp_gt_u32 s86, 13
	s_cbranch_scc0 .LBB0_387
	s_and_b64 vcc, exec, s[8:9]
	s_cbranch_vccz .LBB0_390
	s_barrier

.LBB0_600:
	s_ashr_i32 s49, s48, 31
	s_lshl_b64 s[18:19], s[48:49], 19
	s_add_u32 s52, s38, s18
	s_addc_u32 s53, s39, s19
	s_and_b64 s[18:19], s[4:5], exec
	s_cselect_b32 s49, s53, s59
	s_cselect_b32 s84, s52, s58
	s_ashr_i32 s47, s46, 31
	s_lshl_b64 s[18:19], s[46:47], 19
	s_add_u32 s54, s64, s18
	s_addc_u32 s55, s65, s19
	s_and_b64 s[18:19], s[4:5], exec
	s_cselect_b32 s47, s55, s61
	s_cselect_b32 s85, s54, s60
	s_add_u32 s58, s58, 0x40080
	s_addc_u32 s59, s59, 0
	s_add_u32 s86, s60, 0x100
	s_addc_u32 s87, s61, 0
	s_mov_b32 s88, -2
	ds_read_b128 v[152:155], v149
	ds_read_b128 v[156:159], v149 offset:1024
	ds_read_b128 v[160:163], v149 offset:2048
	ds_read_b128 v[164:167], v149 offset:3072
	ds_read_b128 v[168:171], v150
	ds_read_b128 v[172:175], v150 offset:1024
	ds_read_b128 v[176:179], v150 offset:2048
	ds_read_b128 v[184:187], v150 offset:3072
	s_add_u32 s18, s58, 0xfffc0080
	s_addc_u32 s19, s59, -1
	s_cmp_eq_u32 s88, 12
	s_cselect_b32 s63, s49, s19
	s_cselect_b32 s62, s84, s18
	s_cselect_b32 s61, s47, s87
	s_cselect_b32 s60, s85, s86
	v_lshl_add_u64 v[144:145], s[58:59], 0, v[136:137]
	s_add_i32 m0, s57, 0xc000
	ds_read_b128 v[188:191], v151
	ds_read_b128 v[192:195], v151 offset:1024
	ds_read_b128 v[196:199], v151 offset:2048
	ds_read_b128 v[200:203], v151 offset:3072
	ds_read_b128 v[204:207], v151 offset:4096
	ds_read_b128 v[208:211], v151 offset:5120
	ds_read_b128 v[212:215], v151 offset:6144
	ds_read_b128 v[216:219], v151 offset:7168
	global_load_lds_dwordx4 v[144:145], off
	v_lshl_add_u64 v[144:145], s[58:59], 0, v[138:139]
	s_add_i32 m0, s57, 0xe000
	s_nop 0
	global_load_lds_dwordx4 v[144:145], off
	s_waitcnt vmcnt(8)
	s_waitcnt lgkmcnt(0)
	s_barrier
	s_waitcnt lgkmcnt(0)
	v_mfma_f32_16x16x32_bf16 v[124:127], v[152:155], v[188:191], 0
	v_mfma_f32_16x16x32_bf16 v[124:127], v[156:159], v[192:195], v[124:127]
	v_mfma_f32_16x16x32_bf16 v[120:123], v[160:163], v[188:191], 0
	v_mfma_f32_16x16x32_bf16 v[120:123], v[164:167], v[192:195], v[120:123]
	s_setprio 1
	v_mfma_f32_16x16x32_bf16 v[116:119], v[152:155], v[196:199], 0
	v_mfma_f32_16x16x32_bf16 v[116:119], v[156:159], v[200:203], v[116:119]
	v_mfma_f32_16x16x32_bf16 v[108:111], v[160:163], v[196:199], 0
	v_mfma_f32_16x16x32_bf16 v[108:111], v[164:167], v[200:203], v[108:111]
	v_mfma_f32_16x16x32_bf16 v[100:103], v[152:155], v[204:207], 0
	v_mfma_f32_16x16x32_bf16 v[100:103], v[156:159], v[208:211], v[100:103]
	v_mfma_f32_16x16x32_bf16 v[92:95], v[160:163], v[204:207], 0
	v_mfma_f32_16x16x32_bf16 v[92:95], v[164:167], v[208:211], v[92:95]
	v_mfma_f32_16x16x32_bf16 v[84:87], v[152:155], v[212:215], 0
	v_mfma_f32_16x16x32_bf16 v[84:87], v[156:159], v[216:219], v[84:87]
	v_mfma_f32_16x16x32_bf16 v[76:79], v[160:163], v[212:215], 0
	v_mfma_f32_16x16x32_bf16 v[76:79], v[164:167], v[216:219], v[76:79]
	v_mfma_f32_16x16x32_bf16 v[112:115], v[168:171], v[188:191], 0
	v_mfma_f32_16x16x32_bf16 v[112:115], v[172:175], v[192:195], v[112:115]
	v_mfma_f32_16x16x32_bf16 v[104:107], v[176:179], v[188:191], 0
	v_mfma_f32_16x16x32_bf16 v[104:107], v[184:187], v[192:195], v[104:107]
	v_mfma_f32_16x16x32_bf16 v[96:99], v[168:171], v[196:199], 0
	v_mfma_f32_16x16x32_bf16 v[96:99], v[172:175], v[200:203], v[96:99]
	v_mfma_f32_16x16x32_bf16 v[88:91], v[176:179], v[196:199], 0
	v_mfma_f32_16x16x32_bf16 v[88:91], v[184:187], v[200:203], v[88:91]
	v_mfma_f32_16x16x32_bf16 v[80:83], v[168:171], v[204:207], 0
	v_mfma_f32_16x16x32_bf16 v[80:83], v[172:175], v[208:211], v[80:83]
	v_mfma_f32_16x16x32_bf16 v[72:75], v[176:179], v[204:207], 0
	v_mfma_f32_16x16x32_bf16 v[72:75], v[184:187], v[208:211], v[72:75]
	s_barrier
	v_mfma_f32_16x16x32_bf16 v[68:71], v[168:171], v[212:215], 0
	v_mfma_f32_16x16x32_bf16 v[68:71], v[172:175], v[216:219], v[68:71]
	v_mfma_f32_16x16x32_bf16 v[64:67], v[176:179], v[212:215], 0
	v_mfma_f32_16x16x32_bf16 v[64:67], v[184:187], v[216:219], v[64:67]
	s_setprio 0
	s_add_i32 s18, s73, s66
	v_lshl_add_u64 v[144:145], s[60:61], 0, v[130:131]
	s_mov_b32 m0, s18
	ds_read_b128 v[188:191], v151 offset:16384
	ds_read_b128 v[192:195], v151 offset:17408
	ds_read_b128 v[196:199], v151 offset:18432
	ds_read_b128 v[200:203], v151 offset:19456
	ds_read_b128 v[204:207], v151 offset:20480
	ds_read_b128 v[208:211], v151 offset:21504
	ds_read_b128 v[212:215], v151 offset:22528
	ds_read_b128 v[216:219], v151 offset:23552
	global_load_lds_dwordx4 v[144:145], off
	s_add_i32 m0, s18, 0x2000
	s_add_u32 s18, s60, 0x40000
	v_lshl_add_u64 v[220:221], s[60:61], 0, v[134:135]
	s_addc_u32 s19, s61, 0
	s_add_i32 s79, s74, s66
	global_load_lds_dwordx4 v[220:221], off
	v_lshl_add_u64 v[222:223], s[18:19], 0, v[130:131]
	s_mov_b32 m0, s79
	v_lshl_add_u64 v[224:225], s[62:63], 0, v[132:133]
	global_load_lds_dwordx4 v[222:223], off
	v_lshl_add_u64 v[222:223], s[18:19], 0, v[134:135]
	s_add_i32 m0, s79, 0x2000
	s_nop 0
	global_load_lds_dwordx4 v[222:223], off
	v_lshl_add_u64 v[222:223], s[62:63], 0, v[128:129]
	s_mov_b32 m0, s57
	s_nop 0
	global_load_lds_dwordx4 v[222:223], off
	s_mov_b32 m0, s67
	s_nop 0
	global_load_lds_dwordx4 v[224:225], off
	s_waitcnt vmcnt(8)
	s_waitcnt lgkmcnt(0)
	s_barrier
	s_waitcnt lgkmcnt(0)
	v_mfma_f32_16x16x32_bf16 v[60:63], v[152:155], v[188:191], 0
	v_mfma_f32_16x16x32_bf16 v[60:63], v[156:159], v[192:195], v[60:63]
	v_mfma_f32_16x16x32_bf16 v[56:59], v[160:163], v[188:191], 0
	v_mfma_f32_16x16x32_bf16 v[56:59], v[164:167], v[192:195], v[56:59]
	s_setprio 1
	v_mfma_f32_16x16x32_bf16 v[52:55], v[152:155], v[196:199], 0
	v_mfma_f32_16x16x32_bf16 v[52:55], v[156:159], v[200:203], v[52:55]
	v_mfma_f32_16x16x32_bf16 v[44:47], v[160:163], v[196:199], 0
	v_mfma_f32_16x16x32_bf16 v[44:47], v[164:167], v[200:203], v[44:47]
	v_mfma_f32_16x16x32_bf16 v[36:39], v[152:155], v[204:207], 0
	v_mfma_f32_16x16x32_bf16 v[36:39], v[156:159], v[208:211], v[36:39]
	v_mfma_f32_16x16x32_bf16 v[28:31], v[160:163], v[204:207], 0
	v_mfma_f32_16x16x32_bf16 v[28:31], v[164:167], v[208:211], v[28:31]
	v_mfma_f32_16x16x32_bf16 v[20:23], v[152:155], v[212:215], 0
	v_mfma_f32_16x16x32_bf16 v[20:23], v[156:159], v[216:219], v[20:23]
	v_mfma_f32_16x16x32_bf16 v[12:15], v[160:163], v[212:215], 0
	v_mfma_f32_16x16x32_bf16 v[12:15], v[164:167], v[216:219], v[12:15]
	v_mfma_f32_16x16x32_bf16 v[48:51], v[168:171], v[188:191], 0
	v_mfma_f32_16x16x32_bf16 v[48:51], v[172:175], v[192:195], v[48:51]
	v_mfma_f32_16x16x32_bf16 v[40:43], v[176:179], v[188:191], 0
	v_mfma_f32_16x16x32_bf16 v[40:43], v[184:187], v[192:195], v[40:43]
	v_mfma_f32_16x16x32_bf16 v[32:35], v[168:171], v[196:199], 0
	v_mfma_f32_16x16x32_bf16 v[32:35], v[172:175], v[200:203], v[32:35]
	v_mfma_f32_16x16x32_bf16 v[24:27], v[176:179], v[196:199], 0
	v_mfma_f32_16x16x32_bf16 v[24:27], v[184:187], v[200:203], v[24:27]
	v_mfma_f32_16x16x32_bf16 v[16:19], v[168:171], v[204:207], 0
	v_mfma_f32_16x16x32_bf16 v[16:19], v[172:175], v[208:211], v[16:19]
	v_mfma_f32_16x16x32_bf16 v[8:11], v[176:179], v[204:207], 0
	v_mfma_f32_16x16x32_bf16 v[8:11], v[184:187], v[208:211], v[8:11]
	s_barrier
	v_mfma_f32_16x16x32_bf16 v[4:7], v[168:171], v[212:215], 0
	v_mfma_f32_16x16x32_bf16 v[4:7], v[172:175], v[216:219], v[4:7]
	v_mfma_f32_16x16x32_bf16 v[0:3], v[176:179], v[212:215], 0
	v_mfma_f32_16x16x32_bf16 v[0:3], v[184:187], v[216:219], v[0:3]
	s_setprio 0
	s_branch .Lmid_gemm3
.LBB0_601:
	ds_read_b128 v[152:155], v149
	ds_read_b128 v[156:159], v149 offset:1024
	ds_read_b128 v[160:163], v149 offset:2048
	ds_read_b128 v[164:167], v149 offset:3072
	ds_read_b128 v[168:171], v150
	ds_read_b128 v[172:175], v150 offset:1024
	ds_read_b128 v[176:179], v150 offset:2048
	ds_read_b128 v[184:187], v150 offset:3072
	s_add_u32 s18, s58, 0xfffc0080
	s_addc_u32 s19, s59, -1
	s_cmp_eq_u32 s88, 12
	s_cselect_b32 s63, s49, s19
	s_cselect_b32 s62, s84, s18
	s_cselect_b32 s61, s47, s87
	s_cselect_b32 s60, s85, s86
	v_lshl_add_u64 v[144:145], s[58:59], 0, v[136:137]
	s_add_i32 m0, s57, 0xc000
	ds_read_b128 v[188:191], v151
	ds_read_b128 v[192:195], v151 offset:1024
	ds_read_b128 v[196:199], v151 offset:2048
	ds_read_b128 v[200:203], v151 offset:3072
	ds_read_b128 v[204:207], v151 offset:4096
	ds_read_b128 v[208:211], v151 offset:5120
	ds_read_b128 v[212:215], v151 offset:6144
	ds_read_b128 v[216:219], v151 offset:7168
	global_load_lds_dwordx4 v[144:145], off
	v_lshl_add_u64 v[144:145], s[58:59], 0, v[138:139]
	s_add_i32 m0, s57, 0xe000
	s_nop 0
	global_load_lds_dwordx4 v[144:145], off
	s_waitcnt vmcnt(8)
	s_waitcnt lgkmcnt(0)
	s_barrier
	s_waitcnt lgkmcnt(0)
	v_mfma_f32_16x16x32_bf16 v[124:127], v[152:155], v[188:191], v[124:127]
	v_mfma_f32_16x16x32_bf16 v[124:127], v[156:159], v[192:195], v[124:127]
	v_mfma_f32_16x16x32_bf16 v[120:123], v[160:163], v[188:191], v[120:123]
	v_mfma_f32_16x16x32_bf16 v[120:123], v[164:167], v[192:195], v[120:123]
	s_setprio 1
	v_mfma_f32_16x16x32_bf16 v[116:119], v[152:155], v[196:199], v[116:119]
	v_mfma_f32_16x16x32_bf16 v[116:119], v[156:159], v[200:203], v[116:119]
	v_mfma_f32_16x16x32_bf16 v[108:111], v[160:163], v[196:199], v[108:111]
	v_mfma_f32_16x16x32_bf16 v[108:111], v[164:167], v[200:203], v[108:111]
	v_mfma_f32_16x16x32_bf16 v[100:103], v[152:155], v[204:207], v[100:103]
	v_mfma_f32_16x16x32_bf16 v[100:103], v[156:159], v[208:211], v[100:103]
	v_mfma_f32_16x16x32_bf16 v[92:95], v[160:163], v[204:207], v[92:95]
	v_mfma_f32_16x16x32_bf16 v[92:95], v[164:167], v[208:211], v[92:95]
	v_mfma_f32_16x16x32_bf16 v[84:87], v[152:155], v[212:215], v[84:87]
	v_mfma_f32_16x16x32_bf16 v[84:87], v[156:159], v[216:219], v[84:87]
	v_mfma_f32_16x16x32_bf16 v[76:79], v[160:163], v[212:215], v[76:79]
	v_mfma_f32_16x16x32_bf16 v[76:79], v[164:167], v[216:219], v[76:79]
	v_mfma_f32_16x16x32_bf16 v[112:115], v[168:171], v[188:191], v[112:115]
	v_mfma_f32_16x16x32_bf16 v[112:115], v[172:175], v[192:195], v[112:115]
	v_mfma_f32_16x16x32_bf16 v[104:107], v[176:179], v[188:191], v[104:107]
	v_mfma_f32_16x16x32_bf16 v[104:107], v[184:187], v[192:195], v[104:107]
	v_mfma_f32_16x16x32_bf16 v[96:99], v[168:171], v[196:199], v[96:99]
	v_mfma_f32_16x16x32_bf16 v[96:99], v[172:175], v[200:203], v[96:99]
	v_mfma_f32_16x16x32_bf16 v[88:91], v[176:179], v[196:199], v[88:91]
	v_mfma_f32_16x16x32_bf16 v[88:91], v[184:187], v[200:203], v[88:91]
	v_mfma_f32_16x16x32_bf16 v[80:83], v[168:171], v[204:207], v[80:83]
	v_mfma_f32_16x16x32_bf16 v[80:83], v[172:175], v[208:211], v[80:83]
	v_mfma_f32_16x16x32_bf16 v[72:75], v[176:179], v[204:207], v[72:75]
	v_mfma_f32_16x16x32_bf16 v[72:75], v[184:187], v[208:211], v[72:75]
	s_barrier
	v_mfma_f32_16x16x32_bf16 v[68:71], v[168:171], v[212:215], v[68:71]
	v_mfma_f32_16x16x32_bf16 v[68:71], v[172:175], v[216:219], v[68:71]
	v_mfma_f32_16x16x32_bf16 v[64:67], v[176:179], v[212:215], v[64:67]
	v_mfma_f32_16x16x32_bf16 v[64:67], v[184:187], v[216:219], v[64:67]
	s_setprio 0
	s_add_i32 s18, s73, s66
	v_lshl_add_u64 v[144:145], s[60:61], 0, v[130:131]
	s_mov_b32 m0, s18
	ds_read_b128 v[188:191], v151 offset:16384
	ds_read_b128 v[192:195], v151 offset:17408
	ds_read_b128 v[196:199], v151 offset:18432
	ds_read_b128 v[200:203], v151 offset:19456
	ds_read_b128 v[204:207], v151 offset:20480
	ds_read_b128 v[208:211], v151 offset:21504
	ds_read_b128 v[212:215], v151 offset:22528
	ds_read_b128 v[216:219], v151 offset:23552
	global_load_lds_dwordx4 v[144:145], off
	s_add_i32 m0, s18, 0x2000
	s_add_u32 s18, s60, 0x40000
	v_lshl_add_u64 v[220:221], s[60:61], 0, v[134:135]
	s_addc_u32 s19, s61, 0
	s_add_i32 s79, s74, s66
	global_load_lds_dwordx4 v[220:221], off
	v_lshl_add_u64 v[222:223], s[18:19], 0, v[130:131]
	s_mov_b32 m0, s79
	v_lshl_add_u64 v[224:225], s[62:63], 0, v[132:133]
	global_load_lds_dwordx4 v[222:223], off
	v_lshl_add_u64 v[222:223], s[18:19], 0, v[134:135]
	s_add_i32 m0, s79, 0x2000
	s_nop 0
	global_load_lds_dwordx4 v[222:223], off
	v_lshl_add_u64 v[222:223], s[62:63], 0, v[128:129]
	s_mov_b32 m0, s57
	s_nop 0
	global_load_lds_dwordx4 v[222:223], off
	s_mov_b32 m0, s67
	s_nop 0
	global_load_lds_dwordx4 v[224:225], off
	s_waitcnt vmcnt(8)
	s_waitcnt lgkmcnt(0)
	s_barrier
	s_waitcnt lgkmcnt(0)
	v_mfma_f32_16x16x32_bf16 v[60:63], v[152:155], v[188:191], v[60:63]
	v_mfma_f32_16x16x32_bf16 v[60:63], v[156:159], v[192:195], v[60:63]
	v_mfma_f32_16x16x32_bf16 v[56:59], v[160:163], v[188:191], v[56:59]
	v_mfma_f32_16x16x32_bf16 v[56:59], v[164:167], v[192:195], v[56:59]
	s_setprio 1
	v_mfma_f32_16x16x32_bf16 v[52:55], v[152:155], v[196:199], v[52:55]
	v_mfma_f32_16x16x32_bf16 v[52:55], v[156:159], v[200:203], v[52:55]
	v_mfma_f32_16x16x32_bf16 v[44:47], v[160:163], v[196:199], v[44:47]
	v_mfma_f32_16x16x32_bf16 v[44:47], v[164:167], v[200:203], v[44:47]
	v_mfma_f32_16x16x32_bf16 v[36:39], v[152:155], v[204:207], v[36:39]
	v_mfma_f32_16x16x32_bf16 v[36:39], v[156:159], v[208:211], v[36:39]
	v_mfma_f32_16x16x32_bf16 v[28:31], v[160:163], v[204:207], v[28:31]
	v_mfma_f32_16x16x32_bf16 v[28:31], v[164:167], v[208:211], v[28:31]
	v_mfma_f32_16x16x32_bf16 v[20:23], v[152:155], v[212:215], v[20:23]
	v_mfma_f32_16x16x32_bf16 v[20:23], v[156:159], v[216:219], v[20:23]
	v_mfma_f32_16x16x32_bf16 v[12:15], v[160:163], v[212:215], v[12:15]
	v_mfma_f32_16x16x32_bf16 v[12:15], v[164:167], v[216:219], v[12:15]
	v_mfma_f32_16x16x32_bf16 v[48:51], v[168:171], v[188:191], v[48:51]
	v_mfma_f32_16x16x32_bf16 v[48:51], v[172:175], v[192:195], v[48:51]
	v_mfma_f32_16x16x32_bf16 v[40:43], v[176:179], v[188:191], v[40:43]
	v_mfma_f32_16x16x32_bf16 v[40:43], v[184:187], v[192:195], v[40:43]
	v_mfma_f32_16x16x32_bf16 v[32:35], v[168:171], v[196:199], v[32:35]
	v_mfma_f32_16x16x32_bf16 v[32:35], v[172:175], v[200:203], v[32:35]
	v_mfma_f32_16x16x32_bf16 v[24:27], v[176:179], v[196:199], v[24:27]
	v_mfma_f32_16x16x32_bf16 v[24:27], v[184:187], v[200:203], v[24:27]
	v_mfma_f32_16x16x32_bf16 v[16:19], v[168:171], v[204:207], v[16:19]
	v_mfma_f32_16x16x32_bf16 v[16:19], v[172:175], v[208:211], v[16:19]
	v_mfma_f32_16x16x32_bf16 v[8:11], v[176:179], v[204:207], v[8:11]
	v_mfma_f32_16x16x32_bf16 v[8:11], v[184:187], v[208:211], v[8:11]
	s_barrier
	v_mfma_f32_16x16x32_bf16 v[4:7], v[168:171], v[212:215], v[4:7]
	v_mfma_f32_16x16x32_bf16 v[4:7], v[172:175], v[216:219], v[4:7]
	v_mfma_f32_16x16x32_bf16 v[0:3], v[176:179], v[212:215], v[0:3]
	v_mfma_f32_16x16x32_bf16 v[0:3], v[184:187], v[216:219], v[0:3]
	s_setprio 0
.Lmid_gemm3:
	s_add_i32 s79, 0, 0x18000
	s_add_i32 s89, 0, 0x1c000
	v_add_u32_e32 v164, s79, v147
	v_add_u32_e32 v181, s89, v147
	ds_read_b128 v[152:155], v164
	ds_read_b128 v[156:159], v164 offset:1024
	ds_read_b128 v[160:163], v164 offset:2048
	ds_read_b128 v[164:167], v164 offset:3072
	ds_read_b128 v[168:171], v181
	ds_read_b128 v[172:175], v181 offset:1024
	ds_read_b128 v[176:179], v181 offset:2048
	ds_read_b128 v[184:187], v181 offset:3072
	s_add_u32 s18, s62, 0x40000
	s_addc_u32 s19, s63, 0
	s_mov_b32 m0, s68
	v_lshl_add_u64 v[226:227], s[18:19], 0, v[128:129]
	ds_read_b128 v[188:191], v151 offset:32768
	ds_read_b128 v[192:195], v151 offset:33792
	ds_read_b128 v[196:199], v151 offset:34816
	ds_read_b128 v[200:203], v151 offset:35840
	ds_read_b128 v[204:207], v151 offset:36864
	ds_read_b128 v[208:211], v151 offset:37888
	ds_read_b128 v[212:215], v151 offset:38912
	ds_read_b128 v[216:219], v151 offset:39936
	global_load_lds_dwordx4 v[226:227], off
	v_lshl_add_u64 v[226:227], s[18:19], 0, v[132:133]
	s_mov_b32 m0, s69
	s_nop 0
	global_load_lds_dwordx4 v[226:227], off
	s_waitcnt vmcnt(8)
	s_waitcnt lgkmcnt(0)
	s_barrier
	s_waitcnt lgkmcnt(0)
	v_mfma_f32_16x16x32_bf16 v[124:127], v[152:155], v[188:191], v[124:127]
	v_mfma_f32_16x16x32_bf16 v[124:127], v[156:159], v[192:195], v[124:127]
	v_mfma_f32_16x16x32_bf16 v[120:123], v[160:163], v[188:191], v[120:123]
	v_mfma_f32_16x16x32_bf16 v[120:123], v[164:167], v[192:195], v[120:123]
	s_setprio 1
	v_mfma_f32_16x16x32_bf16 v[116:119], v[152:155], v[196:199], v[116:119]
	v_mfma_f32_16x16x32_bf16 v[116:119], v[156:159], v[200:203], v[116:119]
	v_mfma_f32_16x16x32_bf16 v[108:111], v[160:163], v[196:199], v[108:111]
	v_mfma_f32_16x16x32_bf16 v[108:111], v[164:167], v[200:203], v[108:111]
	v_mfma_f32_16x16x32_bf16 v[100:103], v[152:155], v[204:207], v[100:103]
	v_mfma_f32_16x16x32_bf16 v[100:103], v[156:159], v[208:211], v[100:103]
	v_mfma_f32_16x16x32_bf16 v[92:95], v[160:163], v[204:207], v[92:95]
	v_mfma_f32_16x16x32_bf16 v[92:95], v[164:167], v[208:211], v[92:95]
	v_mfma_f32_16x16x32_bf16 v[84:87], v[152:155], v[212:215], v[84:87]
	v_mfma_f32_16x16x32_bf16 v[84:87], v[156:159], v[216:219], v[84:87]
	v_mfma_f32_16x16x32_bf16 v[76:79], v[160:163], v[212:215], v[76:79]
	v_mfma_f32_16x16x32_bf16 v[76:79], v[164:167], v[216:219], v[76:79]
	v_mfma_f32_16x16x32_bf16 v[112:115], v[168:171], v[188:191], v[112:115]
	v_mfma_f32_16x16x32_bf16 v[112:115], v[172:175], v[192:195], v[112:115]
	v_mfma_f32_16x16x32_bf16 v[104:107], v[176:179], v[188:191], v[104:107]
	v_mfma_f32_16x16x32_bf16 v[104:107], v[184:187], v[192:195], v[104:107]
	v_mfma_f32_16x16x32_bf16 v[96:99], v[168:171], v[196:199], v[96:99]
	v_mfma_f32_16x16x32_bf16 v[96:99], v[172:175], v[200:203], v[96:99]
	v_mfma_f32_16x16x32_bf16 v[88:91], v[176:179], v[196:199], v[88:91]
	v_mfma_f32_16x16x32_bf16 v[88:91], v[184:187], v[200:203], v[88:91]
	v_mfma_f32_16x16x32_bf16 v[80:83], v[168:171], v[204:207], v[80:83]
	v_mfma_f32_16x16x32_bf16 v[80:83], v[172:175], v[208:211], v[80:83]
	v_mfma_f32_16x16x32_bf16 v[72:75], v[176:179], v[204:207], v[72:75]
	v_mfma_f32_16x16x32_bf16 v[72:75], v[184:187], v[208:211], v[72:75]
	s_barrier
	v_mfma_f32_16x16x32_bf16 v[68:71], v[168:171], v[212:215], v[68:71]
	v_mfma_f32_16x16x32_bf16 v[68:71], v[172:175], v[216:219], v[68:71]
	v_mfma_f32_16x16x32_bf16 v[64:67], v[176:179], v[212:215], v[64:67]
	v_mfma_f32_16x16x32_bf16 v[64:67], v[184:187], v[216:219], v[64:67]
	s_setprio 0
	s_add_i32 s18, s79, s66
	v_lshl_add_u64 v[144:145], v[144:145], 0, s[10:11]
	s_mov_b32 m0, s18
	ds_read_b128 v[188:191], v151 offset:49152
	ds_read_b128 v[192:195], v151 offset:50176
	ds_read_b128 v[196:199], v151 offset:51200
	ds_read_b128 v[200:203], v151 offset:52224
	ds_read_b128 v[204:207], v151 offset:53248
	ds_read_b128 v[208:211], v151 offset:54272
	ds_read_b128 v[212:215], v151 offset:55296
	ds_read_b128 v[216:219], v151 offset:56320
	global_load_lds_dwordx4 v[144:145], off
	s_add_i32 m0, s18, 0x2000
	s_add_u32 s18, s60, 0x40080
	v_lshl_add_u64 v[144:145], v[220:221], 0, s[10:11]
	s_addc_u32 s19, s61, 0
	s_add_i32 s60, s89, s66
	global_load_lds_dwordx4 v[144:145], off
	v_lshl_add_u64 v[144:145], s[18:19], 0, v[130:131]
	s_mov_b32 m0, s60
	s_nop 0
	global_load_lds_dwordx4 v[144:145], off
	v_lshl_add_u64 v[144:145], s[18:19], 0, v[134:135]
	s_add_i32 m0, s60, 0x2000
	s_nop 0
	global_load_lds_dwordx4 v[144:145], off
	v_lshl_add_u64 v[144:145], v[222:223], 0, s[10:11]
	s_mov_b32 m0, s71
	s_nop 0
	global_load_lds_dwordx4 v[144:145], off
	v_lshl_add_u64 v[144:145], v[224:225], 0, s[10:11]
	s_mov_b32 m0, s72
	s_nop 0
	global_load_lds_dwordx4 v[144:145], off
	s_waitcnt vmcnt(8)
	s_waitcnt lgkmcnt(0)
	s_barrier
	s_waitcnt lgkmcnt(0)
	v_mfma_f32_16x16x32_bf16 v[60:63], v[152:155], v[188:191], v[60:63]
	v_mfma_f32_16x16x32_bf16 v[60:63], v[156:159], v[192:195], v[60:63]
	v_mfma_f32_16x16x32_bf16 v[56:59], v[160:163], v[188:191], v[56:59]
	v_mfma_f32_16x16x32_bf16 v[56:59], v[164:167], v[192:195], v[56:59]
	s_setprio 1
	v_mfma_f32_16x16x32_bf16 v[52:55], v[152:155], v[196:199], v[52:55]
	v_mfma_f32_16x16x32_bf16 v[52:55], v[156:159], v[200:203], v[52:55]
	v_mfma_f32_16x16x32_bf16 v[44:47], v[160:163], v[196:199], v[44:47]
	v_mfma_f32_16x16x32_bf16 v[44:47], v[164:167], v[200:203], v[44:47]
	v_mfma_f32_16x16x32_bf16 v[36:39], v[152:155], v[204:207], v[36:39]
	v_mfma_f32_16x16x32_bf16 v[36:39], v[156:159], v[208:211], v[36:39]
	v_mfma_f32_16x16x32_bf16 v[28:31], v[160:163], v[204:207], v[28:31]
	v_mfma_f32_16x16x32_bf16 v[28:31], v[164:167], v[208:211], v[28:31]
	v_mfma_f32_16x16x32_bf16 v[20:23], v[152:155], v[212:215], v[20:23]
	v_mfma_f32_16x16x32_bf16 v[20:23], v[156:159], v[216:219], v[20:23]
	v_mfma_f32_16x16x32_bf16 v[12:15], v[160:163], v[212:215], v[12:15]
	v_mfma_f32_16x16x32_bf16 v[12:15], v[164:167], v[216:219], v[12:15]
	v_mfma_f32_16x16x32_bf16 v[48:51], v[168:171], v[188:191], v[48:51]
	v_mfma_f32_16x16x32_bf16 v[48:51], v[172:175], v[192:195], v[48:51]
	v_mfma_f32_16x16x32_bf16 v[40:43], v[176:179], v[188:191], v[40:43]
	v_mfma_f32_16x16x32_bf16 v[40:43], v[184:187], v[192:195], v[40:43]
	v_mfma_f32_16x16x32_bf16 v[32:35], v[168:171], v[196:199], v[32:35]
	v_mfma_f32_16x16x32_bf16 v[32:35], v[172:175], v[200:203], v[32:35]
	v_mfma_f32_16x16x32_bf16 v[24:27], v[176:179], v[196:199], v[24:27]
	v_mfma_f32_16x16x32_bf16 v[24:27], v[184:187], v[200:203], v[24:27]
	v_mfma_f32_16x16x32_bf16 v[16:19], v[168:171], v[204:207], v[16:19]
	v_mfma_f32_16x16x32_bf16 v[16:19], v[172:175], v[208:211], v[16:19]
	v_mfma_f32_16x16x32_bf16 v[8:11], v[176:179], v[204:207], v[8:11]
	v_mfma_f32_16x16x32_bf16 v[8:11], v[184:187], v[208:211], v[8:11]
	s_barrier
	v_mfma_f32_16x16x32_bf16 v[4:7], v[168:171], v[212:215], v[4:7]
	v_mfma_f32_16x16x32_bf16 v[4:7], v[172:175], v[216:219], v[4:7]
	v_mfma_f32_16x16x32_bf16 v[0:3], v[176:179], v[212:215], v[0:3]
	v_mfma_f32_16x16x32_bf16 v[0:3], v[184:187], v[216:219], v[0:3]
	s_setprio 0
	s_add_i32 s88, s88, 2
	s_add_u32 s58, s58, 0x100
	s_addc_u32 s59, s59, 0
	s_add_u32 s86, s86, 0x100
	s_addc_u32 s87, s87, 0
	s_cmp_gt_u32 s88, 13
	s_cbranch_scc0 .LBB0_601
	s_and_b64 vcc, exec, s[12:13]
	s_cbranch_vccz .LBB0_604
	s_barrier

.LBB0_723:
	s_ashr_i32 s31, s30, 31
	s_lshl_b64 s[36:37], s[30:31], 19
	s_add_u32 s36, s80, s36
	s_addc_u32 s37, s81, s37
	s_and_b64 s[44:45], s[10:11], exec
	s_cselect_b32 s31, s37, s49
	s_cselect_b32 s70, s36, s48
	s_ashr_i32 s19, s18, 31
	s_lshl_b64 s[44:45], s[18:19], 19
	s_add_u32 s44, s56, s44
	s_addc_u32 s45, s57, s45
	s_and_b64 s[54:55], s[10:11], exec
	s_cselect_b32 s19, s45, s53
	s_cselect_b32 s71, s44, s52
	s_add_u32 s48, s48, 0x40080
	s_addc_u32 s49, s49, 0
	s_add_u32 s72, s52, 0x100
	s_addc_u32 s73, s53, 0
	s_mov_b32 s74, -2
	ds_read_b128 v[140:143], v147
	ds_read_b128 v[150:153], v147 offset:1024
	ds_read_b128 v[154:157], v147 offset:2048
	ds_read_b128 v[158:161], v147 offset:3072
	ds_read_b128 v[162:165], v148
	ds_read_b128 v[166:169], v148 offset:1024
	ds_read_b128 v[170:173], v148 offset:2048
	ds_read_b128 v[174:177], v148 offset:3072
	s_add_u32 s52, s48, 0xfffc0080
	s_addc_u32 s53, s49, -1
	s_cmp_eq_u32 s74, 12
	s_cselect_b32 s55, s31, s53
	s_cselect_b32 s54, s70, s52
	s_cselect_b32 s53, s19, s73
	s_cselect_b32 s52, s71, s72
	v_lshl_add_u64 v[178:179], s[48:49], 0, v[132:133]
	s_add_i32 m0, s47, 0xc000
	ds_read_b128 v[184:187], v149
	ds_read_b128 v[188:191], v149 offset:1024
	ds_read_b128 v[192:195], v149 offset:2048
	ds_read_b128 v[196:199], v149 offset:3072
	ds_read_b128 v[200:203], v149 offset:4096
	ds_read_b128 v[204:207], v149 offset:5120
	ds_read_b128 v[208:211], v149 offset:6144
	ds_read_b128 v[212:215], v149 offset:7168
	global_load_lds_dwordx4 v[178:179], off
	v_lshl_add_u64 v[178:179], s[48:49], 0, v[134:135]
	s_add_i32 m0, s47, 0xe000
	s_nop 0
	global_load_lds_dwordx4 v[178:179], off
	s_waitcnt vmcnt(8)
	s_waitcnt lgkmcnt(0)
	s_barrier
	s_waitcnt lgkmcnt(0)
	v_mfma_f32_16x16x32_bf16 v[124:127], v[140:143], v[184:187], 0
	v_mfma_f32_16x16x32_bf16 v[124:127], v[150:153], v[188:191], v[124:127]
	v_mfma_f32_16x16x32_bf16 v[120:123], v[154:157], v[184:187], 0
	v_mfma_f32_16x16x32_bf16 v[120:123], v[158:161], v[188:191], v[120:123]
	s_setprio 1
	v_mfma_f32_16x16x32_bf16 v[108:111], v[140:143], v[192:195], 0
	v_mfma_f32_16x16x32_bf16 v[108:111], v[150:153], v[196:199], v[108:111]
	v_mfma_f32_16x16x32_bf16 v[104:107], v[154:157], v[192:195], 0
	v_mfma_f32_16x16x32_bf16 v[104:107], v[158:161], v[196:199], v[104:107]
	v_mfma_f32_16x16x32_bf16 v[92:95], v[140:143], v[200:203], 0
	v_mfma_f32_16x16x32_bf16 v[92:95], v[150:153], v[204:207], v[92:95]
	v_mfma_f32_16x16x32_bf16 v[88:91], v[154:157], v[200:203], 0
	v_mfma_f32_16x16x32_bf16 v[88:91], v[158:161], v[204:207], v[88:91]
	v_mfma_f32_16x16x32_bf16 v[76:79], v[140:143], v[208:211], 0
	v_mfma_f32_16x16x32_bf16 v[76:79], v[150:153], v[212:215], v[76:79]
	v_mfma_f32_16x16x32_bf16 v[72:75], v[154:157], v[208:211], 0
	v_mfma_f32_16x16x32_bf16 v[72:75], v[158:161], v[212:215], v[72:75]
	v_mfma_f32_16x16x32_bf16 v[116:119], v[162:165], v[184:187], 0
	v_mfma_f32_16x16x32_bf16 v[116:119], v[166:169], v[188:191], v[116:119]
	v_mfma_f32_16x16x32_bf16 v[112:115], v[170:173], v[184:187], 0
	v_mfma_f32_16x16x32_bf16 v[112:115], v[174:177], v[188:191], v[112:115]
	v_mfma_f32_16x16x32_bf16 v[100:103], v[162:165], v[192:195], 0
	v_mfma_f32_16x16x32_bf16 v[100:103], v[166:169], v[196:199], v[100:103]
	v_mfma_f32_16x16x32_bf16 v[96:99], v[170:173], v[192:195], 0
	v_mfma_f32_16x16x32_bf16 v[96:99], v[174:177], v[196:199], v[96:99]
	v_mfma_f32_16x16x32_bf16 v[84:87], v[162:165], v[200:203], 0
	v_mfma_f32_16x16x32_bf16 v[84:87], v[166:169], v[204:207], v[84:87]
	v_mfma_f32_16x16x32_bf16 v[80:83], v[170:173], v[200:203], 0
	v_mfma_f32_16x16x32_bf16 v[80:83], v[174:177], v[204:207], v[80:83]
	s_barrier
	v_mfma_f32_16x16x32_bf16 v[68:71], v[162:165], v[208:211], 0
	v_mfma_f32_16x16x32_bf16 v[68:71], v[166:169], v[212:215], v[68:71]
	v_mfma_f32_16x16x32_bf16 v[64:67], v[170:173], v[208:211], 0
	v_mfma_f32_16x16x32_bf16 v[64:67], v[174:177], v[212:215], v[64:67]
	s_setprio 0
	s_add_i32 s75, s66, s58
	v_lshl_add_u64 v[178:179], s[52:53], 0, v[130:131]
	s_mov_b32 m0, s75
	ds_read_b128 v[184:187], v149 offset:16384
	ds_read_b128 v[188:191], v149 offset:17408
	ds_read_b128 v[192:195], v149 offset:18432
	ds_read_b128 v[196:199], v149 offset:19456
	ds_read_b128 v[200:203], v149 offset:20480
	ds_read_b128 v[204:207], v149 offset:21504
	ds_read_b128 v[208:211], v149 offset:22528
	ds_read_b128 v[212:215], v149 offset:23552
	global_load_lds_dwordx4 v[178:179], off
	s_add_i32 m0, s75, 0x2000
	s_add_u32 s76, s52, 0x40000
	v_lshl_add_u64 v[216:217], s[52:53], 0, v[128:129]
	s_addc_u32 s77, s53, 0
	s_add_i32 s75, s67, s58
	global_load_lds_dwordx4 v[216:217], off
	v_lshl_add_u64 v[218:219], s[76:77], 0, v[130:131]
	s_mov_b32 m0, s75
	v_lshl_add_u64 v[220:221], s[54:55], 0, v[128:129]
	global_load_lds_dwordx4 v[218:219], off
	v_lshl_add_u64 v[218:219], s[76:77], 0, v[128:129]
	s_add_i32 m0, s75, 0x2000
	s_nop 0
	global_load_lds_dwordx4 v[218:219], off
	v_lshl_add_u64 v[218:219], s[54:55], 0, v[130:131]
	s_mov_b32 m0, s47
	s_nop 0
	global_load_lds_dwordx4 v[218:219], off
	s_mov_b32 m0, s60
	s_nop 0
	global_load_lds_dwordx4 v[220:221], off
	s_waitcnt vmcnt(8)
	s_waitcnt lgkmcnt(0)
	s_barrier
	s_waitcnt lgkmcnt(0)
	v_mfma_f32_16x16x32_bf16 v[60:63], v[140:143], v[184:187], 0
	v_mfma_f32_16x16x32_bf16 v[60:63], v[150:153], v[188:191], v[60:63]
	v_mfma_f32_16x16x32_bf16 v[56:59], v[154:157], v[184:187], 0
	v_mfma_f32_16x16x32_bf16 v[56:59], v[158:161], v[188:191], v[56:59]
	s_setprio 1
	v_mfma_f32_16x16x32_bf16 v[44:47], v[140:143], v[192:195], 0
	v_mfma_f32_16x16x32_bf16 v[44:47], v[150:153], v[196:199], v[44:47]
	v_mfma_f32_16x16x32_bf16 v[40:43], v[154:157], v[192:195], 0
	v_mfma_f32_16x16x32_bf16 v[40:43], v[158:161], v[196:199], v[40:43]
	v_mfma_f32_16x16x32_bf16 v[28:31], v[140:143], v[200:203], 0
	v_mfma_f32_16x16x32_bf16 v[28:31], v[150:153], v[204:207], v[28:31]
	v_mfma_f32_16x16x32_bf16 v[24:27], v[154:157], v[200:203], 0
	v_mfma_f32_16x16x32_bf16 v[24:27], v[158:161], v[204:207], v[24:27]
	v_mfma_f32_16x16x32_bf16 v[12:15], v[140:143], v[208:211], 0
	v_mfma_f32_16x16x32_bf16 v[12:15], v[150:153], v[212:215], v[12:15]
	v_mfma_f32_16x16x32_bf16 v[8:11], v[154:157], v[208:211], 0
	v_mfma_f32_16x16x32_bf16 v[8:11], v[158:161], v[212:215], v[8:11]
	v_mfma_f32_16x16x32_bf16 v[52:55], v[162:165], v[184:187], 0
	v_mfma_f32_16x16x32_bf16 v[52:55], v[166:169], v[188:191], v[52:55]
	v_mfma_f32_16x16x32_bf16 v[48:51], v[170:173], v[184:187], 0
	v_mfma_f32_16x16x32_bf16 v[48:51], v[174:177], v[188:191], v[48:51]
	v_mfma_f32_16x16x32_bf16 v[36:39], v[162:165], v[192:195], 0
	v_mfma_f32_16x16x32_bf16 v[36:39], v[166:169], v[196:199], v[36:39]
	v_mfma_f32_16x16x32_bf16 v[32:35], v[170:173], v[192:195], 0
	v_mfma_f32_16x16x32_bf16 v[32:35], v[174:177], v[196:199], v[32:35]
	v_mfma_f32_16x16x32_bf16 v[20:23], v[162:165], v[200:203], 0
	v_mfma_f32_16x16x32_bf16 v[20:23], v[166:169], v[204:207], v[20:23]
	v_mfma_f32_16x16x32_bf16 v[16:19], v[170:173], v[200:203], 0
	v_mfma_f32_16x16x32_bf16 v[16:19], v[174:177], v[204:207], v[16:19]
	s_barrier
	v_mfma_f32_16x16x32_bf16 v[4:7], v[162:165], v[208:211], 0
	v_mfma_f32_16x16x32_bf16 v[4:7], v[166:169], v[212:215], v[4:7]
	v_mfma_f32_16x16x32_bf16 v[0:3], v[170:173], v[208:211], 0
	v_mfma_f32_16x16x32_bf16 v[0:3], v[174:177], v[212:215], v[0:3]
	s_setprio 0
	s_branch .Lmid_gemm4
.LBB0_724:
	ds_read_b128 v[140:143], v147
	ds_read_b128 v[150:153], v147 offset:1024
	ds_read_b128 v[154:157], v147 offset:2048
	ds_read_b128 v[158:161], v147 offset:3072
	ds_read_b128 v[162:165], v148
	ds_read_b128 v[166:169], v148 offset:1024
	ds_read_b128 v[170:173], v148 offset:2048
	ds_read_b128 v[174:177], v148 offset:3072
	s_add_u32 s52, s48, 0xfffc0080
	s_addc_u32 s53, s49, -1
	s_cmp_eq_u32 s74, 12
	s_cselect_b32 s55, s31, s53
	s_cselect_b32 s54, s70, s52
	s_cselect_b32 s53, s19, s73
	s_cselect_b32 s52, s71, s72
	v_lshl_add_u64 v[178:179], s[48:49], 0, v[132:133]
	s_add_i32 m0, s47, 0xc000
	ds_read_b128 v[184:187], v149
	ds_read_b128 v[188:191], v149 offset:1024
	ds_read_b128 v[192:195], v149 offset:2048
	ds_read_b128 v[196:199], v149 offset:3072
	ds_read_b128 v[200:203], v149 offset:4096
	ds_read_b128 v[204:207], v149 offset:5120
	ds_read_b128 v[208:211], v149 offset:6144
	ds_read_b128 v[212:215], v149 offset:7168
	global_load_lds_dwordx4 v[178:179], off
	v_lshl_add_u64 v[178:179], s[48:49], 0, v[134:135]
	s_add_i32 m0, s47, 0xe000
	s_nop 0
	global_load_lds_dwordx4 v[178:179], off
	s_waitcnt vmcnt(8)
	s_waitcnt lgkmcnt(0)
	s_barrier
	s_waitcnt lgkmcnt(0)
	v_mfma_f32_16x16x32_bf16 v[124:127], v[140:143], v[184:187], v[124:127]
	v_mfma_f32_16x16x32_bf16 v[124:127], v[150:153], v[188:191], v[124:127]
	v_mfma_f32_16x16x32_bf16 v[120:123], v[154:157], v[184:187], v[120:123]
	v_mfma_f32_16x16x32_bf16 v[120:123], v[158:161], v[188:191], v[120:123]
	s_setprio 1
	v_mfma_f32_16x16x32_bf16 v[108:111], v[140:143], v[192:195], v[108:111]
	v_mfma_f32_16x16x32_bf16 v[108:111], v[150:153], v[196:199], v[108:111]
	v_mfma_f32_16x16x32_bf16 v[104:107], v[154:157], v[192:195], v[104:107]
	v_mfma_f32_16x16x32_bf16 v[104:107], v[158:161], v[196:199], v[104:107]
	v_mfma_f32_16x16x32_bf16 v[92:95], v[140:143], v[200:203], v[92:95]
	v_mfma_f32_16x16x32_bf16 v[92:95], v[150:153], v[204:207], v[92:95]
	v_mfma_f32_16x16x32_bf16 v[88:91], v[154:157], v[200:203], v[88:91]
	v_mfma_f32_16x16x32_bf16 v[88:91], v[158:161], v[204:207], v[88:91]
	v_mfma_f32_16x16x32_bf16 v[76:79], v[140:143], v[208:211], v[76:79]
	v_mfma_f32_16x16x32_bf16 v[76:79], v[150:153], v[212:215], v[76:79]
	v_mfma_f32_16x16x32_bf16 v[72:75], v[154:157], v[208:211], v[72:75]
	v_mfma_f32_16x16x32_bf16 v[72:75], v[158:161], v[212:215], v[72:75]
	v_mfma_f32_16x16x32_bf16 v[116:119], v[162:165], v[184:187], v[116:119]
	v_mfma_f32_16x16x32_bf16 v[116:119], v[166:169], v[188:191], v[116:119]
	v_mfma_f32_16x16x32_bf16 v[112:115], v[170:173], v[184:187], v[112:115]
	v_mfma_f32_16x16x32_bf16 v[112:115], v[174:177], v[188:191], v[112:115]
	v_mfma_f32_16x16x32_bf16 v[100:103], v[162:165], v[192:195], v[100:103]
	v_mfma_f32_16x16x32_bf16 v[100:103], v[166:169], v[196:199], v[100:103]
	v_mfma_f32_16x16x32_bf16 v[96:99], v[170:173], v[192:195], v[96:99]
	v_mfma_f32_16x16x32_bf16 v[96:99], v[174:177], v[196:199], v[96:99]
	v_mfma_f32_16x16x32_bf16 v[84:87], v[162:165], v[200:203], v[84:87]
	v_mfma_f32_16x16x32_bf16 v[84:87], v[166:169], v[204:207], v[84:87]
	v_mfma_f32_16x16x32_bf16 v[80:83], v[170:173], v[200:203], v[80:83]
	v_mfma_f32_16x16x32_bf16 v[80:83], v[174:177], v[204:207], v[80:83]
	s_barrier
	v_mfma_f32_16x16x32_bf16 v[68:71], v[162:165], v[208:211], v[68:71]
	v_mfma_f32_16x16x32_bf16 v[68:71], v[166:169], v[212:215], v[68:71]
	v_mfma_f32_16x16x32_bf16 v[64:67], v[170:173], v[208:211], v[64:67]
	v_mfma_f32_16x16x32_bf16 v[64:67], v[174:177], v[212:215], v[64:67]
	s_setprio 0
	s_add_i32 s75, s66, s58
	v_lshl_add_u64 v[178:179], s[52:53], 0, v[130:131]
	s_mov_b32 m0, s75
	ds_read_b128 v[184:187], v149 offset:16384
	ds_read_b128 v[188:191], v149 offset:17408
	ds_read_b128 v[192:195], v149 offset:18432
	ds_read_b128 v[196:199], v149 offset:19456
	ds_read_b128 v[200:203], v149 offset:20480
	ds_read_b128 v[204:207], v149 offset:21504
	ds_read_b128 v[208:211], v149 offset:22528
	ds_read_b128 v[212:215], v149 offset:23552
	global_load_lds_dwordx4 v[178:179], off
	s_add_i32 m0, s75, 0x2000
	s_add_u32 s76, s52, 0x40000
	v_lshl_add_u64 v[216:217], s[52:53], 0, v[128:129]
	s_addc_u32 s77, s53, 0
	s_add_i32 s75, s67, s58
	global_load_lds_dwordx4 v[216:217], off
	v_lshl_add_u64 v[218:219], s[76:77], 0, v[130:131]
	s_mov_b32 m0, s75
	v_lshl_add_u64 v[220:221], s[54:55], 0, v[128:129]
	global_load_lds_dwordx4 v[218:219], off
	v_lshl_add_u64 v[218:219], s[76:77], 0, v[128:129]
	s_add_i32 m0, s75, 0x2000
	s_nop 0
	global_load_lds_dwordx4 v[218:219], off
	v_lshl_add_u64 v[218:219], s[54:55], 0, v[130:131]
	s_mov_b32 m0, s47
	s_nop 0
	global_load_lds_dwordx4 v[218:219], off
	s_mov_b32 m0, s60
	s_nop 0
	global_load_lds_dwordx4 v[220:221], off
	s_waitcnt vmcnt(8)
	s_waitcnt lgkmcnt(0)
	s_barrier
	s_waitcnt lgkmcnt(0)
	v_mfma_f32_16x16x32_bf16 v[60:63], v[140:143], v[184:187], v[60:63]
	v_mfma_f32_16x16x32_bf16 v[60:63], v[150:153], v[188:191], v[60:63]
	v_mfma_f32_16x16x32_bf16 v[56:59], v[154:157], v[184:187], v[56:59]
	v_mfma_f32_16x16x32_bf16 v[56:59], v[158:161], v[188:191], v[56:59]
	s_setprio 1
	v_mfma_f32_16x16x32_bf16 v[44:47], v[140:143], v[192:195], v[44:47]
	v_mfma_f32_16x16x32_bf16 v[44:47], v[150:153], v[196:199], v[44:47]
	v_mfma_f32_16x16x32_bf16 v[40:43], v[154:157], v[192:195], v[40:43]
	v_mfma_f32_16x16x32_bf16 v[40:43], v[158:161], v[196:199], v[40:43]
	v_mfma_f32_16x16x32_bf16 v[28:31], v[140:143], v[200:203], v[28:31]
	v_mfma_f32_16x16x32_bf16 v[28:31], v[150:153], v[204:207], v[28:31]
	v_mfma_f32_16x16x32_bf16 v[24:27], v[154:157], v[200:203], v[24:27]
	v_mfma_f32_16x16x32_bf16 v[24:27], v[158:161], v[204:207], v[24:27]
	v_mfma_f32_16x16x32_bf16 v[12:15], v[140:143], v[208:211], v[12:15]
	v_mfma_f32_16x16x32_bf16 v[12:15], v[150:153], v[212:215], v[12:15]
	v_mfma_f32_16x16x32_bf16 v[8:11], v[154:157], v[208:211], v[8:11]
	v_mfma_f32_16x16x32_bf16 v[8:11], v[158:161], v[212:215], v[8:11]
	v_mfma_f32_16x16x32_bf16 v[52:55], v[162:165], v[184:187], v[52:55]
	v_mfma_f32_16x16x32_bf16 v[52:55], v[166:169], v[188:191], v[52:55]
	v_mfma_f32_16x16x32_bf16 v[48:51], v[170:173], v[184:187], v[48:51]
	v_mfma_f32_16x16x32_bf16 v[48:51], v[174:177], v[188:191], v[48:51]
	v_mfma_f32_16x16x32_bf16 v[36:39], v[162:165], v[192:195], v[36:39]
	v_mfma_f32_16x16x32_bf16 v[36:39], v[166:169], v[196:199], v[36:39]
	v_mfma_f32_16x16x32_bf16 v[32:35], v[170:173], v[192:195], v[32:35]
	v_mfma_f32_16x16x32_bf16 v[32:35], v[174:177], v[196:199], v[32:35]
	v_mfma_f32_16x16x32_bf16 v[20:23], v[162:165], v[200:203], v[20:23]
	v_mfma_f32_16x16x32_bf16 v[20:23], v[166:169], v[204:207], v[20:23]
	v_mfma_f32_16x16x32_bf16 v[16:19], v[170:173], v[200:203], v[16:19]
	v_mfma_f32_16x16x32_bf16 v[16:19], v[174:177], v[204:207], v[16:19]
	s_barrier
	v_mfma_f32_16x16x32_bf16 v[4:7], v[162:165], v[208:211], v[4:7]
	v_mfma_f32_16x16x32_bf16 v[4:7], v[166:169], v[212:215], v[4:7]
	v_mfma_f32_16x16x32_bf16 v[0:3], v[170:173], v[208:211], v[0:3]
	v_mfma_f32_16x16x32_bf16 v[0:3], v[174:177], v[212:215], v[0:3]
	s_setprio 0
.Lmid_gemm4:
	s_add_i32 s75, 0, 0x18000
	s_add_i32 s76, 0, 0x1c000
	v_add_u32_e32 v158, s75, v145
	v_add_u32_e32 v174, s76, v145
	ds_read_b128 v[140:143], v158
	ds_read_b128 v[150:153], v158 offset:1024
	ds_read_b128 v[154:157], v158 offset:2048
	ds_read_b128 v[158:161], v158 offset:3072
	ds_read_b128 v[162:165], v174
	ds_read_b128 v[166:169], v174 offset:1024
	ds_read_b128 v[170:173], v174 offset:2048
	ds_read_b128 v[174:177], v174 offset:3072
	s_add_u32 s54, s54, 0x40000
	s_addc_u32 s55, s55, 0
	s_mov_b32 m0, s61
	v_lshl_add_u64 v[222:223], s[54:55], 0, v[130:131]
	ds_read_b128 v[184:187], v149 offset:32768
	ds_read_b128 v[188:191], v149 offset:33792
	ds_read_b128 v[192:195], v149 offset:34816
	ds_read_b128 v[196:199], v149 offset:35840
	ds_read_b128 v[200:203], v149 offset:36864
	ds_read_b128 v[204:207], v149 offset:37888
	ds_read_b128 v[208:211], v149 offset:38912
	ds_read_b128 v[212:215], v149 offset:39936
	global_load_lds_dwordx4 v[222:223], off
	v_lshl_add_u64 v[222:223], s[54:55], 0, v[128:129]
	s_mov_b32 m0, s62
	s_nop 0
	global_load_lds_dwordx4 v[222:223], off
	s_waitcnt vmcnt(8)
	s_waitcnt lgkmcnt(0)
	s_barrier
	s_waitcnt lgkmcnt(0)
	v_mfma_f32_16x16x32_bf16 v[124:127], v[140:143], v[184:187], v[124:127]
	v_mfma_f32_16x16x32_bf16 v[124:127], v[150:153], v[188:191], v[124:127]
	v_mfma_f32_16x16x32_bf16 v[120:123], v[154:157], v[184:187], v[120:123]
	v_mfma_f32_16x16x32_bf16 v[120:123], v[158:161], v[188:191], v[120:123]
	s_setprio 1
	v_mfma_f32_16x16x32_bf16 v[108:111], v[140:143], v[192:195], v[108:111]
	v_mfma_f32_16x16x32_bf16 v[108:111], v[150:153], v[196:199], v[108:111]
	v_mfma_f32_16x16x32_bf16 v[104:107], v[154:157], v[192:195], v[104:107]
	v_mfma_f32_16x16x32_bf16 v[104:107], v[158:161], v[196:199], v[104:107]
	v_mfma_f32_16x16x32_bf16 v[92:95], v[140:143], v[200:203], v[92:95]
	v_mfma_f32_16x16x32_bf16 v[92:95], v[150:153], v[204:207], v[92:95]
	v_mfma_f32_16x16x32_bf16 v[88:91], v[154:157], v[200:203], v[88:91]
	v_mfma_f32_16x16x32_bf16 v[88:91], v[158:161], v[204:207], v[88:91]
	v_mfma_f32_16x16x32_bf16 v[76:79], v[140:143], v[208:211], v[76:79]
	v_mfma_f32_16x16x32_bf16 v[76:79], v[150:153], v[212:215], v[76:79]
	v_mfma_f32_16x16x32_bf16 v[72:75], v[154:157], v[208:211], v[72:75]
	v_mfma_f32_16x16x32_bf16 v[72:75], v[158:161], v[212:215], v[72:75]
	v_mfma_f32_16x16x32_bf16 v[116:119], v[162:165], v[184:187], v[116:119]
	v_mfma_f32_16x16x32_bf16 v[116:119], v[166:169], v[188:191], v[116:119]
	v_mfma_f32_16x16x32_bf16 v[112:115], v[170:173], v[184:187], v[112:115]
	v_mfma_f32_16x16x32_bf16 v[112:115], v[174:177], v[188:191], v[112:115]
	v_mfma_f32_16x16x32_bf16 v[100:103], v[162:165], v[192:195], v[100:103]
	v_mfma_f32_16x16x32_bf16 v[100:103], v[166:169], v[196:199], v[100:103]
	v_mfma_f32_16x16x32_bf16 v[96:99], v[170:173], v[192:195], v[96:99]
	v_mfma_f32_16x16x32_bf16 v[96:99], v[174:177], v[196:199], v[96:99]
	v_mfma_f32_16x16x32_bf16 v[84:87], v[162:165], v[200:203], v[84:87]
	v_mfma_f32_16x16x32_bf16 v[84:87], v[166:169], v[204:207], v[84:87]
	v_mfma_f32_16x16x32_bf16 v[80:83], v[170:173], v[200:203], v[80:83]
	v_mfma_f32_16x16x32_bf16 v[80:83], v[174:177], v[204:207], v[80:83]
	s_barrier
	v_mfma_f32_16x16x32_bf16 v[68:71], v[162:165], v[208:211], v[68:71]
	v_mfma_f32_16x16x32_bf16 v[68:71], v[166:169], v[212:215], v[68:71]
	v_mfma_f32_16x16x32_bf16 v[64:67], v[170:173], v[208:211], v[64:67]
	v_mfma_f32_16x16x32_bf16 v[64:67], v[174:177], v[212:215], v[64:67]
	s_setprio 0
	s_add_i32 s54, s75, s58
	v_lshl_add_u64 v[178:179], v[178:179], 0, s[12:13]
	s_mov_b32 m0, s54
	ds_read_b128 v[184:187], v149 offset:49152
	ds_read_b128 v[188:191], v149 offset:50176
	ds_read_b128 v[192:195], v149 offset:51200
	ds_read_b128 v[196:199], v149 offset:52224
	ds_read_b128 v[200:203], v149 offset:53248
	ds_read_b128 v[204:207], v149 offset:54272
	ds_read_b128 v[208:211], v149 offset:55296
	ds_read_b128 v[212:215], v149 offset:56320
	global_load_lds_dwordx4 v[178:179], off
	s_add_i32 m0, s54, 0x2000
	s_add_u32 s52, s52, 0x40080
	v_lshl_add_u64 v[178:179], v[216:217], 0, s[12:13]
	s_addc_u32 s53, s53, 0
	s_add_i32 s54, s76, s58
	global_load_lds_dwordx4 v[178:179], off
	v_lshl_add_u64 v[178:179], s[52:53], 0, v[130:131]
	s_mov_b32 m0, s54
	s_nop 0
	global_load_lds_dwordx4 v[178:179], off
	v_lshl_add_u64 v[178:179], s[52:53], 0, v[128:129]
	s_add_i32 m0, s54, 0x2000
	s_nop 0
	global_load_lds_dwordx4 v[178:179], off
	v_lshl_add_u64 v[178:179], v[218:219], 0, s[12:13]
	s_mov_b32 m0, s64
	s_nop 0
	global_load_lds_dwordx4 v[178:179], off
	v_lshl_add_u64 v[178:179], v[220:221], 0, s[12:13]
	s_mov_b32 m0, s65
	s_nop 0
	global_load_lds_dwordx4 v[178:179], off
	s_waitcnt vmcnt(8)
	s_waitcnt lgkmcnt(0)
	s_barrier
	s_waitcnt lgkmcnt(0)
	v_mfma_f32_16x16x32_bf16 v[60:63], v[140:143], v[184:187], v[60:63]
	v_mfma_f32_16x16x32_bf16 v[60:63], v[150:153], v[188:191], v[60:63]
	v_mfma_f32_16x16x32_bf16 v[56:59], v[154:157], v[184:187], v[56:59]
	v_mfma_f32_16x16x32_bf16 v[56:59], v[158:161], v[188:191], v[56:59]
	s_setprio 1
	v_mfma_f32_16x16x32_bf16 v[44:47], v[140:143], v[192:195], v[44:47]
	v_mfma_f32_16x16x32_bf16 v[44:47], v[150:153], v[196:199], v[44:47]
	v_mfma_f32_16x16x32_bf16 v[40:43], v[154:157], v[192:195], v[40:43]
	v_mfma_f32_16x16x32_bf16 v[40:43], v[158:161], v[196:199], v[40:43]
	v_mfma_f32_16x16x32_bf16 v[28:31], v[140:143], v[200:203], v[28:31]
	v_mfma_f32_16x16x32_bf16 v[28:31], v[150:153], v[204:207], v[28:31]
	v_mfma_f32_16x16x32_bf16 v[24:27], v[154:157], v[200:203], v[24:27]
	v_mfma_f32_16x16x32_bf16 v[24:27], v[158:161], v[204:207], v[24:27]
	v_mfma_f32_16x16x32_bf16 v[12:15], v[140:143], v[208:211], v[12:15]
	v_mfma_f32_16x16x32_bf16 v[12:15], v[150:153], v[212:215], v[12:15]
	v_mfma_f32_16x16x32_bf16 v[8:11], v[154:157], v[208:211], v[8:11]
	v_mfma_f32_16x16x32_bf16 v[8:11], v[158:161], v[212:215], v[8:11]
	v_mfma_f32_16x16x32_bf16 v[52:55], v[162:165], v[184:187], v[52:55]
	v_mfma_f32_16x16x32_bf16 v[52:55], v[166:169], v[188:191], v[52:55]
	v_mfma_f32_16x16x32_bf16 v[48:51], v[170:173], v[184:187], v[48:51]
	v_mfma_f32_16x16x32_bf16 v[48:51], v[174:177], v[188:191], v[48:51]
	v_mfma_f32_16x16x32_bf16 v[36:39], v[162:165], v[192:195], v[36:39]
	v_mfma_f32_16x16x32_bf16 v[36:39], v[166:169], v[196:199], v[36:39]
	v_mfma_f32_16x16x32_bf16 v[32:35], v[170:173], v[192:195], v[32:35]
	v_mfma_f32_16x16x32_bf16 v[32:35], v[174:177], v[196:199], v[32:35]
	v_mfma_f32_16x16x32_bf16 v[20:23], v[162:165], v[200:203], v[20:23]
	v_mfma_f32_16x16x32_bf16 v[20:23], v[166:169], v[204:207], v[20:23]
	v_mfma_f32_16x16x32_bf16 v[16:19], v[170:173], v[200:203], v[16:19]
	v_mfma_f32_16x16x32_bf16 v[16:19], v[174:177], v[204:207], v[16:19]
	s_barrier
	v_mfma_f32_16x16x32_bf16 v[4:7], v[162:165], v[208:211], v[4:7]
	v_mfma_f32_16x16x32_bf16 v[4:7], v[166:169], v[212:215], v[4:7]
	v_mfma_f32_16x16x32_bf16 v[0:3], v[170:173], v[208:211], v[0:3]
	v_mfma_f32_16x16x32_bf16 v[0:3], v[174:177], v[212:215], v[0:3]
	s_setprio 0
	s_add_i32 s74, s74, 2
	s_add_u32 s48, s48, 0x100
	s_addc_u32 s49, s49, 0
	s_add_u32 s72, s72, 0x100
	s_addc_u32 s73, s73, 0
	s_cmp_gt_u32 s74, 13
	s_cbranch_scc0 .LBB0_724
	s_and_b64 vcc, exec, s[16:17]
	s_cbranch_vccz .LBB0_727
	s_barrier

.LBB0_803:
	s_add_u32 s84, s54, 0x100
	s_addc_u32 s85, s55, 0
	s_mov_b32 s86, -2
	ds_read_b128 v[152:155], v149
	ds_read_b128 v[156:159], v149 offset:1024
	ds_read_b128 v[160:163], v149 offset:2048
	ds_read_b128 v[164:167], v149 offset:3072
	ds_read_b128 v[168:171], v150
	ds_read_b128 v[172:175], v150 offset:1024
	ds_read_b128 v[176:179], v150 offset:2048
	ds_read_b128 v[184:187], v150 offset:3072
	s_add_u32 s54, s52, 0x100
	s_addc_u32 s55, s53, 0
	s_cmp_eq_u32 s86, 40
	s_cselect_b32 s59, s13, s55
	s_cselect_b32 s58, s12, s54
	s_cselect_b32 s57, s49, s85
	s_cselect_b32 s56, s48, s84
	v_lshl_add_u64 v[144:145], s[52:53], 0, v[136:137]
	s_add_i32 m0, s63, 0xc000
	ds_read_b128 v[188:191], v151
	ds_read_b128 v[192:195], v151 offset:1024
	ds_read_b128 v[196:199], v151 offset:2048
	ds_read_b128 v[200:203], v151 offset:3072
	ds_read_b128 v[204:207], v151 offset:4096
	ds_read_b128 v[208:211], v151 offset:5120
	ds_read_b128 v[212:215], v151 offset:6144
	ds_read_b128 v[216:219], v151 offset:7168
	global_load_lds_dwordx4 v[144:145], off
	v_lshl_add_u64 v[144:145], s[52:53], 0, v[138:139]
	s_add_i32 m0, s63, 0xe000
	s_nop 0
	global_load_lds_dwordx4 v[144:145], off
	s_waitcnt vmcnt(8)
	s_waitcnt lgkmcnt(0)
	s_barrier
	s_waitcnt lgkmcnt(0)
	v_mfma_f32_16x16x32_bf16 v[124:127], v[152:155], v[188:191], 0
	v_mfma_f32_16x16x32_bf16 v[124:127], v[156:159], v[192:195], v[124:127]
	v_mfma_f32_16x16x32_bf16 v[120:123], v[160:163], v[188:191], 0
	v_mfma_f32_16x16x32_bf16 v[120:123], v[164:167], v[192:195], v[120:123]
	s_setprio 1
	v_mfma_f32_16x16x32_bf16 v[116:119], v[152:155], v[196:199], 0
	v_mfma_f32_16x16x32_bf16 v[116:119], v[156:159], v[200:203], v[116:119]
	v_mfma_f32_16x16x32_bf16 v[108:111], v[160:163], v[196:199], 0
	v_mfma_f32_16x16x32_bf16 v[108:111], v[164:167], v[200:203], v[108:111]
	v_mfma_f32_16x16x32_bf16 v[100:103], v[152:155], v[204:207], 0
	v_mfma_f32_16x16x32_bf16 v[100:103], v[156:159], v[208:211], v[100:103]
	v_mfma_f32_16x16x32_bf16 v[92:95], v[160:163], v[204:207], 0
	v_mfma_f32_16x16x32_bf16 v[92:95], v[164:167], v[208:211], v[92:95]
	v_mfma_f32_16x16x32_bf16 v[84:87], v[152:155], v[212:215], 0
	v_mfma_f32_16x16x32_bf16 v[84:87], v[156:159], v[216:219], v[84:87]
	v_mfma_f32_16x16x32_bf16 v[76:79], v[160:163], v[212:215], 0
	v_mfma_f32_16x16x32_bf16 v[76:79], v[164:167], v[216:219], v[76:79]
	v_mfma_f32_16x16x32_bf16 v[112:115], v[168:171], v[188:191], 0
	v_mfma_f32_16x16x32_bf16 v[112:115], v[172:175], v[192:195], v[112:115]
	v_mfma_f32_16x16x32_bf16 v[104:107], v[176:179], v[188:191], 0
	v_mfma_f32_16x16x32_bf16 v[104:107], v[184:187], v[192:195], v[104:107]
	v_mfma_f32_16x16x32_bf16 v[96:99], v[168:171], v[196:199], 0
	v_mfma_f32_16x16x32_bf16 v[96:99], v[172:175], v[200:203], v[96:99]
	v_mfma_f32_16x16x32_bf16 v[88:91], v[176:179], v[196:199], 0
	v_mfma_f32_16x16x32_bf16 v[88:91], v[184:187], v[200:203], v[88:91]
	v_mfma_f32_16x16x32_bf16 v[80:83], v[168:171], v[204:207], 0
	v_mfma_f32_16x16x32_bf16 v[80:83], v[172:175], v[208:211], v[80:83]
	v_mfma_f32_16x16x32_bf16 v[72:75], v[176:179], v[204:207], 0
	v_mfma_f32_16x16x32_bf16 v[72:75], v[184:187], v[208:211], v[72:75]
	s_barrier
	v_mfma_f32_16x16x32_bf16 v[68:71], v[168:171], v[212:215], 0
	v_mfma_f32_16x16x32_bf16 v[68:71], v[172:175], v[216:219], v[68:71]
	v_mfma_f32_16x16x32_bf16 v[64:67], v[176:179], v[212:215], 0
	v_mfma_f32_16x16x32_bf16 v[64:67], v[184:187], v[216:219], v[64:67]
	s_setprio 0
	s_add_i32 s52, s70, s62
	v_lshl_add_u64 v[144:145], s[56:57], 0, v[130:131]
	s_mov_b32 m0, s52
	ds_read_b128 v[188:191], v151 offset:16384
	ds_read_b128 v[192:195], v151 offset:17408
	ds_read_b128 v[196:199], v151 offset:18432
	ds_read_b128 v[200:203], v151 offset:19456
	ds_read_b128 v[204:207], v151 offset:20480
	ds_read_b128 v[208:211], v151 offset:21504
	ds_read_b128 v[212:215], v151 offset:22528
	ds_read_b128 v[216:219], v151 offset:23552
	global_load_lds_dwordx4 v[144:145], off
	s_add_i32 m0, s52, 0x2000
	s_add_u32 s52, s56, 0xb0000
	v_lshl_add_u64 v[220:221], s[56:57], 0, v[134:135]
	s_addc_u32 s53, s57, 0
	s_add_i32 s79, s71, s62
	global_load_lds_dwordx4 v[220:221], off
	v_lshl_add_u64 v[222:223], s[52:53], 0, v[130:131]
	s_mov_b32 m0, s79
	v_lshl_add_u64 v[224:225], s[58:59], 0, v[132:133]
	global_load_lds_dwordx4 v[222:223], off
	v_lshl_add_u64 v[222:223], s[52:53], 0, v[134:135]
	s_add_i32 m0, s79, 0x2000
	s_nop 0
	global_load_lds_dwordx4 v[222:223], off
	v_lshl_add_u64 v[222:223], s[58:59], 0, v[128:129]
	s_mov_b32 m0, s63
	s_nop 0
	global_load_lds_dwordx4 v[222:223], off
	s_mov_b32 m0, s64
	s_nop 0
	global_load_lds_dwordx4 v[224:225], off
	s_waitcnt vmcnt(8)
	s_waitcnt lgkmcnt(0)
	s_barrier
	s_waitcnt lgkmcnt(0)
	v_mfma_f32_16x16x32_bf16 v[60:63], v[152:155], v[188:191], 0
	v_mfma_f32_16x16x32_bf16 v[60:63], v[156:159], v[192:195], v[60:63]
	v_mfma_f32_16x16x32_bf16 v[56:59], v[160:163], v[188:191], 0
	v_mfma_f32_16x16x32_bf16 v[56:59], v[164:167], v[192:195], v[56:59]
	s_setprio 1
	v_mfma_f32_16x16x32_bf16 v[52:55], v[152:155], v[196:199], 0
	v_mfma_f32_16x16x32_bf16 v[52:55], v[156:159], v[200:203], v[52:55]
	v_mfma_f32_16x16x32_bf16 v[44:47], v[160:163], v[196:199], 0
	v_mfma_f32_16x16x32_bf16 v[44:47], v[164:167], v[200:203], v[44:47]
	v_mfma_f32_16x16x32_bf16 v[36:39], v[152:155], v[204:207], 0
	v_mfma_f32_16x16x32_bf16 v[36:39], v[156:159], v[208:211], v[36:39]
	v_mfma_f32_16x16x32_bf16 v[28:31], v[160:163], v[204:207], 0
	v_mfma_f32_16x16x32_bf16 v[28:31], v[164:167], v[208:211], v[28:31]
	v_mfma_f32_16x16x32_bf16 v[20:23], v[152:155], v[212:215], 0
	v_mfma_f32_16x16x32_bf16 v[20:23], v[156:159], v[216:219], v[20:23]
	v_mfma_f32_16x16x32_bf16 v[12:15], v[160:163], v[212:215], 0
	v_mfma_f32_16x16x32_bf16 v[12:15], v[164:167], v[216:219], v[12:15]
	v_mfma_f32_16x16x32_bf16 v[48:51], v[168:171], v[188:191], 0
	v_mfma_f32_16x16x32_bf16 v[48:51], v[172:175], v[192:195], v[48:51]
	v_mfma_f32_16x16x32_bf16 v[40:43], v[176:179], v[188:191], 0
	v_mfma_f32_16x16x32_bf16 v[40:43], v[184:187], v[192:195], v[40:43]
	v_mfma_f32_16x16x32_bf16 v[32:35], v[168:171], v[196:199], 0
	v_mfma_f32_16x16x32_bf16 v[32:35], v[172:175], v[200:203], v[32:35]
	v_mfma_f32_16x16x32_bf16 v[24:27], v[176:179], v[196:199], 0
	v_mfma_f32_16x16x32_bf16 v[24:27], v[184:187], v[200:203], v[24:27]
	v_mfma_f32_16x16x32_bf16 v[16:19], v[168:171], v[204:207], 0
	v_mfma_f32_16x16x32_bf16 v[16:19], v[172:175], v[208:211], v[16:19]
	v_mfma_f32_16x16x32_bf16 v[8:11], v[176:179], v[204:207], 0
	v_mfma_f32_16x16x32_bf16 v[8:11], v[184:187], v[208:211], v[8:11]
	s_barrier
	v_mfma_f32_16x16x32_bf16 v[4:7], v[168:171], v[212:215], 0
	v_mfma_f32_16x16x32_bf16 v[4:7], v[172:175], v[216:219], v[4:7]
	v_mfma_f32_16x16x32_bf16 v[0:3], v[176:179], v[212:215], 0
	v_mfma_f32_16x16x32_bf16 v[0:3], v[184:187], v[216:219], v[0:3]
	s_setprio 0
	s_branch .Lmid_gemm5
.LBB0_804:
	ds_read_b128 v[152:155], v149
	ds_read_b128 v[156:159], v149 offset:1024
	ds_read_b128 v[160:163], v149 offset:2048
	ds_read_b128 v[164:167], v149 offset:3072
	ds_read_b128 v[168:171], v150
	ds_read_b128 v[172:175], v150 offset:1024
	ds_read_b128 v[176:179], v150 offset:2048
	ds_read_b128 v[184:187], v150 offset:3072
	s_add_u32 s54, s52, 0x100
	s_addc_u32 s55, s53, 0
	s_cmp_eq_u32 s86, 40
	s_cselect_b32 s59, s13, s55
	s_cselect_b32 s58, s12, s54
	s_cselect_b32 s57, s49, s85
	s_cselect_b32 s56, s48, s84
	v_lshl_add_u64 v[144:145], s[52:53], 0, v[136:137]
	s_add_i32 m0, s63, 0xc000
	ds_read_b128 v[188:191], v151
	ds_read_b128 v[192:195], v151 offset:1024
	ds_read_b128 v[196:199], v151 offset:2048
	ds_read_b128 v[200:203], v151 offset:3072
	ds_read_b128 v[204:207], v151 offset:4096
	ds_read_b128 v[208:211], v151 offset:5120
	ds_read_b128 v[212:215], v151 offset:6144
	ds_read_b128 v[216:219], v151 offset:7168
	global_load_lds_dwordx4 v[144:145], off
	v_lshl_add_u64 v[144:145], s[52:53], 0, v[138:139]
	s_add_i32 m0, s63, 0xe000
	s_nop 0
	global_load_lds_dwordx4 v[144:145], off
	s_waitcnt vmcnt(8)
	s_waitcnt lgkmcnt(0)
	s_barrier
	s_waitcnt lgkmcnt(0)
	v_mfma_f32_16x16x32_bf16 v[124:127], v[152:155], v[188:191], v[124:127]
	v_mfma_f32_16x16x32_bf16 v[124:127], v[156:159], v[192:195], v[124:127]
	v_mfma_f32_16x16x32_bf16 v[120:123], v[160:163], v[188:191], v[120:123]
	v_mfma_f32_16x16x32_bf16 v[120:123], v[164:167], v[192:195], v[120:123]
	s_setprio 1
	v_mfma_f32_16x16x32_bf16 v[116:119], v[152:155], v[196:199], v[116:119]
	v_mfma_f32_16x16x32_bf16 v[116:119], v[156:159], v[200:203], v[116:119]
	v_mfma_f32_16x16x32_bf16 v[108:111], v[160:163], v[196:199], v[108:111]
	v_mfma_f32_16x16x32_bf16 v[108:111], v[164:167], v[200:203], v[108:111]
	v_mfma_f32_16x16x32_bf16 v[100:103], v[152:155], v[204:207], v[100:103]
	v_mfma_f32_16x16x32_bf16 v[100:103], v[156:159], v[208:211], v[100:103]
	v_mfma_f32_16x16x32_bf16 v[92:95], v[160:163], v[204:207], v[92:95]
	v_mfma_f32_16x16x32_bf16 v[92:95], v[164:167], v[208:211], v[92:95]
	v_mfma_f32_16x16x32_bf16 v[84:87], v[152:155], v[212:215], v[84:87]
	v_mfma_f32_16x16x32_bf16 v[84:87], v[156:159], v[216:219], v[84:87]
	v_mfma_f32_16x16x32_bf16 v[76:79], v[160:163], v[212:215], v[76:79]
	v_mfma_f32_16x16x32_bf16 v[76:79], v[164:167], v[216:219], v[76:79]
	v_mfma_f32_16x16x32_bf16 v[112:115], v[168:171], v[188:191], v[112:115]
	v_mfma_f32_16x16x32_bf16 v[112:115], v[172:175], v[192:195], v[112:115]
	v_mfma_f32_16x16x32_bf16 v[104:107], v[176:179], v[188:191], v[104:107]
	v_mfma_f32_16x16x32_bf16 v[104:107], v[184:187], v[192:195], v[104:107]
	v_mfma_f32_16x16x32_bf16 v[96:99], v[168:171], v[196:199], v[96:99]
	v_mfma_f32_16x16x32_bf16 v[96:99], v[172:175], v[200:203], v[96:99]
	v_mfma_f32_16x16x32_bf16 v[88:91], v[176:179], v[196:199], v[88:91]
	v_mfma_f32_16x16x32_bf16 v[88:91], v[184:187], v[200:203], v[88:91]
	v_mfma_f32_16x16x32_bf16 v[80:83], v[168:171], v[204:207], v[80:83]
	v_mfma_f32_16x16x32_bf16 v[80:83], v[172:175], v[208:211], v[80:83]
	v_mfma_f32_16x16x32_bf16 v[72:75], v[176:179], v[204:207], v[72:75]
	v_mfma_f32_16x16x32_bf16 v[72:75], v[184:187], v[208:211], v[72:75]
	s_barrier
	v_mfma_f32_16x16x32_bf16 v[68:71], v[168:171], v[212:215], v[68:71]
	v_mfma_f32_16x16x32_bf16 v[68:71], v[172:175], v[216:219], v[68:71]
	v_mfma_f32_16x16x32_bf16 v[64:67], v[176:179], v[212:215], v[64:67]
	v_mfma_f32_16x16x32_bf16 v[64:67], v[184:187], v[216:219], v[64:67]
	s_setprio 0
	s_add_i32 s52, s70, s62
	v_lshl_add_u64 v[144:145], s[56:57], 0, v[130:131]
	s_mov_b32 m0, s52
	ds_read_b128 v[188:191], v151 offset:16384
	ds_read_b128 v[192:195], v151 offset:17408
	ds_read_b128 v[196:199], v151 offset:18432
	ds_read_b128 v[200:203], v151 offset:19456
	ds_read_b128 v[204:207], v151 offset:20480
	ds_read_b128 v[208:211], v151 offset:21504
	ds_read_b128 v[212:215], v151 offset:22528
	ds_read_b128 v[216:219], v151 offset:23552
	global_load_lds_dwordx4 v[144:145], off
	s_add_i32 m0, s52, 0x2000
	s_add_u32 s52, s56, 0xb0000
	v_lshl_add_u64 v[220:221], s[56:57], 0, v[134:135]
	s_addc_u32 s53, s57, 0
	s_add_i32 s79, s71, s62
	global_load_lds_dwordx4 v[220:221], off
	v_lshl_add_u64 v[222:223], s[52:53], 0, v[130:131]
	s_mov_b32 m0, s79
	v_lshl_add_u64 v[224:225], s[58:59], 0, v[132:133]
	global_load_lds_dwordx4 v[222:223], off
	v_lshl_add_u64 v[222:223], s[52:53], 0, v[134:135]
	s_add_i32 m0, s79, 0x2000
	s_nop 0
	global_load_lds_dwordx4 v[222:223], off
	v_lshl_add_u64 v[222:223], s[58:59], 0, v[128:129]
	s_mov_b32 m0, s63
	s_nop 0
	global_load_lds_dwordx4 v[222:223], off
	s_mov_b32 m0, s64
	s_nop 0
	global_load_lds_dwordx4 v[224:225], off
	s_waitcnt vmcnt(8)
	s_waitcnt lgkmcnt(0)
	s_barrier
	s_waitcnt lgkmcnt(0)
	v_mfma_f32_16x16x32_bf16 v[60:63], v[152:155], v[188:191], v[60:63]
	v_mfma_f32_16x16x32_bf16 v[60:63], v[156:159], v[192:195], v[60:63]
	v_mfma_f32_16x16x32_bf16 v[56:59], v[160:163], v[188:191], v[56:59]
	v_mfma_f32_16x16x32_bf16 v[56:59], v[164:167], v[192:195], v[56:59]
	s_setprio 1
	v_mfma_f32_16x16x32_bf16 v[52:55], v[152:155], v[196:199], v[52:55]
	v_mfma_f32_16x16x32_bf16 v[52:55], v[156:159], v[200:203], v[52:55]
	v_mfma_f32_16x16x32_bf16 v[44:47], v[160:163], v[196:199], v[44:47]
	v_mfma_f32_16x16x32_bf16 v[44:47], v[164:167], v[200:203], v[44:47]
	v_mfma_f32_16x16x32_bf16 v[36:39], v[152:155], v[204:207], v[36:39]
	v_mfma_f32_16x16x32_bf16 v[36:39], v[156:159], v[208:211], v[36:39]
	v_mfma_f32_16x16x32_bf16 v[28:31], v[160:163], v[204:207], v[28:31]
	v_mfma_f32_16x16x32_bf16 v[28:31], v[164:167], v[208:211], v[28:31]
	v_mfma_f32_16x16x32_bf16 v[20:23], v[152:155], v[212:215], v[20:23]
	v_mfma_f32_16x16x32_bf16 v[20:23], v[156:159], v[216:219], v[20:23]
	v_mfma_f32_16x16x32_bf16 v[12:15], v[160:163], v[212:215], v[12:15]
	v_mfma_f32_16x16x32_bf16 v[12:15], v[164:167], v[216:219], v[12:15]
	v_mfma_f32_16x16x32_bf16 v[48:51], v[168:171], v[188:191], v[48:51]
	v_mfma_f32_16x16x32_bf16 v[48:51], v[172:175], v[192:195], v[48:51]
	v_mfma_f32_16x16x32_bf16 v[40:43], v[176:179], v[188:191], v[40:43]
	v_mfma_f32_16x16x32_bf16 v[40:43], v[184:187], v[192:195], v[40:43]
	v_mfma_f32_16x16x32_bf16 v[32:35], v[168:171], v[196:199], v[32:35]
	v_mfma_f32_16x16x32_bf16 v[32:35], v[172:175], v[200:203], v[32:35]
	v_mfma_f32_16x16x32_bf16 v[24:27], v[176:179], v[196:199], v[24:27]
	v_mfma_f32_16x16x32_bf16 v[24:27], v[184:187], v[200:203], v[24:27]
	v_mfma_f32_16x16x32_bf16 v[16:19], v[168:171], v[204:207], v[16:19]
	v_mfma_f32_16x16x32_bf16 v[16:19], v[172:175], v[208:211], v[16:19]
	v_mfma_f32_16x16x32_bf16 v[8:11], v[176:179], v[204:207], v[8:11]
	v_mfma_f32_16x16x32_bf16 v[8:11], v[184:187], v[208:211], v[8:11]
	s_barrier
	v_mfma_f32_16x16x32_bf16 v[4:7], v[168:171], v[212:215], v[4:7]
	v_mfma_f32_16x16x32_bf16 v[4:7], v[172:175], v[216:219], v[4:7]
	v_mfma_f32_16x16x32_bf16 v[0:3], v[176:179], v[212:215], v[0:3]
	v_mfma_f32_16x16x32_bf16 v[0:3], v[184:187], v[216:219], v[0:3]
	s_setprio 0
.Lmid_gemm5:
	s_add_i32 s79, 0, 0x18000
	s_add_i32 s87, 0, 0x1c000
	v_add_u32_e32 v164, s79, v147
	v_add_u32_e32 v181, s87, v147
	ds_read_b128 v[152:155], v164
	ds_read_b128 v[156:159], v164 offset:1024
	ds_read_b128 v[160:163], v164 offset:2048
	ds_read_b128 v[164:167], v164 offset:3072
	ds_read_b128 v[168:171], v181
	ds_read_b128 v[172:175], v181 offset:1024
	ds_read_b128 v[176:179], v181 offset:2048
	ds_read_b128 v[184:187], v181 offset:3072
	s_add_u32 s52, s58, 0xb0000
	s_addc_u32 s53, s59, 0
	s_mov_b32 m0, s65
	v_lshl_add_u64 v[226:227], s[52:53], 0, v[128:129]
	ds_read_b128 v[188:191], v151 offset:32768
	ds_read_b128 v[192:195], v151 offset:33792
	ds_read_b128 v[196:199], v151 offset:34816
	ds_read_b128 v[200:203], v151 offset:35840
	ds_read_b128 v[204:207], v151 offset:36864
	ds_read_b128 v[208:211], v151 offset:37888
	ds_read_b128 v[212:215], v151 offset:38912
	ds_read_b128 v[216:219], v151 offset:39936
	global_load_lds_dwordx4 v[226:227], off
	v_lshl_add_u64 v[226:227], s[52:53], 0, v[132:133]
	s_mov_b32 m0, s66
	s_nop 0
	global_load_lds_dwordx4 v[226:227], off
	s_waitcnt vmcnt(8)
	s_waitcnt lgkmcnt(0)
	s_barrier
	s_waitcnt lgkmcnt(0)
	v_mfma_f32_16x16x32_bf16 v[124:127], v[152:155], v[188:191], v[124:127]
	v_mfma_f32_16x16x32_bf16 v[124:127], v[156:159], v[192:195], v[124:127]
	v_mfma_f32_16x16x32_bf16 v[120:123], v[160:163], v[188:191], v[120:123]
	v_mfma_f32_16x16x32_bf16 v[120:123], v[164:167], v[192:195], v[120:123]
	s_setprio 1
	v_mfma_f32_16x16x32_bf16 v[116:119], v[152:155], v[196:199], v[116:119]
	v_mfma_f32_16x16x32_bf16 v[116:119], v[156:159], v[200:203], v[116:119]
	v_mfma_f32_16x16x32_bf16 v[108:111], v[160:163], v[196:199], v[108:111]
	v_mfma_f32_16x16x32_bf16 v[108:111], v[164:167], v[200:203], v[108:111]
	v_mfma_f32_16x16x32_bf16 v[100:103], v[152:155], v[204:207], v[100:103]
	v_mfma_f32_16x16x32_bf16 v[100:103], v[156:159], v[208:211], v[100:103]
	v_mfma_f32_16x16x32_bf16 v[92:95], v[160:163], v[204:207], v[92:95]
	v_mfma_f32_16x16x32_bf16 v[92:95], v[164:167], v[208:211], v[92:95]
	v_mfma_f32_16x16x32_bf16 v[84:87], v[152:155], v[212:215], v[84:87]
	v_mfma_f32_16x16x32_bf16 v[84:87], v[156:159], v[216:219], v[84:87]
	v_mfma_f32_16x16x32_bf16 v[76:79], v[160:163], v[212:215], v[76:79]
	v_mfma_f32_16x16x32_bf16 v[76:79], v[164:167], v[216:219], v[76:79]
	v_mfma_f32_16x16x32_bf16 v[112:115], v[168:171], v[188:191], v[112:115]
	v_mfma_f32_16x16x32_bf16 v[112:115], v[172:175], v[192:195], v[112:115]
	v_mfma_f32_16x16x32_bf16 v[104:107], v[176:179], v[188:191], v[104:107]
	v_mfma_f32_16x16x32_bf16 v[104:107], v[184:187], v[192:195], v[104:107]
	v_mfma_f32_16x16x32_bf16 v[96:99], v[168:171], v[196:199], v[96:99]
	v_mfma_f32_16x16x32_bf16 v[96:99], v[172:175], v[200:203], v[96:99]
	v_mfma_f32_16x16x32_bf16 v[88:91], v[176:179], v[196:199], v[88:91]
	v_mfma_f32_16x16x32_bf16 v[88:91], v[184:187], v[200:203], v[88:91]
	v_mfma_f32_16x16x32_bf16 v[80:83], v[168:171], v[204:207], v[80:83]
	v_mfma_f32_16x16x32_bf16 v[80:83], v[172:175], v[208:211], v[80:83]
	v_mfma_f32_16x16x32_bf16 v[72:75], v[176:179], v[204:207], v[72:75]
	v_mfma_f32_16x16x32_bf16 v[72:75], v[184:187], v[208:211], v[72:75]
	s_barrier
	v_mfma_f32_16x16x32_bf16 v[68:71], v[168:171], v[212:215], v[68:71]
	v_mfma_f32_16x16x32_bf16 v[68:71], v[172:175], v[216:219], v[68:71]
	v_mfma_f32_16x16x32_bf16 v[64:67], v[176:179], v[212:215], v[64:67]
	v_mfma_f32_16x16x32_bf16 v[64:67], v[184:187], v[216:219], v[64:67]
	s_setprio 0
	s_add_i32 s52, s79, s62
	v_lshl_add_u64 v[144:145], v[144:145], 0, s[16:17]
	s_mov_b32 m0, s52
	ds_read_b128 v[188:191], v151 offset:49152
	ds_read_b128 v[192:195], v151 offset:50176
	ds_read_b128 v[196:199], v151 offset:51200
	ds_read_b128 v[200:203], v151 offset:52224
	ds_read_b128 v[204:207], v151 offset:53248
	ds_read_b128 v[208:211], v151 offset:54272
	ds_read_b128 v[212:215], v151 offset:55296
	ds_read_b128 v[216:219], v151 offset:56320
	global_load_lds_dwordx4 v[144:145], off
	s_add_i32 m0, s52, 0x2000
	s_add_u32 s52, s56, 0xb0080
	v_lshl_add_u64 v[144:145], v[220:221], 0, s[16:17]
	s_addc_u32 s53, s57, 0
	s_add_i32 s56, s87, s62
	global_load_lds_dwordx4 v[144:145], off
	v_lshl_add_u64 v[144:145], s[52:53], 0, v[130:131]
	s_mov_b32 m0, s56
	s_nop 0
	global_load_lds_dwordx4 v[144:145], off
	v_lshl_add_u64 v[144:145], s[52:53], 0, v[134:135]
	s_add_i32 m0, s56, 0x2000
	s_nop 0
	global_load_lds_dwordx4 v[144:145], off
	v_lshl_add_u64 v[144:145], v[222:223], 0, s[16:17]
	s_mov_b32 m0, s68
	s_nop 0
	global_load_lds_dwordx4 v[144:145], off
	v_lshl_add_u64 v[144:145], v[224:225], 0, s[16:17]
	s_mov_b32 m0, s69
	s_nop 0
	global_load_lds_dwordx4 v[144:145], off
	s_waitcnt vmcnt(8)
	s_waitcnt lgkmcnt(0)
	s_barrier
	s_waitcnt lgkmcnt(0)
	v_mfma_f32_16x16x32_bf16 v[60:63], v[152:155], v[188:191], v[60:63]
	v_mfma_f32_16x16x32_bf16 v[60:63], v[156:159], v[192:195], v[60:63]
	v_mfma_f32_16x16x32_bf16 v[56:59], v[160:163], v[188:191], v[56:59]
	v_mfma_f32_16x16x32_bf16 v[56:59], v[164:167], v[192:195], v[56:59]
	s_setprio 1
	v_mfma_f32_16x16x32_bf16 v[52:55], v[152:155], v[196:199], v[52:55]
	v_mfma_f32_16x16x32_bf16 v[52:55], v[156:159], v[200:203], v[52:55]
	v_mfma_f32_16x16x32_bf16 v[44:47], v[160:163], v[196:199], v[44:47]
	v_mfma_f32_16x16x32_bf16 v[44:47], v[164:167], v[200:203], v[44:47]
	v_mfma_f32_16x16x32_bf16 v[36:39], v[152:155], v[204:207], v[36:39]
	v_mfma_f32_16x16x32_bf16 v[36:39], v[156:159], v[208:211], v[36:39]
	v_mfma_f32_16x16x32_bf16 v[28:31], v[160:163], v[204:207], v[28:31]
	v_mfma_f32_16x16x32_bf16 v[28:31], v[164:167], v[208:211], v[28:31]
	v_mfma_f32_16x16x32_bf16 v[20:23], v[152:155], v[212:215], v[20:23]
	v_mfma_f32_16x16x32_bf16 v[20:23], v[156:159], v[216:219], v[20:23]
	v_mfma_f32_16x16x32_bf16 v[12:15], v[160:163], v[212:215], v[12:15]
	v_mfma_f32_16x16x32_bf16 v[12:15], v[164:167], v[216:219], v[12:15]
	v_mfma_f32_16x16x32_bf16 v[48:51], v[168:171], v[188:191], v[48:51]
	v_mfma_f32_16x16x32_bf16 v[48:51], v[172:175], v[192:195], v[48:51]
	v_mfma_f32_16x16x32_bf16 v[40:43], v[176:179], v[188:191], v[40:43]
	v_mfma_f32_16x16x32_bf16 v[40:43], v[184:187], v[192:195], v[40:43]
	v_mfma_f32_16x16x32_bf16 v[32:35], v[168:171], v[196:199], v[32:35]
	v_mfma_f32_16x16x32_bf16 v[32:35], v[172:175], v[200:203], v[32:35]
	v_mfma_f32_16x16x32_bf16 v[24:27], v[176:179], v[196:199], v[24:27]
	v_mfma_f32_16x16x32_bf16 v[24:27], v[184:187], v[200:203], v[24:27]
	v_mfma_f32_16x16x32_bf16 v[16:19], v[168:171], v[204:207], v[16:19]
	v_mfma_f32_16x16x32_bf16 v[16:19], v[172:175], v[208:211], v[16:19]
	v_mfma_f32_16x16x32_bf16 v[8:11], v[176:179], v[204:207], v[8:11]
	v_mfma_f32_16x16x32_bf16 v[8:11], v[184:187], v[208:211], v[8:11]
	s_barrier
	v_mfma_f32_16x16x32_bf16 v[4:7], v[168:171], v[212:215], v[4:7]
	v_mfma_f32_16x16x32_bf16 v[4:7], v[172:175], v[216:219], v[4:7]
	v_mfma_f32_16x16x32_bf16 v[0:3], v[176:179], v[212:215], v[0:3]
	v_mfma_f32_16x16x32_bf16 v[0:3], v[184:187], v[216:219], v[0:3]
	s_setprio 0
	s_add_i32 s86, s86, 2
	s_add_u32 s84, s84, 0x100
	s_addc_u32 s85, s85, 0
	s_cmp_gt_u32 s86, 41
	s_mov_b64 s[52:53], s[54:55]
	s_cbranch_scc0 .LBB0_804
	s_and_b64 vcc, exec, s[18:19]
	s_cbranch_vccz .LBB0_807
	s_barrier

.LBB0_934:
	s_ashr_i32 s53, s52, 31
	s_lshl_b64 s[54:55], s[52:53], 19
	s_add_u32 s54, s80, s54
	s_addc_u32 s55, s81, s55
	s_and_b64 s[56:57], s[10:11], exec
	s_cselect_b32 s53, s55, s61
	s_cselect_b32 s83, s54, s60
	s_ashr_i32 s49, s48, 31
	s_lshl_b64 s[56:57], s[48:49], 19
	s_add_u32 s56, s66, s56
	s_addc_u32 s57, s67, s57
	s_and_b64 s[64:65], s[10:11], exec
	s_cselect_b32 s49, s57, s63
	s_cselect_b32 s84, s56, s62
	s_add_u32 s60, s60, 0x40080
	s_addc_u32 s61, s61, 0
	s_add_u32 s85, s62, 0x100
	s_addc_u32 s86, s63, 0
	s_mov_b32 s87, -2
	ds_read_b128 v[152:155], v148
	ds_read_b128 v[156:159], v148 offset:1024
	ds_read_b128 v[160:163], v148 offset:2048
	ds_read_b128 v[164:167], v148 offset:3072
	ds_read_b128 v[168:171], v149
	ds_read_b128 v[172:175], v149 offset:1024
	ds_read_b128 v[176:179], v149 offset:2048
	ds_read_b128 v[184:187], v149 offset:3072
	s_add_u32 s62, s60, 0xfffc0080
	s_addc_u32 s63, s61, -1
	s_cmp_eq_u32 s87, 12
	s_cselect_b32 s65, s53, s63
	s_cselect_b32 s64, s83, s62
	s_cselect_b32 s63, s49, s86
	s_cselect_b32 s62, s84, s85
	v_lshl_add_u64 v[220:221], s[60:61], 0, v[138:139]
	s_add_i32 m0, s69, 0xc000
	ds_read_b128 v[188:191], v150
	ds_read_b128 v[192:195], v150 offset:1024
	ds_read_b128 v[196:199], v150 offset:2048
	ds_read_b128 v[200:203], v150 offset:3072
	ds_read_b128 v[204:207], v150 offset:4096
	ds_read_b128 v[208:211], v150 offset:5120
	ds_read_b128 v[212:215], v150 offset:6144
	ds_read_b128 v[216:219], v150 offset:7168
	global_load_lds_dwordx4 v[220:221], off
	v_lshl_add_u64 v[220:221], s[60:61], 0, v[140:141]
	s_add_i32 m0, s69, 0xe000
	s_nop 0
	global_load_lds_dwordx4 v[220:221], off
	s_waitcnt vmcnt(8)
	s_waitcnt lgkmcnt(0)
	s_barrier
	s_waitcnt lgkmcnt(0)
	v_mfma_f32_16x16x32_bf16 v[124:127], v[152:155], v[188:191], 0
	v_mfma_f32_16x16x32_bf16 v[124:127], v[156:159], v[192:195], v[124:127]
	v_mfma_f32_16x16x32_bf16 v[120:123], v[160:163], v[188:191], 0
	v_mfma_f32_16x16x32_bf16 v[120:123], v[164:167], v[192:195], v[120:123]
	s_setprio 1
	v_mfma_f32_16x16x32_bf16 v[116:119], v[152:155], v[196:199], 0
	v_mfma_f32_16x16x32_bf16 v[116:119], v[156:159], v[200:203], v[116:119]
	v_mfma_f32_16x16x32_bf16 v[112:115], v[160:163], v[196:199], 0
	v_mfma_f32_16x16x32_bf16 v[112:115], v[164:167], v[200:203], v[112:115]
	v_mfma_f32_16x16x32_bf16 v[108:111], v[152:155], v[204:207], 0
	v_mfma_f32_16x16x32_bf16 v[108:111], v[156:159], v[208:211], v[108:111]
	v_mfma_f32_16x16x32_bf16 v[104:107], v[160:163], v[204:207], 0
	v_mfma_f32_16x16x32_bf16 v[104:107], v[164:167], v[208:211], v[104:107]
	v_mfma_f32_16x16x32_bf16 v[100:103], v[152:155], v[212:215], 0
	v_mfma_f32_16x16x32_bf16 v[100:103], v[156:159], v[216:219], v[100:103]
	v_mfma_f32_16x16x32_bf16 v[96:99], v[160:163], v[212:215], 0
	v_mfma_f32_16x16x32_bf16 v[96:99], v[164:167], v[216:219], v[96:99]
	v_mfma_f32_16x16x32_bf16 v[76:79], v[168:171], v[188:191], 0
	v_mfma_f32_16x16x32_bf16 v[76:79], v[172:175], v[192:195], v[76:79]
	v_mfma_f32_16x16x32_bf16 v[68:71], v[176:179], v[188:191], 0
	v_mfma_f32_16x16x32_bf16 v[68:71], v[184:187], v[192:195], v[68:71]
	v_mfma_f32_16x16x32_bf16 v[60:63], v[168:171], v[196:199], 0
	v_mfma_f32_16x16x32_bf16 v[60:63], v[172:175], v[200:203], v[60:63]
	v_mfma_f32_16x16x32_bf16 v[52:55], v[176:179], v[196:199], 0
	v_mfma_f32_16x16x32_bf16 v[52:55], v[184:187], v[200:203], v[52:55]
	v_mfma_f32_16x16x32_bf16 v[44:47], v[168:171], v[204:207], 0
	v_mfma_f32_16x16x32_bf16 v[44:47], v[172:175], v[208:211], v[44:47]
	v_mfma_f32_16x16x32_bf16 v[40:43], v[176:179], v[204:207], 0
	v_mfma_f32_16x16x32_bf16 v[40:43], v[184:187], v[208:211], v[40:43]
	s_barrier
	v_mfma_f32_16x16x32_bf16 v[36:39], v[168:171], v[212:215], 0
	v_mfma_f32_16x16x32_bf16 v[36:39], v[172:175], v[216:219], v[36:39]
	v_mfma_f32_16x16x32_bf16 v[32:35], v[176:179], v[212:215], 0
	v_mfma_f32_16x16x32_bf16 v[32:35], v[184:187], v[216:219], v[32:35]
	s_setprio 0
	s_add_i32 s79, s77, s68
	v_lshl_add_u64 v[220:221], s[62:63], 0, v[130:131]
	s_mov_b32 m0, s79
	ds_read_b128 v[188:191], v150 offset:16384
	ds_read_b128 v[192:195], v150 offset:17408
	ds_read_b128 v[196:199], v150 offset:18432
	ds_read_b128 v[200:203], v150 offset:19456
	ds_read_b128 v[204:207], v150 offset:20480
	ds_read_b128 v[208:211], v150 offset:21504
	ds_read_b128 v[212:215], v150 offset:22528
	ds_read_b128 v[216:219], v150 offset:23552
	global_load_lds_dwordx4 v[220:221], off
	s_add_i32 m0, s79, 0x2000
	s_add_u32 s88, s62, 0x40000
	v_lshl_add_u64 v[222:223], s[62:63], 0, v[134:135]
	s_addc_u32 s89, s63, 0
	s_add_i32 s79, s82, s68
	global_load_lds_dwordx4 v[222:223], off
	v_lshl_add_u64 v[224:225], s[88:89], 0, v[130:131]
	s_mov_b32 m0, s79
	v_lshl_add_u64 v[226:227], s[64:65], 0, v[132:133]
	global_load_lds_dwordx4 v[224:225], off
	v_lshl_add_u64 v[224:225], s[88:89], 0, v[134:135]
	s_add_i32 m0, s79, 0x2000
	s_nop 0
	global_load_lds_dwordx4 v[224:225], off
	v_lshl_add_u64 v[224:225], s[64:65], 0, v[128:129]
	s_mov_b32 m0, s69
	s_nop 0
	global_load_lds_dwordx4 v[224:225], off
	s_mov_b32 m0, s70
	s_nop 0
	global_load_lds_dwordx4 v[226:227], off
	s_waitcnt vmcnt(8)
	s_waitcnt lgkmcnt(0)
	s_barrier
	s_waitcnt lgkmcnt(0)
	v_mfma_f32_16x16x32_bf16 v[92:95], v[152:155], v[188:191], 0
	v_mfma_f32_16x16x32_bf16 v[92:95], v[156:159], v[192:195], v[92:95]
	v_mfma_f32_16x16x32_bf16 v[88:91], v[160:163], v[188:191], 0
	v_mfma_f32_16x16x32_bf16 v[88:91], v[164:167], v[192:195], v[88:91]
	s_setprio 1
	v_mfma_f32_16x16x32_bf16 v[84:87], v[152:155], v[196:199], 0
	v_mfma_f32_16x16x32_bf16 v[84:87], v[156:159], v[200:203], v[84:87]
	v_mfma_f32_16x16x32_bf16 v[80:83], v[160:163], v[196:199], 0
	v_mfma_f32_16x16x32_bf16 v[80:83], v[164:167], v[200:203], v[80:83]
	v_mfma_f32_16x16x32_bf16 v[72:75], v[152:155], v[204:207], 0
	v_mfma_f32_16x16x32_bf16 v[72:75], v[156:159], v[208:211], v[72:75]
	v_mfma_f32_16x16x32_bf16 v[64:67], v[160:163], v[204:207], 0
	v_mfma_f32_16x16x32_bf16 v[64:67], v[164:167], v[208:211], v[64:67]
	v_mfma_f32_16x16x32_bf16 v[56:59], v[152:155], v[212:215], 0
	v_mfma_f32_16x16x32_bf16 v[56:59], v[156:159], v[216:219], v[56:59]
	v_mfma_f32_16x16x32_bf16 v[48:51], v[160:163], v[212:215], 0
	v_mfma_f32_16x16x32_bf16 v[48:51], v[164:167], v[216:219], v[48:51]
	v_mfma_f32_16x16x32_bf16 v[28:31], v[168:171], v[188:191], 0
	v_mfma_f32_16x16x32_bf16 v[28:31], v[172:175], v[192:195], v[28:31]
	v_mfma_f32_16x16x32_bf16 v[24:27], v[176:179], v[188:191], 0
	v_mfma_f32_16x16x32_bf16 v[24:27], v[184:187], v[192:195], v[24:27]
	v_mfma_f32_16x16x32_bf16 v[20:23], v[168:171], v[196:199], 0
	v_mfma_f32_16x16x32_bf16 v[20:23], v[172:175], v[200:203], v[20:23]
	v_mfma_f32_16x16x32_bf16 v[16:19], v[176:179], v[196:199], 0
	v_mfma_f32_16x16x32_bf16 v[16:19], v[184:187], v[200:203], v[16:19]
	v_mfma_f32_16x16x32_bf16 v[12:15], v[168:171], v[204:207], 0
	v_mfma_f32_16x16x32_bf16 v[12:15], v[172:175], v[208:211], v[12:15]
	v_mfma_f32_16x16x32_bf16 v[8:11], v[176:179], v[204:207], 0
	v_mfma_f32_16x16x32_bf16 v[8:11], v[184:187], v[208:211], v[8:11]
	s_barrier
	v_mfma_f32_16x16x32_bf16 v[4:7], v[168:171], v[212:215], 0
	v_mfma_f32_16x16x32_bf16 v[4:7], v[172:175], v[216:219], v[4:7]
	v_mfma_f32_16x16x32_bf16 v[0:3], v[176:179], v[212:215], 0
	v_mfma_f32_16x16x32_bf16 v[0:3], v[184:187], v[216:219], v[0:3]
	s_setprio 0
	s_branch .Lmid_gemm6
.LBB0_935:
	ds_read_b128 v[152:155], v148
	ds_read_b128 v[156:159], v148 offset:1024
	ds_read_b128 v[160:163], v148 offset:2048
	ds_read_b128 v[164:167], v148 offset:3072
	ds_read_b128 v[168:171], v149
	ds_read_b128 v[172:175], v149 offset:1024
	ds_read_b128 v[176:179], v149 offset:2048
	ds_read_b128 v[184:187], v149 offset:3072
	s_add_u32 s62, s60, 0xfffc0080
	s_addc_u32 s63, s61, -1
	s_cmp_eq_u32 s87, 12
	s_cselect_b32 s65, s53, s63
	s_cselect_b32 s64, s83, s62
	s_cselect_b32 s63, s49, s86
	s_cselect_b32 s62, s84, s85
	v_lshl_add_u64 v[220:221], s[60:61], 0, v[138:139]
	s_add_i32 m0, s69, 0xc000
	ds_read_b128 v[188:191], v150
	ds_read_b128 v[192:195], v150 offset:1024
	ds_read_b128 v[196:199], v150 offset:2048
	ds_read_b128 v[200:203], v150 offset:3072
	ds_read_b128 v[204:207], v150 offset:4096
	ds_read_b128 v[208:211], v150 offset:5120
	ds_read_b128 v[212:215], v150 offset:6144
	ds_read_b128 v[216:219], v150 offset:7168
	global_load_lds_dwordx4 v[220:221], off
	v_lshl_add_u64 v[220:221], s[60:61], 0, v[140:141]
	s_add_i32 m0, s69, 0xe000
	s_nop 0
	global_load_lds_dwordx4 v[220:221], off
	s_waitcnt vmcnt(8)
	s_waitcnt lgkmcnt(0)
	s_barrier
	s_waitcnt lgkmcnt(0)
	v_mfma_f32_16x16x32_bf16 v[124:127], v[152:155], v[188:191], v[124:127]
	v_mfma_f32_16x16x32_bf16 v[124:127], v[156:159], v[192:195], v[124:127]
	v_mfma_f32_16x16x32_bf16 v[120:123], v[160:163], v[188:191], v[120:123]
	v_mfma_f32_16x16x32_bf16 v[120:123], v[164:167], v[192:195], v[120:123]
	s_setprio 1
	v_mfma_f32_16x16x32_bf16 v[116:119], v[152:155], v[196:199], v[116:119]
	v_mfma_f32_16x16x32_bf16 v[116:119], v[156:159], v[200:203], v[116:119]
	v_mfma_f32_16x16x32_bf16 v[112:115], v[160:163], v[196:199], v[112:115]
	v_mfma_f32_16x16x32_bf16 v[112:115], v[164:167], v[200:203], v[112:115]
	v_mfma_f32_16x16x32_bf16 v[108:111], v[152:155], v[204:207], v[108:111]
	v_mfma_f32_16x16x32_bf16 v[108:111], v[156:159], v[208:211], v[108:111]
	v_mfma_f32_16x16x32_bf16 v[104:107], v[160:163], v[204:207], v[104:107]
	v_mfma_f32_16x16x32_bf16 v[104:107], v[164:167], v[208:211], v[104:107]
	v_mfma_f32_16x16x32_bf16 v[100:103], v[152:155], v[212:215], v[100:103]
	v_mfma_f32_16x16x32_bf16 v[100:103], v[156:159], v[216:219], v[100:103]
	v_mfma_f32_16x16x32_bf16 v[96:99], v[160:163], v[212:215], v[96:99]
	v_mfma_f32_16x16x32_bf16 v[96:99], v[164:167], v[216:219], v[96:99]
	v_mfma_f32_16x16x32_bf16 v[76:79], v[168:171], v[188:191], v[76:79]
	v_mfma_f32_16x16x32_bf16 v[76:79], v[172:175], v[192:195], v[76:79]
	v_mfma_f32_16x16x32_bf16 v[68:71], v[176:179], v[188:191], v[68:71]
	v_mfma_f32_16x16x32_bf16 v[68:71], v[184:187], v[192:195], v[68:71]
	v_mfma_f32_16x16x32_bf16 v[60:63], v[168:171], v[196:199], v[60:63]
	v_mfma_f32_16x16x32_bf16 v[60:63], v[172:175], v[200:203], v[60:63]
	v_mfma_f32_16x16x32_bf16 v[52:55], v[176:179], v[196:199], v[52:55]
	v_mfma_f32_16x16x32_bf16 v[52:55], v[184:187], v[200:203], v[52:55]
	v_mfma_f32_16x16x32_bf16 v[44:47], v[168:171], v[204:207], v[44:47]
	v_mfma_f32_16x16x32_bf16 v[44:47], v[172:175], v[208:211], v[44:47]
	v_mfma_f32_16x16x32_bf16 v[40:43], v[176:179], v[204:207], v[40:43]
	v_mfma_f32_16x16x32_bf16 v[40:43], v[184:187], v[208:211], v[40:43]
	s_barrier
	v_mfma_f32_16x16x32_bf16 v[36:39], v[168:171], v[212:215], v[36:39]
	v_mfma_f32_16x16x32_bf16 v[36:39], v[172:175], v[216:219], v[36:39]
	v_mfma_f32_16x16x32_bf16 v[32:35], v[176:179], v[212:215], v[32:35]
	v_mfma_f32_16x16x32_bf16 v[32:35], v[184:187], v[216:219], v[32:35]
	s_setprio 0
	s_add_i32 s79, s77, s68
	v_lshl_add_u64 v[220:221], s[62:63], 0, v[130:131]
	s_mov_b32 m0, s79
	ds_read_b128 v[188:191], v150 offset:16384
	ds_read_b128 v[192:195], v150 offset:17408
	ds_read_b128 v[196:199], v150 offset:18432
	ds_read_b128 v[200:203], v150 offset:19456
	ds_read_b128 v[204:207], v150 offset:20480
	ds_read_b128 v[208:211], v150 offset:21504
	ds_read_b128 v[212:215], v150 offset:22528
	ds_read_b128 v[216:219], v150 offset:23552
	global_load_lds_dwordx4 v[220:221], off
	s_add_i32 m0, s79, 0x2000
	s_add_u32 s88, s62, 0x40000
	v_lshl_add_u64 v[222:223], s[62:63], 0, v[134:135]
	s_addc_u32 s89, s63, 0
	s_add_i32 s79, s82, s68
	global_load_lds_dwordx4 v[222:223], off
	v_lshl_add_u64 v[224:225], s[88:89], 0, v[130:131]
	s_mov_b32 m0, s79
	v_lshl_add_u64 v[226:227], s[64:65], 0, v[132:133]
	global_load_lds_dwordx4 v[224:225], off
	v_lshl_add_u64 v[224:225], s[88:89], 0, v[134:135]
	s_add_i32 m0, s79, 0x2000
	s_nop 0
	global_load_lds_dwordx4 v[224:225], off
	v_lshl_add_u64 v[224:225], s[64:65], 0, v[128:129]
	s_mov_b32 m0, s69
	s_nop 0
	global_load_lds_dwordx4 v[224:225], off
	s_mov_b32 m0, s70
	s_nop 0
	global_load_lds_dwordx4 v[226:227], off
	s_waitcnt vmcnt(8)
	s_waitcnt lgkmcnt(0)
	s_barrier
	s_waitcnt lgkmcnt(0)
	v_mfma_f32_16x16x32_bf16 v[92:95], v[152:155], v[188:191], v[92:95]
	v_mfma_f32_16x16x32_bf16 v[92:95], v[156:159], v[192:195], v[92:95]
	v_mfma_f32_16x16x32_bf16 v[88:91], v[160:163], v[188:191], v[88:91]
	v_mfma_f32_16x16x32_bf16 v[88:91], v[164:167], v[192:195], v[88:91]
	s_setprio 1
	v_mfma_f32_16x16x32_bf16 v[84:87], v[152:155], v[196:199], v[84:87]
	v_mfma_f32_16x16x32_bf16 v[84:87], v[156:159], v[200:203], v[84:87]
	v_mfma_f32_16x16x32_bf16 v[80:83], v[160:163], v[196:199], v[80:83]
	v_mfma_f32_16x16x32_bf16 v[80:83], v[164:167], v[200:203], v[80:83]
	v_mfma_f32_16x16x32_bf16 v[72:75], v[152:155], v[204:207], v[72:75]
	v_mfma_f32_16x16x32_bf16 v[72:75], v[156:159], v[208:211], v[72:75]
	v_mfma_f32_16x16x32_bf16 v[64:67], v[160:163], v[204:207], v[64:67]
	v_mfma_f32_16x16x32_bf16 v[64:67], v[164:167], v[208:211], v[64:67]
	v_mfma_f32_16x16x32_bf16 v[56:59], v[152:155], v[212:215], v[56:59]
	v_mfma_f32_16x16x32_bf16 v[56:59], v[156:159], v[216:219], v[56:59]
	v_mfma_f32_16x16x32_bf16 v[48:51], v[160:163], v[212:215], v[48:51]
	v_mfma_f32_16x16x32_bf16 v[48:51], v[164:167], v[216:219], v[48:51]
	v_mfma_f32_16x16x32_bf16 v[28:31], v[168:171], v[188:191], v[28:31]
	v_mfma_f32_16x16x32_bf16 v[28:31], v[172:175], v[192:195], v[28:31]
	v_mfma_f32_16x16x32_bf16 v[24:27], v[176:179], v[188:191], v[24:27]
	v_mfma_f32_16x16x32_bf16 v[24:27], v[184:187], v[192:195], v[24:27]
	v_mfma_f32_16x16x32_bf16 v[20:23], v[168:171], v[196:199], v[20:23]
	v_mfma_f32_16x16x32_bf16 v[20:23], v[172:175], v[200:203], v[20:23]
	v_mfma_f32_16x16x32_bf16 v[16:19], v[176:179], v[196:199], v[16:19]
	v_mfma_f32_16x16x32_bf16 v[16:19], v[184:187], v[200:203], v[16:19]
	v_mfma_f32_16x16x32_bf16 v[12:15], v[168:171], v[204:207], v[12:15]
	v_mfma_f32_16x16x32_bf16 v[12:15], v[172:175], v[208:211], v[12:15]
	v_mfma_f32_16x16x32_bf16 v[8:11], v[176:179], v[204:207], v[8:11]
	v_mfma_f32_16x16x32_bf16 v[8:11], v[184:187], v[208:211], v[8:11]
	s_barrier
	v_mfma_f32_16x16x32_bf16 v[4:7], v[168:171], v[212:215], v[4:7]
	v_mfma_f32_16x16x32_bf16 v[4:7], v[172:175], v[216:219], v[4:7]
	v_mfma_f32_16x16x32_bf16 v[0:3], v[176:179], v[212:215], v[0:3]
	v_mfma_f32_16x16x32_bf16 v[0:3], v[184:187], v[216:219], v[0:3]
	s_setprio 0
.Lmid_gemm6:
	s_add_i32 s79, 0, 0x18000
	v_add_u32_e32 v151, s79, v147
	s_add_i32 s88, 0, 0x1c000
	ds_read_b128 v[152:155], v151
	ds_read_b128 v[156:159], v151 offset:1024
	ds_read_b128 v[160:163], v151 offset:2048
	ds_read_b128 v[164:167], v151 offset:3072
	v_add_u32_e32 v151, s88, v147
	ds_read_b128 v[168:171], v151
	ds_read_b128 v[172:175], v151 offset:1024
	ds_read_b128 v[176:179], v151 offset:2048
	ds_read_b128 v[184:187], v151 offset:3072
	s_add_u32 s64, s64, 0x40000
	s_addc_u32 s65, s65, 0
	s_mov_b32 m0, s71
	v_lshl_add_u64 v[228:229], s[64:65], 0, v[128:129]
	ds_read_b128 v[188:191], v150 offset:32768
	ds_read_b128 v[192:195], v150 offset:33792
	ds_read_b128 v[196:199], v150 offset:34816
	ds_read_b128 v[200:203], v150 offset:35840
	ds_read_b128 v[204:207], v150 offset:36864
	ds_read_b128 v[208:211], v150 offset:37888
	ds_read_b128 v[212:215], v150 offset:38912
	ds_read_b128 v[216:219], v150 offset:39936
	global_load_lds_dwordx4 v[228:229], off
	v_lshl_add_u64 v[228:229], s[64:65], 0, v[132:133]
	s_mov_b32 m0, s72
	s_nop 0
	global_load_lds_dwordx4 v[228:229], off
	s_waitcnt vmcnt(8)
	s_waitcnt lgkmcnt(0)
	s_barrier
	s_waitcnt lgkmcnt(0)
	v_mfma_f32_16x16x32_bf16 v[124:127], v[152:155], v[188:191], v[124:127]
	v_mfma_f32_16x16x32_bf16 v[124:127], v[156:159], v[192:195], v[124:127]
	v_mfma_f32_16x16x32_bf16 v[120:123], v[160:163], v[188:191], v[120:123]
	v_mfma_f32_16x16x32_bf16 v[120:123], v[164:167], v[192:195], v[120:123]
	s_setprio 1
	v_mfma_f32_16x16x32_bf16 v[116:119], v[152:155], v[196:199], v[116:119]
	v_mfma_f32_16x16x32_bf16 v[116:119], v[156:159], v[200:203], v[116:119]
	v_mfma_f32_16x16x32_bf16 v[112:115], v[160:163], v[196:199], v[112:115]
	v_mfma_f32_16x16x32_bf16 v[112:115], v[164:167], v[200:203], v[112:115]
	v_mfma_f32_16x16x32_bf16 v[108:111], v[152:155], v[204:207], v[108:111]
	v_mfma_f32_16x16x32_bf16 v[108:111], v[156:159], v[208:211], v[108:111]
	v_mfma_f32_16x16x32_bf16 v[104:107], v[160:163], v[204:207], v[104:107]
	v_mfma_f32_16x16x32_bf16 v[104:107], v[164:167], v[208:211], v[104:107]
	v_mfma_f32_16x16x32_bf16 v[100:103], v[152:155], v[212:215], v[100:103]
	v_mfma_f32_16x16x32_bf16 v[100:103], v[156:159], v[216:219], v[100:103]
	v_mfma_f32_16x16x32_bf16 v[96:99], v[160:163], v[212:215], v[96:99]
	v_mfma_f32_16x16x32_bf16 v[96:99], v[164:167], v[216:219], v[96:99]
	v_mfma_f32_16x16x32_bf16 v[76:79], v[168:171], v[188:191], v[76:79]
	v_mfma_f32_16x16x32_bf16 v[76:79], v[172:175], v[192:195], v[76:79]
	v_mfma_f32_16x16x32_bf16 v[68:71], v[176:179], v[188:191], v[68:71]
	v_mfma_f32_16x16x32_bf16 v[68:71], v[184:187], v[192:195], v[68:71]
	v_mfma_f32_16x16x32_bf16 v[60:63], v[168:171], v[196:199], v[60:63]
	v_mfma_f32_16x16x32_bf16 v[60:63], v[172:175], v[200:203], v[60:63]
	v_mfma_f32_16x16x32_bf16 v[52:55], v[176:179], v[196:199], v[52:55]
	v_mfma_f32_16x16x32_bf16 v[52:55], v[184:187], v[200:203], v[52:55]
	v_mfma_f32_16x16x32_bf16 v[44:47], v[168:171], v[204:207], v[44:47]
	v_mfma_f32_16x16x32_bf16 v[44:47], v[172:175], v[208:211], v[44:47]
	v_mfma_f32_16x16x32_bf16 v[40:43], v[176:179], v[204:207], v[40:43]
	v_mfma_f32_16x16x32_bf16 v[40:43], v[184:187], v[208:211], v[40:43]
	s_barrier
	v_mfma_f32_16x16x32_bf16 v[36:39], v[168:171], v[212:215], v[36:39]
	v_mfma_f32_16x16x32_bf16 v[36:39], v[172:175], v[216:219], v[36:39]
	v_mfma_f32_16x16x32_bf16 v[32:35], v[176:179], v[212:215], v[32:35]
	v_mfma_f32_16x16x32_bf16 v[32:35], v[184:187], v[216:219], v[32:35]
	s_setprio 0
	s_add_i32 s64, s79, s68
	v_lshl_add_u64 v[220:221], v[220:221], 0, s[12:13]
	s_mov_b32 m0, s64
	ds_read_b128 v[188:191], v150 offset:49152
	ds_read_b128 v[192:195], v150 offset:50176
	ds_read_b128 v[196:199], v150 offset:51200
	ds_read_b128 v[200:203], v150 offset:52224
	ds_read_b128 v[204:207], v150 offset:53248
	ds_read_b128 v[208:211], v150 offset:54272
	ds_read_b128 v[212:215], v150 offset:55296
	ds_read_b128 v[216:219], v150 offset:56320
	global_load_lds_dwordx4 v[220:221], off
	s_add_i32 m0, s64, 0x2000
	s_add_u32 s62, s62, 0x40080
	v_lshl_add_u64 v[220:221], v[222:223], 0, s[12:13]
	s_addc_u32 s63, s63, 0
	s_add_i32 s64, s88, s68
	global_load_lds_dwordx4 v[220:221], off
	v_lshl_add_u64 v[220:221], s[62:63], 0, v[130:131]
	s_mov_b32 m0, s64
	s_nop 0
	global_load_lds_dwordx4 v[220:221], off
	v_lshl_add_u64 v[220:221], s[62:63], 0, v[134:135]
	s_add_i32 m0, s64, 0x2000
	s_nop 0
	global_load_lds_dwordx4 v[220:221], off
	v_lshl_add_u64 v[220:221], v[224:225], 0, s[12:13]
	s_mov_b32 m0, s75
	s_nop 0
	global_load_lds_dwordx4 v[220:221], off
	v_lshl_add_u64 v[220:221], v[226:227], 0, s[12:13]
	s_mov_b32 m0, s76
	s_nop 0
	global_load_lds_dwordx4 v[220:221], off
	s_waitcnt vmcnt(8)
	s_waitcnt lgkmcnt(0)
	s_barrier
	s_waitcnt lgkmcnt(0)
	v_mfma_f32_16x16x32_bf16 v[92:95], v[152:155], v[188:191], v[92:95]
	v_mfma_f32_16x16x32_bf16 v[92:95], v[156:159], v[192:195], v[92:95]
	v_mfma_f32_16x16x32_bf16 v[88:91], v[160:163], v[188:191], v[88:91]
	v_mfma_f32_16x16x32_bf16 v[88:91], v[164:167], v[192:195], v[88:91]
	s_setprio 1
	v_mfma_f32_16x16x32_bf16 v[84:87], v[152:155], v[196:199], v[84:87]
	v_mfma_f32_16x16x32_bf16 v[84:87], v[156:159], v[200:203], v[84:87]
	v_mfma_f32_16x16x32_bf16 v[80:83], v[160:163], v[196:199], v[80:83]
	v_mfma_f32_16x16x32_bf16 v[80:83], v[164:167], v[200:203], v[80:83]
	v_mfma_f32_16x16x32_bf16 v[72:75], v[152:155], v[204:207], v[72:75]
	v_mfma_f32_16x16x32_bf16 v[72:75], v[156:159], v[208:211], v[72:75]
	v_mfma_f32_16x16x32_bf16 v[64:67], v[160:163], v[204:207], v[64:67]
	v_mfma_f32_16x16x32_bf16 v[64:67], v[164:167], v[208:211], v[64:67]
	v_mfma_f32_16x16x32_bf16 v[56:59], v[152:155], v[212:215], v[56:59]
	v_mfma_f32_16x16x32_bf16 v[56:59], v[156:159], v[216:219], v[56:59]
	v_mfma_f32_16x16x32_bf16 v[48:51], v[160:163], v[212:215], v[48:51]
	v_mfma_f32_16x16x32_bf16 v[48:51], v[164:167], v[216:219], v[48:51]
	v_mfma_f32_16x16x32_bf16 v[28:31], v[168:171], v[188:191], v[28:31]
	v_mfma_f32_16x16x32_bf16 v[28:31], v[172:175], v[192:195], v[28:31]
	v_mfma_f32_16x16x32_bf16 v[24:27], v[176:179], v[188:191], v[24:27]
	v_mfma_f32_16x16x32_bf16 v[24:27], v[184:187], v[192:195], v[24:27]
	v_mfma_f32_16x16x32_bf16 v[20:23], v[168:171], v[196:199], v[20:23]
	v_mfma_f32_16x16x32_bf16 v[20:23], v[172:175], v[200:203], v[20:23]
	v_mfma_f32_16x16x32_bf16 v[16:19], v[176:179], v[196:199], v[16:19]
	v_mfma_f32_16x16x32_bf16 v[16:19], v[184:187], v[200:203], v[16:19]
	v_mfma_f32_16x16x32_bf16 v[12:15], v[168:171], v[204:207], v[12:15]
	v_mfma_f32_16x16x32_bf16 v[12:15], v[172:175], v[208:211], v[12:15]
	v_mfma_f32_16x16x32_bf16 v[8:11], v[176:179], v[204:207], v[8:11]
	v_mfma_f32_16x16x32_bf16 v[8:11], v[184:187], v[208:211], v[8:11]
	s_barrier
	v_mfma_f32_16x16x32_bf16 v[4:7], v[168:171], v[212:215], v[4:7]
	v_mfma_f32_16x16x32_bf16 v[4:7], v[172:175], v[216:219], v[4:7]
	v_mfma_f32_16x16x32_bf16 v[0:3], v[176:179], v[212:215], v[0:3]
	v_mfma_f32_16x16x32_bf16 v[0:3], v[184:187], v[216:219], v[0:3]
	s_setprio 0
	s_add_i32 s87, s87, 2
	s_add_u32 s60, s60, 0x100
	s_addc_u32 s61, s61, 0
	s_add_u32 s85, s85, 0x100
	s_addc_u32 s86, s86, 0
	s_cmp_gt_u32 s87, 13
	s_cbranch_scc0 .LBB0_935
	s_and_b64 vcc, exec, s[16:17]
	s_cbranch_vccz .LBB0_938
	s_barrier

.LBB0_950:
	s_ashr_i32 s37, s36, 31
	s_lshl_b64 s[44:45], s[36:37], 19
	s_add_u32 s44, s80, s44
	s_addc_u32 s45, s81, s45
	s_and_b64 s[46:47], s[10:11], exec
	s_cselect_b32 s37, s45, s53
	s_cselect_b32 s72, s44, s52
	s_ashr_i32 s19, s18, 31
	s_lshl_b64 s[46:47], s[18:19], 19
	s_add_u32 s46, s58, s46
	s_addc_u32 s47, s59, s47
	s_and_b64 s[56:57], s[10:11], exec
	s_cselect_b32 s19, s47, s55
	s_cselect_b32 s73, s46, s54
	s_add_u32 s52, s52, 0x40080
	s_addc_u32 s53, s53, 0
	s_add_u32 s74, s54, 0x100
	s_addc_u32 s75, s55, 0
	s_mov_b32 s76, -2
	ds_read_b128 v[140:143], v147
	ds_read_b128 v[150:153], v147 offset:1024
	ds_read_b128 v[154:157], v147 offset:2048
	ds_read_b128 v[158:161], v147 offset:3072
	ds_read_b128 v[162:165], v148
	ds_read_b128 v[166:169], v148 offset:1024
	ds_read_b128 v[170:173], v148 offset:2048
	ds_read_b128 v[174:177], v148 offset:3072
	s_add_u32 s54, s52, 0xfffc0080
	s_addc_u32 s55, s53, -1
	s_cmp_eq_u32 s76, 12
	s_cselect_b32 s57, s37, s55
	s_cselect_b32 s56, s72, s54
	s_cselect_b32 s55, s19, s75
	s_cselect_b32 s54, s73, s74
	v_lshl_add_u64 v[178:179], s[52:53], 0, v[132:133]
	s_add_i32 m0, s49, 0xc000
	ds_read_b128 v[184:187], v149
	ds_read_b128 v[188:191], v149 offset:1024
	ds_read_b128 v[192:195], v149 offset:2048
	ds_read_b128 v[196:199], v149 offset:3072
	ds_read_b128 v[200:203], v149 offset:4096
	ds_read_b128 v[204:207], v149 offset:5120
	ds_read_b128 v[208:211], v149 offset:6144
	ds_read_b128 v[212:215], v149 offset:7168
	global_load_lds_dwordx4 v[178:179], off
	v_lshl_add_u64 v[178:179], s[52:53], 0, v[134:135]
	s_add_i32 m0, s49, 0xe000
	s_nop 0
	global_load_lds_dwordx4 v[178:179], off
	s_waitcnt vmcnt(8)
	s_waitcnt lgkmcnt(0)
	s_barrier
	s_waitcnt lgkmcnt(0)
	v_mfma_f32_16x16x32_bf16 v[124:127], v[140:143], v[184:187], 0
	v_mfma_f32_16x16x32_bf16 v[124:127], v[150:153], v[188:191], v[124:127]
	v_mfma_f32_16x16x32_bf16 v[120:123], v[154:157], v[184:187], 0
	v_mfma_f32_16x16x32_bf16 v[120:123], v[158:161], v[188:191], v[120:123]
	s_setprio 1
	v_mfma_f32_16x16x32_bf16 v[108:111], v[140:143], v[192:195], 0
	v_mfma_f32_16x16x32_bf16 v[108:111], v[150:153], v[196:199], v[108:111]
	v_mfma_f32_16x16x32_bf16 v[104:107], v[154:157], v[192:195], 0
	v_mfma_f32_16x16x32_bf16 v[104:107], v[158:161], v[196:199], v[104:107]
	v_mfma_f32_16x16x32_bf16 v[92:95], v[140:143], v[200:203], 0
	v_mfma_f32_16x16x32_bf16 v[92:95], v[150:153], v[204:207], v[92:95]
	v_mfma_f32_16x16x32_bf16 v[88:91], v[154:157], v[200:203], 0
	v_mfma_f32_16x16x32_bf16 v[88:91], v[158:161], v[204:207], v[88:91]
	v_mfma_f32_16x16x32_bf16 v[76:79], v[140:143], v[208:211], 0
	v_mfma_f32_16x16x32_bf16 v[76:79], v[150:153], v[212:215], v[76:79]
	v_mfma_f32_16x16x32_bf16 v[72:75], v[154:157], v[208:211], 0
	v_mfma_f32_16x16x32_bf16 v[72:75], v[158:161], v[212:215], v[72:75]
	v_mfma_f32_16x16x32_bf16 v[116:119], v[162:165], v[184:187], 0
	v_mfma_f32_16x16x32_bf16 v[116:119], v[166:169], v[188:191], v[116:119]
	v_mfma_f32_16x16x32_bf16 v[112:115], v[170:173], v[184:187], 0
	v_mfma_f32_16x16x32_bf16 v[112:115], v[174:177], v[188:191], v[112:115]
	v_mfma_f32_16x16x32_bf16 v[100:103], v[162:165], v[192:195], 0
	v_mfma_f32_16x16x32_bf16 v[100:103], v[166:169], v[196:199], v[100:103]
	v_mfma_f32_16x16x32_bf16 v[96:99], v[170:173], v[192:195], 0
	v_mfma_f32_16x16x32_bf16 v[96:99], v[174:177], v[196:199], v[96:99]
	v_mfma_f32_16x16x32_bf16 v[84:87], v[162:165], v[200:203], 0
	v_mfma_f32_16x16x32_bf16 v[84:87], v[166:169], v[204:207], v[84:87]
	v_mfma_f32_16x16x32_bf16 v[80:83], v[170:173], v[200:203], 0
	v_mfma_f32_16x16x32_bf16 v[80:83], v[174:177], v[204:207], v[80:83]
	s_barrier
	v_mfma_f32_16x16x32_bf16 v[68:71], v[162:165], v[208:211], 0
	v_mfma_f32_16x16x32_bf16 v[68:71], v[166:169], v[212:215], v[68:71]
	v_mfma_f32_16x16x32_bf16 v[64:67], v[170:173], v[208:211], 0
	v_mfma_f32_16x16x32_bf16 v[64:67], v[174:177], v[212:215], v[64:67]
	s_setprio 0
	s_add_i32 s77, s68, s60
	v_lshl_add_u64 v[178:179], s[54:55], 0, v[130:131]
	s_mov_b32 m0, s77
	ds_read_b128 v[184:187], v149 offset:16384
	ds_read_b128 v[188:191], v149 offset:17408
	ds_read_b128 v[192:195], v149 offset:18432
	ds_read_b128 v[196:199], v149 offset:19456
	ds_read_b128 v[200:203], v149 offset:20480
	ds_read_b128 v[204:207], v149 offset:21504
	ds_read_b128 v[208:211], v149 offset:22528
	ds_read_b128 v[212:215], v149 offset:23552
	global_load_lds_dwordx4 v[178:179], off
	s_add_i32 m0, s77, 0x2000
	s_add_u32 s82, s54, 0x40000
	v_lshl_add_u64 v[216:217], s[54:55], 0, v[128:129]
	s_addc_u32 s83, s55, 0
	s_add_i32 s77, s69, s60
	global_load_lds_dwordx4 v[216:217], off
	v_lshl_add_u64 v[218:219], s[82:83], 0, v[130:131]
	s_mov_b32 m0, s77
	v_lshl_add_u64 v[220:221], s[56:57], 0, v[128:129]
	global_load_lds_dwordx4 v[218:219], off
	v_lshl_add_u64 v[218:219], s[82:83], 0, v[128:129]
	s_add_i32 m0, s77, 0x2000
	s_nop 0
	global_load_lds_dwordx4 v[218:219], off
	v_lshl_add_u64 v[218:219], s[56:57], 0, v[130:131]
	s_mov_b32 m0, s49
	s_nop 0
	global_load_lds_dwordx4 v[218:219], off
	s_mov_b32 m0, s62
	s_nop 0
	global_load_lds_dwordx4 v[220:221], off
	s_waitcnt vmcnt(8)
	s_waitcnt lgkmcnt(0)
	s_barrier
	s_waitcnt lgkmcnt(0)
	v_mfma_f32_16x16x32_bf16 v[60:63], v[140:143], v[184:187], 0
	v_mfma_f32_16x16x32_bf16 v[60:63], v[150:153], v[188:191], v[60:63]
	v_mfma_f32_16x16x32_bf16 v[56:59], v[154:157], v[184:187], 0
	v_mfma_f32_16x16x32_bf16 v[56:59], v[158:161], v[188:191], v[56:59]
	s_setprio 1
	v_mfma_f32_16x16x32_bf16 v[44:47], v[140:143], v[192:195], 0
	v_mfma_f32_16x16x32_bf16 v[44:47], v[150:153], v[196:199], v[44:47]
	v_mfma_f32_16x16x32_bf16 v[40:43], v[154:157], v[192:195], 0
	v_mfma_f32_16x16x32_bf16 v[40:43], v[158:161], v[196:199], v[40:43]
	v_mfma_f32_16x16x32_bf16 v[28:31], v[140:143], v[200:203], 0
	v_mfma_f32_16x16x32_bf16 v[28:31], v[150:153], v[204:207], v[28:31]
	v_mfma_f32_16x16x32_bf16 v[24:27], v[154:157], v[200:203], 0
	v_mfma_f32_16x16x32_bf16 v[24:27], v[158:161], v[204:207], v[24:27]
	v_mfma_f32_16x16x32_bf16 v[12:15], v[140:143], v[208:211], 0
	v_mfma_f32_16x16x32_bf16 v[12:15], v[150:153], v[212:215], v[12:15]
	v_mfma_f32_16x16x32_bf16 v[8:11], v[154:157], v[208:211], 0
	v_mfma_f32_16x16x32_bf16 v[8:11], v[158:161], v[212:215], v[8:11]
	v_mfma_f32_16x16x32_bf16 v[52:55], v[162:165], v[184:187], 0
	v_mfma_f32_16x16x32_bf16 v[52:55], v[166:169], v[188:191], v[52:55]
	v_mfma_f32_16x16x32_bf16 v[48:51], v[170:173], v[184:187], 0
	v_mfma_f32_16x16x32_bf16 v[48:51], v[174:177], v[188:191], v[48:51]
	v_mfma_f32_16x16x32_bf16 v[36:39], v[162:165], v[192:195], 0
	v_mfma_f32_16x16x32_bf16 v[36:39], v[166:169], v[196:199], v[36:39]
	v_mfma_f32_16x16x32_bf16 v[32:35], v[170:173], v[192:195], 0
	v_mfma_f32_16x16x32_bf16 v[32:35], v[174:177], v[196:199], v[32:35]
	v_mfma_f32_16x16x32_bf16 v[20:23], v[162:165], v[200:203], 0
	v_mfma_f32_16x16x32_bf16 v[20:23], v[166:169], v[204:207], v[20:23]
	v_mfma_f32_16x16x32_bf16 v[16:19], v[170:173], v[200:203], 0
	v_mfma_f32_16x16x32_bf16 v[16:19], v[174:177], v[204:207], v[16:19]
	s_barrier
	v_mfma_f32_16x16x32_bf16 v[4:7], v[162:165], v[208:211], 0
	v_mfma_f32_16x16x32_bf16 v[4:7], v[166:169], v[212:215], v[4:7]
	v_mfma_f32_16x16x32_bf16 v[0:3], v[170:173], v[208:211], 0
	v_mfma_f32_16x16x32_bf16 v[0:3], v[174:177], v[212:215], v[0:3]
	s_setprio 0
	s_branch .Lmid_gemm7
.LBB0_951:
	ds_read_b128 v[140:143], v147
	ds_read_b128 v[150:153], v147 offset:1024
	ds_read_b128 v[154:157], v147 offset:2048
	ds_read_b128 v[158:161], v147 offset:3072
	ds_read_b128 v[162:165], v148
	ds_read_b128 v[166:169], v148 offset:1024
	ds_read_b128 v[170:173], v148 offset:2048
	ds_read_b128 v[174:177], v148 offset:3072
	s_add_u32 s54, s52, 0xfffc0080
	s_addc_u32 s55, s53, -1
	s_cmp_eq_u32 s76, 12
	s_cselect_b32 s57, s37, s55
	s_cselect_b32 s56, s72, s54
	s_cselect_b32 s55, s19, s75
	s_cselect_b32 s54, s73, s74
	v_lshl_add_u64 v[178:179], s[52:53], 0, v[132:133]
	s_add_i32 m0, s49, 0xc000
	ds_read_b128 v[184:187], v149
	ds_read_b128 v[188:191], v149 offset:1024
	ds_read_b128 v[192:195], v149 offset:2048
	ds_read_b128 v[196:199], v149 offset:3072
	ds_read_b128 v[200:203], v149 offset:4096
	ds_read_b128 v[204:207], v149 offset:5120
	ds_read_b128 v[208:211], v149 offset:6144
	ds_read_b128 v[212:215], v149 offset:7168
	global_load_lds_dwordx4 v[178:179], off
	v_lshl_add_u64 v[178:179], s[52:53], 0, v[134:135]
	s_add_i32 m0, s49, 0xe000
	s_nop 0
	global_load_lds_dwordx4 v[178:179], off
	s_waitcnt vmcnt(8)
	s_waitcnt lgkmcnt(0)
	s_barrier
	s_waitcnt lgkmcnt(0)
	v_mfma_f32_16x16x32_bf16 v[124:127], v[140:143], v[184:187], v[124:127]
	v_mfma_f32_16x16x32_bf16 v[124:127], v[150:153], v[188:191], v[124:127]
	v_mfma_f32_16x16x32_bf16 v[120:123], v[154:157], v[184:187], v[120:123]
	v_mfma_f32_16x16x32_bf16 v[120:123], v[158:161], v[188:191], v[120:123]
	s_setprio 1
	v_mfma_f32_16x16x32_bf16 v[108:111], v[140:143], v[192:195], v[108:111]
	v_mfma_f32_16x16x32_bf16 v[108:111], v[150:153], v[196:199], v[108:111]
	v_mfma_f32_16x16x32_bf16 v[104:107], v[154:157], v[192:195], v[104:107]
	v_mfma_f32_16x16x32_bf16 v[104:107], v[158:161], v[196:199], v[104:107]
	v_mfma_f32_16x16x32_bf16 v[92:95], v[140:143], v[200:203], v[92:95]
	v_mfma_f32_16x16x32_bf16 v[92:95], v[150:153], v[204:207], v[92:95]
	v_mfma_f32_16x16x32_bf16 v[88:91], v[154:157], v[200:203], v[88:91]
	v_mfma_f32_16x16x32_bf16 v[88:91], v[158:161], v[204:207], v[88:91]
	v_mfma_f32_16x16x32_bf16 v[76:79], v[140:143], v[208:211], v[76:79]
	v_mfma_f32_16x16x32_bf16 v[76:79], v[150:153], v[212:215], v[76:79]
	v_mfma_f32_16x16x32_bf16 v[72:75], v[154:157], v[208:211], v[72:75]
	v_mfma_f32_16x16x32_bf16 v[72:75], v[158:161], v[212:215], v[72:75]
	v_mfma_f32_16x16x32_bf16 v[116:119], v[162:165], v[184:187], v[116:119]
	v_mfma_f32_16x16x32_bf16 v[116:119], v[166:169], v[188:191], v[116:119]
	v_mfma_f32_16x16x32_bf16 v[112:115], v[170:173], v[184:187], v[112:115]
	v_mfma_f32_16x16x32_bf16 v[112:115], v[174:177], v[188:191], v[112:115]
	v_mfma_f32_16x16x32_bf16 v[100:103], v[162:165], v[192:195], v[100:103]
	v_mfma_f32_16x16x32_bf16 v[100:103], v[166:169], v[196:199], v[100:103]
	v_mfma_f32_16x16x32_bf16 v[96:99], v[170:173], v[192:195], v[96:99]
	v_mfma_f32_16x16x32_bf16 v[96:99], v[174:177], v[196:199], v[96:99]
	v_mfma_f32_16x16x32_bf16 v[84:87], v[162:165], v[200:203], v[84:87]
	v_mfma_f32_16x16x32_bf16 v[84:87], v[166:169], v[204:207], v[84:87]
	v_mfma_f32_16x16x32_bf16 v[80:83], v[170:173], v[200:203], v[80:83]
	v_mfma_f32_16x16x32_bf16 v[80:83], v[174:177], v[204:207], v[80:83]
	s_barrier
	v_mfma_f32_16x16x32_bf16 v[68:71], v[162:165], v[208:211], v[68:71]
	v_mfma_f32_16x16x32_bf16 v[68:71], v[166:169], v[212:215], v[68:71]
	v_mfma_f32_16x16x32_bf16 v[64:67], v[170:173], v[208:211], v[64:67]
	v_mfma_f32_16x16x32_bf16 v[64:67], v[174:177], v[212:215], v[64:67]
	s_setprio 0
	s_add_i32 s77, s68, s60
	v_lshl_add_u64 v[178:179], s[54:55], 0, v[130:131]
	s_mov_b32 m0, s77
	ds_read_b128 v[184:187], v149 offset:16384
	ds_read_b128 v[188:191], v149 offset:17408
	ds_read_b128 v[192:195], v149 offset:18432
	ds_read_b128 v[196:199], v149 offset:19456
	ds_read_b128 v[200:203], v149 offset:20480
	ds_read_b128 v[204:207], v149 offset:21504
	ds_read_b128 v[208:211], v149 offset:22528
	ds_read_b128 v[212:215], v149 offset:23552
	global_load_lds_dwordx4 v[178:179], off
	s_add_i32 m0, s77, 0x2000
	s_add_u32 s82, s54, 0x40000
	v_lshl_add_u64 v[216:217], s[54:55], 0, v[128:129]
	s_addc_u32 s83, s55, 0
	s_add_i32 s77, s69, s60
	global_load_lds_dwordx4 v[216:217], off
	v_lshl_add_u64 v[218:219], s[82:83], 0, v[130:131]
	s_mov_b32 m0, s77
	v_lshl_add_u64 v[220:221], s[56:57], 0, v[128:129]
	global_load_lds_dwordx4 v[218:219], off
	v_lshl_add_u64 v[218:219], s[82:83], 0, v[128:129]
	s_add_i32 m0, s77, 0x2000
	s_nop 0
	global_load_lds_dwordx4 v[218:219], off
	v_lshl_add_u64 v[218:219], s[56:57], 0, v[130:131]
	s_mov_b32 m0, s49
	s_nop 0
	global_load_lds_dwordx4 v[218:219], off
	s_mov_b32 m0, s62
	s_nop 0
	global_load_lds_dwordx4 v[220:221], off
	s_waitcnt vmcnt(8)
	s_waitcnt lgkmcnt(0)
	s_barrier
	s_waitcnt lgkmcnt(0)
	v_mfma_f32_16x16x32_bf16 v[60:63], v[140:143], v[184:187], v[60:63]
	v_mfma_f32_16x16x32_bf16 v[60:63], v[150:153], v[188:191], v[60:63]
	v_mfma_f32_16x16x32_bf16 v[56:59], v[154:157], v[184:187], v[56:59]
	v_mfma_f32_16x16x32_bf16 v[56:59], v[158:161], v[188:191], v[56:59]
	s_setprio 1
	v_mfma_f32_16x16x32_bf16 v[44:47], v[140:143], v[192:195], v[44:47]
	v_mfma_f32_16x16x32_bf16 v[44:47], v[150:153], v[196:199], v[44:47]
	v_mfma_f32_16x16x32_bf16 v[40:43], v[154:157], v[192:195], v[40:43]
	v_mfma_f32_16x16x32_bf16 v[40:43], v[158:161], v[196:199], v[40:43]
	v_mfma_f32_16x16x32_bf16 v[28:31], v[140:143], v[200:203], v[28:31]
	v_mfma_f32_16x16x32_bf16 v[28:31], v[150:153], v[204:207], v[28:31]
	v_mfma_f32_16x16x32_bf16 v[24:27], v[154:157], v[200:203], v[24:27]
	v_mfma_f32_16x16x32_bf16 v[24:27], v[158:161], v[204:207], v[24:27]
	v_mfma_f32_16x16x32_bf16 v[12:15], v[140:143], v[208:211], v[12:15]
	v_mfma_f32_16x16x32_bf16 v[12:15], v[150:153], v[212:215], v[12:15]
	v_mfma_f32_16x16x32_bf16 v[8:11], v[154:157], v[208:211], v[8:11]
	v_mfma_f32_16x16x32_bf16 v[8:11], v[158:161], v[212:215], v[8:11]
	v_mfma_f32_16x16x32_bf16 v[52:55], v[162:165], v[184:187], v[52:55]
	v_mfma_f32_16x16x32_bf16 v[52:55], v[166:169], v[188:191], v[52:55]
	v_mfma_f32_16x16x32_bf16 v[48:51], v[170:173], v[184:187], v[48:51]
	v_mfma_f32_16x16x32_bf16 v[48:51], v[174:177], v[188:191], v[48:51]
	v_mfma_f32_16x16x32_bf16 v[36:39], v[162:165], v[192:195], v[36:39]
	v_mfma_f32_16x16x32_bf16 v[36:39], v[166:169], v[196:199], v[36:39]
	v_mfma_f32_16x16x32_bf16 v[32:35], v[170:173], v[192:195], v[32:35]
	v_mfma_f32_16x16x32_bf16 v[32:35], v[174:177], v[196:199], v[32:35]
	v_mfma_f32_16x16x32_bf16 v[20:23], v[162:165], v[200:203], v[20:23]
	v_mfma_f32_16x16x32_bf16 v[20:23], v[166:169], v[204:207], v[20:23]
	v_mfma_f32_16x16x32_bf16 v[16:19], v[170:173], v[200:203], v[16:19]
	v_mfma_f32_16x16x32_bf16 v[16:19], v[174:177], v[204:207], v[16:19]
	s_barrier
	v_mfma_f32_16x16x32_bf16 v[4:7], v[162:165], v[208:211], v[4:7]
	v_mfma_f32_16x16x32_bf16 v[4:7], v[166:169], v[212:215], v[4:7]
	v_mfma_f32_16x16x32_bf16 v[0:3], v[170:173], v[208:211], v[0:3]
	v_mfma_f32_16x16x32_bf16 v[0:3], v[174:177], v[212:215], v[0:3]
	s_setprio 0
.Lmid_gemm7:
	s_add_i32 s77, 0, 0x18000
	s_add_i32 s79, 0, 0x1c000
	v_add_u32_e32 v158, s77, v145
	v_add_u32_e32 v174, s79, v145
	ds_read_b128 v[140:143], v158
	ds_read_b128 v[150:153], v158 offset:1024
	ds_read_b128 v[154:157], v158 offset:2048
	ds_read_b128 v[158:161], v158 offset:3072
	ds_read_b128 v[162:165], v174
	ds_read_b128 v[166:169], v174 offset:1024
	ds_read_b128 v[170:173], v174 offset:2048
	ds_read_b128 v[174:177], v174 offset:3072
	s_add_u32 s56, s56, 0x40000
	s_addc_u32 s57, s57, 0
	s_mov_b32 m0, s63
	v_lshl_add_u64 v[222:223], s[56:57], 0, v[130:131]
	ds_read_b128 v[184:187], v149 offset:32768
	ds_read_b128 v[188:191], v149 offset:33792
	ds_read_b128 v[192:195], v149 offset:34816
	ds_read_b128 v[196:199], v149 offset:35840
	ds_read_b128 v[200:203], v149 offset:36864
	ds_read_b128 v[204:207], v149 offset:37888
	ds_read_b128 v[208:211], v149 offset:38912
	ds_read_b128 v[212:215], v149 offset:39936
	global_load_lds_dwordx4 v[222:223], off
	v_lshl_add_u64 v[222:223], s[56:57], 0, v[128:129]
	s_mov_b32 m0, s64
	s_nop 0
	global_load_lds_dwordx4 v[222:223], off
	s_waitcnt vmcnt(8)
	s_waitcnt lgkmcnt(0)
	s_barrier
	s_waitcnt lgkmcnt(0)
	v_mfma_f32_16x16x32_bf16 v[124:127], v[140:143], v[184:187], v[124:127]
	v_mfma_f32_16x16x32_bf16 v[124:127], v[150:153], v[188:191], v[124:127]
	v_mfma_f32_16x16x32_bf16 v[120:123], v[154:157], v[184:187], v[120:123]
	v_mfma_f32_16x16x32_bf16 v[120:123], v[158:161], v[188:191], v[120:123]
	s_setprio 1
	v_mfma_f32_16x16x32_bf16 v[108:111], v[140:143], v[192:195], v[108:111]
	v_mfma_f32_16x16x32_bf16 v[108:111], v[150:153], v[196:199], v[108:111]
	v_mfma_f32_16x16x32_bf16 v[104:107], v[154:157], v[192:195], v[104:107]
	v_mfma_f32_16x16x32_bf16 v[104:107], v[158:161], v[196:199], v[104:107]
	v_mfma_f32_16x16x32_bf16 v[92:95], v[140:143], v[200:203], v[92:95]
	v_mfma_f32_16x16x32_bf16 v[92:95], v[150:153], v[204:207], v[92:95]
	v_mfma_f32_16x16x32_bf16 v[88:91], v[154:157], v[200:203], v[88:91]
	v_mfma_f32_16x16x32_bf16 v[88:91], v[158:161], v[204:207], v[88:91]
	v_mfma_f32_16x16x32_bf16 v[76:79], v[140:143], v[208:211], v[76:79]
	v_mfma_f32_16x16x32_bf16 v[76:79], v[150:153], v[212:215], v[76:79]
	v_mfma_f32_16x16x32_bf16 v[72:75], v[154:157], v[208:211], v[72:75]
	v_mfma_f32_16x16x32_bf16 v[72:75], v[158:161], v[212:215], v[72:75]
	v_mfma_f32_16x16x32_bf16 v[116:119], v[162:165], v[184:187], v[116:119]
	v_mfma_f32_16x16x32_bf16 v[116:119], v[166:169], v[188:191], v[116:119]
	v_mfma_f32_16x16x32_bf16 v[112:115], v[170:173], v[184:187], v[112:115]
	v_mfma_f32_16x16x32_bf16 v[112:115], v[174:177], v[188:191], v[112:115]
	v_mfma_f32_16x16x32_bf16 v[100:103], v[162:165], v[192:195], v[100:103]
	v_mfma_f32_16x16x32_bf16 v[100:103], v[166:169], v[196:199], v[100:103]
	v_mfma_f32_16x16x32_bf16 v[96:99], v[170:173], v[192:195], v[96:99]
	v_mfma_f32_16x16x32_bf16 v[96:99], v[174:177], v[196:199], v[96:99]
	v_mfma_f32_16x16x32_bf16 v[84:87], v[162:165], v[200:203], v[84:87]
	v_mfma_f32_16x16x32_bf16 v[84:87], v[166:169], v[204:207], v[84:87]
	v_mfma_f32_16x16x32_bf16 v[80:83], v[170:173], v[200:203], v[80:83]
	v_mfma_f32_16x16x32_bf16 v[80:83], v[174:177], v[204:207], v[80:83]
	s_barrier
	v_mfma_f32_16x16x32_bf16 v[68:71], v[162:165], v[208:211], v[68:71]
	v_mfma_f32_16x16x32_bf16 v[68:71], v[166:169], v[212:215], v[68:71]
	v_mfma_f32_16x16x32_bf16 v[64:67], v[170:173], v[208:211], v[64:67]
	v_mfma_f32_16x16x32_bf16 v[64:67], v[174:177], v[212:215], v[64:67]
	s_setprio 0
	s_add_i32 s56, s77, s60
	v_lshl_add_u64 v[178:179], v[178:179], 0, s[12:13]
	s_mov_b32 m0, s56
	ds_read_b128 v[184:187], v149 offset:49152
	ds_read_b128 v[188:191], v149 offset:50176
	ds_read_b128 v[192:195], v149 offset:51200
	ds_read_b128 v[196:199], v149 offset:52224
	ds_read_b128 v[200:203], v149 offset:53248
	ds_read_b128 v[204:207], v149 offset:54272
	ds_read_b128 v[208:211], v149 offset:55296
	ds_read_b128 v[212:215], v149 offset:56320
	global_load_lds_dwordx4 v[178:179], off
	s_add_i32 m0, s56, 0x2000
	s_add_u32 s54, s54, 0x40080
	v_lshl_add_u64 v[178:179], v[216:217], 0, s[12:13]
	s_addc_u32 s55, s55, 0
	s_add_i32 s56, s79, s60
	global_load_lds_dwordx4 v[178:179], off
	v_lshl_add_u64 v[178:179], s[54:55], 0, v[130:131]
	s_mov_b32 m0, s56
	s_nop 0
	global_load_lds_dwordx4 v[178:179], off
	v_lshl_add_u64 v[178:179], s[54:55], 0, v[128:129]
	s_add_i32 m0, s56, 0x2000
	s_nop 0
	global_load_lds_dwordx4 v[178:179], off
	v_lshl_add_u64 v[178:179], v[218:219], 0, s[12:13]
	s_mov_b32 m0, s66
	s_nop 0
	global_load_lds_dwordx4 v[178:179], off
	v_lshl_add_u64 v[178:179], v[220:221], 0, s[12:13]
	s_mov_b32 m0, s67
	s_nop 0
	global_load_lds_dwordx4 v[178:179], off
	s_waitcnt vmcnt(8)
	s_waitcnt lgkmcnt(0)
	s_barrier
	s_waitcnt lgkmcnt(0)
	v_mfma_f32_16x16x32_bf16 v[60:63], v[140:143], v[184:187], v[60:63]
	v_mfma_f32_16x16x32_bf16 v[60:63], v[150:153], v[188:191], v[60:63]
	v_mfma_f32_16x16x32_bf16 v[56:59], v[154:157], v[184:187], v[56:59]
	v_mfma_f32_16x16x32_bf16 v[56:59], v[158:161], v[188:191], v[56:59]
	s_setprio 1
	v_mfma_f32_16x16x32_bf16 v[44:47], v[140:143], v[192:195], v[44:47]
	v_mfma_f32_16x16x32_bf16 v[44:47], v[150:153], v[196:199], v[44:47]
	v_mfma_f32_16x16x32_bf16 v[40:43], v[154:157], v[192:195], v[40:43]
	v_mfma_f32_16x16x32_bf16 v[40:43], v[158:161], v[196:199], v[40:43]
	v_mfma_f32_16x16x32_bf16 v[28:31], v[140:143], v[200:203], v[28:31]
	v_mfma_f32_16x16x32_bf16 v[28:31], v[150:153], v[204:207], v[28:31]
	v_mfma_f32_16x16x32_bf16 v[24:27], v[154:157], v[200:203], v[24:27]
	v_mfma_f32_16x16x32_bf16 v[24:27], v[158:161], v[204:207], v[24:27]
	v_mfma_f32_16x16x32_bf16 v[12:15], v[140:143], v[208:211], v[12:15]
	v_mfma_f32_16x16x32_bf16 v[12:15], v[150:153], v[212:215], v[12:15]
	v_mfma_f32_16x16x32_bf16 v[8:11], v[154:157], v[208:211], v[8:11]
	v_mfma_f32_16x16x32_bf16 v[8:11], v[158:161], v[212:215], v[8:11]
	v_mfma_f32_16x16x32_bf16 v[52:55], v[162:165], v[184:187], v[52:55]
	v_mfma_f32_16x16x32_bf16 v[52:55], v[166:169], v[188:191], v[52:55]
	v_mfma_f32_16x16x32_bf16 v[48:51], v[170:173], v[184:187], v[48:51]
	v_mfma_f32_16x16x32_bf16 v[48:51], v[174:177], v[188:191], v[48:51]
	v_mfma_f32_16x16x32_bf16 v[36:39], v[162:165], v[192:195], v[36:39]
	v_mfma_f32_16x16x32_bf16 v[36:39], v[166:169], v[196:199], v[36:39]
	v_mfma_f32_16x16x32_bf16 v[32:35], v[170:173], v[192:195], v[32:35]
	v_mfma_f32_16x16x32_bf16 v[32:35], v[174:177], v[196:199], v[32:35]
	v_mfma_f32_16x16x32_bf16 v[20:23], v[162:165], v[200:203], v[20:23]
	v_mfma_f32_16x16x32_bf16 v[20:23], v[166:169], v[204:207], v[20:23]
	v_mfma_f32_16x16x32_bf16 v[16:19], v[170:173], v[200:203], v[16:19]
	v_mfma_f32_16x16x32_bf16 v[16:19], v[174:177], v[204:207], v[16:19]
	s_barrier
	v_mfma_f32_16x16x32_bf16 v[4:7], v[162:165], v[208:211], v[4:7]
	v_mfma_f32_16x16x32_bf16 v[4:7], v[166:169], v[212:215], v[4:7]
	v_mfma_f32_16x16x32_bf16 v[0:3], v[170:173], v[208:211], v[0:3]
	v_mfma_f32_16x16x32_bf16 v[0:3], v[174:177], v[212:215], v[0:3]
	s_setprio 0
	s_add_i32 s76, s76, 2
	s_add_u32 s52, s52, 0x100
	s_addc_u32 s53, s53, 0
	s_add_u32 s74, s74, 0x100
	s_addc_u32 s75, s75, 0
	s_cmp_gt_u32 s76, 13
	s_cbranch_scc0 .LBB0_951
	s_and_b64 vcc, exec, s[16:17]
	s_cbranch_vccz .LBB0_954
	s_barrier

.LBB0_1030:
	s_add_u32 s86, s56, 0x100
	s_addc_u32 s87, s57, 0
	s_mov_b32 s88, -2
	ds_read_b128 v[152:155], v149
	ds_read_b128 v[156:159], v149 offset:1024
	ds_read_b128 v[160:163], v149 offset:2048
	ds_read_b128 v[164:167], v149 offset:3072
	ds_read_b128 v[168:171], v150
	ds_read_b128 v[172:175], v150 offset:1024
	ds_read_b128 v[176:179], v150 offset:2048
	ds_read_b128 v[184:187], v150 offset:3072
	s_add_u32 s56, s54, 0x100
	s_addc_u32 s57, s55, 0
	s_cmp_eq_u32 s88, 40
	s_cselect_b32 s61, s13, s57
	s_cselect_b32 s60, s12, s56
	s_cselect_b32 s59, s53, s87
	s_cselect_b32 s58, s52, s86
	v_lshl_add_u64 v[144:145], s[54:55], 0, v[136:137]
	s_add_i32 m0, s65, 0xc000
	ds_read_b128 v[188:191], v151
	ds_read_b128 v[192:195], v151 offset:1024
	ds_read_b128 v[196:199], v151 offset:2048
	ds_read_b128 v[200:203], v151 offset:3072
	ds_read_b128 v[204:207], v151 offset:4096
	ds_read_b128 v[208:211], v151 offset:5120
	ds_read_b128 v[212:215], v151 offset:6144
	ds_read_b128 v[216:219], v151 offset:7168
	global_load_lds_dwordx4 v[144:145], off
	v_lshl_add_u64 v[144:145], s[54:55], 0, v[138:139]
	s_add_i32 m0, s65, 0xe000
	s_nop 0
	global_load_lds_dwordx4 v[144:145], off
	s_waitcnt vmcnt(8)
	s_waitcnt lgkmcnt(0)
	s_barrier
	s_waitcnt lgkmcnt(0)
	v_mfma_f32_16x16x32_bf16 v[124:127], v[152:155], v[188:191], 0
	v_mfma_f32_16x16x32_bf16 v[124:127], v[156:159], v[192:195], v[124:127]
	v_mfma_f32_16x16x32_bf16 v[120:123], v[160:163], v[188:191], 0
	v_mfma_f32_16x16x32_bf16 v[120:123], v[164:167], v[192:195], v[120:123]
	s_setprio 1
	v_mfma_f32_16x16x32_bf16 v[116:119], v[152:155], v[196:199], 0
	v_mfma_f32_16x16x32_bf16 v[116:119], v[156:159], v[200:203], v[116:119]
	v_mfma_f32_16x16x32_bf16 v[108:111], v[160:163], v[196:199], 0
	v_mfma_f32_16x16x32_bf16 v[108:111], v[164:167], v[200:203], v[108:111]
	v_mfma_f32_16x16x32_bf16 v[100:103], v[152:155], v[204:207], 0
	v_mfma_f32_16x16x32_bf16 v[100:103], v[156:159], v[208:211], v[100:103]
	v_mfma_f32_16x16x32_bf16 v[92:95], v[160:163], v[204:207], 0
	v_mfma_f32_16x16x32_bf16 v[92:95], v[164:167], v[208:211], v[92:95]
	v_mfma_f32_16x16x32_bf16 v[84:87], v[152:155], v[212:215], 0
	v_mfma_f32_16x16x32_bf16 v[84:87], v[156:159], v[216:219], v[84:87]
	v_mfma_f32_16x16x32_bf16 v[76:79], v[160:163], v[212:215], 0
	v_mfma_f32_16x16x32_bf16 v[76:79], v[164:167], v[216:219], v[76:79]
	v_mfma_f32_16x16x32_bf16 v[112:115], v[168:171], v[188:191], 0
	v_mfma_f32_16x16x32_bf16 v[112:115], v[172:175], v[192:195], v[112:115]
	v_mfma_f32_16x16x32_bf16 v[104:107], v[176:179], v[188:191], 0
	v_mfma_f32_16x16x32_bf16 v[104:107], v[184:187], v[192:195], v[104:107]
	v_mfma_f32_16x16x32_bf16 v[96:99], v[168:171], v[196:199], 0
	v_mfma_f32_16x16x32_bf16 v[96:99], v[172:175], v[200:203], v[96:99]
	v_mfma_f32_16x16x32_bf16 v[88:91], v[176:179], v[196:199], 0
	v_mfma_f32_16x16x32_bf16 v[88:91], v[184:187], v[200:203], v[88:91]
	v_mfma_f32_16x16x32_bf16 v[80:83], v[168:171], v[204:207], 0
	v_mfma_f32_16x16x32_bf16 v[80:83], v[172:175], v[208:211], v[80:83]
	v_mfma_f32_16x16x32_bf16 v[72:75], v[176:179], v[204:207], 0
	v_mfma_f32_16x16x32_bf16 v[72:75], v[184:187], v[208:211], v[72:75]
	s_barrier
	v_mfma_f32_16x16x32_bf16 v[68:71], v[168:171], v[212:215], 0
	v_mfma_f32_16x16x32_bf16 v[68:71], v[172:175], v[216:219], v[68:71]
	v_mfma_f32_16x16x32_bf16 v[64:67], v[176:179], v[212:215], 0
	v_mfma_f32_16x16x32_bf16 v[64:67], v[184:187], v[216:219], v[64:67]
	s_setprio 0
	s_add_i32 s54, s72, s64
	v_lshl_add_u64 v[144:145], s[58:59], 0, v[130:131]
	s_mov_b32 m0, s54
	ds_read_b128 v[188:191], v151 offset:16384
	ds_read_b128 v[192:195], v151 offset:17408
	ds_read_b128 v[196:199], v151 offset:18432
	ds_read_b128 v[200:203], v151 offset:19456
	ds_read_b128 v[204:207], v151 offset:20480
	ds_read_b128 v[208:211], v151 offset:21504
	ds_read_b128 v[212:215], v151 offset:22528
	ds_read_b128 v[216:219], v151 offset:23552
	global_load_lds_dwordx4 v[144:145], off
	s_add_i32 m0, s54, 0x2000
	s_add_u32 s54, s58, 0xb0000
	v_lshl_add_u64 v[220:221], s[58:59], 0, v[134:135]
	s_addc_u32 s55, s59, 0
	s_add_i32 s79, s73, s64
	global_load_lds_dwordx4 v[220:221], off
	v_lshl_add_u64 v[222:223], s[54:55], 0, v[130:131]
	s_mov_b32 m0, s79
	v_lshl_add_u64 v[224:225], s[60:61], 0, v[132:133]
	global_load_lds_dwordx4 v[222:223], off
	v_lshl_add_u64 v[222:223], s[54:55], 0, v[134:135]
	s_add_i32 m0, s79, 0x2000
	s_nop 0
	global_load_lds_dwordx4 v[222:223], off
	v_lshl_add_u64 v[222:223], s[60:61], 0, v[128:129]
	s_mov_b32 m0, s65
	s_nop 0
	global_load_lds_dwordx4 v[222:223], off
	s_mov_b32 m0, s66
	s_nop 0
	global_load_lds_dwordx4 v[224:225], off
	s_waitcnt vmcnt(8)
	s_waitcnt lgkmcnt(0)
	s_barrier
	s_waitcnt lgkmcnt(0)
	v_mfma_f32_16x16x32_bf16 v[60:63], v[152:155], v[188:191], 0
	v_mfma_f32_16x16x32_bf16 v[60:63], v[156:159], v[192:195], v[60:63]
	v_mfma_f32_16x16x32_bf16 v[56:59], v[160:163], v[188:191], 0
	v_mfma_f32_16x16x32_bf16 v[56:59], v[164:167], v[192:195], v[56:59]
	s_setprio 1
	v_mfma_f32_16x16x32_bf16 v[52:55], v[152:155], v[196:199], 0
	v_mfma_f32_16x16x32_bf16 v[52:55], v[156:159], v[200:203], v[52:55]
	v_mfma_f32_16x16x32_bf16 v[44:47], v[160:163], v[196:199], 0
	v_mfma_f32_16x16x32_bf16 v[44:47], v[164:167], v[200:203], v[44:47]
	v_mfma_f32_16x16x32_bf16 v[36:39], v[152:155], v[204:207], 0
	v_mfma_f32_16x16x32_bf16 v[36:39], v[156:159], v[208:211], v[36:39]
	v_mfma_f32_16x16x32_bf16 v[28:31], v[160:163], v[204:207], 0
	v_mfma_f32_16x16x32_bf16 v[28:31], v[164:167], v[208:211], v[28:31]
	v_mfma_f32_16x16x32_bf16 v[20:23], v[152:155], v[212:215], 0
	v_mfma_f32_16x16x32_bf16 v[20:23], v[156:159], v[216:219], v[20:23]
	v_mfma_f32_16x16x32_bf16 v[12:15], v[160:163], v[212:215], 0
	v_mfma_f32_16x16x32_bf16 v[12:15], v[164:167], v[216:219], v[12:15]
	v_mfma_f32_16x16x32_bf16 v[48:51], v[168:171], v[188:191], 0
	v_mfma_f32_16x16x32_bf16 v[48:51], v[172:175], v[192:195], v[48:51]
	v_mfma_f32_16x16x32_bf16 v[40:43], v[176:179], v[188:191], 0
	v_mfma_f32_16x16x32_bf16 v[40:43], v[184:187], v[192:195], v[40:43]
	v_mfma_f32_16x16x32_bf16 v[32:35], v[168:171], v[196:199], 0
	v_mfma_f32_16x16x32_bf16 v[32:35], v[172:175], v[200:203], v[32:35]
	v_mfma_f32_16x16x32_bf16 v[24:27], v[176:179], v[196:199], 0
	v_mfma_f32_16x16x32_bf16 v[24:27], v[184:187], v[200:203], v[24:27]
	v_mfma_f32_16x16x32_bf16 v[16:19], v[168:171], v[204:207], 0
	v_mfma_f32_16x16x32_bf16 v[16:19], v[172:175], v[208:211], v[16:19]
	v_mfma_f32_16x16x32_bf16 v[8:11], v[176:179], v[204:207], 0
	v_mfma_f32_16x16x32_bf16 v[8:11], v[184:187], v[208:211], v[8:11]
	s_barrier
	v_mfma_f32_16x16x32_bf16 v[4:7], v[168:171], v[212:215], 0
	v_mfma_f32_16x16x32_bf16 v[4:7], v[172:175], v[216:219], v[4:7]
	v_mfma_f32_16x16x32_bf16 v[0:3], v[176:179], v[212:215], 0
	v_mfma_f32_16x16x32_bf16 v[0:3], v[184:187], v[216:219], v[0:3]
	s_setprio 0
	s_branch .Lmid_gemm8
.LBB0_1031:
	ds_read_b128 v[152:155], v149
	ds_read_b128 v[156:159], v149 offset:1024
	ds_read_b128 v[160:163], v149 offset:2048
	ds_read_b128 v[164:167], v149 offset:3072
	ds_read_b128 v[168:171], v150
	ds_read_b128 v[172:175], v150 offset:1024
	ds_read_b128 v[176:179], v150 offset:2048
	ds_read_b128 v[184:187], v150 offset:3072
	s_add_u32 s56, s54, 0x100
	s_addc_u32 s57, s55, 0
	s_cmp_eq_u32 s88, 40
	s_cselect_b32 s61, s13, s57
	s_cselect_b32 s60, s12, s56
	s_cselect_b32 s59, s53, s87
	s_cselect_b32 s58, s52, s86
	v_lshl_add_u64 v[144:145], s[54:55], 0, v[136:137]
	s_add_i32 m0, s65, 0xc000
	ds_read_b128 v[188:191], v151
	ds_read_b128 v[192:195], v151 offset:1024
	ds_read_b128 v[196:199], v151 offset:2048
	ds_read_b128 v[200:203], v151 offset:3072
	ds_read_b128 v[204:207], v151 offset:4096
	ds_read_b128 v[208:211], v151 offset:5120
	ds_read_b128 v[212:215], v151 offset:6144
	ds_read_b128 v[216:219], v151 offset:7168
	global_load_lds_dwordx4 v[144:145], off
	v_lshl_add_u64 v[144:145], s[54:55], 0, v[138:139]
	s_add_i32 m0, s65, 0xe000
	s_nop 0
	global_load_lds_dwordx4 v[144:145], off
	s_waitcnt vmcnt(8)
	s_waitcnt lgkmcnt(0)
	s_barrier
	s_waitcnt lgkmcnt(0)
	v_mfma_f32_16x16x32_bf16 v[124:127], v[152:155], v[188:191], v[124:127]
	v_mfma_f32_16x16x32_bf16 v[124:127], v[156:159], v[192:195], v[124:127]
	v_mfma_f32_16x16x32_bf16 v[120:123], v[160:163], v[188:191], v[120:123]
	v_mfma_f32_16x16x32_bf16 v[120:123], v[164:167], v[192:195], v[120:123]
	s_setprio 1
	v_mfma_f32_16x16x32_bf16 v[116:119], v[152:155], v[196:199], v[116:119]
	v_mfma_f32_16x16x32_bf16 v[116:119], v[156:159], v[200:203], v[116:119]
	v_mfma_f32_16x16x32_bf16 v[108:111], v[160:163], v[196:199], v[108:111]
	v_mfma_f32_16x16x32_bf16 v[108:111], v[164:167], v[200:203], v[108:111]
	v_mfma_f32_16x16x32_bf16 v[100:103], v[152:155], v[204:207], v[100:103]
	v_mfma_f32_16x16x32_bf16 v[100:103], v[156:159], v[208:211], v[100:103]
	v_mfma_f32_16x16x32_bf16 v[92:95], v[160:163], v[204:207], v[92:95]
	v_mfma_f32_16x16x32_bf16 v[92:95], v[164:167], v[208:211], v[92:95]
	v_mfma_f32_16x16x32_bf16 v[84:87], v[152:155], v[212:215], v[84:87]
	v_mfma_f32_16x16x32_bf16 v[84:87], v[156:159], v[216:219], v[84:87]
	v_mfma_f32_16x16x32_bf16 v[76:79], v[160:163], v[212:215], v[76:79]
	v_mfma_f32_16x16x32_bf16 v[76:79], v[164:167], v[216:219], v[76:79]
	v_mfma_f32_16x16x32_bf16 v[112:115], v[168:171], v[188:191], v[112:115]
	v_mfma_f32_16x16x32_bf16 v[112:115], v[172:175], v[192:195], v[112:115]
	v_mfma_f32_16x16x32_bf16 v[104:107], v[176:179], v[188:191], v[104:107]
	v_mfma_f32_16x16x32_bf16 v[104:107], v[184:187], v[192:195], v[104:107]
	v_mfma_f32_16x16x32_bf16 v[96:99], v[168:171], v[196:199], v[96:99]
	v_mfma_f32_16x16x32_bf16 v[96:99], v[172:175], v[200:203], v[96:99]
	v_mfma_f32_16x16x32_bf16 v[88:91], v[176:179], v[196:199], v[88:91]
	v_mfma_f32_16x16x32_bf16 v[88:91], v[184:187], v[200:203], v[88:91]
	v_mfma_f32_16x16x32_bf16 v[80:83], v[168:171], v[204:207], v[80:83]
	v_mfma_f32_16x16x32_bf16 v[80:83], v[172:175], v[208:211], v[80:83]
	v_mfma_f32_16x16x32_bf16 v[72:75], v[176:179], v[204:207], v[72:75]
	v_mfma_f32_16x16x32_bf16 v[72:75], v[184:187], v[208:211], v[72:75]
	s_barrier
	v_mfma_f32_16x16x32_bf16 v[68:71], v[168:171], v[212:215], v[68:71]
	v_mfma_f32_16x16x32_bf16 v[68:71], v[172:175], v[216:219], v[68:71]
	v_mfma_f32_16x16x32_bf16 v[64:67], v[176:179], v[212:215], v[64:67]
	v_mfma_f32_16x16x32_bf16 v[64:67], v[184:187], v[216:219], v[64:67]
	s_setprio 0
	s_add_i32 s54, s72, s64
	v_lshl_add_u64 v[144:145], s[58:59], 0, v[130:131]
	s_mov_b32 m0, s54
	ds_read_b128 v[188:191], v151 offset:16384
	ds_read_b128 v[192:195], v151 offset:17408
	ds_read_b128 v[196:199], v151 offset:18432
	ds_read_b128 v[200:203], v151 offset:19456
	ds_read_b128 v[204:207], v151 offset:20480
	ds_read_b128 v[208:211], v151 offset:21504
	ds_read_b128 v[212:215], v151 offset:22528
	ds_read_b128 v[216:219], v151 offset:23552
	global_load_lds_dwordx4 v[144:145], off
	s_add_i32 m0, s54, 0x2000
	s_add_u32 s54, s58, 0xb0000
	v_lshl_add_u64 v[220:221], s[58:59], 0, v[134:135]
	s_addc_u32 s55, s59, 0
	s_add_i32 s79, s73, s64
	global_load_lds_dwordx4 v[220:221], off
	v_lshl_add_u64 v[222:223], s[54:55], 0, v[130:131]
	s_mov_b32 m0, s79
	v_lshl_add_u64 v[224:225], s[60:61], 0, v[132:133]
	global_load_lds_dwordx4 v[222:223], off
	v_lshl_add_u64 v[222:223], s[54:55], 0, v[134:135]
	s_add_i32 m0, s79, 0x2000
	s_nop 0
	global_load_lds_dwordx4 v[222:223], off
	v_lshl_add_u64 v[222:223], s[60:61], 0, v[128:129]
	s_mov_b32 m0, s65
	s_nop 0
	global_load_lds_dwordx4 v[222:223], off
	s_mov_b32 m0, s66
	s_nop 0
	global_load_lds_dwordx4 v[224:225], off
	s_waitcnt vmcnt(8)
	s_waitcnt lgkmcnt(0)
	s_barrier
	s_waitcnt lgkmcnt(0)
	v_mfma_f32_16x16x32_bf16 v[60:63], v[152:155], v[188:191], v[60:63]
	v_mfma_f32_16x16x32_bf16 v[60:63], v[156:159], v[192:195], v[60:63]
	v_mfma_f32_16x16x32_bf16 v[56:59], v[160:163], v[188:191], v[56:59]
	v_mfma_f32_16x16x32_bf16 v[56:59], v[164:167], v[192:195], v[56:59]
	s_setprio 1
	v_mfma_f32_16x16x32_bf16 v[52:55], v[152:155], v[196:199], v[52:55]
	v_mfma_f32_16x16x32_bf16 v[52:55], v[156:159], v[200:203], v[52:55]
	v_mfma_f32_16x16x32_bf16 v[44:47], v[160:163], v[196:199], v[44:47]
	v_mfma_f32_16x16x32_bf16 v[44:47], v[164:167], v[200:203], v[44:47]
	v_mfma_f32_16x16x32_bf16 v[36:39], v[152:155], v[204:207], v[36:39]
	v_mfma_f32_16x16x32_bf16 v[36:39], v[156:159], v[208:211], v[36:39]
	v_mfma_f32_16x16x32_bf16 v[28:31], v[160:163], v[204:207], v[28:31]
	v_mfma_f32_16x16x32_bf16 v[28:31], v[164:167], v[208:211], v[28:31]
	v_mfma_f32_16x16x32_bf16 v[20:23], v[152:155], v[212:215], v[20:23]
	v_mfma_f32_16x16x32_bf16 v[20:23], v[156:159], v[216:219], v[20:23]
	v_mfma_f32_16x16x32_bf16 v[12:15], v[160:163], v[212:215], v[12:15]
	v_mfma_f32_16x16x32_bf16 v[12:15], v[164:167], v[216:219], v[12:15]
	v_mfma_f32_16x16x32_bf16 v[48:51], v[168:171], v[188:191], v[48:51]
	v_mfma_f32_16x16x32_bf16 v[48:51], v[172:175], v[192:195], v[48:51]
	v_mfma_f32_16x16x32_bf16 v[40:43], v[176:179], v[188:191], v[40:43]
	v_mfma_f32_16x16x32_bf16 v[40:43], v[184:187], v[192:195], v[40:43]
	v_mfma_f32_16x16x32_bf16 v[32:35], v[168:171], v[196:199], v[32:35]
	v_mfma_f32_16x16x32_bf16 v[32:35], v[172:175], v[200:203], v[32:35]
	v_mfma_f32_16x16x32_bf16 v[24:27], v[176:179], v[196:199], v[24:27]
	v_mfma_f32_16x16x32_bf16 v[24:27], v[184:187], v[200:203], v[24:27]
	v_mfma_f32_16x16x32_bf16 v[16:19], v[168:171], v[204:207], v[16:19]
	v_mfma_f32_16x16x32_bf16 v[16:19], v[172:175], v[208:211], v[16:19]
	v_mfma_f32_16x16x32_bf16 v[8:11], v[176:179], v[204:207], v[8:11]
	v_mfma_f32_16x16x32_bf16 v[8:11], v[184:187], v[208:211], v[8:11]
	s_barrier
	v_mfma_f32_16x16x32_bf16 v[4:7], v[168:171], v[212:215], v[4:7]
	v_mfma_f32_16x16x32_bf16 v[4:7], v[172:175], v[216:219], v[4:7]
	v_mfma_f32_16x16x32_bf16 v[0:3], v[176:179], v[212:215], v[0:3]
	v_mfma_f32_16x16x32_bf16 v[0:3], v[184:187], v[216:219], v[0:3]
	s_setprio 0
.Lmid_gemm8:
	s_add_i32 s79, 0, 0x18000
	s_add_i32 s89, 0, 0x1c000
	v_add_u32_e32 v164, s79, v147
	v_add_u32_e32 v181, s89, v147
	ds_read_b128 v[152:155], v164
	ds_read_b128 v[156:159], v164 offset:1024
	ds_read_b128 v[160:163], v164 offset:2048
	ds_read_b128 v[164:167], v164 offset:3072
	ds_read_b128 v[168:171], v181
	ds_read_b128 v[172:175], v181 offset:1024
	ds_read_b128 v[176:179], v181 offset:2048
	ds_read_b128 v[184:187], v181 offset:3072
	s_add_u32 s54, s60, 0xb0000
	s_addc_u32 s55, s61, 0
	s_mov_b32 m0, s67
	v_lshl_add_u64 v[226:227], s[54:55], 0, v[128:129]
	ds_read_b128 v[188:191], v151 offset:32768
	ds_read_b128 v[192:195], v151 offset:33792
	ds_read_b128 v[196:199], v151 offset:34816
	ds_read_b128 v[200:203], v151 offset:35840
	ds_read_b128 v[204:207], v151 offset:36864
	ds_read_b128 v[208:211], v151 offset:37888
	ds_read_b128 v[212:215], v151 offset:38912
	ds_read_b128 v[216:219], v151 offset:39936
	global_load_lds_dwordx4 v[226:227], off
	v_lshl_add_u64 v[226:227], s[54:55], 0, v[132:133]
	s_mov_b32 m0, s68
	s_nop 0
	global_load_lds_dwordx4 v[226:227], off
	s_waitcnt vmcnt(8)
	s_waitcnt lgkmcnt(0)
	s_barrier
	s_waitcnt lgkmcnt(0)
	v_mfma_f32_16x16x32_bf16 v[124:127], v[152:155], v[188:191], v[124:127]
	v_mfma_f32_16x16x32_bf16 v[124:127], v[156:159], v[192:195], v[124:127]
	v_mfma_f32_16x16x32_bf16 v[120:123], v[160:163], v[188:191], v[120:123]
	v_mfma_f32_16x16x32_bf16 v[120:123], v[164:167], v[192:195], v[120:123]
	s_setprio 1
	v_mfma_f32_16x16x32_bf16 v[116:119], v[152:155], v[196:199], v[116:119]
	v_mfma_f32_16x16x32_bf16 v[116:119], v[156:159], v[200:203], v[116:119]
	v_mfma_f32_16x16x32_bf16 v[108:111], v[160:163], v[196:199], v[108:111]
	v_mfma_f32_16x16x32_bf16 v[108:111], v[164:167], v[200:203], v[108:111]
	v_mfma_f32_16x16x32_bf16 v[100:103], v[152:155], v[204:207], v[100:103]
	v_mfma_f32_16x16x32_bf16 v[100:103], v[156:159], v[208:211], v[100:103]
	v_mfma_f32_16x16x32_bf16 v[92:95], v[160:163], v[204:207], v[92:95]
	v_mfma_f32_16x16x32_bf16 v[92:95], v[164:167], v[208:211], v[92:95]
	v_mfma_f32_16x16x32_bf16 v[84:87], v[152:155], v[212:215], v[84:87]
	v_mfma_f32_16x16x32_bf16 v[84:87], v[156:159], v[216:219], v[84:87]
	v_mfma_f32_16x16x32_bf16 v[76:79], v[160:163], v[212:215], v[76:79]
	v_mfma_f32_16x16x32_bf16 v[76:79], v[164:167], v[216:219], v[76:79]
	v_mfma_f32_16x16x32_bf16 v[112:115], v[168:171], v[188:191], v[112:115]
	v_mfma_f32_16x16x32_bf16 v[112:115], v[172:175], v[192:195], v[112:115]
	v_mfma_f32_16x16x32_bf16 v[104:107], v[176:179], v[188:191], v[104:107]
	v_mfma_f32_16x16x32_bf16 v[104:107], v[184:187], v[192:195], v[104:107]
	v_mfma_f32_16x16x32_bf16 v[96:99], v[168:171], v[196:199], v[96:99]
	v_mfma_f32_16x16x32_bf16 v[96:99], v[172:175], v[200:203], v[96:99]
	v_mfma_f32_16x16x32_bf16 v[88:91], v[176:179], v[196:199], v[88:91]
	v_mfma_f32_16x16x32_bf16 v[88:91], v[184:187], v[200:203], v[88:91]
	v_mfma_f32_16x16x32_bf16 v[80:83], v[168:171], v[204:207], v[80:83]
	v_mfma_f32_16x16x32_bf16 v[80:83], v[172:175], v[208:211], v[80:83]
	v_mfma_f32_16x16x32_bf16 v[72:75], v[176:179], v[204:207], v[72:75]
	v_mfma_f32_16x16x32_bf16 v[72:75], v[184:187], v[208:211], v[72:75]
	s_barrier
	v_mfma_f32_16x16x32_bf16 v[68:71], v[168:171], v[212:215], v[68:71]
	v_mfma_f32_16x16x32_bf16 v[68:71], v[172:175], v[216:219], v[68:71]
	v_mfma_f32_16x16x32_bf16 v[64:67], v[176:179], v[212:215], v[64:67]
	v_mfma_f32_16x16x32_bf16 v[64:67], v[184:187], v[216:219], v[64:67]
	s_setprio 0
	s_add_i32 s54, s79, s64
	v_lshl_add_u64 v[144:145], v[144:145], 0, s[16:17]
	s_mov_b32 m0, s54
	ds_read_b128 v[188:191], v151 offset:49152
	ds_read_b128 v[192:195], v151 offset:50176
	ds_read_b128 v[196:199], v151 offset:51200
	ds_read_b128 v[200:203], v151 offset:52224
	ds_read_b128 v[204:207], v151 offset:53248
	ds_read_b128 v[208:211], v151 offset:54272
	ds_read_b128 v[212:215], v151 offset:55296
	ds_read_b128 v[216:219], v151 offset:56320
	global_load_lds_dwordx4 v[144:145], off
	s_add_i32 m0, s54, 0x2000
	s_add_u32 s54, s58, 0xb0080
	v_lshl_add_u64 v[144:145], v[220:221], 0, s[16:17]
	s_addc_u32 s55, s59, 0
	s_add_i32 s58, s89, s64
	global_load_lds_dwordx4 v[144:145], off
	v_lshl_add_u64 v[144:145], s[54:55], 0, v[130:131]
	s_mov_b32 m0, s58
	s_nop 0
	global_load_lds_dwordx4 v[144:145], off
	v_lshl_add_u64 v[144:145], s[54:55], 0, v[134:135]
	s_add_i32 m0, s58, 0x2000
	s_nop 0
	global_load_lds_dwordx4 v[144:145], off
	v_lshl_add_u64 v[144:145], v[222:223], 0, s[16:17]
	s_mov_b32 m0, s70
	s_nop 0
	global_load_lds_dwordx4 v[144:145], off
	v_lshl_add_u64 v[144:145], v[224:225], 0, s[16:17]
	s_mov_b32 m0, s71
	s_nop 0
	global_load_lds_dwordx4 v[144:145], off
	s_waitcnt vmcnt(8)
	s_waitcnt lgkmcnt(0)
	s_barrier
	s_waitcnt lgkmcnt(0)
	v_mfma_f32_16x16x32_bf16 v[60:63], v[152:155], v[188:191], v[60:63]
	v_mfma_f32_16x16x32_bf16 v[60:63], v[156:159], v[192:195], v[60:63]
	v_mfma_f32_16x16x32_bf16 v[56:59], v[160:163], v[188:191], v[56:59]
	v_mfma_f32_16x16x32_bf16 v[56:59], v[164:167], v[192:195], v[56:59]
	s_setprio 1
	v_mfma_f32_16x16x32_bf16 v[52:55], v[152:155], v[196:199], v[52:55]
	v_mfma_f32_16x16x32_bf16 v[52:55], v[156:159], v[200:203], v[52:55]
	v_mfma_f32_16x16x32_bf16 v[44:47], v[160:163], v[196:199], v[44:47]
	v_mfma_f32_16x16x32_bf16 v[44:47], v[164:167], v[200:203], v[44:47]
	v_mfma_f32_16x16x32_bf16 v[36:39], v[152:155], v[204:207], v[36:39]
	v_mfma_f32_16x16x32_bf16 v[36:39], v[156:159], v[208:211], v[36:39]
	v_mfma_f32_16x16x32_bf16 v[28:31], v[160:163], v[204:207], v[28:31]
	v_mfma_f32_16x16x32_bf16 v[28:31], v[164:167], v[208:211], v[28:31]
	v_mfma_f32_16x16x32_bf16 v[20:23], v[152:155], v[212:215], v[20:23]
	v_mfma_f32_16x16x32_bf16 v[20:23], v[156:159], v[216:219], v[20:23]
	v_mfma_f32_16x16x32_bf16 v[12:15], v[160:163], v[212:215], v[12:15]
	v_mfma_f32_16x16x32_bf16 v[12:15], v[164:167], v[216:219], v[12:15]
	v_mfma_f32_16x16x32_bf16 v[48:51], v[168:171], v[188:191], v[48:51]
	v_mfma_f32_16x16x32_bf16 v[48:51], v[172:175], v[192:195], v[48:51]
	v_mfma_f32_16x16x32_bf16 v[40:43], v[176:179], v[188:191], v[40:43]
	v_mfma_f32_16x16x32_bf16 v[40:43], v[184:187], v[192:195], v[40:43]
	v_mfma_f32_16x16x32_bf16 v[32:35], v[168:171], v[196:199], v[32:35]
	v_mfma_f32_16x16x32_bf16 v[32:35], v[172:175], v[200:203], v[32:35]
	v_mfma_f32_16x16x32_bf16 v[24:27], v[176:179], v[196:199], v[24:27]
	v_mfma_f32_16x16x32_bf16 v[24:27], v[184:187], v[200:203], v[24:27]
	v_mfma_f32_16x16x32_bf16 v[16:19], v[168:171], v[204:207], v[16:19]
	v_mfma_f32_16x16x32_bf16 v[16:19], v[172:175], v[208:211], v[16:19]
	v_mfma_f32_16x16x32_bf16 v[8:11], v[176:179], v[204:207], v[8:11]
	v_mfma_f32_16x16x32_bf16 v[8:11], v[184:187], v[208:211], v[8:11]
	s_barrier
	v_mfma_f32_16x16x32_bf16 v[4:7], v[168:171], v[212:215], v[4:7]
	v_mfma_f32_16x16x32_bf16 v[4:7], v[172:175], v[216:219], v[4:7]
	v_mfma_f32_16x16x32_bf16 v[0:3], v[176:179], v[212:215], v[0:3]
	v_mfma_f32_16x16x32_bf16 v[0:3], v[184:187], v[216:219], v[0:3]
	s_setprio 0
	s_add_i32 s88, s88, 2
	s_add_u32 s86, s86, 0x100
	s_addc_u32 s87, s87, 0
	s_cmp_gt_u32 s88, 41
	s_mov_b64 s[54:55], s[56:57]
	s_cbranch_scc0 .LBB0_1031
	s_and_b64 vcc, exec, s[18:19]
	s_cbranch_vccz .LBB0_1034
	s_barrier

.LBB0_1161:
	s_ashr_i32 s53, s52, 31
	s_lshl_b64 s[54:55], s[52:53], 19
	s_add_u32 s54, s80, s54
	s_addc_u32 s55, s81, s55
	s_and_b64 s[56:57], s[10:11], exec
	s_cselect_b32 s53, s55, s61
	s_cselect_b32 s83, s54, s60
	s_ashr_i32 s49, s48, 31
	s_lshl_b64 s[56:57], s[48:49], 19
	s_add_u32 s56, s66, s56
	s_addc_u32 s57, s67, s57
	s_and_b64 s[64:65], s[10:11], exec
	s_cselect_b32 s49, s57, s63
	s_cselect_b32 s84, s56, s62
	s_add_u32 s60, s60, 0x40080
	s_addc_u32 s61, s61, 0
	s_add_u32 s85, s62, 0x100
	s_addc_u32 s86, s63, 0
	s_mov_b32 s87, -2
	ds_read_b128 v[152:155], v148
	ds_read_b128 v[156:159], v148 offset:1024
	ds_read_b128 v[160:163], v148 offset:2048
	ds_read_b128 v[164:167], v148 offset:3072
	ds_read_b128 v[168:171], v149
	ds_read_b128 v[172:175], v149 offset:1024
	ds_read_b128 v[176:179], v149 offset:2048
	ds_read_b128 v[184:187], v149 offset:3072
	s_add_u32 s62, s60, 0xfffc0080
	s_addc_u32 s63, s61, -1
	s_cmp_eq_u32 s87, 12
	s_cselect_b32 s65, s53, s63
	s_cselect_b32 s64, s83, s62
	s_cselect_b32 s63, s49, s86
	s_cselect_b32 s62, s84, s85
	v_lshl_add_u64 v[220:221], s[60:61], 0, v[138:139]
	s_add_i32 m0, s69, 0xc000
	ds_read_b128 v[188:191], v150
	ds_read_b128 v[192:195], v150 offset:1024
	ds_read_b128 v[196:199], v150 offset:2048
	ds_read_b128 v[200:203], v150 offset:3072
	ds_read_b128 v[204:207], v150 offset:4096
	ds_read_b128 v[208:211], v150 offset:5120
	ds_read_b128 v[212:215], v150 offset:6144
	ds_read_b128 v[216:219], v150 offset:7168
	global_load_lds_dwordx4 v[220:221], off
	v_lshl_add_u64 v[220:221], s[60:61], 0, v[140:141]
	s_add_i32 m0, s69, 0xe000
	s_nop 0
	global_load_lds_dwordx4 v[220:221], off
	s_waitcnt vmcnt(8)
	s_waitcnt lgkmcnt(0)
	s_barrier
	s_waitcnt lgkmcnt(0)
	v_mfma_f32_16x16x32_bf16 v[124:127], v[152:155], v[188:191], 0
	v_mfma_f32_16x16x32_bf16 v[124:127], v[156:159], v[192:195], v[124:127]
	v_mfma_f32_16x16x32_bf16 v[120:123], v[160:163], v[188:191], 0
	v_mfma_f32_16x16x32_bf16 v[120:123], v[164:167], v[192:195], v[120:123]
	s_setprio 1
	v_mfma_f32_16x16x32_bf16 v[116:119], v[152:155], v[196:199], 0
	v_mfma_f32_16x16x32_bf16 v[116:119], v[156:159], v[200:203], v[116:119]
	v_mfma_f32_16x16x32_bf16 v[112:115], v[160:163], v[196:199], 0
	v_mfma_f32_16x16x32_bf16 v[112:115], v[164:167], v[200:203], v[112:115]
	v_mfma_f32_16x16x32_bf16 v[108:111], v[152:155], v[204:207], 0
	v_mfma_f32_16x16x32_bf16 v[108:111], v[156:159], v[208:211], v[108:111]
	v_mfma_f32_16x16x32_bf16 v[104:107], v[160:163], v[204:207], 0
	v_mfma_f32_16x16x32_bf16 v[104:107], v[164:167], v[208:211], v[104:107]
	v_mfma_f32_16x16x32_bf16 v[100:103], v[152:155], v[212:215], 0
	v_mfma_f32_16x16x32_bf16 v[100:103], v[156:159], v[216:219], v[100:103]
	v_mfma_f32_16x16x32_bf16 v[96:99], v[160:163], v[212:215], 0
	v_mfma_f32_16x16x32_bf16 v[96:99], v[164:167], v[216:219], v[96:99]
	v_mfma_f32_16x16x32_bf16 v[68:71], v[168:171], v[188:191], 0
	v_mfma_f32_16x16x32_bf16 v[68:71], v[172:175], v[192:195], v[68:71]
	v_mfma_f32_16x16x32_bf16 v[64:67], v[176:179], v[188:191], 0
	v_mfma_f32_16x16x32_bf16 v[64:67], v[184:187], v[192:195], v[64:67]
	v_mfma_f32_16x16x32_bf16 v[52:55], v[168:171], v[196:199], 0
	v_mfma_f32_16x16x32_bf16 v[52:55], v[172:175], v[200:203], v[52:55]
	v_mfma_f32_16x16x32_bf16 v[48:51], v[176:179], v[196:199], 0
	v_mfma_f32_16x16x32_bf16 v[48:51], v[184:187], v[200:203], v[48:51]
	v_mfma_f32_16x16x32_bf16 v[44:47], v[168:171], v[204:207], 0
	v_mfma_f32_16x16x32_bf16 v[44:47], v[172:175], v[208:211], v[44:47]
	v_mfma_f32_16x16x32_bf16 v[40:43], v[176:179], v[204:207], 0
	v_mfma_f32_16x16x32_bf16 v[40:43], v[184:187], v[208:211], v[40:43]
	s_barrier
	v_mfma_f32_16x16x32_bf16 v[36:39], v[168:171], v[212:215], 0
	v_mfma_f32_16x16x32_bf16 v[36:39], v[172:175], v[216:219], v[36:39]
	v_mfma_f32_16x16x32_bf16 v[32:35], v[176:179], v[212:215], 0
	v_mfma_f32_16x16x32_bf16 v[32:35], v[184:187], v[216:219], v[32:35]
	s_setprio 0
	s_add_i32 s79, s77, s68
	v_lshl_add_u64 v[220:221], s[62:63], 0, v[130:131]
	s_mov_b32 m0, s79
	ds_read_b128 v[188:191], v150 offset:16384
	ds_read_b128 v[192:195], v150 offset:17408
	ds_read_b128 v[196:199], v150 offset:18432
	ds_read_b128 v[200:203], v150 offset:19456
	ds_read_b128 v[204:207], v150 offset:20480
	ds_read_b128 v[208:211], v150 offset:21504
	ds_read_b128 v[212:215], v150 offset:22528
	ds_read_b128 v[216:219], v150 offset:23552
	global_load_lds_dwordx4 v[220:221], off
	s_add_i32 m0, s79, 0x2000
	s_add_u32 s88, s62, 0x40000
	v_lshl_add_u64 v[222:223], s[62:63], 0, v[134:135]
	s_addc_u32 s89, s63, 0
	s_add_i32 s79, s82, s68
	global_load_lds_dwordx4 v[222:223], off
	v_lshl_add_u64 v[224:225], s[88:89], 0, v[130:131]
	s_mov_b32 m0, s79
	v_lshl_add_u64 v[226:227], s[64:65], 0, v[132:133]
	global_load_lds_dwordx4 v[224:225], off
	v_lshl_add_u64 v[224:225], s[88:89], 0, v[134:135]
	s_add_i32 m0, s79, 0x2000
	s_nop 0
	global_load_lds_dwordx4 v[224:225], off
	v_lshl_add_u64 v[224:225], s[64:65], 0, v[128:129]
	s_mov_b32 m0, s69
	s_nop 0
	global_load_lds_dwordx4 v[224:225], off
	s_mov_b32 m0, s70
	s_nop 0
	global_load_lds_dwordx4 v[226:227], off
	s_waitcnt vmcnt(8)
	s_waitcnt lgkmcnt(0)
	s_barrier
	s_waitcnt lgkmcnt(0)
	v_mfma_f32_16x16x32_bf16 v[92:95], v[152:155], v[188:191], 0
	v_mfma_f32_16x16x32_bf16 v[92:95], v[156:159], v[192:195], v[92:95]
	v_mfma_f32_16x16x32_bf16 v[88:91], v[160:163], v[188:191], 0
	v_mfma_f32_16x16x32_bf16 v[88:91], v[164:167], v[192:195], v[88:91]
	s_setprio 1
	v_mfma_f32_16x16x32_bf16 v[84:87], v[152:155], v[196:199], 0
	v_mfma_f32_16x16x32_bf16 v[84:87], v[156:159], v[200:203], v[84:87]
	v_mfma_f32_16x16x32_bf16 v[80:83], v[160:163], v[196:199], 0
	v_mfma_f32_16x16x32_bf16 v[80:83], v[164:167], v[200:203], v[80:83]
	v_mfma_f32_16x16x32_bf16 v[76:79], v[152:155], v[204:207], 0
	v_mfma_f32_16x16x32_bf16 v[76:79], v[156:159], v[208:211], v[76:79]
	v_mfma_f32_16x16x32_bf16 v[72:75], v[160:163], v[204:207], 0
	v_mfma_f32_16x16x32_bf16 v[72:75], v[164:167], v[208:211], v[72:75]
	v_mfma_f32_16x16x32_bf16 v[60:63], v[152:155], v[212:215], 0
	v_mfma_f32_16x16x32_bf16 v[60:63], v[156:159], v[216:219], v[60:63]
	v_mfma_f32_16x16x32_bf16 v[56:59], v[160:163], v[212:215], 0
	v_mfma_f32_16x16x32_bf16 v[56:59], v[164:167], v[216:219], v[56:59]
	v_mfma_f32_16x16x32_bf16 v[28:31], v[168:171], v[188:191], 0
	v_mfma_f32_16x16x32_bf16 v[28:31], v[172:175], v[192:195], v[28:31]
	v_mfma_f32_16x16x32_bf16 v[24:27], v[176:179], v[188:191], 0
	v_mfma_f32_16x16x32_bf16 v[24:27], v[184:187], v[192:195], v[24:27]
	v_mfma_f32_16x16x32_bf16 v[20:23], v[168:171], v[196:199], 0
	v_mfma_f32_16x16x32_bf16 v[20:23], v[172:175], v[200:203], v[20:23]
	v_mfma_f32_16x16x32_bf16 v[16:19], v[176:179], v[196:199], 0
	v_mfma_f32_16x16x32_bf16 v[16:19], v[184:187], v[200:203], v[16:19]
	v_mfma_f32_16x16x32_bf16 v[12:15], v[168:171], v[204:207], 0
	v_mfma_f32_16x16x32_bf16 v[12:15], v[172:175], v[208:211], v[12:15]
	v_mfma_f32_16x16x32_bf16 v[8:11], v[176:179], v[204:207], 0
	v_mfma_f32_16x16x32_bf16 v[8:11], v[184:187], v[208:211], v[8:11]
	s_barrier
	v_mfma_f32_16x16x32_bf16 v[4:7], v[168:171], v[212:215], 0
	v_mfma_f32_16x16x32_bf16 v[4:7], v[172:175], v[216:219], v[4:7]
	v_mfma_f32_16x16x32_bf16 v[0:3], v[176:179], v[212:215], 0
	v_mfma_f32_16x16x32_bf16 v[0:3], v[184:187], v[216:219], v[0:3]
	s_setprio 0
	s_branch .Lmid_gemm9
.LBB0_1162:
	ds_read_b128 v[152:155], v148
	ds_read_b128 v[156:159], v148 offset:1024
	ds_read_b128 v[160:163], v148 offset:2048
	ds_read_b128 v[164:167], v148 offset:3072
	ds_read_b128 v[168:171], v149
	ds_read_b128 v[172:175], v149 offset:1024
	ds_read_b128 v[176:179], v149 offset:2048
	ds_read_b128 v[184:187], v149 offset:3072
	s_add_u32 s62, s60, 0xfffc0080
	s_addc_u32 s63, s61, -1
	s_cmp_eq_u32 s87, 12
	s_cselect_b32 s65, s53, s63
	s_cselect_b32 s64, s83, s62
	s_cselect_b32 s63, s49, s86
	s_cselect_b32 s62, s84, s85
	v_lshl_add_u64 v[220:221], s[60:61], 0, v[138:139]
	s_add_i32 m0, s69, 0xc000
	ds_read_b128 v[188:191], v150
	ds_read_b128 v[192:195], v150 offset:1024
	ds_read_b128 v[196:199], v150 offset:2048
	ds_read_b128 v[200:203], v150 offset:3072
	ds_read_b128 v[204:207], v150 offset:4096
	ds_read_b128 v[208:211], v150 offset:5120
	ds_read_b128 v[212:215], v150 offset:6144
	ds_read_b128 v[216:219], v150 offset:7168
	global_load_lds_dwordx4 v[220:221], off
	v_lshl_add_u64 v[220:221], s[60:61], 0, v[140:141]
	s_add_i32 m0, s69, 0xe000
	s_nop 0
	global_load_lds_dwordx4 v[220:221], off
	s_waitcnt vmcnt(8)
	s_waitcnt lgkmcnt(0)
	s_barrier
	s_waitcnt lgkmcnt(0)
	v_mfma_f32_16x16x32_bf16 v[124:127], v[152:155], v[188:191], v[124:127]
	v_mfma_f32_16x16x32_bf16 v[124:127], v[156:159], v[192:195], v[124:127]
	v_mfma_f32_16x16x32_bf16 v[120:123], v[160:163], v[188:191], v[120:123]
	v_mfma_f32_16x16x32_bf16 v[120:123], v[164:167], v[192:195], v[120:123]
	s_setprio 1
	v_mfma_f32_16x16x32_bf16 v[116:119], v[152:155], v[196:199], v[116:119]
	v_mfma_f32_16x16x32_bf16 v[116:119], v[156:159], v[200:203], v[116:119]
	v_mfma_f32_16x16x32_bf16 v[112:115], v[160:163], v[196:199], v[112:115]
	v_mfma_f32_16x16x32_bf16 v[112:115], v[164:167], v[200:203], v[112:115]
	v_mfma_f32_16x16x32_bf16 v[108:111], v[152:155], v[204:207], v[108:111]
	v_mfma_f32_16x16x32_bf16 v[108:111], v[156:159], v[208:211], v[108:111]
	v_mfma_f32_16x16x32_bf16 v[104:107], v[160:163], v[204:207], v[104:107]
	v_mfma_f32_16x16x32_bf16 v[104:107], v[164:167], v[208:211], v[104:107]
	v_mfma_f32_16x16x32_bf16 v[100:103], v[152:155], v[212:215], v[100:103]
	v_mfma_f32_16x16x32_bf16 v[100:103], v[156:159], v[216:219], v[100:103]
	v_mfma_f32_16x16x32_bf16 v[96:99], v[160:163], v[212:215], v[96:99]
	v_mfma_f32_16x16x32_bf16 v[96:99], v[164:167], v[216:219], v[96:99]
	v_mfma_f32_16x16x32_bf16 v[68:71], v[168:171], v[188:191], v[68:71]
	v_mfma_f32_16x16x32_bf16 v[68:71], v[172:175], v[192:195], v[68:71]
	v_mfma_f32_16x16x32_bf16 v[64:67], v[176:179], v[188:191], v[64:67]
	v_mfma_f32_16x16x32_bf16 v[64:67], v[184:187], v[192:195], v[64:67]
	v_mfma_f32_16x16x32_bf16 v[52:55], v[168:171], v[196:199], v[52:55]
	v_mfma_f32_16x16x32_bf16 v[52:55], v[172:175], v[200:203], v[52:55]
	v_mfma_f32_16x16x32_bf16 v[48:51], v[176:179], v[196:199], v[48:51]
	v_mfma_f32_16x16x32_bf16 v[48:51], v[184:187], v[200:203], v[48:51]
	v_mfma_f32_16x16x32_bf16 v[44:47], v[168:171], v[204:207], v[44:47]
	v_mfma_f32_16x16x32_bf16 v[44:47], v[172:175], v[208:211], v[44:47]
	v_mfma_f32_16x16x32_bf16 v[40:43], v[176:179], v[204:207], v[40:43]
	v_mfma_f32_16x16x32_bf16 v[40:43], v[184:187], v[208:211], v[40:43]
	s_barrier
	v_mfma_f32_16x16x32_bf16 v[36:39], v[168:171], v[212:215], v[36:39]
	v_mfma_f32_16x16x32_bf16 v[36:39], v[172:175], v[216:219], v[36:39]
	v_mfma_f32_16x16x32_bf16 v[32:35], v[176:179], v[212:215], v[32:35]
	v_mfma_f32_16x16x32_bf16 v[32:35], v[184:187], v[216:219], v[32:35]
	s_setprio 0
	s_add_i32 s79, s77, s68
	v_lshl_add_u64 v[220:221], s[62:63], 0, v[130:131]
	s_mov_b32 m0, s79
	ds_read_b128 v[188:191], v150 offset:16384
	ds_read_b128 v[192:195], v150 offset:17408
	ds_read_b128 v[196:199], v150 offset:18432
	ds_read_b128 v[200:203], v150 offset:19456
	ds_read_b128 v[204:207], v150 offset:20480
	ds_read_b128 v[208:211], v150 offset:21504
	ds_read_b128 v[212:215], v150 offset:22528
	ds_read_b128 v[216:219], v150 offset:23552
	global_load_lds_dwordx4 v[220:221], off
	s_add_i32 m0, s79, 0x2000
	s_add_u32 s88, s62, 0x40000
	v_lshl_add_u64 v[222:223], s[62:63], 0, v[134:135]
	s_addc_u32 s89, s63, 0
	s_add_i32 s79, s82, s68
	global_load_lds_dwordx4 v[222:223], off
	v_lshl_add_u64 v[224:225], s[88:89], 0, v[130:131]
	s_mov_b32 m0, s79
	v_lshl_add_u64 v[226:227], s[64:65], 0, v[132:133]
	global_load_lds_dwordx4 v[224:225], off
	v_lshl_add_u64 v[224:225], s[88:89], 0, v[134:135]
	s_add_i32 m0, s79, 0x2000
	s_nop 0
	global_load_lds_dwordx4 v[224:225], off
	v_lshl_add_u64 v[224:225], s[64:65], 0, v[128:129]
	s_mov_b32 m0, s69
	s_nop 0
	global_load_lds_dwordx4 v[224:225], off
	s_mov_b32 m0, s70
	s_nop 0
	global_load_lds_dwordx4 v[226:227], off
	s_waitcnt vmcnt(8)
	s_waitcnt lgkmcnt(0)
	s_barrier
	s_waitcnt lgkmcnt(0)
	v_mfma_f32_16x16x32_bf16 v[92:95], v[152:155], v[188:191], v[92:95]
	v_mfma_f32_16x16x32_bf16 v[92:95], v[156:159], v[192:195], v[92:95]
	v_mfma_f32_16x16x32_bf16 v[88:91], v[160:163], v[188:191], v[88:91]
	v_mfma_f32_16x16x32_bf16 v[88:91], v[164:167], v[192:195], v[88:91]
	s_setprio 1
	v_mfma_f32_16x16x32_bf16 v[84:87], v[152:155], v[196:199], v[84:87]
	v_mfma_f32_16x16x32_bf16 v[84:87], v[156:159], v[200:203], v[84:87]
	v_mfma_f32_16x16x32_bf16 v[80:83], v[160:163], v[196:199], v[80:83]
	v_mfma_f32_16x16x32_bf16 v[80:83], v[164:167], v[200:203], v[80:83]
	v_mfma_f32_16x16x32_bf16 v[76:79], v[152:155], v[204:207], v[76:79]
	v_mfma_f32_16x16x32_bf16 v[76:79], v[156:159], v[208:211], v[76:79]
	v_mfma_f32_16x16x32_bf16 v[72:75], v[160:163], v[204:207], v[72:75]
	v_mfma_f32_16x16x32_bf16 v[72:75], v[164:167], v[208:211], v[72:75]
	v_mfma_f32_16x16x32_bf16 v[60:63], v[152:155], v[212:215], v[60:63]
	v_mfma_f32_16x16x32_bf16 v[60:63], v[156:159], v[216:219], v[60:63]
	v_mfma_f32_16x16x32_bf16 v[56:59], v[160:163], v[212:215], v[56:59]
	v_mfma_f32_16x16x32_bf16 v[56:59], v[164:167], v[216:219], v[56:59]
	v_mfma_f32_16x16x32_bf16 v[28:31], v[168:171], v[188:191], v[28:31]
	v_mfma_f32_16x16x32_bf16 v[28:31], v[172:175], v[192:195], v[28:31]
	v_mfma_f32_16x16x32_bf16 v[24:27], v[176:179], v[188:191], v[24:27]
	v_mfma_f32_16x16x32_bf16 v[24:27], v[184:187], v[192:195], v[24:27]
	v_mfma_f32_16x16x32_bf16 v[20:23], v[168:171], v[196:199], v[20:23]
	v_mfma_f32_16x16x32_bf16 v[20:23], v[172:175], v[200:203], v[20:23]
	v_mfma_f32_16x16x32_bf16 v[16:19], v[176:179], v[196:199], v[16:19]
	v_mfma_f32_16x16x32_bf16 v[16:19], v[184:187], v[200:203], v[16:19]
	v_mfma_f32_16x16x32_bf16 v[12:15], v[168:171], v[204:207], v[12:15]
	v_mfma_f32_16x16x32_bf16 v[12:15], v[172:175], v[208:211], v[12:15]
	v_mfma_f32_16x16x32_bf16 v[8:11], v[176:179], v[204:207], v[8:11]
	v_mfma_f32_16x16x32_bf16 v[8:11], v[184:187], v[208:211], v[8:11]
	s_barrier
	v_mfma_f32_16x16x32_bf16 v[4:7], v[168:171], v[212:215], v[4:7]
	v_mfma_f32_16x16x32_bf16 v[4:7], v[172:175], v[216:219], v[4:7]
	v_mfma_f32_16x16x32_bf16 v[0:3], v[176:179], v[212:215], v[0:3]
	v_mfma_f32_16x16x32_bf16 v[0:3], v[184:187], v[216:219], v[0:3]
	s_setprio 0
.Lmid_gemm9:
	s_add_i32 s79, 0, 0x18000
	s_add_i32 s88, 0, 0x1c000
	v_add_u32_e32 v164, s79, v147
	v_add_u32_e32 v181, s88, v147
	ds_read_b128 v[152:155], v164
	ds_read_b128 v[156:159], v164 offset:1024
	ds_read_b128 v[160:163], v164 offset:2048
	ds_read_b128 v[164:167], v164 offset:3072
	ds_read_b128 v[168:171], v181
	ds_read_b128 v[172:175], v181 offset:1024
	ds_read_b128 v[176:179], v181 offset:2048
	ds_read_b128 v[184:187], v181 offset:3072
	s_add_u32 s64, s64, 0x40000
	s_addc_u32 s65, s65, 0
	s_mov_b32 m0, s71
	v_lshl_add_u64 v[228:229], s[64:65], 0, v[128:129]
	ds_read_b128 v[188:191], v150 offset:32768
	ds_read_b128 v[192:195], v150 offset:33792
	ds_read_b128 v[196:199], v150 offset:34816
	ds_read_b128 v[200:203], v150 offset:35840
	ds_read_b128 v[204:207], v150 offset:36864
	ds_read_b128 v[208:211], v150 offset:37888
	ds_read_b128 v[212:215], v150 offset:38912
	ds_read_b128 v[216:219], v150 offset:39936
	global_load_lds_dwordx4 v[228:229], off
	v_lshl_add_u64 v[228:229], s[64:65], 0, v[132:133]
	s_mov_b32 m0, s72
	s_nop 0
	global_load_lds_dwordx4 v[228:229], off
	s_waitcnt vmcnt(8)
	s_waitcnt lgkmcnt(0)
	s_barrier
	s_waitcnt lgkmcnt(0)
	v_mfma_f32_16x16x32_bf16 v[124:127], v[152:155], v[188:191], v[124:127]
	v_mfma_f32_16x16x32_bf16 v[124:127], v[156:159], v[192:195], v[124:127]
	v_mfma_f32_16x16x32_bf16 v[120:123], v[160:163], v[188:191], v[120:123]
	v_mfma_f32_16x16x32_bf16 v[120:123], v[164:167], v[192:195], v[120:123]
	s_setprio 1
	v_mfma_f32_16x16x32_bf16 v[116:119], v[152:155], v[196:199], v[116:119]
	v_mfma_f32_16x16x32_bf16 v[116:119], v[156:159], v[200:203], v[116:119]
	v_mfma_f32_16x16x32_bf16 v[112:115], v[160:163], v[196:199], v[112:115]
	v_mfma_f32_16x16x32_bf16 v[112:115], v[164:167], v[200:203], v[112:115]
	v_mfma_f32_16x16x32_bf16 v[108:111], v[152:155], v[204:207], v[108:111]
	v_mfma_f32_16x16x32_bf16 v[108:111], v[156:159], v[208:211], v[108:111]
	v_mfma_f32_16x16x32_bf16 v[104:107], v[160:163], v[204:207], v[104:107]
	v_mfma_f32_16x16x32_bf16 v[104:107], v[164:167], v[208:211], v[104:107]
	v_mfma_f32_16x16x32_bf16 v[100:103], v[152:155], v[212:215], v[100:103]
	v_mfma_f32_16x16x32_bf16 v[100:103], v[156:159], v[216:219], v[100:103]
	v_mfma_f32_16x16x32_bf16 v[96:99], v[160:163], v[212:215], v[96:99]
	v_mfma_f32_16x16x32_bf16 v[96:99], v[164:167], v[216:219], v[96:99]
	v_mfma_f32_16x16x32_bf16 v[68:71], v[168:171], v[188:191], v[68:71]
	v_mfma_f32_16x16x32_bf16 v[68:71], v[172:175], v[192:195], v[68:71]
	v_mfma_f32_16x16x32_bf16 v[64:67], v[176:179], v[188:191], v[64:67]
	v_mfma_f32_16x16x32_bf16 v[64:67], v[184:187], v[192:195], v[64:67]
	v_mfma_f32_16x16x32_bf16 v[52:55], v[168:171], v[196:199], v[52:55]
	v_mfma_f32_16x16x32_bf16 v[52:55], v[172:175], v[200:203], v[52:55]
	v_mfma_f32_16x16x32_bf16 v[48:51], v[176:179], v[196:199], v[48:51]
	v_mfma_f32_16x16x32_bf16 v[48:51], v[184:187], v[200:203], v[48:51]
	v_mfma_f32_16x16x32_bf16 v[44:47], v[168:171], v[204:207], v[44:47]
	v_mfma_f32_16x16x32_bf16 v[44:47], v[172:175], v[208:211], v[44:47]
	v_mfma_f32_16x16x32_bf16 v[40:43], v[176:179], v[204:207], v[40:43]
	v_mfma_f32_16x16x32_bf16 v[40:43], v[184:187], v[208:211], v[40:43]
	s_barrier
	v_mfma_f32_16x16x32_bf16 v[36:39], v[168:171], v[212:215], v[36:39]
	v_mfma_f32_16x16x32_bf16 v[36:39], v[172:175], v[216:219], v[36:39]
	v_mfma_f32_16x16x32_bf16 v[32:35], v[176:179], v[212:215], v[32:35]
	v_mfma_f32_16x16x32_bf16 v[32:35], v[184:187], v[216:219], v[32:35]
	s_setprio 0
	s_add_i32 s64, s79, s68
	v_lshl_add_u64 v[220:221], v[220:221], 0, s[12:13]
	s_mov_b32 m0, s64
	ds_read_b128 v[188:191], v150 offset:49152
	ds_read_b128 v[192:195], v150 offset:50176
	ds_read_b128 v[196:199], v150 offset:51200
	ds_read_b128 v[200:203], v150 offset:52224
	ds_read_b128 v[204:207], v150 offset:53248
	ds_read_b128 v[208:211], v150 offset:54272
	ds_read_b128 v[212:215], v150 offset:55296
	ds_read_b128 v[216:219], v150 offset:56320
	global_load_lds_dwordx4 v[220:221], off
	s_add_i32 m0, s64, 0x2000
	s_add_u32 s62, s62, 0x40080
	v_lshl_add_u64 v[220:221], v[222:223], 0, s[12:13]
	s_addc_u32 s63, s63, 0
	s_add_i32 s64, s88, s68
	global_load_lds_dwordx4 v[220:221], off
	v_lshl_add_u64 v[220:221], s[62:63], 0, v[130:131]
	s_mov_b32 m0, s64
	s_nop 0
	global_load_lds_dwordx4 v[220:221], off
	v_lshl_add_u64 v[220:221], s[62:63], 0, v[134:135]
	s_add_i32 m0, s64, 0x2000
	s_nop 0
	global_load_lds_dwordx4 v[220:221], off
	v_lshl_add_u64 v[220:221], v[224:225], 0, s[12:13]
	s_mov_b32 m0, s75
	s_nop 0
	global_load_lds_dwordx4 v[220:221], off
	v_lshl_add_u64 v[220:221], v[226:227], 0, s[12:13]
	s_mov_b32 m0, s76
	s_nop 0
	global_load_lds_dwordx4 v[220:221], off
	s_waitcnt vmcnt(8)
	s_waitcnt lgkmcnt(0)
	s_barrier
	s_waitcnt lgkmcnt(0)
	v_mfma_f32_16x16x32_bf16 v[92:95], v[152:155], v[188:191], v[92:95]
	v_mfma_f32_16x16x32_bf16 v[92:95], v[156:159], v[192:195], v[92:95]
	v_mfma_f32_16x16x32_bf16 v[88:91], v[160:163], v[188:191], v[88:91]
	v_mfma_f32_16x16x32_bf16 v[88:91], v[164:167], v[192:195], v[88:91]
	s_setprio 1
	v_mfma_f32_16x16x32_bf16 v[84:87], v[152:155], v[196:199], v[84:87]
	v_mfma_f32_16x16x32_bf16 v[84:87], v[156:159], v[200:203], v[84:87]
	v_mfma_f32_16x16x32_bf16 v[80:83], v[160:163], v[196:199], v[80:83]
	v_mfma_f32_16x16x32_bf16 v[80:83], v[164:167], v[200:203], v[80:83]
	v_mfma_f32_16x16x32_bf16 v[76:79], v[152:155], v[204:207], v[76:79]
	v_mfma_f32_16x16x32_bf16 v[76:79], v[156:159], v[208:211], v[76:79]
	v_mfma_f32_16x16x32_bf16 v[72:75], v[160:163], v[204:207], v[72:75]
	v_mfma_f32_16x16x32_bf16 v[72:75], v[164:167], v[208:211], v[72:75]
	v_mfma_f32_16x16x32_bf16 v[60:63], v[152:155], v[212:215], v[60:63]
	v_mfma_f32_16x16x32_bf16 v[60:63], v[156:159], v[216:219], v[60:63]
	v_mfma_f32_16x16x32_bf16 v[56:59], v[160:163], v[212:215], v[56:59]
	v_mfma_f32_16x16x32_bf16 v[56:59], v[164:167], v[216:219], v[56:59]
	v_mfma_f32_16x16x32_bf16 v[28:31], v[168:171], v[188:191], v[28:31]
	v_mfma_f32_16x16x32_bf16 v[28:31], v[172:175], v[192:195], v[28:31]
	v_mfma_f32_16x16x32_bf16 v[24:27], v[176:179], v[188:191], v[24:27]
	v_mfma_f32_16x16x32_bf16 v[24:27], v[184:187], v[192:195], v[24:27]
	v_mfma_f32_16x16x32_bf16 v[20:23], v[168:171], v[196:199], v[20:23]
	v_mfma_f32_16x16x32_bf16 v[20:23], v[172:175], v[200:203], v[20:23]
	v_mfma_f32_16x16x32_bf16 v[16:19], v[176:179], v[196:199], v[16:19]
	v_mfma_f32_16x16x32_bf16 v[16:19], v[184:187], v[200:203], v[16:19]
	v_mfma_f32_16x16x32_bf16 v[12:15], v[168:171], v[204:207], v[12:15]
	v_mfma_f32_16x16x32_bf16 v[12:15], v[172:175], v[208:211], v[12:15]
	v_mfma_f32_16x16x32_bf16 v[8:11], v[176:179], v[204:207], v[8:11]
	v_mfma_f32_16x16x32_bf16 v[8:11], v[184:187], v[208:211], v[8:11]
	s_barrier
	v_mfma_f32_16x16x32_bf16 v[4:7], v[168:171], v[212:215], v[4:7]
	v_mfma_f32_16x16x32_bf16 v[4:7], v[172:175], v[216:219], v[4:7]
	v_mfma_f32_16x16x32_bf16 v[0:3], v[176:179], v[212:215], v[0:3]
	v_mfma_f32_16x16x32_bf16 v[0:3], v[184:187], v[216:219], v[0:3]
	s_setprio 0
	s_add_i32 s87, s87, 2
	s_add_u32 s60, s60, 0x100
	s_addc_u32 s61, s61, 0
	s_add_u32 s85, s85, 0x100
	s_addc_u32 s86, s86, 0
	s_cmp_gt_u32 s87, 13
	s_cbranch_scc0 .LBB0_1162
	s_and_b64 vcc, exec, s[16:17]
	s_cbranch_vccz .LBB0_1165
	s_barrier

.LBB0_1310:
	s_ashr_i32 s49, s48, 31
	s_lshl_b64 s[50:51], s[48:49], 19
	s_add_u32 s50, s38, s50
	s_addc_u32 s51, s39, s51
	s_and_b64 s[52:53], s[10:11], exec
	s_cselect_b32 s49, s51, s57
	s_cselect_b32 s82, s50, s56
	s_ashr_i32 s47, s46, 31
	s_lshl_b64 s[52:53], s[46:47], 19
	s_add_u32 s52, s62, s52
	s_addc_u32 s53, s63, s53
	s_and_b64 s[60:61], s[10:11], exec
	s_cselect_b32 s47, s53, s59
	s_cselect_b32 s83, s52, s58
	s_add_u32 s56, s56, 0x40080
	s_addc_u32 s57, s57, 0
	s_add_u32 s84, s58, 0x100
	s_addc_u32 s85, s59, 0
	s_mov_b32 s86, -2
	ds_read_b128 v[152:155], v149
	ds_read_b128 v[156:159], v149 offset:1024
	ds_read_b128 v[160:163], v149 offset:2048
	ds_read_b128 v[164:167], v149 offset:3072
	ds_read_b128 v[168:171], v150
	ds_read_b128 v[172:175], v150 offset:1024
	ds_read_b128 v[176:179], v150 offset:2048
	ds_read_b128 v[184:187], v150 offset:3072
	s_add_u32 s58, s56, 0xfffc0080
	s_addc_u32 s59, s57, -1
	s_cmp_eq_u32 s86, 12
	s_cselect_b32 s61, s49, s59
	s_cselect_b32 s60, s82, s58
	s_cselect_b32 s59, s47, s85
	s_cselect_b32 s58, s83, s84
	v_lshl_add_u64 v[144:145], s[56:57], 0, v[136:137]
	s_add_i32 m0, s55, 0xc000
	ds_read_b128 v[188:191], v151
	ds_read_b128 v[192:195], v151 offset:1024
	ds_read_b128 v[196:199], v151 offset:2048
	ds_read_b128 v[200:203], v151 offset:3072
	ds_read_b128 v[204:207], v151 offset:4096
	ds_read_b128 v[208:211], v151 offset:5120
	ds_read_b128 v[212:215], v151 offset:6144
	ds_read_b128 v[216:219], v151 offset:7168
	global_load_lds_dwordx4 v[144:145], off
	v_lshl_add_u64 v[144:145], s[56:57], 0, v[138:139]
	s_add_i32 m0, s55, 0xe000
	s_nop 0
	global_load_lds_dwordx4 v[144:145], off
	s_waitcnt vmcnt(8)
	s_waitcnt lgkmcnt(0)
	s_barrier
	s_waitcnt lgkmcnt(0)
	v_mfma_f32_16x16x32_bf16 v[124:127], v[152:155], v[188:191], 0
	v_mfma_f32_16x16x32_bf16 v[124:127], v[156:159], v[192:195], v[124:127]
	v_mfma_f32_16x16x32_bf16 v[120:123], v[160:163], v[188:191], 0
	v_mfma_f32_16x16x32_bf16 v[120:123], v[164:167], v[192:195], v[120:123]
	s_setprio 1
	v_mfma_f32_16x16x32_bf16 v[116:119], v[152:155], v[196:199], 0
	v_mfma_f32_16x16x32_bf16 v[116:119], v[156:159], v[200:203], v[116:119]
	v_mfma_f32_16x16x32_bf16 v[108:111], v[160:163], v[196:199], 0
	v_mfma_f32_16x16x32_bf16 v[108:111], v[164:167], v[200:203], v[108:111]
	v_mfma_f32_16x16x32_bf16 v[100:103], v[152:155], v[204:207], 0
	v_mfma_f32_16x16x32_bf16 v[100:103], v[156:159], v[208:211], v[100:103]
	v_mfma_f32_16x16x32_bf16 v[92:95], v[160:163], v[204:207], 0
	v_mfma_f32_16x16x32_bf16 v[92:95], v[164:167], v[208:211], v[92:95]
	v_mfma_f32_16x16x32_bf16 v[84:87], v[152:155], v[212:215], 0
	v_mfma_f32_16x16x32_bf16 v[84:87], v[156:159], v[216:219], v[84:87]
	v_mfma_f32_16x16x32_bf16 v[76:79], v[160:163], v[212:215], 0
	v_mfma_f32_16x16x32_bf16 v[76:79], v[164:167], v[216:219], v[76:79]
	v_mfma_f32_16x16x32_bf16 v[112:115], v[168:171], v[188:191], 0
	v_mfma_f32_16x16x32_bf16 v[112:115], v[172:175], v[192:195], v[112:115]
	v_mfma_f32_16x16x32_bf16 v[104:107], v[176:179], v[188:191], 0
	v_mfma_f32_16x16x32_bf16 v[104:107], v[184:187], v[192:195], v[104:107]
	v_mfma_f32_16x16x32_bf16 v[96:99], v[168:171], v[196:199], 0
	v_mfma_f32_16x16x32_bf16 v[96:99], v[172:175], v[200:203], v[96:99]
	v_mfma_f32_16x16x32_bf16 v[88:91], v[176:179], v[196:199], 0
	v_mfma_f32_16x16x32_bf16 v[88:91], v[184:187], v[200:203], v[88:91]
	v_mfma_f32_16x16x32_bf16 v[80:83], v[168:171], v[204:207], 0
	v_mfma_f32_16x16x32_bf16 v[80:83], v[172:175], v[208:211], v[80:83]
	v_mfma_f32_16x16x32_bf16 v[72:75], v[176:179], v[204:207], 0
	v_mfma_f32_16x16x32_bf16 v[72:75], v[184:187], v[208:211], v[72:75]
	s_barrier
	v_mfma_f32_16x16x32_bf16 v[68:71], v[168:171], v[212:215], 0
	v_mfma_f32_16x16x32_bf16 v[68:71], v[172:175], v[216:219], v[68:71]
	v_mfma_f32_16x16x32_bf16 v[64:67], v[176:179], v[212:215], 0
	v_mfma_f32_16x16x32_bf16 v[64:67], v[184:187], v[216:219], v[64:67]
	s_setprio 0
	s_add_i32 s79, s71, s64
	v_lshl_add_u64 v[144:145], s[58:59], 0, v[130:131]
	s_mov_b32 m0, s79
	ds_read_b128 v[188:191], v151 offset:16384
	ds_read_b128 v[192:195], v151 offset:17408
	ds_read_b128 v[196:199], v151 offset:18432
	ds_read_b128 v[200:203], v151 offset:19456
	ds_read_b128 v[204:207], v151 offset:20480
	ds_read_b128 v[208:211], v151 offset:21504
	ds_read_b128 v[212:215], v151 offset:22528
	ds_read_b128 v[216:219], v151 offset:23552
	global_load_lds_dwordx4 v[144:145], off
	s_add_i32 m0, s79, 0x2000
	s_add_u32 s88, s58, 0x40000
	v_lshl_add_u64 v[220:221], s[58:59], 0, v[134:135]
	s_addc_u32 s89, s59, 0
	s_add_i32 s79, s72, s64
	global_load_lds_dwordx4 v[220:221], off
	v_lshl_add_u64 v[222:223], s[88:89], 0, v[130:131]
	s_mov_b32 m0, s79
	v_lshl_add_u64 v[224:225], s[60:61], 0, v[132:133]
	global_load_lds_dwordx4 v[222:223], off
	v_lshl_add_u64 v[222:223], s[88:89], 0, v[134:135]
	s_add_i32 m0, s79, 0x2000
	s_nop 0
	global_load_lds_dwordx4 v[222:223], off
	v_lshl_add_u64 v[222:223], s[60:61], 0, v[128:129]
	s_mov_b32 m0, s55
	s_nop 0
	global_load_lds_dwordx4 v[222:223], off
	s_mov_b32 m0, s65
	s_nop 0
	global_load_lds_dwordx4 v[224:225], off
	s_waitcnt vmcnt(8)
	s_waitcnt lgkmcnt(0)
	s_barrier
	s_waitcnt lgkmcnt(0)
	v_mfma_f32_16x16x32_bf16 v[60:63], v[152:155], v[188:191], 0
	v_mfma_f32_16x16x32_bf16 v[60:63], v[156:159], v[192:195], v[60:63]
	v_mfma_f32_16x16x32_bf16 v[56:59], v[160:163], v[188:191], 0
	v_mfma_f32_16x16x32_bf16 v[56:59], v[164:167], v[192:195], v[56:59]
	s_setprio 1
	v_mfma_f32_16x16x32_bf16 v[52:55], v[152:155], v[196:199], 0
	v_mfma_f32_16x16x32_bf16 v[52:55], v[156:159], v[200:203], v[52:55]
	v_mfma_f32_16x16x32_bf16 v[44:47], v[160:163], v[196:199], 0
	v_mfma_f32_16x16x32_bf16 v[44:47], v[164:167], v[200:203], v[44:47]
	v_mfma_f32_16x16x32_bf16 v[36:39], v[152:155], v[204:207], 0
	v_mfma_f32_16x16x32_bf16 v[36:39], v[156:159], v[208:211], v[36:39]
	v_mfma_f32_16x16x32_bf16 v[28:31], v[160:163], v[204:207], 0
	v_mfma_f32_16x16x32_bf16 v[28:31], v[164:167], v[208:211], v[28:31]
	v_mfma_f32_16x16x32_bf16 v[20:23], v[152:155], v[212:215], 0
	v_mfma_f32_16x16x32_bf16 v[20:23], v[156:159], v[216:219], v[20:23]
	v_mfma_f32_16x16x32_bf16 v[12:15], v[160:163], v[212:215], 0
	v_mfma_f32_16x16x32_bf16 v[12:15], v[164:167], v[216:219], v[12:15]
	v_mfma_f32_16x16x32_bf16 v[48:51], v[168:171], v[188:191], 0
	v_mfma_f32_16x16x32_bf16 v[48:51], v[172:175], v[192:195], v[48:51]
	v_mfma_f32_16x16x32_bf16 v[40:43], v[176:179], v[188:191], 0
	v_mfma_f32_16x16x32_bf16 v[40:43], v[184:187], v[192:195], v[40:43]
	v_mfma_f32_16x16x32_bf16 v[32:35], v[168:171], v[196:199], 0
	v_mfma_f32_16x16x32_bf16 v[32:35], v[172:175], v[200:203], v[32:35]
	v_mfma_f32_16x16x32_bf16 v[24:27], v[176:179], v[196:199], 0
	v_mfma_f32_16x16x32_bf16 v[24:27], v[184:187], v[200:203], v[24:27]
	v_mfma_f32_16x16x32_bf16 v[16:19], v[168:171], v[204:207], 0
	v_mfma_f32_16x16x32_bf16 v[16:19], v[172:175], v[208:211], v[16:19]
	v_mfma_f32_16x16x32_bf16 v[8:11], v[176:179], v[204:207], 0
	v_mfma_f32_16x16x32_bf16 v[8:11], v[184:187], v[208:211], v[8:11]
	s_barrier
	v_mfma_f32_16x16x32_bf16 v[4:7], v[168:171], v[212:215], 0
	v_mfma_f32_16x16x32_bf16 v[4:7], v[172:175], v[216:219], v[4:7]
	v_mfma_f32_16x16x32_bf16 v[0:3], v[176:179], v[212:215], 0
	v_mfma_f32_16x16x32_bf16 v[0:3], v[184:187], v[216:219], v[0:3]
	s_setprio 0
	s_branch .Lmid_gemm10
.LBB0_1311:
	ds_read_b128 v[152:155], v149
	ds_read_b128 v[156:159], v149 offset:1024
	ds_read_b128 v[160:163], v149 offset:2048
	ds_read_b128 v[164:167], v149 offset:3072
	ds_read_b128 v[168:171], v150
	ds_read_b128 v[172:175], v150 offset:1024
	ds_read_b128 v[176:179], v150 offset:2048
	ds_read_b128 v[184:187], v150 offset:3072
	s_add_u32 s58, s56, 0xfffc0080
	s_addc_u32 s59, s57, -1
	s_cmp_eq_u32 s86, 12
	s_cselect_b32 s61, s49, s59
	s_cselect_b32 s60, s82, s58
	s_cselect_b32 s59, s47, s85
	s_cselect_b32 s58, s83, s84
	v_lshl_add_u64 v[144:145], s[56:57], 0, v[136:137]
	s_add_i32 m0, s55, 0xc000
	ds_read_b128 v[188:191], v151
	ds_read_b128 v[192:195], v151 offset:1024
	ds_read_b128 v[196:199], v151 offset:2048
	ds_read_b128 v[200:203], v151 offset:3072
	ds_read_b128 v[204:207], v151 offset:4096
	ds_read_b128 v[208:211], v151 offset:5120
	ds_read_b128 v[212:215], v151 offset:6144
	ds_read_b128 v[216:219], v151 offset:7168
	global_load_lds_dwordx4 v[144:145], off
	v_lshl_add_u64 v[144:145], s[56:57], 0, v[138:139]
	s_add_i32 m0, s55, 0xe000
	s_nop 0
	global_load_lds_dwordx4 v[144:145], off
	s_waitcnt vmcnt(8)
	s_waitcnt lgkmcnt(0)
	s_barrier
	s_waitcnt lgkmcnt(0)
	v_mfma_f32_16x16x32_bf16 v[124:127], v[152:155], v[188:191], v[124:127]
	v_mfma_f32_16x16x32_bf16 v[124:127], v[156:159], v[192:195], v[124:127]
	v_mfma_f32_16x16x32_bf16 v[120:123], v[160:163], v[188:191], v[120:123]
	v_mfma_f32_16x16x32_bf16 v[120:123], v[164:167], v[192:195], v[120:123]
	s_setprio 1
	v_mfma_f32_16x16x32_bf16 v[116:119], v[152:155], v[196:199], v[116:119]
	v_mfma_f32_16x16x32_bf16 v[116:119], v[156:159], v[200:203], v[116:119]
	v_mfma_f32_16x16x32_bf16 v[108:111], v[160:163], v[196:199], v[108:111]
	v_mfma_f32_16x16x32_bf16 v[108:111], v[164:167], v[200:203], v[108:111]
	v_mfma_f32_16x16x32_bf16 v[100:103], v[152:155], v[204:207], v[100:103]
	v_mfma_f32_16x16x32_bf16 v[100:103], v[156:159], v[208:211], v[100:103]
	v_mfma_f32_16x16x32_bf16 v[92:95], v[160:163], v[204:207], v[92:95]
	v_mfma_f32_16x16x32_bf16 v[92:95], v[164:167], v[208:211], v[92:95]
	v_mfma_f32_16x16x32_bf16 v[84:87], v[152:155], v[212:215], v[84:87]
	v_mfma_f32_16x16x32_bf16 v[84:87], v[156:159], v[216:219], v[84:87]
	v_mfma_f32_16x16x32_bf16 v[76:79], v[160:163], v[212:215], v[76:79]
	v_mfma_f32_16x16x32_bf16 v[76:79], v[164:167], v[216:219], v[76:79]
	v_mfma_f32_16x16x32_bf16 v[112:115], v[168:171], v[188:191], v[112:115]
	v_mfma_f32_16x16x32_bf16 v[112:115], v[172:175], v[192:195], v[112:115]
	v_mfma_f32_16x16x32_bf16 v[104:107], v[176:179], v[188:191], v[104:107]
	v_mfma_f32_16x16x32_bf16 v[104:107], v[184:187], v[192:195], v[104:107]
	v_mfma_f32_16x16x32_bf16 v[96:99], v[168:171], v[196:199], v[96:99]
	v_mfma_f32_16x16x32_bf16 v[96:99], v[172:175], v[200:203], v[96:99]
	v_mfma_f32_16x16x32_bf16 v[88:91], v[176:179], v[196:199], v[88:91]
	v_mfma_f32_16x16x32_bf16 v[88:91], v[184:187], v[200:203], v[88:91]
	v_mfma_f32_16x16x32_bf16 v[80:83], v[168:171], v[204:207], v[80:83]
	v_mfma_f32_16x16x32_bf16 v[80:83], v[172:175], v[208:211], v[80:83]
	v_mfma_f32_16x16x32_bf16 v[72:75], v[176:179], v[204:207], v[72:75]
	v_mfma_f32_16x16x32_bf16 v[72:75], v[184:187], v[208:211], v[72:75]
	s_barrier
	v_mfma_f32_16x16x32_bf16 v[68:71], v[168:171], v[212:215], v[68:71]
	v_mfma_f32_16x16x32_bf16 v[68:71], v[172:175], v[216:219], v[68:71]
	v_mfma_f32_16x16x32_bf16 v[64:67], v[176:179], v[212:215], v[64:67]
	v_mfma_f32_16x16x32_bf16 v[64:67], v[184:187], v[216:219], v[64:67]
	s_setprio 0
	s_add_i32 s79, s71, s64
	v_lshl_add_u64 v[144:145], s[58:59], 0, v[130:131]
	s_mov_b32 m0, s79
	ds_read_b128 v[188:191], v151 offset:16384
	ds_read_b128 v[192:195], v151 offset:17408
	ds_read_b128 v[196:199], v151 offset:18432
	ds_read_b128 v[200:203], v151 offset:19456
	ds_read_b128 v[204:207], v151 offset:20480
	ds_read_b128 v[208:211], v151 offset:21504
	ds_read_b128 v[212:215], v151 offset:22528
	ds_read_b128 v[216:219], v151 offset:23552
	global_load_lds_dwordx4 v[144:145], off
	s_add_i32 m0, s79, 0x2000
	s_add_u32 s88, s58, 0x40000
	v_lshl_add_u64 v[220:221], s[58:59], 0, v[134:135]
	s_addc_u32 s89, s59, 0
	s_add_i32 s79, s72, s64
	global_load_lds_dwordx4 v[220:221], off
	v_lshl_add_u64 v[222:223], s[88:89], 0, v[130:131]
	s_mov_b32 m0, s79
	v_lshl_add_u64 v[224:225], s[60:61], 0, v[132:133]
	global_load_lds_dwordx4 v[222:223], off
	v_lshl_add_u64 v[222:223], s[88:89], 0, v[134:135]
	s_add_i32 m0, s79, 0x2000
	s_nop 0
	global_load_lds_dwordx4 v[222:223], off
	v_lshl_add_u64 v[222:223], s[60:61], 0, v[128:129]
	s_mov_b32 m0, s55
	s_nop 0
	global_load_lds_dwordx4 v[222:223], off
	s_mov_b32 m0, s65
	s_nop 0
	global_load_lds_dwordx4 v[224:225], off
	s_waitcnt vmcnt(8)
	s_waitcnt lgkmcnt(0)
	s_barrier
	s_waitcnt lgkmcnt(0)
	v_mfma_f32_16x16x32_bf16 v[60:63], v[152:155], v[188:191], v[60:63]
	v_mfma_f32_16x16x32_bf16 v[60:63], v[156:159], v[192:195], v[60:63]
	v_mfma_f32_16x16x32_bf16 v[56:59], v[160:163], v[188:191], v[56:59]
	v_mfma_f32_16x16x32_bf16 v[56:59], v[164:167], v[192:195], v[56:59]
	s_setprio 1
	v_mfma_f32_16x16x32_bf16 v[52:55], v[152:155], v[196:199], v[52:55]
	v_mfma_f32_16x16x32_bf16 v[52:55], v[156:159], v[200:203], v[52:55]
	v_mfma_f32_16x16x32_bf16 v[44:47], v[160:163], v[196:199], v[44:47]
	v_mfma_f32_16x16x32_bf16 v[44:47], v[164:167], v[200:203], v[44:47]
	v_mfma_f32_16x16x32_bf16 v[36:39], v[152:155], v[204:207], v[36:39]
	v_mfma_f32_16x16x32_bf16 v[36:39], v[156:159], v[208:211], v[36:39]
	v_mfma_f32_16x16x32_bf16 v[28:31], v[160:163], v[204:207], v[28:31]
	v_mfma_f32_16x16x32_bf16 v[28:31], v[164:167], v[208:211], v[28:31]
	v_mfma_f32_16x16x32_bf16 v[20:23], v[152:155], v[212:215], v[20:23]
	v_mfma_f32_16x16x32_bf16 v[20:23], v[156:159], v[216:219], v[20:23]
	v_mfma_f32_16x16x32_bf16 v[12:15], v[160:163], v[212:215], v[12:15]
	v_mfma_f32_16x16x32_bf16 v[12:15], v[164:167], v[216:219], v[12:15]
	v_mfma_f32_16x16x32_bf16 v[48:51], v[168:171], v[188:191], v[48:51]
	v_mfma_f32_16x16x32_bf16 v[48:51], v[172:175], v[192:195], v[48:51]
	v_mfma_f32_16x16x32_bf16 v[40:43], v[176:179], v[188:191], v[40:43]
	v_mfma_f32_16x16x32_bf16 v[40:43], v[184:187], v[192:195], v[40:43]
	v_mfma_f32_16x16x32_bf16 v[32:35], v[168:171], v[196:199], v[32:35]
	v_mfma_f32_16x16x32_bf16 v[32:35], v[172:175], v[200:203], v[32:35]
	v_mfma_f32_16x16x32_bf16 v[24:27], v[176:179], v[196:199], v[24:27]
	v_mfma_f32_16x16x32_bf16 v[24:27], v[184:187], v[200:203], v[24:27]
	v_mfma_f32_16x16x32_bf16 v[16:19], v[168:171], v[204:207], v[16:19]
	v_mfma_f32_16x16x32_bf16 v[16:19], v[172:175], v[208:211], v[16:19]
	v_mfma_f32_16x16x32_bf16 v[8:11], v[176:179], v[204:207], v[8:11]
	v_mfma_f32_16x16x32_bf16 v[8:11], v[184:187], v[208:211], v[8:11]
	s_barrier
	v_mfma_f32_16x16x32_bf16 v[4:7], v[168:171], v[212:215], v[4:7]
	v_mfma_f32_16x16x32_bf16 v[4:7], v[172:175], v[216:219], v[4:7]
	v_mfma_f32_16x16x32_bf16 v[0:3], v[176:179], v[212:215], v[0:3]
	v_mfma_f32_16x16x32_bf16 v[0:3], v[184:187], v[216:219], v[0:3]
	s_setprio 0
.Lmid_gemm10:
	s_add_i32 s79, 0, 0x18000
	s_add_i32 s87, 0, 0x1c000
	v_add_u32_e32 v164, s79, v147
	v_add_u32_e32 v181, s87, v147
	ds_read_b128 v[152:155], v164
	ds_read_b128 v[156:159], v164 offset:1024
	ds_read_b128 v[160:163], v164 offset:2048
	ds_read_b128 v[164:167], v164 offset:3072
	ds_read_b128 v[168:171], v181
	ds_read_b128 v[172:175], v181 offset:1024
	ds_read_b128 v[176:179], v181 offset:2048
	ds_read_b128 v[184:187], v181 offset:3072
	s_add_u32 s60, s60, 0x40000
	s_addc_u32 s61, s61, 0
	s_mov_b32 m0, s66
	v_lshl_add_u64 v[226:227], s[60:61], 0, v[128:129]
	ds_read_b128 v[188:191], v151 offset:32768
	ds_read_b128 v[192:195], v151 offset:33792
	ds_read_b128 v[196:199], v151 offset:34816
	ds_read_b128 v[200:203], v151 offset:35840
	ds_read_b128 v[204:207], v151 offset:36864
	ds_read_b128 v[208:211], v151 offset:37888
	ds_read_b128 v[212:215], v151 offset:38912
	ds_read_b128 v[216:219], v151 offset:39936
	global_load_lds_dwordx4 v[226:227], off
	v_lshl_add_u64 v[226:227], s[60:61], 0, v[132:133]
	s_mov_b32 m0, s67
	s_nop 0
	global_load_lds_dwordx4 v[226:227], off
	s_waitcnt vmcnt(8)
	s_waitcnt lgkmcnt(0)
	s_barrier
	s_waitcnt lgkmcnt(0)
	v_mfma_f32_16x16x32_bf16 v[124:127], v[152:155], v[188:191], v[124:127]
	v_mfma_f32_16x16x32_bf16 v[124:127], v[156:159], v[192:195], v[124:127]
	v_mfma_f32_16x16x32_bf16 v[120:123], v[160:163], v[188:191], v[120:123]
	v_mfma_f32_16x16x32_bf16 v[120:123], v[164:167], v[192:195], v[120:123]
	s_setprio 1
	v_mfma_f32_16x16x32_bf16 v[116:119], v[152:155], v[196:199], v[116:119]
	v_mfma_f32_16x16x32_bf16 v[116:119], v[156:159], v[200:203], v[116:119]
	v_mfma_f32_16x16x32_bf16 v[108:111], v[160:163], v[196:199], v[108:111]
	v_mfma_f32_16x16x32_bf16 v[108:111], v[164:167], v[200:203], v[108:111]
	v_mfma_f32_16x16x32_bf16 v[100:103], v[152:155], v[204:207], v[100:103]
	v_mfma_f32_16x16x32_bf16 v[100:103], v[156:159], v[208:211], v[100:103]
	v_mfma_f32_16x16x32_bf16 v[92:95], v[160:163], v[204:207], v[92:95]
	v_mfma_f32_16x16x32_bf16 v[92:95], v[164:167], v[208:211], v[92:95]
	v_mfma_f32_16x16x32_bf16 v[84:87], v[152:155], v[212:215], v[84:87]
	v_mfma_f32_16x16x32_bf16 v[84:87], v[156:159], v[216:219], v[84:87]
	v_mfma_f32_16x16x32_bf16 v[76:79], v[160:163], v[212:215], v[76:79]
	v_mfma_f32_16x16x32_bf16 v[76:79], v[164:167], v[216:219], v[76:79]
	v_mfma_f32_16x16x32_bf16 v[112:115], v[168:171], v[188:191], v[112:115]
	v_mfma_f32_16x16x32_bf16 v[112:115], v[172:175], v[192:195], v[112:115]
	v_mfma_f32_16x16x32_bf16 v[104:107], v[176:179], v[188:191], v[104:107]
	v_mfma_f32_16x16x32_bf16 v[104:107], v[184:187], v[192:195], v[104:107]
	v_mfma_f32_16x16x32_bf16 v[96:99], v[168:171], v[196:199], v[96:99]
	v_mfma_f32_16x16x32_bf16 v[96:99], v[172:175], v[200:203], v[96:99]
	v_mfma_f32_16x16x32_bf16 v[88:91], v[176:179], v[196:199], v[88:91]
	v_mfma_f32_16x16x32_bf16 v[88:91], v[184:187], v[200:203], v[88:91]
	v_mfma_f32_16x16x32_bf16 v[80:83], v[168:171], v[204:207], v[80:83]
	v_mfma_f32_16x16x32_bf16 v[80:83], v[172:175], v[208:211], v[80:83]
	v_mfma_f32_16x16x32_bf16 v[72:75], v[176:179], v[204:207], v[72:75]
	v_mfma_f32_16x16x32_bf16 v[72:75], v[184:187], v[208:211], v[72:75]
	s_barrier
	v_mfma_f32_16x16x32_bf16 v[68:71], v[168:171], v[212:215], v[68:71]
	v_mfma_f32_16x16x32_bf16 v[68:71], v[172:175], v[216:219], v[68:71]
	v_mfma_f32_16x16x32_bf16 v[64:67], v[176:179], v[212:215], v[64:67]
	v_mfma_f32_16x16x32_bf16 v[64:67], v[184:187], v[216:219], v[64:67]
	s_setprio 0
	s_add_i32 s60, s79, s64
	v_lshl_add_u64 v[144:145], v[144:145], 0, s[16:17]
	s_mov_b32 m0, s60
	ds_read_b128 v[188:191], v151 offset:49152
	ds_read_b128 v[192:195], v151 offset:50176
	ds_read_b128 v[196:199], v151 offset:51200
	ds_read_b128 v[200:203], v151 offset:52224
	ds_read_b128 v[204:207], v151 offset:53248
	ds_read_b128 v[208:211], v151 offset:54272
	ds_read_b128 v[212:215], v151 offset:55296
	ds_read_b128 v[216:219], v151 offset:56320
	global_load_lds_dwordx4 v[144:145], off
	s_add_i32 m0, s60, 0x2000
	s_add_u32 s58, s58, 0x40080
	v_lshl_add_u64 v[144:145], v[220:221], 0, s[16:17]
	s_addc_u32 s59, s59, 0
	s_add_i32 s60, s87, s64
	global_load_lds_dwordx4 v[144:145], off
	v_lshl_add_u64 v[144:145], s[58:59], 0, v[130:131]
	s_mov_b32 m0, s60
	s_nop 0
	global_load_lds_dwordx4 v[144:145], off
	v_lshl_add_u64 v[144:145], s[58:59], 0, v[134:135]
	s_add_i32 m0, s60, 0x2000
	s_nop 0
	global_load_lds_dwordx4 v[144:145], off
	v_lshl_add_u64 v[144:145], v[222:223], 0, s[16:17]
	s_mov_b32 m0, s69
	s_nop 0
	global_load_lds_dwordx4 v[144:145], off
	v_lshl_add_u64 v[144:145], v[224:225], 0, s[16:17]
	s_mov_b32 m0, s70
	s_nop 0
	global_load_lds_dwordx4 v[144:145], off
	s_waitcnt vmcnt(8)
	s_waitcnt lgkmcnt(0)
	s_barrier
	s_waitcnt lgkmcnt(0)
	v_mfma_f32_16x16x32_bf16 v[60:63], v[152:155], v[188:191], v[60:63]
	v_mfma_f32_16x16x32_bf16 v[60:63], v[156:159], v[192:195], v[60:63]
	v_mfma_f32_16x16x32_bf16 v[56:59], v[160:163], v[188:191], v[56:59]
	v_mfma_f32_16x16x32_bf16 v[56:59], v[164:167], v[192:195], v[56:59]
	s_setprio 1
	v_mfma_f32_16x16x32_bf16 v[52:55], v[152:155], v[196:199], v[52:55]
	v_mfma_f32_16x16x32_bf16 v[52:55], v[156:159], v[200:203], v[52:55]
	v_mfma_f32_16x16x32_bf16 v[44:47], v[160:163], v[196:199], v[44:47]
	v_mfma_f32_16x16x32_bf16 v[44:47], v[164:167], v[200:203], v[44:47]
	v_mfma_f32_16x16x32_bf16 v[36:39], v[152:155], v[204:207], v[36:39]
	v_mfma_f32_16x16x32_bf16 v[36:39], v[156:159], v[208:211], v[36:39]
	v_mfma_f32_16x16x32_bf16 v[28:31], v[160:163], v[204:207], v[28:31]
	v_mfma_f32_16x16x32_bf16 v[28:31], v[164:167], v[208:211], v[28:31]
	v_mfma_f32_16x16x32_bf16 v[20:23], v[152:155], v[212:215], v[20:23]
	v_mfma_f32_16x16x32_bf16 v[20:23], v[156:159], v[216:219], v[20:23]
	v_mfma_f32_16x16x32_bf16 v[12:15], v[160:163], v[212:215], v[12:15]
	v_mfma_f32_16x16x32_bf16 v[12:15], v[164:167], v[216:219], v[12:15]
	v_mfma_f32_16x16x32_bf16 v[48:51], v[168:171], v[188:191], v[48:51]
	v_mfma_f32_16x16x32_bf16 v[48:51], v[172:175], v[192:195], v[48:51]
	v_mfma_f32_16x16x32_bf16 v[40:43], v[176:179], v[188:191], v[40:43]
	v_mfma_f32_16x16x32_bf16 v[40:43], v[184:187], v[192:195], v[40:43]
	v_mfma_f32_16x16x32_bf16 v[32:35], v[168:171], v[196:199], v[32:35]
	v_mfma_f32_16x16x32_bf16 v[32:35], v[172:175], v[200:203], v[32:35]
	v_mfma_f32_16x16x32_bf16 v[24:27], v[176:179], v[196:199], v[24:27]
	v_mfma_f32_16x16x32_bf16 v[24:27], v[184:187], v[200:203], v[24:27]
	v_mfma_f32_16x16x32_bf16 v[16:19], v[168:171], v[204:207], v[16:19]
	v_mfma_f32_16x16x32_bf16 v[16:19], v[172:175], v[208:211], v[16:19]
	v_mfma_f32_16x16x32_bf16 v[8:11], v[176:179], v[204:207], v[8:11]
	v_mfma_f32_16x16x32_bf16 v[8:11], v[184:187], v[208:211], v[8:11]
	s_barrier
	v_mfma_f32_16x16x32_bf16 v[4:7], v[168:171], v[212:215], v[4:7]
	v_mfma_f32_16x16x32_bf16 v[4:7], v[172:175], v[216:219], v[4:7]
	v_mfma_f32_16x16x32_bf16 v[0:3], v[176:179], v[212:215], v[0:3]
	v_mfma_f32_16x16x32_bf16 v[0:3], v[184:187], v[216:219], v[0:3]
	s_setprio 0
	s_add_i32 s86, s86, 2
	s_add_u32 s56, s56, 0x100
	s_addc_u32 s57, s57, 0
	s_add_u32 s84, s84, 0x100
	s_addc_u32 s85, s85, 0
	s_cmp_gt_u32 s86, 13
	s_cbranch_scc0 .LBB0_1311
	s_and_b64 vcc, exec, s[18:19]
	s_cbranch_vccz .LBB0_1314
	s_barrier

.LBB0_1433:
	s_ashr_i32 s19, s18, 31
	s_lshl_b64 s[30:31], s[18:19], 19
	s_add_u32 s30, s80, s30
	s_addc_u32 s31, s81, s31
	s_and_b64 s[36:37], s[8:9], exec
	s_cselect_b32 s19, s31, s47
	s_cselect_b32 s66, s30, s46
	s_ashr_i32 s17, s16, 31
	s_lshl_b64 s[36:37], s[16:17], 19
	s_add_u32 s36, s52, s36
	s_addc_u32 s37, s53, s37
	s_and_b64 s[50:51], s[8:9], exec
	s_cselect_b32 s17, s37, s49
	s_cselect_b32 s67, s36, s48
	s_add_u32 s46, s46, 0x40080
	s_addc_u32 s47, s47, 0
	s_add_u32 s68, s48, 0x100
	s_addc_u32 s69, s49, 0
	s_mov_b32 s70, -2
	ds_read_b128 v[140:143], v147
	ds_read_b128 v[150:153], v147 offset:1024
	ds_read_b128 v[154:157], v147 offset:2048
	ds_read_b128 v[158:161], v147 offset:3072
	ds_read_b128 v[162:165], v148
	ds_read_b128 v[166:169], v148 offset:1024
	ds_read_b128 v[170:173], v148 offset:2048
	ds_read_b128 v[174:177], v148 offset:3072
	s_add_u32 s48, s46, 0xfffc0080
	s_addc_u32 s49, s47, -1
	s_cmp_eq_u32 s70, 12
	s_cselect_b32 s51, s19, s49
	s_cselect_b32 s50, s66, s48
	s_cselect_b32 s49, s17, s69
	s_cselect_b32 s48, s67, s68
	v_lshl_add_u64 v[178:179], s[46:47], 0, v[132:133]
	s_add_i32 m0, s45, 0xc000
	ds_read_b128 v[184:187], v149
	ds_read_b128 v[188:191], v149 offset:1024
	ds_read_b128 v[192:195], v149 offset:2048
	ds_read_b128 v[196:199], v149 offset:3072
	ds_read_b128 v[200:203], v149 offset:4096
	ds_read_b128 v[204:207], v149 offset:5120
	ds_read_b128 v[208:211], v149 offset:6144
	ds_read_b128 v[212:215], v149 offset:7168
	global_load_lds_dwordx4 v[178:179], off
	v_lshl_add_u64 v[178:179], s[46:47], 0, v[134:135]
	s_add_i32 m0, s45, 0xe000
	s_nop 0
	global_load_lds_dwordx4 v[178:179], off
	s_waitcnt vmcnt(8)
	s_waitcnt lgkmcnt(0)
	s_barrier
	s_waitcnt lgkmcnt(0)
	v_mfma_f32_16x16x32_bf16 v[124:127], v[140:143], v[184:187], 0
	v_mfma_f32_16x16x32_bf16 v[124:127], v[150:153], v[188:191], v[124:127]
	v_mfma_f32_16x16x32_bf16 v[120:123], v[154:157], v[184:187], 0
	v_mfma_f32_16x16x32_bf16 v[120:123], v[158:161], v[188:191], v[120:123]
	s_setprio 1
	v_mfma_f32_16x16x32_bf16 v[108:111], v[140:143], v[192:195], 0
	v_mfma_f32_16x16x32_bf16 v[108:111], v[150:153], v[196:199], v[108:111]
	v_mfma_f32_16x16x32_bf16 v[104:107], v[154:157], v[192:195], 0
	v_mfma_f32_16x16x32_bf16 v[104:107], v[158:161], v[196:199], v[104:107]
	v_mfma_f32_16x16x32_bf16 v[92:95], v[140:143], v[200:203], 0
	v_mfma_f32_16x16x32_bf16 v[92:95], v[150:153], v[204:207], v[92:95]
	v_mfma_f32_16x16x32_bf16 v[88:91], v[154:157], v[200:203], 0
	v_mfma_f32_16x16x32_bf16 v[88:91], v[158:161], v[204:207], v[88:91]
	v_mfma_f32_16x16x32_bf16 v[76:79], v[140:143], v[208:211], 0
	v_mfma_f32_16x16x32_bf16 v[76:79], v[150:153], v[212:215], v[76:79]
	v_mfma_f32_16x16x32_bf16 v[72:75], v[154:157], v[208:211], 0
	v_mfma_f32_16x16x32_bf16 v[72:75], v[158:161], v[212:215], v[72:75]
	v_mfma_f32_16x16x32_bf16 v[116:119], v[162:165], v[184:187], 0
	v_mfma_f32_16x16x32_bf16 v[116:119], v[166:169], v[188:191], v[116:119]
	v_mfma_f32_16x16x32_bf16 v[112:115], v[170:173], v[184:187], 0
	v_mfma_f32_16x16x32_bf16 v[112:115], v[174:177], v[188:191], v[112:115]
	v_mfma_f32_16x16x32_bf16 v[100:103], v[162:165], v[192:195], 0
	v_mfma_f32_16x16x32_bf16 v[100:103], v[166:169], v[196:199], v[100:103]
	v_mfma_f32_16x16x32_bf16 v[96:99], v[170:173], v[192:195], 0
	v_mfma_f32_16x16x32_bf16 v[96:99], v[174:177], v[196:199], v[96:99]
	v_mfma_f32_16x16x32_bf16 v[84:87], v[162:165], v[200:203], 0
	v_mfma_f32_16x16x32_bf16 v[84:87], v[166:169], v[204:207], v[84:87]
	v_mfma_f32_16x16x32_bf16 v[80:83], v[170:173], v[200:203], 0
	v_mfma_f32_16x16x32_bf16 v[80:83], v[174:177], v[204:207], v[80:83]
	s_barrier
	v_mfma_f32_16x16x32_bf16 v[68:71], v[162:165], v[208:211], 0
	v_mfma_f32_16x16x32_bf16 v[68:71], v[166:169], v[212:215], v[68:71]
	v_mfma_f32_16x16x32_bf16 v[64:67], v[170:173], v[208:211], 0
	v_mfma_f32_16x16x32_bf16 v[64:67], v[174:177], v[212:215], v[64:67]
	s_setprio 0
	s_add_i32 s71, s62, s54
	v_lshl_add_u64 v[178:179], s[48:49], 0, v[130:131]
	s_mov_b32 m0, s71
	ds_read_b128 v[184:187], v149 offset:16384
	ds_read_b128 v[188:191], v149 offset:17408
	ds_read_b128 v[192:195], v149 offset:18432
	ds_read_b128 v[196:199], v149 offset:19456
	ds_read_b128 v[200:203], v149 offset:20480
	ds_read_b128 v[204:207], v149 offset:21504
	ds_read_b128 v[208:211], v149 offset:22528
	ds_read_b128 v[212:215], v149 offset:23552
	global_load_lds_dwordx4 v[178:179], off
	s_add_i32 m0, s71, 0x2000
	s_add_u32 s72, s48, 0x40000
	v_lshl_add_u64 v[216:217], s[48:49], 0, v[128:129]
	s_addc_u32 s73, s49, 0
	s_add_i32 s71, s63, s54
	global_load_lds_dwordx4 v[216:217], off
	v_lshl_add_u64 v[218:219], s[72:73], 0, v[130:131]
	s_mov_b32 m0, s71
	v_lshl_add_u64 v[220:221], s[50:51], 0, v[128:129]
	global_load_lds_dwordx4 v[218:219], off
	v_lshl_add_u64 v[218:219], s[72:73], 0, v[128:129]
	s_add_i32 m0, s71, 0x2000
	s_nop 0
	global_load_lds_dwordx4 v[218:219], off
	v_lshl_add_u64 v[218:219], s[50:51], 0, v[130:131]
	s_mov_b32 m0, s45
	s_nop 0
	global_load_lds_dwordx4 v[218:219], off
	s_mov_b32 m0, s56
	s_nop 0
	global_load_lds_dwordx4 v[220:221], off
	s_waitcnt vmcnt(8)
	s_waitcnt lgkmcnt(0)
	s_barrier
	s_waitcnt lgkmcnt(0)
	v_mfma_f32_16x16x32_bf16 v[60:63], v[140:143], v[184:187], 0
	v_mfma_f32_16x16x32_bf16 v[60:63], v[150:153], v[188:191], v[60:63]
	v_mfma_f32_16x16x32_bf16 v[56:59], v[154:157], v[184:187], 0
	v_mfma_f32_16x16x32_bf16 v[56:59], v[158:161], v[188:191], v[56:59]
	s_setprio 1
	v_mfma_f32_16x16x32_bf16 v[44:47], v[140:143], v[192:195], 0
	v_mfma_f32_16x16x32_bf16 v[44:47], v[150:153], v[196:199], v[44:47]
	v_mfma_f32_16x16x32_bf16 v[40:43], v[154:157], v[192:195], 0
	v_mfma_f32_16x16x32_bf16 v[40:43], v[158:161], v[196:199], v[40:43]
	v_mfma_f32_16x16x32_bf16 v[28:31], v[140:143], v[200:203], 0
	v_mfma_f32_16x16x32_bf16 v[28:31], v[150:153], v[204:207], v[28:31]
	v_mfma_f32_16x16x32_bf16 v[24:27], v[154:157], v[200:203], 0
	v_mfma_f32_16x16x32_bf16 v[24:27], v[158:161], v[204:207], v[24:27]
	v_mfma_f32_16x16x32_bf16 v[12:15], v[140:143], v[208:211], 0
	v_mfma_f32_16x16x32_bf16 v[12:15], v[150:153], v[212:215], v[12:15]
	v_mfma_f32_16x16x32_bf16 v[8:11], v[154:157], v[208:211], 0
	v_mfma_f32_16x16x32_bf16 v[8:11], v[158:161], v[212:215], v[8:11]
	v_mfma_f32_16x16x32_bf16 v[52:55], v[162:165], v[184:187], 0
	v_mfma_f32_16x16x32_bf16 v[52:55], v[166:169], v[188:191], v[52:55]
	v_mfma_f32_16x16x32_bf16 v[48:51], v[170:173], v[184:187], 0
	v_mfma_f32_16x16x32_bf16 v[48:51], v[174:177], v[188:191], v[48:51]
	v_mfma_f32_16x16x32_bf16 v[36:39], v[162:165], v[192:195], 0
	v_mfma_f32_16x16x32_bf16 v[36:39], v[166:169], v[196:199], v[36:39]
	v_mfma_f32_16x16x32_bf16 v[32:35], v[170:173], v[192:195], 0
	v_mfma_f32_16x16x32_bf16 v[32:35], v[174:177], v[196:199], v[32:35]
	v_mfma_f32_16x16x32_bf16 v[20:23], v[162:165], v[200:203], 0
	v_mfma_f32_16x16x32_bf16 v[20:23], v[166:169], v[204:207], v[20:23]
	v_mfma_f32_16x16x32_bf16 v[16:19], v[170:173], v[200:203], 0
	v_mfma_f32_16x16x32_bf16 v[16:19], v[174:177], v[204:207], v[16:19]
	s_barrier
	v_mfma_f32_16x16x32_bf16 v[4:7], v[162:165], v[208:211], 0
	v_mfma_f32_16x16x32_bf16 v[4:7], v[166:169], v[212:215], v[4:7]
	v_mfma_f32_16x16x32_bf16 v[0:3], v[170:173], v[208:211], 0
	v_mfma_f32_16x16x32_bf16 v[0:3], v[174:177], v[212:215], v[0:3]
	s_setprio 0
	s_branch .Lmid_gemm11
.LBB0_1434:
	ds_read_b128 v[140:143], v147
	ds_read_b128 v[150:153], v147 offset:1024
	ds_read_b128 v[154:157], v147 offset:2048
	ds_read_b128 v[158:161], v147 offset:3072
	ds_read_b128 v[162:165], v148
	ds_read_b128 v[166:169], v148 offset:1024
	ds_read_b128 v[170:173], v148 offset:2048
	ds_read_b128 v[174:177], v148 offset:3072
	s_add_u32 s48, s46, 0xfffc0080
	s_addc_u32 s49, s47, -1
	s_cmp_eq_u32 s70, 12
	s_cselect_b32 s51, s19, s49
	s_cselect_b32 s50, s66, s48
	s_cselect_b32 s49, s17, s69
	s_cselect_b32 s48, s67, s68
	v_lshl_add_u64 v[178:179], s[46:47], 0, v[132:133]
	s_add_i32 m0, s45, 0xc000
	ds_read_b128 v[184:187], v149
	ds_read_b128 v[188:191], v149 offset:1024
	ds_read_b128 v[192:195], v149 offset:2048
	ds_read_b128 v[196:199], v149 offset:3072
	ds_read_b128 v[200:203], v149 offset:4096
	ds_read_b128 v[204:207], v149 offset:5120
	ds_read_b128 v[208:211], v149 offset:6144
	ds_read_b128 v[212:215], v149 offset:7168
	global_load_lds_dwordx4 v[178:179], off
	v_lshl_add_u64 v[178:179], s[46:47], 0, v[134:135]
	s_add_i32 m0, s45, 0xe000
	s_nop 0
	global_load_lds_dwordx4 v[178:179], off
	s_waitcnt vmcnt(8)
	s_waitcnt lgkmcnt(0)
	s_barrier
	s_waitcnt lgkmcnt(0)
	v_mfma_f32_16x16x32_bf16 v[124:127], v[140:143], v[184:187], v[124:127]
	v_mfma_f32_16x16x32_bf16 v[124:127], v[150:153], v[188:191], v[124:127]
	v_mfma_f32_16x16x32_bf16 v[120:123], v[154:157], v[184:187], v[120:123]
	v_mfma_f32_16x16x32_bf16 v[120:123], v[158:161], v[188:191], v[120:123]
	s_setprio 1
	v_mfma_f32_16x16x32_bf16 v[108:111], v[140:143], v[192:195], v[108:111]
	v_mfma_f32_16x16x32_bf16 v[108:111], v[150:153], v[196:199], v[108:111]
	v_mfma_f32_16x16x32_bf16 v[104:107], v[154:157], v[192:195], v[104:107]
	v_mfma_f32_16x16x32_bf16 v[104:107], v[158:161], v[196:199], v[104:107]
	v_mfma_f32_16x16x32_bf16 v[92:95], v[140:143], v[200:203], v[92:95]
	v_mfma_f32_16x16x32_bf16 v[92:95], v[150:153], v[204:207], v[92:95]
	v_mfma_f32_16x16x32_bf16 v[88:91], v[154:157], v[200:203], v[88:91]
	v_mfma_f32_16x16x32_bf16 v[88:91], v[158:161], v[204:207], v[88:91]
	v_mfma_f32_16x16x32_bf16 v[76:79], v[140:143], v[208:211], v[76:79]
	v_mfma_f32_16x16x32_bf16 v[76:79], v[150:153], v[212:215], v[76:79]
	v_mfma_f32_16x16x32_bf16 v[72:75], v[154:157], v[208:211], v[72:75]
	v_mfma_f32_16x16x32_bf16 v[72:75], v[158:161], v[212:215], v[72:75]
	v_mfma_f32_16x16x32_bf16 v[116:119], v[162:165], v[184:187], v[116:119]
	v_mfma_f32_16x16x32_bf16 v[116:119], v[166:169], v[188:191], v[116:119]
	v_mfma_f32_16x16x32_bf16 v[112:115], v[170:173], v[184:187], v[112:115]
	v_mfma_f32_16x16x32_bf16 v[112:115], v[174:177], v[188:191], v[112:115]
	v_mfma_f32_16x16x32_bf16 v[100:103], v[162:165], v[192:195], v[100:103]
	v_mfma_f32_16x16x32_bf16 v[100:103], v[166:169], v[196:199], v[100:103]
	v_mfma_f32_16x16x32_bf16 v[96:99], v[170:173], v[192:195], v[96:99]
	v_mfma_f32_16x16x32_bf16 v[96:99], v[174:177], v[196:199], v[96:99]
	v_mfma_f32_16x16x32_bf16 v[84:87], v[162:165], v[200:203], v[84:87]
	v_mfma_f32_16x16x32_bf16 v[84:87], v[166:169], v[204:207], v[84:87]
	v_mfma_f32_16x16x32_bf16 v[80:83], v[170:173], v[200:203], v[80:83]
	v_mfma_f32_16x16x32_bf16 v[80:83], v[174:177], v[204:207], v[80:83]
	s_barrier
	v_mfma_f32_16x16x32_bf16 v[68:71], v[162:165], v[208:211], v[68:71]
	v_mfma_f32_16x16x32_bf16 v[68:71], v[166:169], v[212:215], v[68:71]
	v_mfma_f32_16x16x32_bf16 v[64:67], v[170:173], v[208:211], v[64:67]
	v_mfma_f32_16x16x32_bf16 v[64:67], v[174:177], v[212:215], v[64:67]
	s_setprio 0
	s_add_i32 s71, s62, s54
	v_lshl_add_u64 v[178:179], s[48:49], 0, v[130:131]
	s_mov_b32 m0, s71
	ds_read_b128 v[184:187], v149 offset:16384
	ds_read_b128 v[188:191], v149 offset:17408
	ds_read_b128 v[192:195], v149 offset:18432
	ds_read_b128 v[196:199], v149 offset:19456
	ds_read_b128 v[200:203], v149 offset:20480
	ds_read_b128 v[204:207], v149 offset:21504
	ds_read_b128 v[208:211], v149 offset:22528
	ds_read_b128 v[212:215], v149 offset:23552
	global_load_lds_dwordx4 v[178:179], off
	s_add_i32 m0, s71, 0x2000
	s_add_u32 s72, s48, 0x40000
	v_lshl_add_u64 v[216:217], s[48:49], 0, v[128:129]
	s_addc_u32 s73, s49, 0
	s_add_i32 s71, s63, s54
	global_load_lds_dwordx4 v[216:217], off
	v_lshl_add_u64 v[218:219], s[72:73], 0, v[130:131]
	s_mov_b32 m0, s71
	v_lshl_add_u64 v[220:221], s[50:51], 0, v[128:129]
	global_load_lds_dwordx4 v[218:219], off
	v_lshl_add_u64 v[218:219], s[72:73], 0, v[128:129]
	s_add_i32 m0, s71, 0x2000
	s_nop 0
	global_load_lds_dwordx4 v[218:219], off
	v_lshl_add_u64 v[218:219], s[50:51], 0, v[130:131]
	s_mov_b32 m0, s45
	s_nop 0
	global_load_lds_dwordx4 v[218:219], off
	s_mov_b32 m0, s56
	s_nop 0
	global_load_lds_dwordx4 v[220:221], off
	s_waitcnt vmcnt(8)
	s_waitcnt lgkmcnt(0)
	s_barrier
	s_waitcnt lgkmcnt(0)
	v_mfma_f32_16x16x32_bf16 v[60:63], v[140:143], v[184:187], v[60:63]
	v_mfma_f32_16x16x32_bf16 v[60:63], v[150:153], v[188:191], v[60:63]
	v_mfma_f32_16x16x32_bf16 v[56:59], v[154:157], v[184:187], v[56:59]
	v_mfma_f32_16x16x32_bf16 v[56:59], v[158:161], v[188:191], v[56:59]
	s_setprio 1
	v_mfma_f32_16x16x32_bf16 v[44:47], v[140:143], v[192:195], v[44:47]
	v_mfma_f32_16x16x32_bf16 v[44:47], v[150:153], v[196:199], v[44:47]
	v_mfma_f32_16x16x32_bf16 v[40:43], v[154:157], v[192:195], v[40:43]
	v_mfma_f32_16x16x32_bf16 v[40:43], v[158:161], v[196:199], v[40:43]
	v_mfma_f32_16x16x32_bf16 v[28:31], v[140:143], v[200:203], v[28:31]
	v_mfma_f32_16x16x32_bf16 v[28:31], v[150:153], v[204:207], v[28:31]
	v_mfma_f32_16x16x32_bf16 v[24:27], v[154:157], v[200:203], v[24:27]
	v_mfma_f32_16x16x32_bf16 v[24:27], v[158:161], v[204:207], v[24:27]
	v_mfma_f32_16x16x32_bf16 v[12:15], v[140:143], v[208:211], v[12:15]
	v_mfma_f32_16x16x32_bf16 v[12:15], v[150:153], v[212:215], v[12:15]
	v_mfma_f32_16x16x32_bf16 v[8:11], v[154:157], v[208:211], v[8:11]
	v_mfma_f32_16x16x32_bf16 v[8:11], v[158:161], v[212:215], v[8:11]
	v_mfma_f32_16x16x32_bf16 v[52:55], v[162:165], v[184:187], v[52:55]
	v_mfma_f32_16x16x32_bf16 v[52:55], v[166:169], v[188:191], v[52:55]
	v_mfma_f32_16x16x32_bf16 v[48:51], v[170:173], v[184:187], v[48:51]
	v_mfma_f32_16x16x32_bf16 v[48:51], v[174:177], v[188:191], v[48:51]
	v_mfma_f32_16x16x32_bf16 v[36:39], v[162:165], v[192:195], v[36:39]
	v_mfma_f32_16x16x32_bf16 v[36:39], v[166:169], v[196:199], v[36:39]
	v_mfma_f32_16x16x32_bf16 v[32:35], v[170:173], v[192:195], v[32:35]
	v_mfma_f32_16x16x32_bf16 v[32:35], v[174:177], v[196:199], v[32:35]
	v_mfma_f32_16x16x32_bf16 v[20:23], v[162:165], v[200:203], v[20:23]
	v_mfma_f32_16x16x32_bf16 v[20:23], v[166:169], v[204:207], v[20:23]
	v_mfma_f32_16x16x32_bf16 v[16:19], v[170:173], v[200:203], v[16:19]
	v_mfma_f32_16x16x32_bf16 v[16:19], v[174:177], v[204:207], v[16:19]
	s_barrier
	v_mfma_f32_16x16x32_bf16 v[4:7], v[162:165], v[208:211], v[4:7]
	v_mfma_f32_16x16x32_bf16 v[4:7], v[166:169], v[212:215], v[4:7]
	v_mfma_f32_16x16x32_bf16 v[0:3], v[170:173], v[208:211], v[0:3]
	v_mfma_f32_16x16x32_bf16 v[0:3], v[174:177], v[212:215], v[0:3]
	s_setprio 0
.Lmid_gemm11:
	s_add_i32 s71, 0, 0x18000
	s_add_i32 s72, 0, 0x1c000
	v_add_u32_e32 v158, s71, v145
	v_add_u32_e32 v174, s72, v145
	ds_read_b128 v[140:143], v158
	ds_read_b128 v[150:153], v158 offset:1024
	ds_read_b128 v[154:157], v158 offset:2048
	ds_read_b128 v[158:161], v158 offset:3072
	ds_read_b128 v[162:165], v174
	ds_read_b128 v[166:169], v174 offset:1024
	ds_read_b128 v[170:173], v174 offset:2048
	ds_read_b128 v[174:177], v174 offset:3072
	s_add_u32 s50, s50, 0x40000
	s_addc_u32 s51, s51, 0
	s_mov_b32 m0, s57
	v_lshl_add_u64 v[222:223], s[50:51], 0, v[130:131]
	ds_read_b128 v[184:187], v149 offset:32768
	ds_read_b128 v[188:191], v149 offset:33792
	ds_read_b128 v[192:195], v149 offset:34816
	ds_read_b128 v[196:199], v149 offset:35840
	ds_read_b128 v[200:203], v149 offset:36864
	ds_read_b128 v[204:207], v149 offset:37888
	ds_read_b128 v[208:211], v149 offset:38912
	ds_read_b128 v[212:215], v149 offset:39936
	global_load_lds_dwordx4 v[222:223], off
	v_lshl_add_u64 v[222:223], s[50:51], 0, v[128:129]
	s_mov_b32 m0, s58
	s_nop 0
	global_load_lds_dwordx4 v[222:223], off
	s_waitcnt vmcnt(8)
	s_waitcnt lgkmcnt(0)
	s_barrier
	s_waitcnt lgkmcnt(0)
	v_mfma_f32_16x16x32_bf16 v[124:127], v[140:143], v[184:187], v[124:127]
	v_mfma_f32_16x16x32_bf16 v[124:127], v[150:153], v[188:191], v[124:127]
	v_mfma_f32_16x16x32_bf16 v[120:123], v[154:157], v[184:187], v[120:123]
	v_mfma_f32_16x16x32_bf16 v[120:123], v[158:161], v[188:191], v[120:123]
	s_setprio 1
	v_mfma_f32_16x16x32_bf16 v[108:111], v[140:143], v[192:195], v[108:111]
	v_mfma_f32_16x16x32_bf16 v[108:111], v[150:153], v[196:199], v[108:111]
	v_mfma_f32_16x16x32_bf16 v[104:107], v[154:157], v[192:195], v[104:107]
	v_mfma_f32_16x16x32_bf16 v[104:107], v[158:161], v[196:199], v[104:107]
	v_mfma_f32_16x16x32_bf16 v[92:95], v[140:143], v[200:203], v[92:95]
	v_mfma_f32_16x16x32_bf16 v[92:95], v[150:153], v[204:207], v[92:95]
	v_mfma_f32_16x16x32_bf16 v[88:91], v[154:157], v[200:203], v[88:91]
	v_mfma_f32_16x16x32_bf16 v[88:91], v[158:161], v[204:207], v[88:91]
	v_mfma_f32_16x16x32_bf16 v[76:79], v[140:143], v[208:211], v[76:79]
	v_mfma_f32_16x16x32_bf16 v[76:79], v[150:153], v[212:215], v[76:79]
	v_mfma_f32_16x16x32_bf16 v[72:75], v[154:157], v[208:211], v[72:75]
	v_mfma_f32_16x16x32_bf16 v[72:75], v[158:161], v[212:215], v[72:75]
	v_mfma_f32_16x16x32_bf16 v[116:119], v[162:165], v[184:187], v[116:119]
	v_mfma_f32_16x16x32_bf16 v[116:119], v[166:169], v[188:191], v[116:119]
	v_mfma_f32_16x16x32_bf16 v[112:115], v[170:173], v[184:187], v[112:115]
	v_mfma_f32_16x16x32_bf16 v[112:115], v[174:177], v[188:191], v[112:115]
	v_mfma_f32_16x16x32_bf16 v[100:103], v[162:165], v[192:195], v[100:103]
	v_mfma_f32_16x16x32_bf16 v[100:103], v[166:169], v[196:199], v[100:103]
	v_mfma_f32_16x16x32_bf16 v[96:99], v[170:173], v[192:195], v[96:99]
	v_mfma_f32_16x16x32_bf16 v[96:99], v[174:177], v[196:199], v[96:99]
	v_mfma_f32_16x16x32_bf16 v[84:87], v[162:165], v[200:203], v[84:87]
	v_mfma_f32_16x16x32_bf16 v[84:87], v[166:169], v[204:207], v[84:87]
	v_mfma_f32_16x16x32_bf16 v[80:83], v[170:173], v[200:203], v[80:83]
	v_mfma_f32_16x16x32_bf16 v[80:83], v[174:177], v[204:207], v[80:83]
	s_barrier
	v_mfma_f32_16x16x32_bf16 v[68:71], v[162:165], v[208:211], v[68:71]
	v_mfma_f32_16x16x32_bf16 v[68:71], v[166:169], v[212:215], v[68:71]
	v_mfma_f32_16x16x32_bf16 v[64:67], v[170:173], v[208:211], v[64:67]
	v_mfma_f32_16x16x32_bf16 v[64:67], v[174:177], v[212:215], v[64:67]
	s_setprio 0
	s_add_i32 s50, s71, s54
	v_lshl_add_u64 v[178:179], v[178:179], 0, s[10:11]
	s_mov_b32 m0, s50
	ds_read_b128 v[184:187], v149 offset:49152
	ds_read_b128 v[188:191], v149 offset:50176
	ds_read_b128 v[192:195], v149 offset:51200
	ds_read_b128 v[196:199], v149 offset:52224
	ds_read_b128 v[200:203], v149 offset:53248
	ds_read_b128 v[204:207], v149 offset:54272
	ds_read_b128 v[208:211], v149 offset:55296
	ds_read_b128 v[212:215], v149 offset:56320
	global_load_lds_dwordx4 v[178:179], off
	s_add_i32 m0, s50, 0x2000
	s_add_u32 s48, s48, 0x40080
	v_lshl_add_u64 v[178:179], v[216:217], 0, s[10:11]
	s_addc_u32 s49, s49, 0
	s_add_i32 s50, s72, s54
	global_load_lds_dwordx4 v[178:179], off
	v_lshl_add_u64 v[178:179], s[48:49], 0, v[130:131]
	s_mov_b32 m0, s50
	s_nop 0
	global_load_lds_dwordx4 v[178:179], off
	v_lshl_add_u64 v[178:179], s[48:49], 0, v[128:129]
	s_add_i32 m0, s50, 0x2000
	s_nop 0
	global_load_lds_dwordx4 v[178:179], off
	v_lshl_add_u64 v[178:179], v[218:219], 0, s[10:11]
	s_mov_b32 m0, s60
	s_nop 0
	global_load_lds_dwordx4 v[178:179], off
	v_lshl_add_u64 v[178:179], v[220:221], 0, s[10:11]
	s_mov_b32 m0, s61
	s_nop 0
	global_load_lds_dwordx4 v[178:179], off
	s_waitcnt vmcnt(8)
	s_waitcnt lgkmcnt(0)
	s_barrier
	s_waitcnt lgkmcnt(0)
	v_mfma_f32_16x16x32_bf16 v[60:63], v[140:143], v[184:187], v[60:63]
	v_mfma_f32_16x16x32_bf16 v[60:63], v[150:153], v[188:191], v[60:63]
	v_mfma_f32_16x16x32_bf16 v[56:59], v[154:157], v[184:187], v[56:59]
	v_mfma_f32_16x16x32_bf16 v[56:59], v[158:161], v[188:191], v[56:59]
	s_setprio 1
	v_mfma_f32_16x16x32_bf16 v[44:47], v[140:143], v[192:195], v[44:47]
	v_mfma_f32_16x16x32_bf16 v[44:47], v[150:153], v[196:199], v[44:47]
	v_mfma_f32_16x16x32_bf16 v[40:43], v[154:157], v[192:195], v[40:43]
	v_mfma_f32_16x16x32_bf16 v[40:43], v[158:161], v[196:199], v[40:43]
	v_mfma_f32_16x16x32_bf16 v[28:31], v[140:143], v[200:203], v[28:31]
	v_mfma_f32_16x16x32_bf16 v[28:31], v[150:153], v[204:207], v[28:31]
	v_mfma_f32_16x16x32_bf16 v[24:27], v[154:157], v[200:203], v[24:27]
	v_mfma_f32_16x16x32_bf16 v[24:27], v[158:161], v[204:207], v[24:27]
	v_mfma_f32_16x16x32_bf16 v[12:15], v[140:143], v[208:211], v[12:15]
	v_mfma_f32_16x16x32_bf16 v[12:15], v[150:153], v[212:215], v[12:15]
	v_mfma_f32_16x16x32_bf16 v[8:11], v[154:157], v[208:211], v[8:11]
	v_mfma_f32_16x16x32_bf16 v[8:11], v[158:161], v[212:215], v[8:11]
	v_mfma_f32_16x16x32_bf16 v[52:55], v[162:165], v[184:187], v[52:55]
	v_mfma_f32_16x16x32_bf16 v[52:55], v[166:169], v[188:191], v[52:55]
	v_mfma_f32_16x16x32_bf16 v[48:51], v[170:173], v[184:187], v[48:51]
	v_mfma_f32_16x16x32_bf16 v[48:51], v[174:177], v[188:191], v[48:51]
	v_mfma_f32_16x16x32_bf16 v[36:39], v[162:165], v[192:195], v[36:39]
	v_mfma_f32_16x16x32_bf16 v[36:39], v[166:169], v[196:199], v[36:39]
	v_mfma_f32_16x16x32_bf16 v[32:35], v[170:173], v[192:195], v[32:35]
	v_mfma_f32_16x16x32_bf16 v[32:35], v[174:177], v[196:199], v[32:35]
	v_mfma_f32_16x16x32_bf16 v[20:23], v[162:165], v[200:203], v[20:23]
	v_mfma_f32_16x16x32_bf16 v[20:23], v[166:169], v[204:207], v[20:23]
	v_mfma_f32_16x16x32_bf16 v[16:19], v[170:173], v[200:203], v[16:19]
	v_mfma_f32_16x16x32_bf16 v[16:19], v[174:177], v[204:207], v[16:19]
	s_barrier
	v_mfma_f32_16x16x32_bf16 v[4:7], v[162:165], v[208:211], v[4:7]
	v_mfma_f32_16x16x32_bf16 v[4:7], v[166:169], v[212:215], v[4:7]
	v_mfma_f32_16x16x32_bf16 v[0:3], v[170:173], v[208:211], v[0:3]
	v_mfma_f32_16x16x32_bf16 v[0:3], v[174:177], v[212:215], v[0:3]
	s_setprio 0
	s_add_i32 s70, s70, 2
	s_add_u32 s46, s46, 0x100
	s_addc_u32 s47, s47, 0
	s_add_u32 s68, s68, 0x100
	s_addc_u32 s69, s69, 0
	s_cmp_gt_u32 s70, 13
	s_cbranch_scc0 .LBB0_1434
	s_and_b64 vcc, exec, s[12:13]
	s_cbranch_vccz .LBB0_1437
	s_barrier

.LBB0_1513:
	s_add_u32 s74, s48, 0x100
	s_addc_u32 s75, s49, 0
	s_mov_b32 s76, -2
	ds_read_b128 v[152:155], v149
	ds_read_b128 v[156:159], v149 offset:1024
	ds_read_b128 v[160:163], v149 offset:2048
	ds_read_b128 v[164:167], v149 offset:3072
	ds_read_b128 v[168:171], v150
	ds_read_b128 v[172:175], v150 offset:1024
	ds_read_b128 v[176:179], v150 offset:2048
	ds_read_b128 v[184:187], v150 offset:3072
	s_add_u32 s48, s46, 0x100
	s_addc_u32 s49, s47, 0
	s_cmp_eq_u32 s76, 40
	s_cselect_b32 s53, s9, s49
	s_cselect_b32 s52, s8, s48
	s_cselect_b32 s51, s45, s75
	s_cselect_b32 s50, s44, s74
	v_lshl_add_u64 v[144:145], s[46:47], 0, v[136:137]
	s_add_i32 m0, s57, 0xc000
	ds_read_b128 v[188:191], v151
	ds_read_b128 v[192:195], v151 offset:1024
	ds_read_b128 v[196:199], v151 offset:2048
	ds_read_b128 v[200:203], v151 offset:3072
	ds_read_b128 v[204:207], v151 offset:4096
	ds_read_b128 v[208:211], v151 offset:5120
	ds_read_b128 v[212:215], v151 offset:6144
	ds_read_b128 v[216:219], v151 offset:7168
	global_load_lds_dwordx4 v[144:145], off
	v_lshl_add_u64 v[144:145], s[46:47], 0, v[138:139]
	s_add_i32 m0, s57, 0xe000
	s_nop 0
	global_load_lds_dwordx4 v[144:145], off
	s_waitcnt vmcnt(8)
	s_waitcnt lgkmcnt(0)
	s_barrier
	s_waitcnt lgkmcnt(0)
	v_mfma_f32_16x16x32_bf16 v[124:127], v[152:155], v[188:191], 0
	v_mfma_f32_16x16x32_bf16 v[124:127], v[156:159], v[192:195], v[124:127]
	v_mfma_f32_16x16x32_bf16 v[120:123], v[160:163], v[188:191], 0
	v_mfma_f32_16x16x32_bf16 v[120:123], v[164:167], v[192:195], v[120:123]
	s_setprio 1
	v_mfma_f32_16x16x32_bf16 v[116:119], v[152:155], v[196:199], 0
	v_mfma_f32_16x16x32_bf16 v[116:119], v[156:159], v[200:203], v[116:119]
	v_mfma_f32_16x16x32_bf16 v[108:111], v[160:163], v[196:199], 0
	v_mfma_f32_16x16x32_bf16 v[108:111], v[164:167], v[200:203], v[108:111]
	v_mfma_f32_16x16x32_bf16 v[100:103], v[152:155], v[204:207], 0
	v_mfma_f32_16x16x32_bf16 v[100:103], v[156:159], v[208:211], v[100:103]
	v_mfma_f32_16x16x32_bf16 v[92:95], v[160:163], v[204:207], 0
	v_mfma_f32_16x16x32_bf16 v[92:95], v[164:167], v[208:211], v[92:95]
	v_mfma_f32_16x16x32_bf16 v[84:87], v[152:155], v[212:215], 0
	v_mfma_f32_16x16x32_bf16 v[84:87], v[156:159], v[216:219], v[84:87]
	v_mfma_f32_16x16x32_bf16 v[76:79], v[160:163], v[212:215], 0
	v_mfma_f32_16x16x32_bf16 v[76:79], v[164:167], v[216:219], v[76:79]
	v_mfma_f32_16x16x32_bf16 v[112:115], v[168:171], v[188:191], 0
	v_mfma_f32_16x16x32_bf16 v[112:115], v[172:175], v[192:195], v[112:115]
	v_mfma_f32_16x16x32_bf16 v[104:107], v[176:179], v[188:191], 0
	v_mfma_f32_16x16x32_bf16 v[104:107], v[184:187], v[192:195], v[104:107]
	v_mfma_f32_16x16x32_bf16 v[96:99], v[168:171], v[196:199], 0
	v_mfma_f32_16x16x32_bf16 v[96:99], v[172:175], v[200:203], v[96:99]
	v_mfma_f32_16x16x32_bf16 v[88:91], v[176:179], v[196:199], 0
	v_mfma_f32_16x16x32_bf16 v[88:91], v[184:187], v[200:203], v[88:91]
	v_mfma_f32_16x16x32_bf16 v[80:83], v[168:171], v[204:207], 0
	v_mfma_f32_16x16x32_bf16 v[80:83], v[172:175], v[208:211], v[80:83]
	v_mfma_f32_16x16x32_bf16 v[72:75], v[176:179], v[204:207], 0
	v_mfma_f32_16x16x32_bf16 v[72:75], v[184:187], v[208:211], v[72:75]
	s_barrier
	v_mfma_f32_16x16x32_bf16 v[68:71], v[168:171], v[212:215], 0
	v_mfma_f32_16x16x32_bf16 v[68:71], v[172:175], v[216:219], v[68:71]
	v_mfma_f32_16x16x32_bf16 v[64:67], v[176:179], v[212:215], 0
	v_mfma_f32_16x16x32_bf16 v[64:67], v[184:187], v[216:219], v[64:67]
	s_setprio 0
	s_add_i32 s46, s64, s56
	v_lshl_add_u64 v[144:145], s[50:51], 0, v[130:131]
	s_mov_b32 m0, s46
	ds_read_b128 v[188:191], v151 offset:16384
	ds_read_b128 v[192:195], v151 offset:17408
	ds_read_b128 v[196:199], v151 offset:18432
	ds_read_b128 v[200:203], v151 offset:19456
	ds_read_b128 v[204:207], v151 offset:20480
	ds_read_b128 v[208:211], v151 offset:21504
	ds_read_b128 v[212:215], v151 offset:22528
	ds_read_b128 v[216:219], v151 offset:23552
	global_load_lds_dwordx4 v[144:145], off
	s_add_i32 m0, s46, 0x2000
	s_add_u32 s46, s50, 0xb0000
	v_lshl_add_u64 v[220:221], s[50:51], 0, v[134:135]
	s_addc_u32 s47, s51, 0
	s_add_i32 s77, s65, s56
	global_load_lds_dwordx4 v[220:221], off
	v_lshl_add_u64 v[222:223], s[46:47], 0, v[130:131]
	s_mov_b32 m0, s77
	v_lshl_add_u64 v[224:225], s[52:53], 0, v[132:133]
	global_load_lds_dwordx4 v[222:223], off
	v_lshl_add_u64 v[222:223], s[46:47], 0, v[134:135]
	s_add_i32 m0, s77, 0x2000
	s_nop 0
	global_load_lds_dwordx4 v[222:223], off
	v_lshl_add_u64 v[222:223], s[52:53], 0, v[128:129]
	s_mov_b32 m0, s57
	s_nop 0
	global_load_lds_dwordx4 v[222:223], off
	s_mov_b32 m0, s58
	s_nop 0
	global_load_lds_dwordx4 v[224:225], off
	s_waitcnt vmcnt(8)
	s_waitcnt lgkmcnt(0)
	s_barrier
	s_waitcnt lgkmcnt(0)
	v_mfma_f32_16x16x32_bf16 v[60:63], v[152:155], v[188:191], 0
	v_mfma_f32_16x16x32_bf16 v[60:63], v[156:159], v[192:195], v[60:63]
	v_mfma_f32_16x16x32_bf16 v[56:59], v[160:163], v[188:191], 0
	v_mfma_f32_16x16x32_bf16 v[56:59], v[164:167], v[192:195], v[56:59]
	s_setprio 1
	v_mfma_f32_16x16x32_bf16 v[52:55], v[152:155], v[196:199], 0
	v_mfma_f32_16x16x32_bf16 v[52:55], v[156:159], v[200:203], v[52:55]
	v_mfma_f32_16x16x32_bf16 v[44:47], v[160:163], v[196:199], 0
	v_mfma_f32_16x16x32_bf16 v[44:47], v[164:167], v[200:203], v[44:47]
	v_mfma_f32_16x16x32_bf16 v[36:39], v[152:155], v[204:207], 0
	v_mfma_f32_16x16x32_bf16 v[36:39], v[156:159], v[208:211], v[36:39]
	v_mfma_f32_16x16x32_bf16 v[28:31], v[160:163], v[204:207], 0
	v_mfma_f32_16x16x32_bf16 v[28:31], v[164:167], v[208:211], v[28:31]
	v_mfma_f32_16x16x32_bf16 v[20:23], v[152:155], v[212:215], 0
	v_mfma_f32_16x16x32_bf16 v[20:23], v[156:159], v[216:219], v[20:23]
	v_mfma_f32_16x16x32_bf16 v[12:15], v[160:163], v[212:215], 0
	v_mfma_f32_16x16x32_bf16 v[12:15], v[164:167], v[216:219], v[12:15]
	v_mfma_f32_16x16x32_bf16 v[48:51], v[168:171], v[188:191], 0
	v_mfma_f32_16x16x32_bf16 v[48:51], v[172:175], v[192:195], v[48:51]
	v_mfma_f32_16x16x32_bf16 v[40:43], v[176:179], v[188:191], 0
	v_mfma_f32_16x16x32_bf16 v[40:43], v[184:187], v[192:195], v[40:43]
	v_mfma_f32_16x16x32_bf16 v[32:35], v[168:171], v[196:199], 0
	v_mfma_f32_16x16x32_bf16 v[32:35], v[172:175], v[200:203], v[32:35]
	v_mfma_f32_16x16x32_bf16 v[24:27], v[176:179], v[196:199], 0
	v_mfma_f32_16x16x32_bf16 v[24:27], v[184:187], v[200:203], v[24:27]
	v_mfma_f32_16x16x32_bf16 v[16:19], v[168:171], v[204:207], 0
	v_mfma_f32_16x16x32_bf16 v[16:19], v[172:175], v[208:211], v[16:19]
	v_mfma_f32_16x16x32_bf16 v[8:11], v[176:179], v[204:207], 0
	v_mfma_f32_16x16x32_bf16 v[8:11], v[184:187], v[208:211], v[8:11]
	s_barrier
	v_mfma_f32_16x16x32_bf16 v[4:7], v[168:171], v[212:215], 0
	v_mfma_f32_16x16x32_bf16 v[4:7], v[172:175], v[216:219], v[4:7]
	v_mfma_f32_16x16x32_bf16 v[0:3], v[176:179], v[212:215], 0
	v_mfma_f32_16x16x32_bf16 v[0:3], v[184:187], v[216:219], v[0:3]
	s_setprio 0
	s_branch .Lmid_gemm12
.LBB0_1514:
	ds_read_b128 v[152:155], v149
	ds_read_b128 v[156:159], v149 offset:1024
	ds_read_b128 v[160:163], v149 offset:2048
	ds_read_b128 v[164:167], v149 offset:3072
	ds_read_b128 v[168:171], v150
	ds_read_b128 v[172:175], v150 offset:1024
	ds_read_b128 v[176:179], v150 offset:2048
	ds_read_b128 v[184:187], v150 offset:3072
	s_add_u32 s48, s46, 0x100
	s_addc_u32 s49, s47, 0
	s_cmp_eq_u32 s76, 40
	s_cselect_b32 s53, s9, s49
	s_cselect_b32 s52, s8, s48
	s_cselect_b32 s51, s45, s75
	s_cselect_b32 s50, s44, s74
	v_lshl_add_u64 v[144:145], s[46:47], 0, v[136:137]
	s_add_i32 m0, s57, 0xc000
	ds_read_b128 v[188:191], v151
	ds_read_b128 v[192:195], v151 offset:1024
	ds_read_b128 v[196:199], v151 offset:2048
	ds_read_b128 v[200:203], v151 offset:3072
	ds_read_b128 v[204:207], v151 offset:4096
	ds_read_b128 v[208:211], v151 offset:5120
	ds_read_b128 v[212:215], v151 offset:6144
	ds_read_b128 v[216:219], v151 offset:7168
	global_load_lds_dwordx4 v[144:145], off
	v_lshl_add_u64 v[144:145], s[46:47], 0, v[138:139]
	s_add_i32 m0, s57, 0xe000
	s_nop 0
	global_load_lds_dwordx4 v[144:145], off
	s_waitcnt vmcnt(8)
	s_waitcnt lgkmcnt(0)
	s_barrier
	s_waitcnt lgkmcnt(0)
	v_mfma_f32_16x16x32_bf16 v[124:127], v[152:155], v[188:191], v[124:127]
	v_mfma_f32_16x16x32_bf16 v[124:127], v[156:159], v[192:195], v[124:127]
	v_mfma_f32_16x16x32_bf16 v[120:123], v[160:163], v[188:191], v[120:123]
	v_mfma_f32_16x16x32_bf16 v[120:123], v[164:167], v[192:195], v[120:123]
	s_setprio 1
	v_mfma_f32_16x16x32_bf16 v[116:119], v[152:155], v[196:199], v[116:119]
	v_mfma_f32_16x16x32_bf16 v[116:119], v[156:159], v[200:203], v[116:119]
	v_mfma_f32_16x16x32_bf16 v[108:111], v[160:163], v[196:199], v[108:111]
	v_mfma_f32_16x16x32_bf16 v[108:111], v[164:167], v[200:203], v[108:111]
	v_mfma_f32_16x16x32_bf16 v[100:103], v[152:155], v[204:207], v[100:103]
	v_mfma_f32_16x16x32_bf16 v[100:103], v[156:159], v[208:211], v[100:103]
	v_mfma_f32_16x16x32_bf16 v[92:95], v[160:163], v[204:207], v[92:95]
	v_mfma_f32_16x16x32_bf16 v[92:95], v[164:167], v[208:211], v[92:95]
	v_mfma_f32_16x16x32_bf16 v[84:87], v[152:155], v[212:215], v[84:87]
	v_mfma_f32_16x16x32_bf16 v[84:87], v[156:159], v[216:219], v[84:87]
	v_mfma_f32_16x16x32_bf16 v[76:79], v[160:163], v[212:215], v[76:79]
	v_mfma_f32_16x16x32_bf16 v[76:79], v[164:167], v[216:219], v[76:79]
	v_mfma_f32_16x16x32_bf16 v[112:115], v[168:171], v[188:191], v[112:115]
	v_mfma_f32_16x16x32_bf16 v[112:115], v[172:175], v[192:195], v[112:115]
	v_mfma_f32_16x16x32_bf16 v[104:107], v[176:179], v[188:191], v[104:107]
	v_mfma_f32_16x16x32_bf16 v[104:107], v[184:187], v[192:195], v[104:107]
	v_mfma_f32_16x16x32_bf16 v[96:99], v[168:171], v[196:199], v[96:99]
	v_mfma_f32_16x16x32_bf16 v[96:99], v[172:175], v[200:203], v[96:99]
	v_mfma_f32_16x16x32_bf16 v[88:91], v[176:179], v[196:199], v[88:91]
	v_mfma_f32_16x16x32_bf16 v[88:91], v[184:187], v[200:203], v[88:91]
	v_mfma_f32_16x16x32_bf16 v[80:83], v[168:171], v[204:207], v[80:83]
	v_mfma_f32_16x16x32_bf16 v[80:83], v[172:175], v[208:211], v[80:83]
	v_mfma_f32_16x16x32_bf16 v[72:75], v[176:179], v[204:207], v[72:75]
	v_mfma_f32_16x16x32_bf16 v[72:75], v[184:187], v[208:211], v[72:75]
	s_barrier
	v_mfma_f32_16x16x32_bf16 v[68:71], v[168:171], v[212:215], v[68:71]
	v_mfma_f32_16x16x32_bf16 v[68:71], v[172:175], v[216:219], v[68:71]
	v_mfma_f32_16x16x32_bf16 v[64:67], v[176:179], v[212:215], v[64:67]
	v_mfma_f32_16x16x32_bf16 v[64:67], v[184:187], v[216:219], v[64:67]
	s_setprio 0
	s_add_i32 s46, s64, s56
	v_lshl_add_u64 v[144:145], s[50:51], 0, v[130:131]
	s_mov_b32 m0, s46
	ds_read_b128 v[188:191], v151 offset:16384
	ds_read_b128 v[192:195], v151 offset:17408
	ds_read_b128 v[196:199], v151 offset:18432
	ds_read_b128 v[200:203], v151 offset:19456
	ds_read_b128 v[204:207], v151 offset:20480
	ds_read_b128 v[208:211], v151 offset:21504
	ds_read_b128 v[212:215], v151 offset:22528
	ds_read_b128 v[216:219], v151 offset:23552
	global_load_lds_dwordx4 v[144:145], off
	s_add_i32 m0, s46, 0x2000
	s_add_u32 s46, s50, 0xb0000
	v_lshl_add_u64 v[220:221], s[50:51], 0, v[134:135]
	s_addc_u32 s47, s51, 0
	s_add_i32 s77, s65, s56
	global_load_lds_dwordx4 v[220:221], off
	v_lshl_add_u64 v[222:223], s[46:47], 0, v[130:131]
	s_mov_b32 m0, s77
	v_lshl_add_u64 v[224:225], s[52:53], 0, v[132:133]
	global_load_lds_dwordx4 v[222:223], off
	v_lshl_add_u64 v[222:223], s[46:47], 0, v[134:135]
	s_add_i32 m0, s77, 0x2000
	s_nop 0
	global_load_lds_dwordx4 v[222:223], off
	v_lshl_add_u64 v[222:223], s[52:53], 0, v[128:129]
	s_mov_b32 m0, s57
	s_nop 0
	global_load_lds_dwordx4 v[222:223], off
	s_mov_b32 m0, s58
	s_nop 0
	global_load_lds_dwordx4 v[224:225], off
	s_waitcnt vmcnt(8)
	s_waitcnt lgkmcnt(0)
	s_barrier
	s_waitcnt lgkmcnt(0)
	v_mfma_f32_16x16x32_bf16 v[60:63], v[152:155], v[188:191], v[60:63]
	v_mfma_f32_16x16x32_bf16 v[60:63], v[156:159], v[192:195], v[60:63]
	v_mfma_f32_16x16x32_bf16 v[56:59], v[160:163], v[188:191], v[56:59]
	v_mfma_f32_16x16x32_bf16 v[56:59], v[164:167], v[192:195], v[56:59]
	s_setprio 1
	v_mfma_f32_16x16x32_bf16 v[52:55], v[152:155], v[196:199], v[52:55]
	v_mfma_f32_16x16x32_bf16 v[52:55], v[156:159], v[200:203], v[52:55]
	v_mfma_f32_16x16x32_bf16 v[44:47], v[160:163], v[196:199], v[44:47]
	v_mfma_f32_16x16x32_bf16 v[44:47], v[164:167], v[200:203], v[44:47]
	v_mfma_f32_16x16x32_bf16 v[36:39], v[152:155], v[204:207], v[36:39]
	v_mfma_f32_16x16x32_bf16 v[36:39], v[156:159], v[208:211], v[36:39]
	v_mfma_f32_16x16x32_bf16 v[28:31], v[160:163], v[204:207], v[28:31]
	v_mfma_f32_16x16x32_bf16 v[28:31], v[164:167], v[208:211], v[28:31]
	v_mfma_f32_16x16x32_bf16 v[20:23], v[152:155], v[212:215], v[20:23]
	v_mfma_f32_16x16x32_bf16 v[20:23], v[156:159], v[216:219], v[20:23]
	v_mfma_f32_16x16x32_bf16 v[12:15], v[160:163], v[212:215], v[12:15]
	v_mfma_f32_16x16x32_bf16 v[12:15], v[164:167], v[216:219], v[12:15]
	v_mfma_f32_16x16x32_bf16 v[48:51], v[168:171], v[188:191], v[48:51]
	v_mfma_f32_16x16x32_bf16 v[48:51], v[172:175], v[192:195], v[48:51]
	v_mfma_f32_16x16x32_bf16 v[40:43], v[176:179], v[188:191], v[40:43]
	v_mfma_f32_16x16x32_bf16 v[40:43], v[184:187], v[192:195], v[40:43]
	v_mfma_f32_16x16x32_bf16 v[32:35], v[168:171], v[196:199], v[32:35]
	v_mfma_f32_16x16x32_bf16 v[32:35], v[172:175], v[200:203], v[32:35]
	v_mfma_f32_16x16x32_bf16 v[24:27], v[176:179], v[196:199], v[24:27]
	v_mfma_f32_16x16x32_bf16 v[24:27], v[184:187], v[200:203], v[24:27]
	v_mfma_f32_16x16x32_bf16 v[16:19], v[168:171], v[204:207], v[16:19]
	v_mfma_f32_16x16x32_bf16 v[16:19], v[172:175], v[208:211], v[16:19]
	v_mfma_f32_16x16x32_bf16 v[8:11], v[176:179], v[204:207], v[8:11]
	v_mfma_f32_16x16x32_bf16 v[8:11], v[184:187], v[208:211], v[8:11]
	s_barrier
	v_mfma_f32_16x16x32_bf16 v[4:7], v[168:171], v[212:215], v[4:7]
	v_mfma_f32_16x16x32_bf16 v[4:7], v[172:175], v[216:219], v[4:7]
	v_mfma_f32_16x16x32_bf16 v[0:3], v[176:179], v[212:215], v[0:3]
	v_mfma_f32_16x16x32_bf16 v[0:3], v[184:187], v[216:219], v[0:3]
	s_setprio 0
.Lmid_gemm12:
	s_add_i32 s77, 0, 0x18000
	s_add_i32 s79, 0, 0x1c000
	v_add_u32_e32 v164, s77, v147
	v_add_u32_e32 v181, s79, v147
	ds_read_b128 v[152:155], v164
	ds_read_b128 v[156:159], v164 offset:1024
	ds_read_b128 v[160:163], v164 offset:2048
	ds_read_b128 v[164:167], v164 offset:3072
	ds_read_b128 v[168:171], v181
	ds_read_b128 v[172:175], v181 offset:1024
	ds_read_b128 v[176:179], v181 offset:2048
	ds_read_b128 v[184:187], v181 offset:3072
	s_add_u32 s46, s52, 0xb0000
	s_addc_u32 s47, s53, 0
	s_mov_b32 m0, s59
	v_lshl_add_u64 v[226:227], s[46:47], 0, v[128:129]
	ds_read_b128 v[188:191], v151 offset:32768
	ds_read_b128 v[192:195], v151 offset:33792
	ds_read_b128 v[196:199], v151 offset:34816
	ds_read_b128 v[200:203], v151 offset:35840
	ds_read_b128 v[204:207], v151 offset:36864
	ds_read_b128 v[208:211], v151 offset:37888
	ds_read_b128 v[212:215], v151 offset:38912
	ds_read_b128 v[216:219], v151 offset:39936
	global_load_lds_dwordx4 v[226:227], off
	v_lshl_add_u64 v[226:227], s[46:47], 0, v[132:133]
	s_mov_b32 m0, s60
	s_nop 0
	global_load_lds_dwordx4 v[226:227], off
	s_waitcnt vmcnt(8)
	s_waitcnt lgkmcnt(0)
	s_barrier
	s_waitcnt lgkmcnt(0)
	v_mfma_f32_16x16x32_bf16 v[124:127], v[152:155], v[188:191], v[124:127]
	v_mfma_f32_16x16x32_bf16 v[124:127], v[156:159], v[192:195], v[124:127]
	v_mfma_f32_16x16x32_bf16 v[120:123], v[160:163], v[188:191], v[120:123]
	v_mfma_f32_16x16x32_bf16 v[120:123], v[164:167], v[192:195], v[120:123]
	s_setprio 1
	v_mfma_f32_16x16x32_bf16 v[116:119], v[152:155], v[196:199], v[116:119]
	v_mfma_f32_16x16x32_bf16 v[116:119], v[156:159], v[200:203], v[116:119]
	v_mfma_f32_16x16x32_bf16 v[108:111], v[160:163], v[196:199], v[108:111]
	v_mfma_f32_16x16x32_bf16 v[108:111], v[164:167], v[200:203], v[108:111]
	v_mfma_f32_16x16x32_bf16 v[100:103], v[152:155], v[204:207], v[100:103]
	v_mfma_f32_16x16x32_bf16 v[100:103], v[156:159], v[208:211], v[100:103]
	v_mfma_f32_16x16x32_bf16 v[92:95], v[160:163], v[204:207], v[92:95]
	v_mfma_f32_16x16x32_bf16 v[92:95], v[164:167], v[208:211], v[92:95]
	v_mfma_f32_16x16x32_bf16 v[84:87], v[152:155], v[212:215], v[84:87]
	v_mfma_f32_16x16x32_bf16 v[84:87], v[156:159], v[216:219], v[84:87]
	v_mfma_f32_16x16x32_bf16 v[76:79], v[160:163], v[212:215], v[76:79]
	v_mfma_f32_16x16x32_bf16 v[76:79], v[164:167], v[216:219], v[76:79]
	v_mfma_f32_16x16x32_bf16 v[112:115], v[168:171], v[188:191], v[112:115]
	v_mfma_f32_16x16x32_bf16 v[112:115], v[172:175], v[192:195], v[112:115]
	v_mfma_f32_16x16x32_bf16 v[104:107], v[176:179], v[188:191], v[104:107]
	v_mfma_f32_16x16x32_bf16 v[104:107], v[184:187], v[192:195], v[104:107]
	v_mfma_f32_16x16x32_bf16 v[96:99], v[168:171], v[196:199], v[96:99]
	v_mfma_f32_16x16x32_bf16 v[96:99], v[172:175], v[200:203], v[96:99]
	v_mfma_f32_16x16x32_bf16 v[88:91], v[176:179], v[196:199], v[88:91]
	v_mfma_f32_16x16x32_bf16 v[88:91], v[184:187], v[200:203], v[88:91]
	v_mfma_f32_16x16x32_bf16 v[80:83], v[168:171], v[204:207], v[80:83]
	v_mfma_f32_16x16x32_bf16 v[80:83], v[172:175], v[208:211], v[80:83]
	v_mfma_f32_16x16x32_bf16 v[72:75], v[176:179], v[204:207], v[72:75]
	v_mfma_f32_16x16x32_bf16 v[72:75], v[184:187], v[208:211], v[72:75]
	s_barrier
	v_mfma_f32_16x16x32_bf16 v[68:71], v[168:171], v[212:215], v[68:71]
	v_mfma_f32_16x16x32_bf16 v[68:71], v[172:175], v[216:219], v[68:71]
	v_mfma_f32_16x16x32_bf16 v[64:67], v[176:179], v[212:215], v[64:67]
	v_mfma_f32_16x16x32_bf16 v[64:67], v[184:187], v[216:219], v[64:67]
	s_setprio 0
	s_add_i32 s46, s77, s56
	v_lshl_add_u64 v[144:145], v[144:145], 0, s[10:11]
	s_mov_b32 m0, s46
	ds_read_b128 v[188:191], v151 offset:49152
	ds_read_b128 v[192:195], v151 offset:50176
	ds_read_b128 v[196:199], v151 offset:51200
	ds_read_b128 v[200:203], v151 offset:52224
	ds_read_b128 v[204:207], v151 offset:53248
	ds_read_b128 v[208:211], v151 offset:54272
	ds_read_b128 v[212:215], v151 offset:55296
	ds_read_b128 v[216:219], v151 offset:56320
	global_load_lds_dwordx4 v[144:145], off
	s_add_i32 m0, s46, 0x2000
	s_add_u32 s46, s50, 0xb0080
	v_lshl_add_u64 v[144:145], v[220:221], 0, s[10:11]
	s_addc_u32 s47, s51, 0
	s_add_i32 s50, s79, s56
	global_load_lds_dwordx4 v[144:145], off
	v_lshl_add_u64 v[144:145], s[46:47], 0, v[130:131]
	s_mov_b32 m0, s50
	s_nop 0
	global_load_lds_dwordx4 v[144:145], off
	v_lshl_add_u64 v[144:145], s[46:47], 0, v[134:135]
	s_add_i32 m0, s50, 0x2000
	s_nop 0
	global_load_lds_dwordx4 v[144:145], off
	v_lshl_add_u64 v[144:145], v[222:223], 0, s[10:11]
	s_mov_b32 m0, s62
	s_nop 0
	global_load_lds_dwordx4 v[144:145], off
	v_lshl_add_u64 v[144:145], v[224:225], 0, s[10:11]
	s_mov_b32 m0, s63
	s_nop 0
	global_load_lds_dwordx4 v[144:145], off
	s_waitcnt vmcnt(8)
	s_waitcnt lgkmcnt(0)
	s_barrier
	s_waitcnt lgkmcnt(0)
	v_mfma_f32_16x16x32_bf16 v[60:63], v[152:155], v[188:191], v[60:63]
	v_mfma_f32_16x16x32_bf16 v[60:63], v[156:159], v[192:195], v[60:63]
	v_mfma_f32_16x16x32_bf16 v[56:59], v[160:163], v[188:191], v[56:59]
	v_mfma_f32_16x16x32_bf16 v[56:59], v[164:167], v[192:195], v[56:59]
	s_setprio 1
	v_mfma_f32_16x16x32_bf16 v[52:55], v[152:155], v[196:199], v[52:55]
	v_mfma_f32_16x16x32_bf16 v[52:55], v[156:159], v[200:203], v[52:55]
	v_mfma_f32_16x16x32_bf16 v[44:47], v[160:163], v[196:199], v[44:47]
	v_mfma_f32_16x16x32_bf16 v[44:47], v[164:167], v[200:203], v[44:47]
	v_mfma_f32_16x16x32_bf16 v[36:39], v[152:155], v[204:207], v[36:39]
	v_mfma_f32_16x16x32_bf16 v[36:39], v[156:159], v[208:211], v[36:39]
	v_mfma_f32_16x16x32_bf16 v[28:31], v[160:163], v[204:207], v[28:31]
	v_mfma_f32_16x16x32_bf16 v[28:31], v[164:167], v[208:211], v[28:31]
	v_mfma_f32_16x16x32_bf16 v[20:23], v[152:155], v[212:215], v[20:23]
	v_mfma_f32_16x16x32_bf16 v[20:23], v[156:159], v[216:219], v[20:23]
	v_mfma_f32_16x16x32_bf16 v[12:15], v[160:163], v[212:215], v[12:15]
	v_mfma_f32_16x16x32_bf16 v[12:15], v[164:167], v[216:219], v[12:15]
	v_mfma_f32_16x16x32_bf16 v[48:51], v[168:171], v[188:191], v[48:51]
	v_mfma_f32_16x16x32_bf16 v[48:51], v[172:175], v[192:195], v[48:51]
	v_mfma_f32_16x16x32_bf16 v[40:43], v[176:179], v[188:191], v[40:43]
	v_mfma_f32_16x16x32_bf16 v[40:43], v[184:187], v[192:195], v[40:43]
	v_mfma_f32_16x16x32_bf16 v[32:35], v[168:171], v[196:199], v[32:35]
	v_mfma_f32_16x16x32_bf16 v[32:35], v[172:175], v[200:203], v[32:35]
	v_mfma_f32_16x16x32_bf16 v[24:27], v[176:179], v[196:199], v[24:27]
	v_mfma_f32_16x16x32_bf16 v[24:27], v[184:187], v[200:203], v[24:27]
	v_mfma_f32_16x16x32_bf16 v[16:19], v[168:171], v[204:207], v[16:19]
	v_mfma_f32_16x16x32_bf16 v[16:19], v[172:175], v[208:211], v[16:19]
	v_mfma_f32_16x16x32_bf16 v[8:11], v[176:179], v[204:207], v[8:11]
	v_mfma_f32_16x16x32_bf16 v[8:11], v[184:187], v[208:211], v[8:11]
	s_barrier
	v_mfma_f32_16x16x32_bf16 v[4:7], v[168:171], v[212:215], v[4:7]
	v_mfma_f32_16x16x32_bf16 v[4:7], v[172:175], v[216:219], v[4:7]
	v_mfma_f32_16x16x32_bf16 v[0:3], v[176:179], v[212:215], v[0:3]
	v_mfma_f32_16x16x32_bf16 v[0:3], v[184:187], v[216:219], v[0:3]
	s_setprio 0
	s_add_i32 s76, s76, 2
	s_add_u32 s74, s74, 0x100
	s_addc_u32 s75, s75, 0
	s_cmp_gt_u32 s76, 41
	s_mov_b64 s[46:47], s[48:49]
	s_cbranch_scc0 .LBB0_1514
	s_and_b64 vcc, exec, s[12:13]
	s_cbranch_vccz .LBB0_1517
	s_barrier
